# M3 stage D RMS-norm loop rewritten: pipelined row loads (4 rows in flight), DPP reduce, gains hoisted
# speedup vs baseline: 1.0105x; 1.0105x over previous
.LBB0_430:
	v_lshlrev_b32_e32 v15, 4, v242
	ds_write_b128 v15, v[44:47]
	ds_write_b128 v15, v[48:51] offset:8192
	ds_write_b128 v15, v[52:55] offset:16384
	ds_write_b128 v15, v[56:59] offset:24576
	ds_write_b128 v15, v[60:63] offset:32768
	ds_write_b128 v15, v[64:67] offset:40960
	s_mov_b64 s[4:5], 0x16a00000
	s_mov_b64 s[100:101], 0x1000
	v_lshl_add_u64 v[2:3], v[0:1], 0, s[4:5]
	v_lshl_add_u64 v[4:5], v[0:1], 0, s[4:5]
	global_load_dwordx4 v[16:19], v[106:107], off
	global_load_dwordx4 v[20:23], v[106:107], off offset:16
	global_load_dwordx4 v[24:27], v[106:107], off offset:32
	global_load_dwordx4 v[28:31], v[106:107], off offset:48
	s_waitcnt lgkmcnt(0)
	global_load_dwordx4 v[32:35], v[2:3], off
	global_load_dwordx4 v[36:39], v[2:3], off offset:16
	global_load_dwordx4 v[44:47], v[2:3], off offset:2048
	global_load_dwordx4 v[48:51], v[2:3], off offset:2064
	v_lshl_add_u64 v[2:3], v[2:3], 0, s[100:101]
	global_load_dwordx4 v[52:55], v[2:3], off
	global_load_dwordx4 v[56:59], v[2:3], off offset:16
	global_load_dwordx4 v[60:63], v[2:3], off offset:2048
	global_load_dwordx4 v[64:67], v[2:3], off offset:2064
	v_lshl_add_u64 v[2:3], v[2:3], 0, s[100:101]
	s_waitcnt vmcnt(4)
	v_lshlrev_b32_e32 v6, 16, v32
	v_and_b32_e32 v7, 0xffff0000, v32
	v_pk_mul_f32 v[8:9], v[6:7], v[6:7]
	v_lshlrev_b32_e32 v40, 16, v44
	v_and_b32_e32 v41, 0xffff0000, v44
	v_pk_mul_f32 v[250:251], v[40:41], v[40:41]
	v_lshlrev_b32_e32 v6, 16, v33
	v_and_b32_e32 v7, 0xffff0000, v33
	v_pk_fma_f32 v[8:9], v[6:7], v[6:7], v[8:9]
	v_lshlrev_b32_e32 v40, 16, v45
	v_and_b32_e32 v41, 0xffff0000, v45
	v_pk_fma_f32 v[250:251], v[40:41], v[40:41], v[250:251]
	v_lshlrev_b32_e32 v6, 16, v34
	v_and_b32_e32 v7, 0xffff0000, v34
	v_pk_fma_f32 v[8:9], v[6:7], v[6:7], v[8:9]
	v_lshlrev_b32_e32 v40, 16, v46
	v_and_b32_e32 v41, 0xffff0000, v46
	v_pk_fma_f32 v[250:251], v[40:41], v[40:41], v[250:251]
	v_lshlrev_b32_e32 v6, 16, v35
	v_and_b32_e32 v7, 0xffff0000, v35
	v_pk_fma_f32 v[8:9], v[6:7], v[6:7], v[8:9]
	v_lshlrev_b32_e32 v40, 16, v47
	v_and_b32_e32 v41, 0xffff0000, v47
	v_pk_fma_f32 v[250:251], v[40:41], v[40:41], v[250:251]
	v_lshlrev_b32_e32 v6, 16, v36
	v_and_b32_e32 v7, 0xffff0000, v36
	v_pk_fma_f32 v[8:9], v[6:7], v[6:7], v[8:9]
	v_lshlrev_b32_e32 v40, 16, v48
	v_and_b32_e32 v41, 0xffff0000, v48
	v_pk_fma_f32 v[250:251], v[40:41], v[40:41], v[250:251]
	v_lshlrev_b32_e32 v6, 16, v37
	v_and_b32_e32 v7, 0xffff0000, v37
	v_pk_fma_f32 v[8:9], v[6:7], v[6:7], v[8:9]
	v_lshlrev_b32_e32 v40, 16, v49
	v_and_b32_e32 v41, 0xffff0000, v49
	v_pk_fma_f32 v[250:251], v[40:41], v[40:41], v[250:251]
	v_lshlrev_b32_e32 v6, 16, v38
	v_and_b32_e32 v7, 0xffff0000, v38
	v_pk_fma_f32 v[8:9], v[6:7], v[6:7], v[8:9]
	v_lshlrev_b32_e32 v40, 16, v50
	v_and_b32_e32 v41, 0xffff0000, v50
	v_pk_fma_f32 v[250:251], v[40:41], v[40:41], v[250:251]
	v_lshlrev_b32_e32 v6, 16, v39
	v_and_b32_e32 v7, 0xffff0000, v39
	v_pk_fma_f32 v[8:9], v[6:7], v[6:7], v[8:9]
	v_lshlrev_b32_e32 v40, 16, v51
	v_and_b32_e32 v41, 0xffff0000, v51
	v_pk_fma_f32 v[250:251], v[40:41], v[40:41], v[250:251]
	v_add_f32_e32 v8, v8, v9
	v_add_f32_e32 v250, v250, v251
	s_nop 1
	v_add_f32_dpp v8, v8, v8 quad_perm:[1,0,3,2] row_mask:0xf bank_mask:0xf
	v_add_f32_dpp v250, v250, v250 quad_perm:[1,0,3,2] row_mask:0xf bank_mask:0xf
	s_nop 1
	v_add_f32_dpp v8, v8, v8 quad_perm:[2,3,0,1] row_mask:0xf bank_mask:0xf
	v_add_f32_dpp v250, v250, v250 quad_perm:[2,3,0,1] row_mask:0xf bank_mask:0xf
	s_nop 1
	v_add_f32_dpp v8, v8, v8 row_half_mirror row_mask:0xf bank_mask:0xf
	v_add_f32_dpp v250, v250, v250 row_half_mirror row_mask:0xf bank_mask:0xf
	s_nop 1
	v_add_f32_dpp v8, v8, v8 row_mirror row_mask:0xf bank_mask:0xf
	v_add_f32_dpp v250, v250, v250 row_mirror row_mask:0xf bank_mask:0xf
	s_nop 1
	ds_bpermute_b32 v6, v14, v8
	ds_bpermute_b32 v40, v14, v250
	s_waitcnt lgkmcnt(0)
	v_add_f32_e32 v6, v8, v6
	v_mul_f32_e32 v6, 0x3b000000, v6
	v_mul_f32_e32 v8, 0x3b800000, v8
	v_cndmask_b32_e64 v8, v8, v6, s[6:7]
	v_add_f32_e32 v8, 0x358637bd, v8
	v_rsq_f32_e32 v252, v8
	v_add_f32_e32 v40, v250, v40
	v_mul_f32_e32 v40, 0x3b000000, v40
	v_mul_f32_e32 v250, 0x3b800000, v250
	v_cndmask_b32_e64 v250, v250, v40, s[6:7]
	v_add_f32_e32 v250, 0x358637bd, v250
	v_rsq_f32_e32 v254, v250
	s_nop 1
	v_lshlrev_b32_e32 v6, 16, v32
	v_and_b32_e32 v7, 0xffff0000, v32
	v_pk_mul_f32 v[6:7], v[6:7], v[252:253] op_sel_hi:[1,0]
	v_pk_mul_f32 v[6:7], v[6:7], v[16:17]
	v_cvt_pk_bf16_f32 v32, v6, v7
	v_lshlrev_b32_e32 v40, 16, v44
	v_and_b32_e32 v41, 0xffff0000, v44
	v_pk_mul_f32 v[40:41], v[40:41], v[254:255] op_sel_hi:[1,0]
	v_pk_mul_f32 v[40:41], v[40:41], v[16:17]
	v_cvt_pk_bf16_f32 v44, v40, v41
	v_lshlrev_b32_e32 v6, 16, v33
	v_and_b32_e32 v7, 0xffff0000, v33
	v_pk_mul_f32 v[6:7], v[6:7], v[252:253] op_sel_hi:[1,0]
	v_pk_mul_f32 v[6:7], v[6:7], v[18:19]
	v_cvt_pk_bf16_f32 v33, v6, v7
	v_lshlrev_b32_e32 v40, 16, v45
	v_and_b32_e32 v41, 0xffff0000, v45
	v_pk_mul_f32 v[40:41], v[40:41], v[254:255] op_sel_hi:[1,0]
	v_pk_mul_f32 v[40:41], v[40:41], v[18:19]
	v_cvt_pk_bf16_f32 v45, v40, v41
	v_lshlrev_b32_e32 v6, 16, v34
	v_and_b32_e32 v7, 0xffff0000, v34
	v_pk_mul_f32 v[6:7], v[6:7], v[252:253] op_sel_hi:[1,0]
	v_pk_mul_f32 v[6:7], v[6:7], v[20:21]
	v_cvt_pk_bf16_f32 v34, v6, v7
	v_lshlrev_b32_e32 v40, 16, v46
	v_and_b32_e32 v41, 0xffff0000, v46
	v_pk_mul_f32 v[40:41], v[40:41], v[254:255] op_sel_hi:[1,0]
	v_pk_mul_f32 v[40:41], v[40:41], v[20:21]
	v_cvt_pk_bf16_f32 v46, v40, v41
	v_lshlrev_b32_e32 v6, 16, v35
	v_and_b32_e32 v7, 0xffff0000, v35
	v_pk_mul_f32 v[6:7], v[6:7], v[252:253] op_sel_hi:[1,0]
	v_pk_mul_f32 v[6:7], v[6:7], v[22:23]
	v_cvt_pk_bf16_f32 v35, v6, v7
	v_lshlrev_b32_e32 v40, 16, v47
	v_and_b32_e32 v41, 0xffff0000, v47
	v_pk_mul_f32 v[40:41], v[40:41], v[254:255] op_sel_hi:[1,0]
	v_pk_mul_f32 v[40:41], v[40:41], v[22:23]
	v_cvt_pk_bf16_f32 v47, v40, v41
	v_lshlrev_b32_e32 v6, 16, v36
	v_and_b32_e32 v7, 0xffff0000, v36
	v_pk_mul_f32 v[6:7], v[6:7], v[252:253] op_sel_hi:[1,0]
	v_pk_mul_f32 v[6:7], v[6:7], v[24:25]
	v_cvt_pk_bf16_f32 v36, v6, v7
	v_lshlrev_b32_e32 v40, 16, v48
	v_and_b32_e32 v41, 0xffff0000, v48
	v_pk_mul_f32 v[40:41], v[40:41], v[254:255] op_sel_hi:[1,0]
	v_pk_mul_f32 v[40:41], v[40:41], v[24:25]
	v_cvt_pk_bf16_f32 v48, v40, v41
	v_lshlrev_b32_e32 v6, 16, v37
	v_and_b32_e32 v7, 0xffff0000, v37
	v_pk_mul_f32 v[6:7], v[6:7], v[252:253] op_sel_hi:[1,0]
	v_pk_mul_f32 v[6:7], v[6:7], v[26:27]
	v_cvt_pk_bf16_f32 v37, v6, v7
	v_lshlrev_b32_e32 v40, 16, v49
	v_and_b32_e32 v41, 0xffff0000, v49
	v_pk_mul_f32 v[40:41], v[40:41], v[254:255] op_sel_hi:[1,0]
	v_pk_mul_f32 v[40:41], v[40:41], v[26:27]
	v_cvt_pk_bf16_f32 v49, v40, v41
	v_lshlrev_b32_e32 v6, 16, v38
	v_and_b32_e32 v7, 0xffff0000, v38
	v_pk_mul_f32 v[6:7], v[6:7], v[252:253] op_sel_hi:[1,0]
	v_pk_mul_f32 v[6:7], v[6:7], v[28:29]
	v_cvt_pk_bf16_f32 v38, v6, v7
	v_lshlrev_b32_e32 v40, 16, v50
	v_and_b32_e32 v41, 0xffff0000, v50
	v_pk_mul_f32 v[40:41], v[40:41], v[254:255] op_sel_hi:[1,0]
	v_pk_mul_f32 v[40:41], v[40:41], v[28:29]
	v_cvt_pk_bf16_f32 v50, v40, v41
	v_lshlrev_b32_e32 v6, 16, v39
	v_and_b32_e32 v7, 0xffff0000, v39
	v_pk_mul_f32 v[6:7], v[6:7], v[252:253] op_sel_hi:[1,0]
	v_pk_mul_f32 v[6:7], v[6:7], v[30:31]
	v_cvt_pk_bf16_f32 v39, v6, v7
	v_lshlrev_b32_e32 v40, 16, v51
	v_and_b32_e32 v41, 0xffff0000, v51
	v_pk_mul_f32 v[40:41], v[40:41], v[254:255] op_sel_hi:[1,0]
	v_pk_mul_f32 v[40:41], v[40:41], v[30:31]
	v_cvt_pk_bf16_f32 v51, v40, v41
	global_store_dwordx4 v[4:5], v[32:35], off
	global_store_dwordx4 v[4:5], v[36:39], off offset:16
	global_store_dwordx4 v[4:5], v[44:47], off offset:2048
	global_store_dwordx4 v[4:5], v[48:51], off offset:2064
	v_lshl_add_u64 v[4:5], v[4:5], 0, s[100:101]
	s_nop 1
	global_load_dwordx4 v[32:35], v[2:3], off
	global_load_dwordx4 v[36:39], v[2:3], off offset:16
	global_load_dwordx4 v[44:47], v[2:3], off offset:2048
	global_load_dwordx4 v[48:51], v[2:3], off offset:2064
	v_lshl_add_u64 v[2:3], v[2:3], 0, s[100:101]
	s_waitcnt vmcnt(8)
	v_lshlrev_b32_e32 v6, 16, v52
	v_and_b32_e32 v7, 0xffff0000, v52
	v_pk_mul_f32 v[8:9], v[6:7], v[6:7]
	v_lshlrev_b32_e32 v40, 16, v60
	v_and_b32_e32 v41, 0xffff0000, v60
	v_pk_mul_f32 v[250:251], v[40:41], v[40:41]
	v_lshlrev_b32_e32 v6, 16, v53
	v_and_b32_e32 v7, 0xffff0000, v53
	v_pk_fma_f32 v[8:9], v[6:7], v[6:7], v[8:9]
	v_lshlrev_b32_e32 v40, 16, v61
	v_and_b32_e32 v41, 0xffff0000, v61
	v_pk_fma_f32 v[250:251], v[40:41], v[40:41], v[250:251]
	v_lshlrev_b32_e32 v6, 16, v54
	v_and_b32_e32 v7, 0xffff0000, v54
	v_pk_fma_f32 v[8:9], v[6:7], v[6:7], v[8:9]
	v_lshlrev_b32_e32 v40, 16, v62
	v_and_b32_e32 v41, 0xffff0000, v62
	v_pk_fma_f32 v[250:251], v[40:41], v[40:41], v[250:251]
	v_lshlrev_b32_e32 v6, 16, v55
	v_and_b32_e32 v7, 0xffff0000, v55
	v_pk_fma_f32 v[8:9], v[6:7], v[6:7], v[8:9]
	v_lshlrev_b32_e32 v40, 16, v63
	v_and_b32_e32 v41, 0xffff0000, v63
	v_pk_fma_f32 v[250:251], v[40:41], v[40:41], v[250:251]
	v_lshlrev_b32_e32 v6, 16, v56
	v_and_b32_e32 v7, 0xffff0000, v56
	v_pk_fma_f32 v[8:9], v[6:7], v[6:7], v[8:9]
	v_lshlrev_b32_e32 v40, 16, v64
	v_and_b32_e32 v41, 0xffff0000, v64
	v_pk_fma_f32 v[250:251], v[40:41], v[40:41], v[250:251]
	v_lshlrev_b32_e32 v6, 16, v57
	v_and_b32_e32 v7, 0xffff0000, v57
	v_pk_fma_f32 v[8:9], v[6:7], v[6:7], v[8:9]
	v_lshlrev_b32_e32 v40, 16, v65
	v_and_b32_e32 v41, 0xffff0000, v65
	v_pk_fma_f32 v[250:251], v[40:41], v[40:41], v[250:251]
	v_lshlrev_b32_e32 v6, 16, v58
	v_and_b32_e32 v7, 0xffff0000, v58
	v_pk_fma_f32 v[8:9], v[6:7], v[6:7], v[8:9]
	v_lshlrev_b32_e32 v40, 16, v66
	v_and_b32_e32 v41, 0xffff0000, v66
	v_pk_fma_f32 v[250:251], v[40:41], v[40:41], v[250:251]
	v_lshlrev_b32_e32 v6, 16, v59
	v_and_b32_e32 v7, 0xffff0000, v59
	v_pk_fma_f32 v[8:9], v[6:7], v[6:7], v[8:9]
	v_lshlrev_b32_e32 v40, 16, v67
	v_and_b32_e32 v41, 0xffff0000, v67
	v_pk_fma_f32 v[250:251], v[40:41], v[40:41], v[250:251]
	v_add_f32_e32 v8, v8, v9
	v_add_f32_e32 v250, v250, v251
	s_nop 1
	v_add_f32_dpp v8, v8, v8 quad_perm:[1,0,3,2] row_mask:0xf bank_mask:0xf
	v_add_f32_dpp v250, v250, v250 quad_perm:[1,0,3,2] row_mask:0xf bank_mask:0xf
	s_nop 1
	v_add_f32_dpp v8, v8, v8 quad_perm:[2,3,0,1] row_mask:0xf bank_mask:0xf
	v_add_f32_dpp v250, v250, v250 quad_perm:[2,3,0,1] row_mask:0xf bank_mask:0xf
	s_nop 1
	v_add_f32_dpp v8, v8, v8 row_half_mirror row_mask:0xf bank_mask:0xf
	v_add_f32_dpp v250, v250, v250 row_half_mirror row_mask:0xf bank_mask:0xf
	s_nop 1
	v_add_f32_dpp v8, v8, v8 row_mirror row_mask:0xf bank_mask:0xf
	v_add_f32_dpp v250, v250, v250 row_mirror row_mask:0xf bank_mask:0xf
	s_nop 1
	ds_bpermute_b32 v6, v14, v8
	ds_bpermute_b32 v40, v14, v250
	s_waitcnt lgkmcnt(0)
	v_add_f32_e32 v6, v8, v6
	v_mul_f32_e32 v6, 0x3b000000, v6
	v_mul_f32_e32 v8, 0x3b800000, v8
	v_cndmask_b32_e64 v8, v8, v6, s[6:7]
	v_add_f32_e32 v8, 0x358637bd, v8
	v_rsq_f32_e32 v252, v8
	v_add_f32_e32 v40, v250, v40
	v_mul_f32_e32 v40, 0x3b000000, v40
	v_mul_f32_e32 v250, 0x3b800000, v250
	v_cndmask_b32_e64 v250, v250, v40, s[6:7]
	v_add_f32_e32 v250, 0x358637bd, v250
	v_rsq_f32_e32 v254, v250
	s_nop 1
	v_lshlrev_b32_e32 v6, 16, v52
	v_and_b32_e32 v7, 0xffff0000, v52
	v_pk_mul_f32 v[6:7], v[6:7], v[252:253] op_sel_hi:[1,0]
	v_pk_mul_f32 v[6:7], v[6:7], v[16:17]
	v_cvt_pk_bf16_f32 v52, v6, v7
	v_lshlrev_b32_e32 v40, 16, v60
	v_and_b32_e32 v41, 0xffff0000, v60
	v_pk_mul_f32 v[40:41], v[40:41], v[254:255] op_sel_hi:[1,0]
	v_pk_mul_f32 v[40:41], v[40:41], v[16:17]
	v_cvt_pk_bf16_f32 v60, v40, v41
	v_lshlrev_b32_e32 v6, 16, v53
	v_and_b32_e32 v7, 0xffff0000, v53
	v_pk_mul_f32 v[6:7], v[6:7], v[252:253] op_sel_hi:[1,0]
	v_pk_mul_f32 v[6:7], v[6:7], v[18:19]
	v_cvt_pk_bf16_f32 v53, v6, v7
	v_lshlrev_b32_e32 v40, 16, v61
	v_and_b32_e32 v41, 0xffff0000, v61
	v_pk_mul_f32 v[40:41], v[40:41], v[254:255] op_sel_hi:[1,0]
	v_pk_mul_f32 v[40:41], v[40:41], v[18:19]
	v_cvt_pk_bf16_f32 v61, v40, v41
	v_lshlrev_b32_e32 v6, 16, v54
	v_and_b32_e32 v7, 0xffff0000, v54
	v_pk_mul_f32 v[6:7], v[6:7], v[252:253] op_sel_hi:[1,0]
	v_pk_mul_f32 v[6:7], v[6:7], v[20:21]
	v_cvt_pk_bf16_f32 v54, v6, v7
	v_lshlrev_b32_e32 v40, 16, v62
	v_and_b32_e32 v41, 0xffff0000, v62
	v_pk_mul_f32 v[40:41], v[40:41], v[254:255] op_sel_hi:[1,0]
	v_pk_mul_f32 v[40:41], v[40:41], v[20:21]
	v_cvt_pk_bf16_f32 v62, v40, v41
	v_lshlrev_b32_e32 v6, 16, v55
	v_and_b32_e32 v7, 0xffff0000, v55
	v_pk_mul_f32 v[6:7], v[6:7], v[252:253] op_sel_hi:[1,0]
	v_pk_mul_f32 v[6:7], v[6:7], v[22:23]
	v_cvt_pk_bf16_f32 v55, v6, v7
	v_lshlrev_b32_e32 v40, 16, v63
	v_and_b32_e32 v41, 0xffff0000, v63
	v_pk_mul_f32 v[40:41], v[40:41], v[254:255] op_sel_hi:[1,0]
	v_pk_mul_f32 v[40:41], v[40:41], v[22:23]
	v_cvt_pk_bf16_f32 v63, v40, v41
	v_lshlrev_b32_e32 v6, 16, v56
	v_and_b32_e32 v7, 0xffff0000, v56
	v_pk_mul_f32 v[6:7], v[6:7], v[252:253] op_sel_hi:[1,0]
	v_pk_mul_f32 v[6:7], v[6:7], v[24:25]
	v_cvt_pk_bf16_f32 v56, v6, v7
	v_lshlrev_b32_e32 v40, 16, v64
	v_and_b32_e32 v41, 0xffff0000, v64
	v_pk_mul_f32 v[40:41], v[40:41], v[254:255] op_sel_hi:[1,0]
	v_pk_mul_f32 v[40:41], v[40:41], v[24:25]
	v_cvt_pk_bf16_f32 v64, v40, v41
	v_lshlrev_b32_e32 v6, 16, v57
	v_and_b32_e32 v7, 0xffff0000, v57
	v_pk_mul_f32 v[6:7], v[6:7], v[252:253] op_sel_hi:[1,0]
	v_pk_mul_f32 v[6:7], v[6:7], v[26:27]
	v_cvt_pk_bf16_f32 v57, v6, v7
	v_lshlrev_b32_e32 v40, 16, v65
	v_and_b32_e32 v41, 0xffff0000, v65
	v_pk_mul_f32 v[40:41], v[40:41], v[254:255] op_sel_hi:[1,0]
	v_pk_mul_f32 v[40:41], v[40:41], v[26:27]
	v_cvt_pk_bf16_f32 v65, v40, v41
	v_lshlrev_b32_e32 v6, 16, v58
	v_and_b32_e32 v7, 0xffff0000, v58
	v_pk_mul_f32 v[6:7], v[6:7], v[252:253] op_sel_hi:[1,0]
	v_pk_mul_f32 v[6:7], v[6:7], v[28:29]
	v_cvt_pk_bf16_f32 v58, v6, v7
	v_lshlrev_b32_e32 v40, 16, v66
	v_and_b32_e32 v41, 0xffff0000, v66
	v_pk_mul_f32 v[40:41], v[40:41], v[254:255] op_sel_hi:[1,0]
	v_pk_mul_f32 v[40:41], v[40:41], v[28:29]
	v_cvt_pk_bf16_f32 v66, v40, v41
	v_lshlrev_b32_e32 v6, 16, v59
	v_and_b32_e32 v7, 0xffff0000, v59
	v_pk_mul_f32 v[6:7], v[6:7], v[252:253] op_sel_hi:[1,0]
	v_pk_mul_f32 v[6:7], v[6:7], v[30:31]
	v_cvt_pk_bf16_f32 v59, v6, v7
	v_lshlrev_b32_e32 v40, 16, v67
	v_and_b32_e32 v41, 0xffff0000, v67
	v_pk_mul_f32 v[40:41], v[40:41], v[254:255] op_sel_hi:[1,0]
	v_pk_mul_f32 v[40:41], v[40:41], v[30:31]
	v_cvt_pk_bf16_f32 v67, v40, v41
	global_store_dwordx4 v[4:5], v[52:55], off
	global_store_dwordx4 v[4:5], v[56:59], off offset:16
	global_store_dwordx4 v[4:5], v[60:63], off offset:2048
	global_store_dwordx4 v[4:5], v[64:67], off offset:2064
	v_lshl_add_u64 v[4:5], v[4:5], 0, s[100:101]
	s_nop 1
	global_load_dwordx4 v[52:55], v[2:3], off
	global_load_dwordx4 v[56:59], v[2:3], off offset:16
	global_load_dwordx4 v[60:63], v[2:3], off offset:2048
	global_load_dwordx4 v[64:67], v[2:3], off offset:2064
	v_lshl_add_u64 v[2:3], v[2:3], 0, s[100:101]
	s_waitcnt vmcnt(8)
	v_lshlrev_b32_e32 v6, 16, v32
	v_and_b32_e32 v7, 0xffff0000, v32
	v_pk_mul_f32 v[8:9], v[6:7], v[6:7]
	v_lshlrev_b32_e32 v40, 16, v44
	v_and_b32_e32 v41, 0xffff0000, v44
	v_pk_mul_f32 v[250:251], v[40:41], v[40:41]
	v_lshlrev_b32_e32 v6, 16, v33
	v_and_b32_e32 v7, 0xffff0000, v33
	v_pk_fma_f32 v[8:9], v[6:7], v[6:7], v[8:9]
	v_lshlrev_b32_e32 v40, 16, v45
	v_and_b32_e32 v41, 0xffff0000, v45
	v_pk_fma_f32 v[250:251], v[40:41], v[40:41], v[250:251]
	v_lshlrev_b32_e32 v6, 16, v34
	v_and_b32_e32 v7, 0xffff0000, v34
	v_pk_fma_f32 v[8:9], v[6:7], v[6:7], v[8:9]
	v_lshlrev_b32_e32 v40, 16, v46
	v_and_b32_e32 v41, 0xffff0000, v46
	v_pk_fma_f32 v[250:251], v[40:41], v[40:41], v[250:251]
	v_lshlrev_b32_e32 v6, 16, v35
	v_and_b32_e32 v7, 0xffff0000, v35
	v_pk_fma_f32 v[8:9], v[6:7], v[6:7], v[8:9]
	v_lshlrev_b32_e32 v40, 16, v47
	v_and_b32_e32 v41, 0xffff0000, v47
	v_pk_fma_f32 v[250:251], v[40:41], v[40:41], v[250:251]
	v_lshlrev_b32_e32 v6, 16, v36
	v_and_b32_e32 v7, 0xffff0000, v36
	v_pk_fma_f32 v[8:9], v[6:7], v[6:7], v[8:9]
	v_lshlrev_b32_e32 v40, 16, v48
	v_and_b32_e32 v41, 0xffff0000, v48
	v_pk_fma_f32 v[250:251], v[40:41], v[40:41], v[250:251]
	v_lshlrev_b32_e32 v6, 16, v37
	v_and_b32_e32 v7, 0xffff0000, v37
	v_pk_fma_f32 v[8:9], v[6:7], v[6:7], v[8:9]
	v_lshlrev_b32_e32 v40, 16, v49
	v_and_b32_e32 v41, 0xffff0000, v49
	v_pk_fma_f32 v[250:251], v[40:41], v[40:41], v[250:251]
	v_lshlrev_b32_e32 v6, 16, v38
	v_and_b32_e32 v7, 0xffff0000, v38
	v_pk_fma_f32 v[8:9], v[6:7], v[6:7], v[8:9]
	v_lshlrev_b32_e32 v40, 16, v50
	v_and_b32_e32 v41, 0xffff0000, v50
	v_pk_fma_f32 v[250:251], v[40:41], v[40:41], v[250:251]
	v_lshlrev_b32_e32 v6, 16, v39
	v_and_b32_e32 v7, 0xffff0000, v39
	v_pk_fma_f32 v[8:9], v[6:7], v[6:7], v[8:9]
	v_lshlrev_b32_e32 v40, 16, v51
	v_and_b32_e32 v41, 0xffff0000, v51
	v_pk_fma_f32 v[250:251], v[40:41], v[40:41], v[250:251]
	v_add_f32_e32 v8, v8, v9
	v_add_f32_e32 v250, v250, v251
	s_nop 1
	v_add_f32_dpp v8, v8, v8 quad_perm:[1,0,3,2] row_mask:0xf bank_mask:0xf
	v_add_f32_dpp v250, v250, v250 quad_perm:[1,0,3,2] row_mask:0xf bank_mask:0xf
	s_nop 1
	v_add_f32_dpp v8, v8, v8 quad_perm:[2,3,0,1] row_mask:0xf bank_mask:0xf
	v_add_f32_dpp v250, v250, v250 quad_perm:[2,3,0,1] row_mask:0xf bank_mask:0xf
	s_nop 1
	v_add_f32_dpp v8, v8, v8 row_half_mirror row_mask:0xf bank_mask:0xf
	v_add_f32_dpp v250, v250, v250 row_half_mirror row_mask:0xf bank_mask:0xf
	s_nop 1
	v_add_f32_dpp v8, v8, v8 row_mirror row_mask:0xf bank_mask:0xf
	v_add_f32_dpp v250, v250, v250 row_mirror row_mask:0xf bank_mask:0xf
	s_nop 1
	ds_bpermute_b32 v6, v14, v8
	ds_bpermute_b32 v40, v14, v250
	s_waitcnt lgkmcnt(0)
	v_add_f32_e32 v6, v8, v6
	v_mul_f32_e32 v6, 0x3b000000, v6
	v_mul_f32_e32 v8, 0x3b800000, v8
	v_cndmask_b32_e64 v8, v8, v6, s[6:7]
	v_add_f32_e32 v8, 0x358637bd, v8
	v_rsq_f32_e32 v252, v8
	v_add_f32_e32 v40, v250, v40
	v_mul_f32_e32 v40, 0x3b000000, v40
	v_mul_f32_e32 v250, 0x3b800000, v250
	v_cndmask_b32_e64 v250, v250, v40, s[6:7]
	v_add_f32_e32 v250, 0x358637bd, v250
	v_rsq_f32_e32 v254, v250
	s_nop 1
	v_lshlrev_b32_e32 v6, 16, v32
	v_and_b32_e32 v7, 0xffff0000, v32
	v_pk_mul_f32 v[6:7], v[6:7], v[252:253] op_sel_hi:[1,0]
	v_pk_mul_f32 v[6:7], v[6:7], v[16:17]
	v_cvt_pk_bf16_f32 v32, v6, v7
	v_lshlrev_b32_e32 v40, 16, v44
	v_and_b32_e32 v41, 0xffff0000, v44
	v_pk_mul_f32 v[40:41], v[40:41], v[254:255] op_sel_hi:[1,0]
	v_pk_mul_f32 v[40:41], v[40:41], v[16:17]
	v_cvt_pk_bf16_f32 v44, v40, v41
	v_lshlrev_b32_e32 v6, 16, v33
	v_and_b32_e32 v7, 0xffff0000, v33
	v_pk_mul_f32 v[6:7], v[6:7], v[252:253] op_sel_hi:[1,0]
	v_pk_mul_f32 v[6:7], v[6:7], v[18:19]
	v_cvt_pk_bf16_f32 v33, v6, v7
	v_lshlrev_b32_e32 v40, 16, v45
	v_and_b32_e32 v41, 0xffff0000, v45
	v_pk_mul_f32 v[40:41], v[40:41], v[254:255] op_sel_hi:[1,0]
	v_pk_mul_f32 v[40:41], v[40:41], v[18:19]
	v_cvt_pk_bf16_f32 v45, v40, v41
	v_lshlrev_b32_e32 v6, 16, v34
	v_and_b32_e32 v7, 0xffff0000, v34
	v_pk_mul_f32 v[6:7], v[6:7], v[252:253] op_sel_hi:[1,0]
	v_pk_mul_f32 v[6:7], v[6:7], v[20:21]
	v_cvt_pk_bf16_f32 v34, v6, v7
	v_lshlrev_b32_e32 v40, 16, v46
	v_and_b32_e32 v41, 0xffff0000, v46
	v_pk_mul_f32 v[40:41], v[40:41], v[254:255] op_sel_hi:[1,0]
	v_pk_mul_f32 v[40:41], v[40:41], v[20:21]
	v_cvt_pk_bf16_f32 v46, v40, v41
	v_lshlrev_b32_e32 v6, 16, v35
	v_and_b32_e32 v7, 0xffff0000, v35
	v_pk_mul_f32 v[6:7], v[6:7], v[252:253] op_sel_hi:[1,0]
	v_pk_mul_f32 v[6:7], v[6:7], v[22:23]
	v_cvt_pk_bf16_f32 v35, v6, v7
	v_lshlrev_b32_e32 v40, 16, v47
	v_and_b32_e32 v41, 0xffff0000, v47
	v_pk_mul_f32 v[40:41], v[40:41], v[254:255] op_sel_hi:[1,0]
	v_pk_mul_f32 v[40:41], v[40:41], v[22:23]
	v_cvt_pk_bf16_f32 v47, v40, v41
	v_lshlrev_b32_e32 v6, 16, v36
	v_and_b32_e32 v7, 0xffff0000, v36
	v_pk_mul_f32 v[6:7], v[6:7], v[252:253] op_sel_hi:[1,0]
	v_pk_mul_f32 v[6:7], v[6:7], v[24:25]
	v_cvt_pk_bf16_f32 v36, v6, v7
	v_lshlrev_b32_e32 v40, 16, v48
	v_and_b32_e32 v41, 0xffff0000, v48
	v_pk_mul_f32 v[40:41], v[40:41], v[254:255] op_sel_hi:[1,0]
	v_pk_mul_f32 v[40:41], v[40:41], v[24:25]
	v_cvt_pk_bf16_f32 v48, v40, v41
	v_lshlrev_b32_e32 v6, 16, v37
	v_and_b32_e32 v7, 0xffff0000, v37
	v_pk_mul_f32 v[6:7], v[6:7], v[252:253] op_sel_hi:[1,0]
	v_pk_mul_f32 v[6:7], v[6:7], v[26:27]
	v_cvt_pk_bf16_f32 v37, v6, v7
	v_lshlrev_b32_e32 v40, 16, v49
	v_and_b32_e32 v41, 0xffff0000, v49
	v_pk_mul_f32 v[40:41], v[40:41], v[254:255] op_sel_hi:[1,0]
	v_pk_mul_f32 v[40:41], v[40:41], v[26:27]
	v_cvt_pk_bf16_f32 v49, v40, v41
	v_lshlrev_b32_e32 v6, 16, v38
	v_and_b32_e32 v7, 0xffff0000, v38
	v_pk_mul_f32 v[6:7], v[6:7], v[252:253] op_sel_hi:[1,0]
	v_pk_mul_f32 v[6:7], v[6:7], v[28:29]
	v_cvt_pk_bf16_f32 v38, v6, v7
	v_lshlrev_b32_e32 v40, 16, v50
	v_and_b32_e32 v41, 0xffff0000, v50
	v_pk_mul_f32 v[40:41], v[40:41], v[254:255] op_sel_hi:[1,0]
	v_pk_mul_f32 v[40:41], v[40:41], v[28:29]
	v_cvt_pk_bf16_f32 v50, v40, v41
	v_lshlrev_b32_e32 v6, 16, v39
	v_and_b32_e32 v7, 0xffff0000, v39
	v_pk_mul_f32 v[6:7], v[6:7], v[252:253] op_sel_hi:[1,0]
	v_pk_mul_f32 v[6:7], v[6:7], v[30:31]
	v_cvt_pk_bf16_f32 v39, v6, v7
	v_lshlrev_b32_e32 v40, 16, v51
	v_and_b32_e32 v41, 0xffff0000, v51
	v_pk_mul_f32 v[40:41], v[40:41], v[254:255] op_sel_hi:[1,0]
	v_pk_mul_f32 v[40:41], v[40:41], v[30:31]
	v_cvt_pk_bf16_f32 v51, v40, v41
	global_store_dwordx4 v[4:5], v[32:35], off
	global_store_dwordx4 v[4:5], v[36:39], off offset:16
	global_store_dwordx4 v[4:5], v[44:47], off offset:2048
	global_store_dwordx4 v[4:5], v[48:51], off offset:2064
	v_lshl_add_u64 v[4:5], v[4:5], 0, s[100:101]
	s_nop 1
	global_load_dwordx4 v[32:35], v[2:3], off
	global_load_dwordx4 v[36:39], v[2:3], off offset:16
	global_load_dwordx4 v[44:47], v[2:3], off offset:2048
	global_load_dwordx4 v[48:51], v[2:3], off offset:2064
	v_lshl_add_u64 v[2:3], v[2:3], 0, s[100:101]
	s_waitcnt vmcnt(8)
	v_lshlrev_b32_e32 v6, 16, v52
	v_and_b32_e32 v7, 0xffff0000, v52
	v_pk_mul_f32 v[8:9], v[6:7], v[6:7]
	v_lshlrev_b32_e32 v40, 16, v60
	v_and_b32_e32 v41, 0xffff0000, v60
	v_pk_mul_f32 v[250:251], v[40:41], v[40:41]
	v_lshlrev_b32_e32 v6, 16, v53
	v_and_b32_e32 v7, 0xffff0000, v53
	v_pk_fma_f32 v[8:9], v[6:7], v[6:7], v[8:9]
	v_lshlrev_b32_e32 v40, 16, v61
	v_and_b32_e32 v41, 0xffff0000, v61
	v_pk_fma_f32 v[250:251], v[40:41], v[40:41], v[250:251]
	v_lshlrev_b32_e32 v6, 16, v54
	v_and_b32_e32 v7, 0xffff0000, v54
	v_pk_fma_f32 v[8:9], v[6:7], v[6:7], v[8:9]
	v_lshlrev_b32_e32 v40, 16, v62
	v_and_b32_e32 v41, 0xffff0000, v62
	v_pk_fma_f32 v[250:251], v[40:41], v[40:41], v[250:251]
	v_lshlrev_b32_e32 v6, 16, v55
	v_and_b32_e32 v7, 0xffff0000, v55
	v_pk_fma_f32 v[8:9], v[6:7], v[6:7], v[8:9]
	v_lshlrev_b32_e32 v40, 16, v63
	v_and_b32_e32 v41, 0xffff0000, v63
	v_pk_fma_f32 v[250:251], v[40:41], v[40:41], v[250:251]
	v_lshlrev_b32_e32 v6, 16, v56
	v_and_b32_e32 v7, 0xffff0000, v56
	v_pk_fma_f32 v[8:9], v[6:7], v[6:7], v[8:9]
	v_lshlrev_b32_e32 v40, 16, v64
	v_and_b32_e32 v41, 0xffff0000, v64
	v_pk_fma_f32 v[250:251], v[40:41], v[40:41], v[250:251]
	v_lshlrev_b32_e32 v6, 16, v57
	v_and_b32_e32 v7, 0xffff0000, v57
	v_pk_fma_f32 v[8:9], v[6:7], v[6:7], v[8:9]
	v_lshlrev_b32_e32 v40, 16, v65
	v_and_b32_e32 v41, 0xffff0000, v65
	v_pk_fma_f32 v[250:251], v[40:41], v[40:41], v[250:251]
	v_lshlrev_b32_e32 v6, 16, v58
	v_and_b32_e32 v7, 0xffff0000, v58
	v_pk_fma_f32 v[8:9], v[6:7], v[6:7], v[8:9]
	v_lshlrev_b32_e32 v40, 16, v66
	v_and_b32_e32 v41, 0xffff0000, v66
	v_pk_fma_f32 v[250:251], v[40:41], v[40:41], v[250:251]
	v_lshlrev_b32_e32 v6, 16, v59
	v_and_b32_e32 v7, 0xffff0000, v59
	v_pk_fma_f32 v[8:9], v[6:7], v[6:7], v[8:9]
	v_lshlrev_b32_e32 v40, 16, v67
	v_and_b32_e32 v41, 0xffff0000, v67
	v_pk_fma_f32 v[250:251], v[40:41], v[40:41], v[250:251]
	v_add_f32_e32 v8, v8, v9
	v_add_f32_e32 v250, v250, v251
	s_nop 1
	v_add_f32_dpp v8, v8, v8 quad_perm:[1,0,3,2] row_mask:0xf bank_mask:0xf
	v_add_f32_dpp v250, v250, v250 quad_perm:[1,0,3,2] row_mask:0xf bank_mask:0xf
	s_nop 1
	v_add_f32_dpp v8, v8, v8 quad_perm:[2,3,0,1] row_mask:0xf bank_mask:0xf
	v_add_f32_dpp v250, v250, v250 quad_perm:[2,3,0,1] row_mask:0xf bank_mask:0xf
	s_nop 1
	v_add_f32_dpp v8, v8, v8 row_half_mirror row_mask:0xf bank_mask:0xf
	v_add_f32_dpp v250, v250, v250 row_half_mirror row_mask:0xf bank_mask:0xf
	s_nop 1
	v_add_f32_dpp v8, v8, v8 row_mirror row_mask:0xf bank_mask:0xf
	v_add_f32_dpp v250, v250, v250 row_mirror row_mask:0xf bank_mask:0xf
	s_nop 1
	ds_bpermute_b32 v6, v14, v8
	ds_bpermute_b32 v40, v14, v250
	s_waitcnt lgkmcnt(0)
	v_add_f32_e32 v6, v8, v6
	v_mul_f32_e32 v6, 0x3b000000, v6
	v_mul_f32_e32 v8, 0x3b800000, v8
	v_cndmask_b32_e64 v8, v8, v6, s[6:7]
	v_add_f32_e32 v8, 0x358637bd, v8
	v_rsq_f32_e32 v252, v8
	v_add_f32_e32 v40, v250, v40
	v_mul_f32_e32 v40, 0x3b000000, v40
	v_mul_f32_e32 v250, 0x3b800000, v250
	v_cndmask_b32_e64 v250, v250, v40, s[6:7]
	v_add_f32_e32 v250, 0x358637bd, v250
	v_rsq_f32_e32 v254, v250
	s_nop 1
	v_lshlrev_b32_e32 v6, 16, v52
	v_and_b32_e32 v7, 0xffff0000, v52
	v_pk_mul_f32 v[6:7], v[6:7], v[252:253] op_sel_hi:[1,0]
	v_pk_mul_f32 v[6:7], v[6:7], v[16:17]
	v_cvt_pk_bf16_f32 v52, v6, v7
	v_lshlrev_b32_e32 v40, 16, v60
	v_and_b32_e32 v41, 0xffff0000, v60
	v_pk_mul_f32 v[40:41], v[40:41], v[254:255] op_sel_hi:[1,0]
	v_pk_mul_f32 v[40:41], v[40:41], v[16:17]
	v_cvt_pk_bf16_f32 v60, v40, v41
	v_lshlrev_b32_e32 v6, 16, v53
	v_and_b32_e32 v7, 0xffff0000, v53
	v_pk_mul_f32 v[6:7], v[6:7], v[252:253] op_sel_hi:[1,0]
	v_pk_mul_f32 v[6:7], v[6:7], v[18:19]
	v_cvt_pk_bf16_f32 v53, v6, v7
	v_lshlrev_b32_e32 v40, 16, v61
	v_and_b32_e32 v41, 0xffff0000, v61
	v_pk_mul_f32 v[40:41], v[40:41], v[254:255] op_sel_hi:[1,0]
	v_pk_mul_f32 v[40:41], v[40:41], v[18:19]
	v_cvt_pk_bf16_f32 v61, v40, v41
	v_lshlrev_b32_e32 v6, 16, v54
	v_and_b32_e32 v7, 0xffff0000, v54
	v_pk_mul_f32 v[6:7], v[6:7], v[252:253] op_sel_hi:[1,0]
	v_pk_mul_f32 v[6:7], v[6:7], v[20:21]
	v_cvt_pk_bf16_f32 v54, v6, v7
	v_lshlrev_b32_e32 v40, 16, v62
	v_and_b32_e32 v41, 0xffff0000, v62
	v_pk_mul_f32 v[40:41], v[40:41], v[254:255] op_sel_hi:[1,0]
	v_pk_mul_f32 v[40:41], v[40:41], v[20:21]
	v_cvt_pk_bf16_f32 v62, v40, v41
	v_lshlrev_b32_e32 v6, 16, v55
	v_and_b32_e32 v7, 0xffff0000, v55
	v_pk_mul_f32 v[6:7], v[6:7], v[252:253] op_sel_hi:[1,0]
	v_pk_mul_f32 v[6:7], v[6:7], v[22:23]
	v_cvt_pk_bf16_f32 v55, v6, v7
	v_lshlrev_b32_e32 v40, 16, v63
	v_and_b32_e32 v41, 0xffff0000, v63
	v_pk_mul_f32 v[40:41], v[40:41], v[254:255] op_sel_hi:[1,0]
	v_pk_mul_f32 v[40:41], v[40:41], v[22:23]
	v_cvt_pk_bf16_f32 v63, v40, v41
	v_lshlrev_b32_e32 v6, 16, v56
	v_and_b32_e32 v7, 0xffff0000, v56
	v_pk_mul_f32 v[6:7], v[6:7], v[252:253] op_sel_hi:[1,0]
	v_pk_mul_f32 v[6:7], v[6:7], v[24:25]
	v_cvt_pk_bf16_f32 v56, v6, v7
	v_lshlrev_b32_e32 v40, 16, v64
	v_and_b32_e32 v41, 0xffff0000, v64
	v_pk_mul_f32 v[40:41], v[40:41], v[254:255] op_sel_hi:[1,0]
	v_pk_mul_f32 v[40:41], v[40:41], v[24:25]
	v_cvt_pk_bf16_f32 v64, v40, v41
	v_lshlrev_b32_e32 v6, 16, v57
	v_and_b32_e32 v7, 0xffff0000, v57
	v_pk_mul_f32 v[6:7], v[6:7], v[252:253] op_sel_hi:[1,0]
	v_pk_mul_f32 v[6:7], v[6:7], v[26:27]
	v_cvt_pk_bf16_f32 v57, v6, v7
	v_lshlrev_b32_e32 v40, 16, v65
	v_and_b32_e32 v41, 0xffff0000, v65
	v_pk_mul_f32 v[40:41], v[40:41], v[254:255] op_sel_hi:[1,0]
	v_pk_mul_f32 v[40:41], v[40:41], v[26:27]
	v_cvt_pk_bf16_f32 v65, v40, v41
	v_lshlrev_b32_e32 v6, 16, v58
	v_and_b32_e32 v7, 0xffff0000, v58
	v_pk_mul_f32 v[6:7], v[6:7], v[252:253] op_sel_hi:[1,0]
	v_pk_mul_f32 v[6:7], v[6:7], v[28:29]
	v_cvt_pk_bf16_f32 v58, v6, v7
	v_lshlrev_b32_e32 v40, 16, v66
	v_and_b32_e32 v41, 0xffff0000, v66
	v_pk_mul_f32 v[40:41], v[40:41], v[254:255] op_sel_hi:[1,0]
	v_pk_mul_f32 v[40:41], v[40:41], v[28:29]
	v_cvt_pk_bf16_f32 v66, v40, v41
	v_lshlrev_b32_e32 v6, 16, v59
	v_and_b32_e32 v7, 0xffff0000, v59
	v_pk_mul_f32 v[6:7], v[6:7], v[252:253] op_sel_hi:[1,0]
	v_pk_mul_f32 v[6:7], v[6:7], v[30:31]
	v_cvt_pk_bf16_f32 v59, v6, v7
	v_lshlrev_b32_e32 v40, 16, v67
	v_and_b32_e32 v41, 0xffff0000, v67
	v_pk_mul_f32 v[40:41], v[40:41], v[254:255] op_sel_hi:[1,0]
	v_pk_mul_f32 v[40:41], v[40:41], v[30:31]
	v_cvt_pk_bf16_f32 v67, v40, v41
	global_store_dwordx4 v[4:5], v[52:55], off
	global_store_dwordx4 v[4:5], v[56:59], off offset:16
	global_store_dwordx4 v[4:5], v[60:63], off offset:2048
	global_store_dwordx4 v[4:5], v[64:67], off offset:2064
	v_lshl_add_u64 v[4:5], v[4:5], 0, s[100:101]
	s_nop 1
	global_load_dwordx4 v[52:55], v[2:3], off
	global_load_dwordx4 v[56:59], v[2:3], off offset:16
	global_load_dwordx4 v[60:63], v[2:3], off offset:2048
	global_load_dwordx4 v[64:67], v[2:3], off offset:2064
	v_lshl_add_u64 v[2:3], v[2:3], 0, s[100:101]
	s_waitcnt vmcnt(8)
	v_lshlrev_b32_e32 v6, 16, v32
	v_and_b32_e32 v7, 0xffff0000, v32
	v_pk_mul_f32 v[8:9], v[6:7], v[6:7]
	v_lshlrev_b32_e32 v40, 16, v44
	v_and_b32_e32 v41, 0xffff0000, v44
	v_pk_mul_f32 v[250:251], v[40:41], v[40:41]
	v_lshlrev_b32_e32 v6, 16, v33
	v_and_b32_e32 v7, 0xffff0000, v33
	v_pk_fma_f32 v[8:9], v[6:7], v[6:7], v[8:9]
	v_lshlrev_b32_e32 v40, 16, v45
	v_and_b32_e32 v41, 0xffff0000, v45
	v_pk_fma_f32 v[250:251], v[40:41], v[40:41], v[250:251]
	v_lshlrev_b32_e32 v6, 16, v34
	v_and_b32_e32 v7, 0xffff0000, v34
	v_pk_fma_f32 v[8:9], v[6:7], v[6:7], v[8:9]
	v_lshlrev_b32_e32 v40, 16, v46
	v_and_b32_e32 v41, 0xffff0000, v46
	v_pk_fma_f32 v[250:251], v[40:41], v[40:41], v[250:251]
	v_lshlrev_b32_e32 v6, 16, v35
	v_and_b32_e32 v7, 0xffff0000, v35
	v_pk_fma_f32 v[8:9], v[6:7], v[6:7], v[8:9]
	v_lshlrev_b32_e32 v40, 16, v47
	v_and_b32_e32 v41, 0xffff0000, v47
	v_pk_fma_f32 v[250:251], v[40:41], v[40:41], v[250:251]
	v_lshlrev_b32_e32 v6, 16, v36
	v_and_b32_e32 v7, 0xffff0000, v36
	v_pk_fma_f32 v[8:9], v[6:7], v[6:7], v[8:9]
	v_lshlrev_b32_e32 v40, 16, v48
	v_and_b32_e32 v41, 0xffff0000, v48
	v_pk_fma_f32 v[250:251], v[40:41], v[40:41], v[250:251]
	v_lshlrev_b32_e32 v6, 16, v37
	v_and_b32_e32 v7, 0xffff0000, v37
	v_pk_fma_f32 v[8:9], v[6:7], v[6:7], v[8:9]
	v_lshlrev_b32_e32 v40, 16, v49
	v_and_b32_e32 v41, 0xffff0000, v49
	v_pk_fma_f32 v[250:251], v[40:41], v[40:41], v[250:251]
	v_lshlrev_b32_e32 v6, 16, v38
	v_and_b32_e32 v7, 0xffff0000, v38
	v_pk_fma_f32 v[8:9], v[6:7], v[6:7], v[8:9]
	v_lshlrev_b32_e32 v40, 16, v50
	v_and_b32_e32 v41, 0xffff0000, v50
	v_pk_fma_f32 v[250:251], v[40:41], v[40:41], v[250:251]
	v_lshlrev_b32_e32 v6, 16, v39
	v_and_b32_e32 v7, 0xffff0000, v39
	v_pk_fma_f32 v[8:9], v[6:7], v[6:7], v[8:9]
	v_lshlrev_b32_e32 v40, 16, v51
	v_and_b32_e32 v41, 0xffff0000, v51
	v_pk_fma_f32 v[250:251], v[40:41], v[40:41], v[250:251]
	v_add_f32_e32 v8, v8, v9
	v_add_f32_e32 v250, v250, v251
	s_nop 1
	v_add_f32_dpp v8, v8, v8 quad_perm:[1,0,3,2] row_mask:0xf bank_mask:0xf
	v_add_f32_dpp v250, v250, v250 quad_perm:[1,0,3,2] row_mask:0xf bank_mask:0xf
	s_nop 1
	v_add_f32_dpp v8, v8, v8 quad_perm:[2,3,0,1] row_mask:0xf bank_mask:0xf
	v_add_f32_dpp v250, v250, v250 quad_perm:[2,3,0,1] row_mask:0xf bank_mask:0xf
	s_nop 1
	v_add_f32_dpp v8, v8, v8 row_half_mirror row_mask:0xf bank_mask:0xf
	v_add_f32_dpp v250, v250, v250 row_half_mirror row_mask:0xf bank_mask:0xf
	s_nop 1
	v_add_f32_dpp v8, v8, v8 row_mirror row_mask:0xf bank_mask:0xf
	v_add_f32_dpp v250, v250, v250 row_mirror row_mask:0xf bank_mask:0xf
	s_nop 1
	ds_bpermute_b32 v6, v14, v8
	ds_bpermute_b32 v40, v14, v250
	s_waitcnt lgkmcnt(0)
	v_add_f32_e32 v6, v8, v6
	v_mul_f32_e32 v6, 0x3b000000, v6
	v_mul_f32_e32 v8, 0x3b800000, v8
	v_cndmask_b32_e64 v8, v8, v6, s[6:7]
	v_add_f32_e32 v8, 0x358637bd, v8
	v_rsq_f32_e32 v252, v8
	v_add_f32_e32 v40, v250, v40
	v_mul_f32_e32 v40, 0x3b000000, v40
	v_mul_f32_e32 v250, 0x3b800000, v250
	v_cndmask_b32_e64 v250, v250, v40, s[6:7]
	v_add_f32_e32 v250, 0x358637bd, v250
	v_rsq_f32_e32 v254, v250
	s_nop 1
	v_lshlrev_b32_e32 v6, 16, v32
	v_and_b32_e32 v7, 0xffff0000, v32
	v_pk_mul_f32 v[6:7], v[6:7], v[252:253] op_sel_hi:[1,0]
	v_pk_mul_f32 v[6:7], v[6:7], v[16:17]
	v_cvt_pk_bf16_f32 v32, v6, v7
	v_lshlrev_b32_e32 v40, 16, v44
	v_and_b32_e32 v41, 0xffff0000, v44
	v_pk_mul_f32 v[40:41], v[40:41], v[254:255] op_sel_hi:[1,0]
	v_pk_mul_f32 v[40:41], v[40:41], v[16:17]
	v_cvt_pk_bf16_f32 v44, v40, v41
	v_lshlrev_b32_e32 v6, 16, v33
	v_and_b32_e32 v7, 0xffff0000, v33
	v_pk_mul_f32 v[6:7], v[6:7], v[252:253] op_sel_hi:[1,0]
	v_pk_mul_f32 v[6:7], v[6:7], v[18:19]
	v_cvt_pk_bf16_f32 v33, v6, v7
	v_lshlrev_b32_e32 v40, 16, v45
	v_and_b32_e32 v41, 0xffff0000, v45
	v_pk_mul_f32 v[40:41], v[40:41], v[254:255] op_sel_hi:[1,0]
	v_pk_mul_f32 v[40:41], v[40:41], v[18:19]
	v_cvt_pk_bf16_f32 v45, v40, v41
	v_lshlrev_b32_e32 v6, 16, v34
	v_and_b32_e32 v7, 0xffff0000, v34
	v_pk_mul_f32 v[6:7], v[6:7], v[252:253] op_sel_hi:[1,0]
	v_pk_mul_f32 v[6:7], v[6:7], v[20:21]
	v_cvt_pk_bf16_f32 v34, v6, v7
	v_lshlrev_b32_e32 v40, 16, v46
	v_and_b32_e32 v41, 0xffff0000, v46
	v_pk_mul_f32 v[40:41], v[40:41], v[254:255] op_sel_hi:[1,0]
	v_pk_mul_f32 v[40:41], v[40:41], v[20:21]
	v_cvt_pk_bf16_f32 v46, v40, v41
	v_lshlrev_b32_e32 v6, 16, v35
	v_and_b32_e32 v7, 0xffff0000, v35
	v_pk_mul_f32 v[6:7], v[6:7], v[252:253] op_sel_hi:[1,0]
	v_pk_mul_f32 v[6:7], v[6:7], v[22:23]
	v_cvt_pk_bf16_f32 v35, v6, v7
	v_lshlrev_b32_e32 v40, 16, v47
	v_and_b32_e32 v41, 0xffff0000, v47
	v_pk_mul_f32 v[40:41], v[40:41], v[254:255] op_sel_hi:[1,0]
	v_pk_mul_f32 v[40:41], v[40:41], v[22:23]
	v_cvt_pk_bf16_f32 v47, v40, v41
	v_lshlrev_b32_e32 v6, 16, v36
	v_and_b32_e32 v7, 0xffff0000, v36
	v_pk_mul_f32 v[6:7], v[6:7], v[252:253] op_sel_hi:[1,0]
	v_pk_mul_f32 v[6:7], v[6:7], v[24:25]
	v_cvt_pk_bf16_f32 v36, v6, v7
	v_lshlrev_b32_e32 v40, 16, v48
	v_and_b32_e32 v41, 0xffff0000, v48
	v_pk_mul_f32 v[40:41], v[40:41], v[254:255] op_sel_hi:[1,0]
	v_pk_mul_f32 v[40:41], v[40:41], v[24:25]
	v_cvt_pk_bf16_f32 v48, v40, v41
	v_lshlrev_b32_e32 v6, 16, v37
	v_and_b32_e32 v7, 0xffff0000, v37
	v_pk_mul_f32 v[6:7], v[6:7], v[252:253] op_sel_hi:[1,0]
	v_pk_mul_f32 v[6:7], v[6:7], v[26:27]
	v_cvt_pk_bf16_f32 v37, v6, v7
	v_lshlrev_b32_e32 v40, 16, v49
	v_and_b32_e32 v41, 0xffff0000, v49
	v_pk_mul_f32 v[40:41], v[40:41], v[254:255] op_sel_hi:[1,0]
	v_pk_mul_f32 v[40:41], v[40:41], v[26:27]
	v_cvt_pk_bf16_f32 v49, v40, v41
	v_lshlrev_b32_e32 v6, 16, v38
	v_and_b32_e32 v7, 0xffff0000, v38
	v_pk_mul_f32 v[6:7], v[6:7], v[252:253] op_sel_hi:[1,0]
	v_pk_mul_f32 v[6:7], v[6:7], v[28:29]
	v_cvt_pk_bf16_f32 v38, v6, v7
	v_lshlrev_b32_e32 v40, 16, v50
	v_and_b32_e32 v41, 0xffff0000, v50
	v_pk_mul_f32 v[40:41], v[40:41], v[254:255] op_sel_hi:[1,0]
	v_pk_mul_f32 v[40:41], v[40:41], v[28:29]
	v_cvt_pk_bf16_f32 v50, v40, v41
	v_lshlrev_b32_e32 v6, 16, v39
	v_and_b32_e32 v7, 0xffff0000, v39
	v_pk_mul_f32 v[6:7], v[6:7], v[252:253] op_sel_hi:[1,0]
	v_pk_mul_f32 v[6:7], v[6:7], v[30:31]
	v_cvt_pk_bf16_f32 v39, v6, v7
	v_lshlrev_b32_e32 v40, 16, v51
	v_and_b32_e32 v41, 0xffff0000, v51
	v_pk_mul_f32 v[40:41], v[40:41], v[254:255] op_sel_hi:[1,0]
	v_pk_mul_f32 v[40:41], v[40:41], v[30:31]
	v_cvt_pk_bf16_f32 v51, v40, v41
	global_store_dwordx4 v[4:5], v[32:35], off
	global_store_dwordx4 v[4:5], v[36:39], off offset:16
	global_store_dwordx4 v[4:5], v[44:47], off offset:2048
	global_store_dwordx4 v[4:5], v[48:51], off offset:2064
	v_lshl_add_u64 v[4:5], v[4:5], 0, s[100:101]
	s_nop 1
	global_load_dwordx4 v[32:35], v[2:3], off
	global_load_dwordx4 v[36:39], v[2:3], off offset:16
	global_load_dwordx4 v[44:47], v[2:3], off offset:2048
	global_load_dwordx4 v[48:51], v[2:3], off offset:2064
	v_lshl_add_u64 v[2:3], v[2:3], 0, s[100:101]
	s_waitcnt vmcnt(8)
	v_lshlrev_b32_e32 v6, 16, v52
	v_and_b32_e32 v7, 0xffff0000, v52
	v_pk_mul_f32 v[8:9], v[6:7], v[6:7]
	v_lshlrev_b32_e32 v40, 16, v60
	v_and_b32_e32 v41, 0xffff0000, v60
	v_pk_mul_f32 v[250:251], v[40:41], v[40:41]
	v_lshlrev_b32_e32 v6, 16, v53
	v_and_b32_e32 v7, 0xffff0000, v53
	v_pk_fma_f32 v[8:9], v[6:7], v[6:7], v[8:9]
	v_lshlrev_b32_e32 v40, 16, v61
	v_and_b32_e32 v41, 0xffff0000, v61
	v_pk_fma_f32 v[250:251], v[40:41], v[40:41], v[250:251]
	v_lshlrev_b32_e32 v6, 16, v54
	v_and_b32_e32 v7, 0xffff0000, v54
	v_pk_fma_f32 v[8:9], v[6:7], v[6:7], v[8:9]
	v_lshlrev_b32_e32 v40, 16, v62
	v_and_b32_e32 v41, 0xffff0000, v62
	v_pk_fma_f32 v[250:251], v[40:41], v[40:41], v[250:251]
	v_lshlrev_b32_e32 v6, 16, v55
	v_and_b32_e32 v7, 0xffff0000, v55
	v_pk_fma_f32 v[8:9], v[6:7], v[6:7], v[8:9]
	v_lshlrev_b32_e32 v40, 16, v63
	v_and_b32_e32 v41, 0xffff0000, v63
	v_pk_fma_f32 v[250:251], v[40:41], v[40:41], v[250:251]
	v_lshlrev_b32_e32 v6, 16, v56
	v_and_b32_e32 v7, 0xffff0000, v56
	v_pk_fma_f32 v[8:9], v[6:7], v[6:7], v[8:9]
	v_lshlrev_b32_e32 v40, 16, v64
	v_and_b32_e32 v41, 0xffff0000, v64
	v_pk_fma_f32 v[250:251], v[40:41], v[40:41], v[250:251]
	v_lshlrev_b32_e32 v6, 16, v57
	v_and_b32_e32 v7, 0xffff0000, v57
	v_pk_fma_f32 v[8:9], v[6:7], v[6:7], v[8:9]
	v_lshlrev_b32_e32 v40, 16, v65
	v_and_b32_e32 v41, 0xffff0000, v65
	v_pk_fma_f32 v[250:251], v[40:41], v[40:41], v[250:251]
	v_lshlrev_b32_e32 v6, 16, v58
	v_and_b32_e32 v7, 0xffff0000, v58
	v_pk_fma_f32 v[8:9], v[6:7], v[6:7], v[8:9]
	v_lshlrev_b32_e32 v40, 16, v66
	v_and_b32_e32 v41, 0xffff0000, v66
	v_pk_fma_f32 v[250:251], v[40:41], v[40:41], v[250:251]
	v_lshlrev_b32_e32 v6, 16, v59
	v_and_b32_e32 v7, 0xffff0000, v59
	v_pk_fma_f32 v[8:9], v[6:7], v[6:7], v[8:9]
	v_lshlrev_b32_e32 v40, 16, v67
	v_and_b32_e32 v41, 0xffff0000, v67
	v_pk_fma_f32 v[250:251], v[40:41], v[40:41], v[250:251]
	v_add_f32_e32 v8, v8, v9
	v_add_f32_e32 v250, v250, v251
	s_nop 1
	v_add_f32_dpp v8, v8, v8 quad_perm:[1,0,3,2] row_mask:0xf bank_mask:0xf
	v_add_f32_dpp v250, v250, v250 quad_perm:[1,0,3,2] row_mask:0xf bank_mask:0xf
	s_nop 1
	v_add_f32_dpp v8, v8, v8 quad_perm:[2,3,0,1] row_mask:0xf bank_mask:0xf
	v_add_f32_dpp v250, v250, v250 quad_perm:[2,3,0,1] row_mask:0xf bank_mask:0xf
	s_nop 1
	v_add_f32_dpp v8, v8, v8 row_half_mirror row_mask:0xf bank_mask:0xf
	v_add_f32_dpp v250, v250, v250 row_half_mirror row_mask:0xf bank_mask:0xf
	s_nop 1
	v_add_f32_dpp v8, v8, v8 row_mirror row_mask:0xf bank_mask:0xf
	v_add_f32_dpp v250, v250, v250 row_mirror row_mask:0xf bank_mask:0xf
	s_nop 1
	ds_bpermute_b32 v6, v14, v8
	ds_bpermute_b32 v40, v14, v250
	s_waitcnt lgkmcnt(0)
	v_add_f32_e32 v6, v8, v6
	v_mul_f32_e32 v6, 0x3b000000, v6
	v_mul_f32_e32 v8, 0x3b800000, v8
	v_cndmask_b32_e64 v8, v8, v6, s[6:7]
	v_add_f32_e32 v8, 0x358637bd, v8
	v_rsq_f32_e32 v252, v8
	v_add_f32_e32 v40, v250, v40
	v_mul_f32_e32 v40, 0x3b000000, v40
	v_mul_f32_e32 v250, 0x3b800000, v250
	v_cndmask_b32_e64 v250, v250, v40, s[6:7]
	v_add_f32_e32 v250, 0x358637bd, v250
	v_rsq_f32_e32 v254, v250
	s_nop 1
	v_lshlrev_b32_e32 v6, 16, v52
	v_and_b32_e32 v7, 0xffff0000, v52
	v_pk_mul_f32 v[6:7], v[6:7], v[252:253] op_sel_hi:[1,0]
	v_pk_mul_f32 v[6:7], v[6:7], v[16:17]
	v_cvt_pk_bf16_f32 v52, v6, v7
	v_lshlrev_b32_e32 v40, 16, v60
	v_and_b32_e32 v41, 0xffff0000, v60
	v_pk_mul_f32 v[40:41], v[40:41], v[254:255] op_sel_hi:[1,0]
	v_pk_mul_f32 v[40:41], v[40:41], v[16:17]
	v_cvt_pk_bf16_f32 v60, v40, v41
	v_lshlrev_b32_e32 v6, 16, v53
	v_and_b32_e32 v7, 0xffff0000, v53
	v_pk_mul_f32 v[6:7], v[6:7], v[252:253] op_sel_hi:[1,0]
	v_pk_mul_f32 v[6:7], v[6:7], v[18:19]
	v_cvt_pk_bf16_f32 v53, v6, v7
	v_lshlrev_b32_e32 v40, 16, v61
	v_and_b32_e32 v41, 0xffff0000, v61
	v_pk_mul_f32 v[40:41], v[40:41], v[254:255] op_sel_hi:[1,0]
	v_pk_mul_f32 v[40:41], v[40:41], v[18:19]
	v_cvt_pk_bf16_f32 v61, v40, v41
	v_lshlrev_b32_e32 v6, 16, v54
	v_and_b32_e32 v7, 0xffff0000, v54
	v_pk_mul_f32 v[6:7], v[6:7], v[252:253] op_sel_hi:[1,0]
	v_pk_mul_f32 v[6:7], v[6:7], v[20:21]
	v_cvt_pk_bf16_f32 v54, v6, v7
	v_lshlrev_b32_e32 v40, 16, v62
	v_and_b32_e32 v41, 0xffff0000, v62
	v_pk_mul_f32 v[40:41], v[40:41], v[254:255] op_sel_hi:[1,0]
	v_pk_mul_f32 v[40:41], v[40:41], v[20:21]
	v_cvt_pk_bf16_f32 v62, v40, v41
	v_lshlrev_b32_e32 v6, 16, v55
	v_and_b32_e32 v7, 0xffff0000, v55
	v_pk_mul_f32 v[6:7], v[6:7], v[252:253] op_sel_hi:[1,0]
	v_pk_mul_f32 v[6:7], v[6:7], v[22:23]
	v_cvt_pk_bf16_f32 v55, v6, v7
	v_lshlrev_b32_e32 v40, 16, v63
	v_and_b32_e32 v41, 0xffff0000, v63
	v_pk_mul_f32 v[40:41], v[40:41], v[254:255] op_sel_hi:[1,0]
	v_pk_mul_f32 v[40:41], v[40:41], v[22:23]
	v_cvt_pk_bf16_f32 v63, v40, v41
	v_lshlrev_b32_e32 v6, 16, v56
	v_and_b32_e32 v7, 0xffff0000, v56
	v_pk_mul_f32 v[6:7], v[6:7], v[252:253] op_sel_hi:[1,0]
	v_pk_mul_f32 v[6:7], v[6:7], v[24:25]
	v_cvt_pk_bf16_f32 v56, v6, v7
	v_lshlrev_b32_e32 v40, 16, v64
	v_and_b32_e32 v41, 0xffff0000, v64
	v_pk_mul_f32 v[40:41], v[40:41], v[254:255] op_sel_hi:[1,0]
	v_pk_mul_f32 v[40:41], v[40:41], v[24:25]
	v_cvt_pk_bf16_f32 v64, v40, v41
	v_lshlrev_b32_e32 v6, 16, v57
	v_and_b32_e32 v7, 0xffff0000, v57
	v_pk_mul_f32 v[6:7], v[6:7], v[252:253] op_sel_hi:[1,0]
	v_pk_mul_f32 v[6:7], v[6:7], v[26:27]
	v_cvt_pk_bf16_f32 v57, v6, v7
	v_lshlrev_b32_e32 v40, 16, v65
	v_and_b32_e32 v41, 0xffff0000, v65
	v_pk_mul_f32 v[40:41], v[40:41], v[254:255] op_sel_hi:[1,0]
	v_pk_mul_f32 v[40:41], v[40:41], v[26:27]
	v_cvt_pk_bf16_f32 v65, v40, v41
	v_lshlrev_b32_e32 v6, 16, v58
	v_and_b32_e32 v7, 0xffff0000, v58
	v_pk_mul_f32 v[6:7], v[6:7], v[252:253] op_sel_hi:[1,0]
	v_pk_mul_f32 v[6:7], v[6:7], v[28:29]
	v_cvt_pk_bf16_f32 v58, v6, v7
	v_lshlrev_b32_e32 v40, 16, v66
	v_and_b32_e32 v41, 0xffff0000, v66
	v_pk_mul_f32 v[40:41], v[40:41], v[254:255] op_sel_hi:[1,0]
	v_pk_mul_f32 v[40:41], v[40:41], v[28:29]
	v_cvt_pk_bf16_f32 v66, v40, v41
	v_lshlrev_b32_e32 v6, 16, v59
	v_and_b32_e32 v7, 0xffff0000, v59
	v_pk_mul_f32 v[6:7], v[6:7], v[252:253] op_sel_hi:[1,0]
	v_pk_mul_f32 v[6:7], v[6:7], v[30:31]
	v_cvt_pk_bf16_f32 v59, v6, v7
	v_lshlrev_b32_e32 v40, 16, v67
	v_and_b32_e32 v41, 0xffff0000, v67
	v_pk_mul_f32 v[40:41], v[40:41], v[254:255] op_sel_hi:[1,0]
	v_pk_mul_f32 v[40:41], v[40:41], v[30:31]
	v_cvt_pk_bf16_f32 v67, v40, v41
	global_store_dwordx4 v[4:5], v[52:55], off
	global_store_dwordx4 v[4:5], v[56:59], off offset:16
	global_store_dwordx4 v[4:5], v[60:63], off offset:2048
	global_store_dwordx4 v[4:5], v[64:67], off offset:2064
	v_lshl_add_u64 v[4:5], v[4:5], 0, s[100:101]
	s_nop 1
	global_load_dwordx4 v[52:55], v[2:3], off
	global_load_dwordx4 v[56:59], v[2:3], off offset:16
	global_load_dwordx4 v[60:63], v[2:3], off offset:2048
	global_load_dwordx4 v[64:67], v[2:3], off offset:2064
	v_lshl_add_u64 v[2:3], v[2:3], 0, s[100:101]
	s_waitcnt vmcnt(8)
	v_lshlrev_b32_e32 v6, 16, v32
	v_and_b32_e32 v7, 0xffff0000, v32
	v_pk_mul_f32 v[8:9], v[6:7], v[6:7]
	v_lshlrev_b32_e32 v40, 16, v44
	v_and_b32_e32 v41, 0xffff0000, v44
	v_pk_mul_f32 v[250:251], v[40:41], v[40:41]
	v_lshlrev_b32_e32 v6, 16, v33
	v_and_b32_e32 v7, 0xffff0000, v33
	v_pk_fma_f32 v[8:9], v[6:7], v[6:7], v[8:9]
	v_lshlrev_b32_e32 v40, 16, v45
	v_and_b32_e32 v41, 0xffff0000, v45
	v_pk_fma_f32 v[250:251], v[40:41], v[40:41], v[250:251]
	v_lshlrev_b32_e32 v6, 16, v34
	v_and_b32_e32 v7, 0xffff0000, v34
	v_pk_fma_f32 v[8:9], v[6:7], v[6:7], v[8:9]
	v_lshlrev_b32_e32 v40, 16, v46
	v_and_b32_e32 v41, 0xffff0000, v46
	v_pk_fma_f32 v[250:251], v[40:41], v[40:41], v[250:251]
	v_lshlrev_b32_e32 v6, 16, v35
	v_and_b32_e32 v7, 0xffff0000, v35
	v_pk_fma_f32 v[8:9], v[6:7], v[6:7], v[8:9]
	v_lshlrev_b32_e32 v40, 16, v47
	v_and_b32_e32 v41, 0xffff0000, v47
	v_pk_fma_f32 v[250:251], v[40:41], v[40:41], v[250:251]
	v_lshlrev_b32_e32 v6, 16, v36
	v_and_b32_e32 v7, 0xffff0000, v36
	v_pk_fma_f32 v[8:9], v[6:7], v[6:7], v[8:9]
	v_lshlrev_b32_e32 v40, 16, v48
	v_and_b32_e32 v41, 0xffff0000, v48
	v_pk_fma_f32 v[250:251], v[40:41], v[40:41], v[250:251]
	v_lshlrev_b32_e32 v6, 16, v37
	v_and_b32_e32 v7, 0xffff0000, v37
	v_pk_fma_f32 v[8:9], v[6:7], v[6:7], v[8:9]
	v_lshlrev_b32_e32 v40, 16, v49
	v_and_b32_e32 v41, 0xffff0000, v49
	v_pk_fma_f32 v[250:251], v[40:41], v[40:41], v[250:251]
	v_lshlrev_b32_e32 v6, 16, v38
	v_and_b32_e32 v7, 0xffff0000, v38
	v_pk_fma_f32 v[8:9], v[6:7], v[6:7], v[8:9]
	v_lshlrev_b32_e32 v40, 16, v50
	v_and_b32_e32 v41, 0xffff0000, v50
	v_pk_fma_f32 v[250:251], v[40:41], v[40:41], v[250:251]
	v_lshlrev_b32_e32 v6, 16, v39
	v_and_b32_e32 v7, 0xffff0000, v39
	v_pk_fma_f32 v[8:9], v[6:7], v[6:7], v[8:9]
	v_lshlrev_b32_e32 v40, 16, v51
	v_and_b32_e32 v41, 0xffff0000, v51
	v_pk_fma_f32 v[250:251], v[40:41], v[40:41], v[250:251]
	v_add_f32_e32 v8, v8, v9
	v_add_f32_e32 v250, v250, v251
	s_nop 1
	v_add_f32_dpp v8, v8, v8 quad_perm:[1,0,3,2] row_mask:0xf bank_mask:0xf
	v_add_f32_dpp v250, v250, v250 quad_perm:[1,0,3,2] row_mask:0xf bank_mask:0xf
	s_nop 1
	v_add_f32_dpp v8, v8, v8 quad_perm:[2,3,0,1] row_mask:0xf bank_mask:0xf
	v_add_f32_dpp v250, v250, v250 quad_perm:[2,3,0,1] row_mask:0xf bank_mask:0xf
	s_nop 1
	v_add_f32_dpp v8, v8, v8 row_half_mirror row_mask:0xf bank_mask:0xf
	v_add_f32_dpp v250, v250, v250 row_half_mirror row_mask:0xf bank_mask:0xf
	s_nop 1
	v_add_f32_dpp v8, v8, v8 row_mirror row_mask:0xf bank_mask:0xf
	v_add_f32_dpp v250, v250, v250 row_mirror row_mask:0xf bank_mask:0xf
	s_nop 1
	ds_bpermute_b32 v6, v14, v8
	ds_bpermute_b32 v40, v14, v250
	s_waitcnt lgkmcnt(0)
	v_add_f32_e32 v6, v8, v6
	v_mul_f32_e32 v6, 0x3b000000, v6
	v_mul_f32_e32 v8, 0x3b800000, v8
	v_cndmask_b32_e64 v8, v8, v6, s[6:7]
	v_add_f32_e32 v8, 0x358637bd, v8
	v_rsq_f32_e32 v252, v8
	v_add_f32_e32 v40, v250, v40
	v_mul_f32_e32 v40, 0x3b000000, v40
	v_mul_f32_e32 v250, 0x3b800000, v250
	v_cndmask_b32_e64 v250, v250, v40, s[6:7]
	v_add_f32_e32 v250, 0x358637bd, v250
	v_rsq_f32_e32 v254, v250
	s_nop 1
	v_lshlrev_b32_e32 v6, 16, v32
	v_and_b32_e32 v7, 0xffff0000, v32
	v_pk_mul_f32 v[6:7], v[6:7], v[252:253] op_sel_hi:[1,0]
	v_pk_mul_f32 v[6:7], v[6:7], v[16:17]
	v_cvt_pk_bf16_f32 v32, v6, v7
	v_lshlrev_b32_e32 v40, 16, v44
	v_and_b32_e32 v41, 0xffff0000, v44
	v_pk_mul_f32 v[40:41], v[40:41], v[254:255] op_sel_hi:[1,0]
	v_pk_mul_f32 v[40:41], v[40:41], v[16:17]
	v_cvt_pk_bf16_f32 v44, v40, v41
	v_lshlrev_b32_e32 v6, 16, v33
	v_and_b32_e32 v7, 0xffff0000, v33
	v_pk_mul_f32 v[6:7], v[6:7], v[252:253] op_sel_hi:[1,0]
	v_pk_mul_f32 v[6:7], v[6:7], v[18:19]
	v_cvt_pk_bf16_f32 v33, v6, v7
	v_lshlrev_b32_e32 v40, 16, v45
	v_and_b32_e32 v41, 0xffff0000, v45
	v_pk_mul_f32 v[40:41], v[40:41], v[254:255] op_sel_hi:[1,0]
	v_pk_mul_f32 v[40:41], v[40:41], v[18:19]
	v_cvt_pk_bf16_f32 v45, v40, v41
	v_lshlrev_b32_e32 v6, 16, v34
	v_and_b32_e32 v7, 0xffff0000, v34
	v_pk_mul_f32 v[6:7], v[6:7], v[252:253] op_sel_hi:[1,0]
	v_pk_mul_f32 v[6:7], v[6:7], v[20:21]
	v_cvt_pk_bf16_f32 v34, v6, v7
	v_lshlrev_b32_e32 v40, 16, v46
	v_and_b32_e32 v41, 0xffff0000, v46
	v_pk_mul_f32 v[40:41], v[40:41], v[254:255] op_sel_hi:[1,0]
	v_pk_mul_f32 v[40:41], v[40:41], v[20:21]
	v_cvt_pk_bf16_f32 v46, v40, v41
	v_lshlrev_b32_e32 v6, 16, v35
	v_and_b32_e32 v7, 0xffff0000, v35
	v_pk_mul_f32 v[6:7], v[6:7], v[252:253] op_sel_hi:[1,0]
	v_pk_mul_f32 v[6:7], v[6:7], v[22:23]
	v_cvt_pk_bf16_f32 v35, v6, v7
	v_lshlrev_b32_e32 v40, 16, v47
	v_and_b32_e32 v41, 0xffff0000, v47
	v_pk_mul_f32 v[40:41], v[40:41], v[254:255] op_sel_hi:[1,0]
	v_pk_mul_f32 v[40:41], v[40:41], v[22:23]
	v_cvt_pk_bf16_f32 v47, v40, v41
	v_lshlrev_b32_e32 v6, 16, v36
	v_and_b32_e32 v7, 0xffff0000, v36
	v_pk_mul_f32 v[6:7], v[6:7], v[252:253] op_sel_hi:[1,0]
	v_pk_mul_f32 v[6:7], v[6:7], v[24:25]
	v_cvt_pk_bf16_f32 v36, v6, v7
	v_lshlrev_b32_e32 v40, 16, v48
	v_and_b32_e32 v41, 0xffff0000, v48
	v_pk_mul_f32 v[40:41], v[40:41], v[254:255] op_sel_hi:[1,0]
	v_pk_mul_f32 v[40:41], v[40:41], v[24:25]
	v_cvt_pk_bf16_f32 v48, v40, v41
	v_lshlrev_b32_e32 v6, 16, v37
	v_and_b32_e32 v7, 0xffff0000, v37
	v_pk_mul_f32 v[6:7], v[6:7], v[252:253] op_sel_hi:[1,0]
	v_pk_mul_f32 v[6:7], v[6:7], v[26:27]
	v_cvt_pk_bf16_f32 v37, v6, v7
	v_lshlrev_b32_e32 v40, 16, v49
	v_and_b32_e32 v41, 0xffff0000, v49
	v_pk_mul_f32 v[40:41], v[40:41], v[254:255] op_sel_hi:[1,0]
	v_pk_mul_f32 v[40:41], v[40:41], v[26:27]
	v_cvt_pk_bf16_f32 v49, v40, v41
	v_lshlrev_b32_e32 v6, 16, v38
	v_and_b32_e32 v7, 0xffff0000, v38
	v_pk_mul_f32 v[6:7], v[6:7], v[252:253] op_sel_hi:[1,0]
	v_pk_mul_f32 v[6:7], v[6:7], v[28:29]
	v_cvt_pk_bf16_f32 v38, v6, v7
	v_lshlrev_b32_e32 v40, 16, v50
	v_and_b32_e32 v41, 0xffff0000, v50
	v_pk_mul_f32 v[40:41], v[40:41], v[254:255] op_sel_hi:[1,0]
	v_pk_mul_f32 v[40:41], v[40:41], v[28:29]
	v_cvt_pk_bf16_f32 v50, v40, v41
	v_lshlrev_b32_e32 v6, 16, v39
	v_and_b32_e32 v7, 0xffff0000, v39
	v_pk_mul_f32 v[6:7], v[6:7], v[252:253] op_sel_hi:[1,0]
	v_pk_mul_f32 v[6:7], v[6:7], v[30:31]
	v_cvt_pk_bf16_f32 v39, v6, v7
	v_lshlrev_b32_e32 v40, 16, v51
	v_and_b32_e32 v41, 0xffff0000, v51
	v_pk_mul_f32 v[40:41], v[40:41], v[254:255] op_sel_hi:[1,0]
	v_pk_mul_f32 v[40:41], v[40:41], v[30:31]
	v_cvt_pk_bf16_f32 v51, v40, v41
	global_store_dwordx4 v[4:5], v[32:35], off
	global_store_dwordx4 v[4:5], v[36:39], off offset:16
	global_store_dwordx4 v[4:5], v[44:47], off offset:2048
	global_store_dwordx4 v[4:5], v[48:51], off offset:2064
	v_lshl_add_u64 v[4:5], v[4:5], 0, s[100:101]
	s_nop 1
	s_waitcnt vmcnt(4)
	v_lshlrev_b32_e32 v6, 16, v52
	v_and_b32_e32 v7, 0xffff0000, v52
	v_pk_mul_f32 v[8:9], v[6:7], v[6:7]
	v_lshlrev_b32_e32 v40, 16, v60
	v_and_b32_e32 v41, 0xffff0000, v60
	v_pk_mul_f32 v[250:251], v[40:41], v[40:41]
	v_lshlrev_b32_e32 v6, 16, v53
	v_and_b32_e32 v7, 0xffff0000, v53
	v_pk_fma_f32 v[8:9], v[6:7], v[6:7], v[8:9]
	v_lshlrev_b32_e32 v40, 16, v61
	v_and_b32_e32 v41, 0xffff0000, v61
	v_pk_fma_f32 v[250:251], v[40:41], v[40:41], v[250:251]
	v_lshlrev_b32_e32 v6, 16, v54
	v_and_b32_e32 v7, 0xffff0000, v54
	v_pk_fma_f32 v[8:9], v[6:7], v[6:7], v[8:9]
	v_lshlrev_b32_e32 v40, 16, v62
	v_and_b32_e32 v41, 0xffff0000, v62
	v_pk_fma_f32 v[250:251], v[40:41], v[40:41], v[250:251]
	v_lshlrev_b32_e32 v6, 16, v55
	v_and_b32_e32 v7, 0xffff0000, v55
	v_pk_fma_f32 v[8:9], v[6:7], v[6:7], v[8:9]
	v_lshlrev_b32_e32 v40, 16, v63
	v_and_b32_e32 v41, 0xffff0000, v63
	v_pk_fma_f32 v[250:251], v[40:41], v[40:41], v[250:251]
	v_lshlrev_b32_e32 v6, 16, v56
	v_and_b32_e32 v7, 0xffff0000, v56
	v_pk_fma_f32 v[8:9], v[6:7], v[6:7], v[8:9]
	v_lshlrev_b32_e32 v40, 16, v64
	v_and_b32_e32 v41, 0xffff0000, v64
	v_pk_fma_f32 v[250:251], v[40:41], v[40:41], v[250:251]
	v_lshlrev_b32_e32 v6, 16, v57
	v_and_b32_e32 v7, 0xffff0000, v57
	v_pk_fma_f32 v[8:9], v[6:7], v[6:7], v[8:9]
	v_lshlrev_b32_e32 v40, 16, v65
	v_and_b32_e32 v41, 0xffff0000, v65
	v_pk_fma_f32 v[250:251], v[40:41], v[40:41], v[250:251]
	v_lshlrev_b32_e32 v6, 16, v58
	v_and_b32_e32 v7, 0xffff0000, v58
	v_pk_fma_f32 v[8:9], v[6:7], v[6:7], v[8:9]
	v_lshlrev_b32_e32 v40, 16, v66
	v_and_b32_e32 v41, 0xffff0000, v66
	v_pk_fma_f32 v[250:251], v[40:41], v[40:41], v[250:251]
	v_lshlrev_b32_e32 v6, 16, v59
	v_and_b32_e32 v7, 0xffff0000, v59
	v_pk_fma_f32 v[8:9], v[6:7], v[6:7], v[8:9]
	v_lshlrev_b32_e32 v40, 16, v67
	v_and_b32_e32 v41, 0xffff0000, v67
	v_pk_fma_f32 v[250:251], v[40:41], v[40:41], v[250:251]
	v_add_f32_e32 v8, v8, v9
	v_add_f32_e32 v250, v250, v251
	s_nop 1
	v_add_f32_dpp v8, v8, v8 quad_perm:[1,0,3,2] row_mask:0xf bank_mask:0xf
	v_add_f32_dpp v250, v250, v250 quad_perm:[1,0,3,2] row_mask:0xf bank_mask:0xf
	s_nop 1
	v_add_f32_dpp v8, v8, v8 quad_perm:[2,3,0,1] row_mask:0xf bank_mask:0xf
	v_add_f32_dpp v250, v250, v250 quad_perm:[2,3,0,1] row_mask:0xf bank_mask:0xf
	s_nop 1
	v_add_f32_dpp v8, v8, v8 row_half_mirror row_mask:0xf bank_mask:0xf
	v_add_f32_dpp v250, v250, v250 row_half_mirror row_mask:0xf bank_mask:0xf
	s_nop 1
	v_add_f32_dpp v8, v8, v8 row_mirror row_mask:0xf bank_mask:0xf
	v_add_f32_dpp v250, v250, v250 row_mirror row_mask:0xf bank_mask:0xf
	s_nop 1
	ds_bpermute_b32 v6, v14, v8
	ds_bpermute_b32 v40, v14, v250
	s_waitcnt lgkmcnt(0)
	v_add_f32_e32 v6, v8, v6
	v_mul_f32_e32 v6, 0x3b000000, v6
	v_mul_f32_e32 v8, 0x3b800000, v8
	v_cndmask_b32_e64 v8, v8, v6, s[6:7]
	v_add_f32_e32 v8, 0x358637bd, v8
	v_rsq_f32_e32 v252, v8
	v_add_f32_e32 v40, v250, v40
	v_mul_f32_e32 v40, 0x3b000000, v40
	v_mul_f32_e32 v250, 0x3b800000, v250
	v_cndmask_b32_e64 v250, v250, v40, s[6:7]
	v_add_f32_e32 v250, 0x358637bd, v250
	v_rsq_f32_e32 v254, v250
	s_nop 1
	v_lshlrev_b32_e32 v6, 16, v52
	v_and_b32_e32 v7, 0xffff0000, v52
	v_pk_mul_f32 v[6:7], v[6:7], v[252:253] op_sel_hi:[1,0]
	v_pk_mul_f32 v[6:7], v[6:7], v[16:17]
	v_cvt_pk_bf16_f32 v52, v6, v7
	v_lshlrev_b32_e32 v40, 16, v60
	v_and_b32_e32 v41, 0xffff0000, v60
	v_pk_mul_f32 v[40:41], v[40:41], v[254:255] op_sel_hi:[1,0]
	v_pk_mul_f32 v[40:41], v[40:41], v[16:17]
	v_cvt_pk_bf16_f32 v60, v40, v41
	v_lshlrev_b32_e32 v6, 16, v53
	v_and_b32_e32 v7, 0xffff0000, v53
	v_pk_mul_f32 v[6:7], v[6:7], v[252:253] op_sel_hi:[1,0]
	v_pk_mul_f32 v[6:7], v[6:7], v[18:19]
	v_cvt_pk_bf16_f32 v53, v6, v7
	v_lshlrev_b32_e32 v40, 16, v61
	v_and_b32_e32 v41, 0xffff0000, v61
	v_pk_mul_f32 v[40:41], v[40:41], v[254:255] op_sel_hi:[1,0]
	v_pk_mul_f32 v[40:41], v[40:41], v[18:19]
	v_cvt_pk_bf16_f32 v61, v40, v41
	v_lshlrev_b32_e32 v6, 16, v54
	v_and_b32_e32 v7, 0xffff0000, v54
	v_pk_mul_f32 v[6:7], v[6:7], v[252:253] op_sel_hi:[1,0]
	v_pk_mul_f32 v[6:7], v[6:7], v[20:21]
	v_cvt_pk_bf16_f32 v54, v6, v7
	v_lshlrev_b32_e32 v40, 16, v62
	v_and_b32_e32 v41, 0xffff0000, v62
	v_pk_mul_f32 v[40:41], v[40:41], v[254:255] op_sel_hi:[1,0]
	v_pk_mul_f32 v[40:41], v[40:41], v[20:21]
	v_cvt_pk_bf16_f32 v62, v40, v41
	v_lshlrev_b32_e32 v6, 16, v55
	v_and_b32_e32 v7, 0xffff0000, v55
	v_pk_mul_f32 v[6:7], v[6:7], v[252:253] op_sel_hi:[1,0]
	v_pk_mul_f32 v[6:7], v[6:7], v[22:23]
	v_cvt_pk_bf16_f32 v55, v6, v7
	v_lshlrev_b32_e32 v40, 16, v63
	v_and_b32_e32 v41, 0xffff0000, v63
	v_pk_mul_f32 v[40:41], v[40:41], v[254:255] op_sel_hi:[1,0]
	v_pk_mul_f32 v[40:41], v[40:41], v[22:23]
	v_cvt_pk_bf16_f32 v63, v40, v41
	v_lshlrev_b32_e32 v6, 16, v56
	v_and_b32_e32 v7, 0xffff0000, v56
	v_pk_mul_f32 v[6:7], v[6:7], v[252:253] op_sel_hi:[1,0]
	v_pk_mul_f32 v[6:7], v[6:7], v[24:25]
	v_cvt_pk_bf16_f32 v56, v6, v7
	v_lshlrev_b32_e32 v40, 16, v64
	v_and_b32_e32 v41, 0xffff0000, v64
	v_pk_mul_f32 v[40:41], v[40:41], v[254:255] op_sel_hi:[1,0]
	v_pk_mul_f32 v[40:41], v[40:41], v[24:25]
	v_cvt_pk_bf16_f32 v64, v40, v41
	v_lshlrev_b32_e32 v6, 16, v57
	v_and_b32_e32 v7, 0xffff0000, v57
	v_pk_mul_f32 v[6:7], v[6:7], v[252:253] op_sel_hi:[1,0]
	v_pk_mul_f32 v[6:7], v[6:7], v[26:27]
	v_cvt_pk_bf16_f32 v57, v6, v7
	v_lshlrev_b32_e32 v40, 16, v65
	v_and_b32_e32 v41, 0xffff0000, v65
	v_pk_mul_f32 v[40:41], v[40:41], v[254:255] op_sel_hi:[1,0]
	v_pk_mul_f32 v[40:41], v[40:41], v[26:27]
	v_cvt_pk_bf16_f32 v65, v40, v41
	v_lshlrev_b32_e32 v6, 16, v58
	v_and_b32_e32 v7, 0xffff0000, v58
	v_pk_mul_f32 v[6:7], v[6:7], v[252:253] op_sel_hi:[1,0]
	v_pk_mul_f32 v[6:7], v[6:7], v[28:29]
	v_cvt_pk_bf16_f32 v58, v6, v7
	v_lshlrev_b32_e32 v40, 16, v66
	v_and_b32_e32 v41, 0xffff0000, v66
	v_pk_mul_f32 v[40:41], v[40:41], v[254:255] op_sel_hi:[1,0]
	v_pk_mul_f32 v[40:41], v[40:41], v[28:29]
	v_cvt_pk_bf16_f32 v66, v40, v41
	v_lshlrev_b32_e32 v6, 16, v59
	v_and_b32_e32 v7, 0xffff0000, v59
	v_pk_mul_f32 v[6:7], v[6:7], v[252:253] op_sel_hi:[1,0]
	v_pk_mul_f32 v[6:7], v[6:7], v[30:31]
	v_cvt_pk_bf16_f32 v59, v6, v7
	v_lshlrev_b32_e32 v40, 16, v67
	v_and_b32_e32 v41, 0xffff0000, v67
	v_pk_mul_f32 v[40:41], v[40:41], v[254:255] op_sel_hi:[1,0]
	v_pk_mul_f32 v[40:41], v[40:41], v[30:31]
	v_cvt_pk_bf16_f32 v67, v40, v41
	global_store_dwordx4 v[4:5], v[52:55], off
	global_store_dwordx4 v[4:5], v[56:59], off offset:16
	global_store_dwordx4 v[4:5], v[60:63], off offset:2048
	global_store_dwordx4 v[4:5], v[64:67], off offset:2064
	v_lshl_add_u64 v[4:5], v[4:5], 0, s[100:101]
	s_nop 1
	s_nop 1
	ds_read_b128 v[44:47], v15
	ds_read_b128 v[48:51], v15 offset:8192
	ds_read_b128 v[52:55], v15 offset:16384
	ds_read_b128 v[56:59], v15 offset:24576
	ds_read_b128 v[60:63], v15 offset:32768
	ds_read_b128 v[64:67], v15 offset:40960
	s_mov_b64 s[80:81], 0x8000
	s_mov_b32 s1, 0x800000
	s_cmpk_eq_u32 s80, 0x8000
	s_waitcnt lgkmcnt(0)
	v_readlane_b32 s1, v249, 63
	s_barrier
	s_add_i32 s0, s1, s0
	s_cmpk_gt_i32 s0, 0xff
	s_cbranch_scc0 .LBB0_389
	v_readlane_b32 s44, v249, 59
	v_readlane_b32 s89, v249, 63
	v_readlane_b32 s46, v249, 61
	v_readlane_b32 s47, v249, 62
	v_readlane_b32 s45, v249, 60

.LBB0_1252:
	v_lshlrev_b32_e32 v15, 4, v242
	ds_write_b128 v15, v[44:47]
	ds_write_b128 v15, v[48:51] offset:8192
	ds_write_b128 v15, v[52:55] offset:16384
	ds_write_b128 v15, v[56:59] offset:24576
	ds_write_b128 v15, v[60:63] offset:32768
	ds_write_b128 v15, v[64:67] offset:40960
	s_mov_b64 s[8:9], 0x16a00000
	s_mov_b64 s[100:101], 0x1000
	v_lshl_add_u64 v[2:3], v[0:1], 0, s[8:9]
	v_lshl_add_u64 v[4:5], v[0:1], 0, s[8:9]
	global_load_dwordx4 v[16:19], v[112:113], off
	global_load_dwordx4 v[20:23], v[112:113], off offset:16
	global_load_dwordx4 v[24:27], v[112:113], off offset:32
	global_load_dwordx4 v[28:31], v[112:113], off offset:48
	s_waitcnt lgkmcnt(0)
	global_load_dwordx4 v[32:35], v[2:3], off
	global_load_dwordx4 v[36:39], v[2:3], off offset:16
	global_load_dwordx4 v[44:47], v[2:3], off offset:2048
	global_load_dwordx4 v[48:51], v[2:3], off offset:2064
	v_lshl_add_u64 v[2:3], v[2:3], 0, s[100:101]
	global_load_dwordx4 v[52:55], v[2:3], off
	global_load_dwordx4 v[56:59], v[2:3], off offset:16
	global_load_dwordx4 v[60:63], v[2:3], off offset:2048
	global_load_dwordx4 v[64:67], v[2:3], off offset:2064
	v_lshl_add_u64 v[2:3], v[2:3], 0, s[100:101]
	s_waitcnt vmcnt(4)
	v_lshlrev_b32_e32 v6, 16, v32
	v_and_b32_e32 v7, 0xffff0000, v32
	v_pk_mul_f32 v[8:9], v[6:7], v[6:7]
	v_lshlrev_b32_e32 v40, 16, v44
	v_and_b32_e32 v41, 0xffff0000, v44
	v_pk_mul_f32 v[250:251], v[40:41], v[40:41]
	v_lshlrev_b32_e32 v6, 16, v33
	v_and_b32_e32 v7, 0xffff0000, v33
	v_pk_fma_f32 v[8:9], v[6:7], v[6:7], v[8:9]
	v_lshlrev_b32_e32 v40, 16, v45
	v_and_b32_e32 v41, 0xffff0000, v45
	v_pk_fma_f32 v[250:251], v[40:41], v[40:41], v[250:251]
	v_lshlrev_b32_e32 v6, 16, v34
	v_and_b32_e32 v7, 0xffff0000, v34
	v_pk_fma_f32 v[8:9], v[6:7], v[6:7], v[8:9]
	v_lshlrev_b32_e32 v40, 16, v46
	v_and_b32_e32 v41, 0xffff0000, v46
	v_pk_fma_f32 v[250:251], v[40:41], v[40:41], v[250:251]
	v_lshlrev_b32_e32 v6, 16, v35
	v_and_b32_e32 v7, 0xffff0000, v35
	v_pk_fma_f32 v[8:9], v[6:7], v[6:7], v[8:9]
	v_lshlrev_b32_e32 v40, 16, v47
	v_and_b32_e32 v41, 0xffff0000, v47
	v_pk_fma_f32 v[250:251], v[40:41], v[40:41], v[250:251]
	v_lshlrev_b32_e32 v6, 16, v36
	v_and_b32_e32 v7, 0xffff0000, v36
	v_pk_fma_f32 v[8:9], v[6:7], v[6:7], v[8:9]
	v_lshlrev_b32_e32 v40, 16, v48
	v_and_b32_e32 v41, 0xffff0000, v48
	v_pk_fma_f32 v[250:251], v[40:41], v[40:41], v[250:251]
	v_lshlrev_b32_e32 v6, 16, v37
	v_and_b32_e32 v7, 0xffff0000, v37
	v_pk_fma_f32 v[8:9], v[6:7], v[6:7], v[8:9]
	v_lshlrev_b32_e32 v40, 16, v49
	v_and_b32_e32 v41, 0xffff0000, v49
	v_pk_fma_f32 v[250:251], v[40:41], v[40:41], v[250:251]
	v_lshlrev_b32_e32 v6, 16, v38
	v_and_b32_e32 v7, 0xffff0000, v38
	v_pk_fma_f32 v[8:9], v[6:7], v[6:7], v[8:9]
	v_lshlrev_b32_e32 v40, 16, v50
	v_and_b32_e32 v41, 0xffff0000, v50
	v_pk_fma_f32 v[250:251], v[40:41], v[40:41], v[250:251]
	v_lshlrev_b32_e32 v6, 16, v39
	v_and_b32_e32 v7, 0xffff0000, v39
	v_pk_fma_f32 v[8:9], v[6:7], v[6:7], v[8:9]
	v_lshlrev_b32_e32 v40, 16, v51
	v_and_b32_e32 v41, 0xffff0000, v51
	v_pk_fma_f32 v[250:251], v[40:41], v[40:41], v[250:251]
	v_add_f32_e32 v8, v8, v9
	v_add_f32_e32 v250, v250, v251
	s_nop 1
	v_add_f32_dpp v8, v8, v8 quad_perm:[1,0,3,2] row_mask:0xf bank_mask:0xf
	v_add_f32_dpp v250, v250, v250 quad_perm:[1,0,3,2] row_mask:0xf bank_mask:0xf
	s_nop 1
	v_add_f32_dpp v8, v8, v8 quad_perm:[2,3,0,1] row_mask:0xf bank_mask:0xf
	v_add_f32_dpp v250, v250, v250 quad_perm:[2,3,0,1] row_mask:0xf bank_mask:0xf
	s_nop 1
	v_add_f32_dpp v8, v8, v8 row_half_mirror row_mask:0xf bank_mask:0xf
	v_add_f32_dpp v250, v250, v250 row_half_mirror row_mask:0xf bank_mask:0xf
	s_nop 1
	v_add_f32_dpp v8, v8, v8 row_mirror row_mask:0xf bank_mask:0xf
	v_add_f32_dpp v250, v250, v250 row_mirror row_mask:0xf bank_mask:0xf
	s_nop 1
	ds_bpermute_b32 v6, v14, v8
	ds_bpermute_b32 v40, v14, v250
	s_waitcnt lgkmcnt(0)
	v_add_f32_e32 v6, v8, v6
	v_mul_f32_e32 v6, 0x3b000000, v6
	v_mul_f32_e32 v8, 0x3b800000, v8
	v_cndmask_b32_e64 v8, v8, v6, s[6:7]
	v_add_f32_e32 v8, 0x358637bd, v8
	v_rsq_f32_e32 v252, v8
	v_add_f32_e32 v40, v250, v40
	v_mul_f32_e32 v40, 0x3b000000, v40
	v_mul_f32_e32 v250, 0x3b800000, v250
	v_cndmask_b32_e64 v250, v250, v40, s[6:7]
	v_add_f32_e32 v250, 0x358637bd, v250
	v_rsq_f32_e32 v254, v250
	s_nop 1
	v_lshlrev_b32_e32 v6, 16, v32
	v_and_b32_e32 v7, 0xffff0000, v32
	v_pk_mul_f32 v[6:7], v[6:7], v[252:253] op_sel_hi:[1,0]
	v_pk_mul_f32 v[6:7], v[6:7], v[16:17]
	v_cvt_pk_bf16_f32 v32, v6, v7
	v_lshlrev_b32_e32 v40, 16, v44
	v_and_b32_e32 v41, 0xffff0000, v44
	v_pk_mul_f32 v[40:41], v[40:41], v[254:255] op_sel_hi:[1,0]
	v_pk_mul_f32 v[40:41], v[40:41], v[16:17]
	v_cvt_pk_bf16_f32 v44, v40, v41
	v_lshlrev_b32_e32 v6, 16, v33
	v_and_b32_e32 v7, 0xffff0000, v33
	v_pk_mul_f32 v[6:7], v[6:7], v[252:253] op_sel_hi:[1,0]
	v_pk_mul_f32 v[6:7], v[6:7], v[18:19]
	v_cvt_pk_bf16_f32 v33, v6, v7
	v_lshlrev_b32_e32 v40, 16, v45
	v_and_b32_e32 v41, 0xffff0000, v45
	v_pk_mul_f32 v[40:41], v[40:41], v[254:255] op_sel_hi:[1,0]
	v_pk_mul_f32 v[40:41], v[40:41], v[18:19]
	v_cvt_pk_bf16_f32 v45, v40, v41
	v_lshlrev_b32_e32 v6, 16, v34
	v_and_b32_e32 v7, 0xffff0000, v34
	v_pk_mul_f32 v[6:7], v[6:7], v[252:253] op_sel_hi:[1,0]
	v_pk_mul_f32 v[6:7], v[6:7], v[20:21]
	v_cvt_pk_bf16_f32 v34, v6, v7
	v_lshlrev_b32_e32 v40, 16, v46
	v_and_b32_e32 v41, 0xffff0000, v46
	v_pk_mul_f32 v[40:41], v[40:41], v[254:255] op_sel_hi:[1,0]
	v_pk_mul_f32 v[40:41], v[40:41], v[20:21]
	v_cvt_pk_bf16_f32 v46, v40, v41
	v_lshlrev_b32_e32 v6, 16, v35
	v_and_b32_e32 v7, 0xffff0000, v35
	v_pk_mul_f32 v[6:7], v[6:7], v[252:253] op_sel_hi:[1,0]
	v_pk_mul_f32 v[6:7], v[6:7], v[22:23]
	v_cvt_pk_bf16_f32 v35, v6, v7
	v_lshlrev_b32_e32 v40, 16, v47
	v_and_b32_e32 v41, 0xffff0000, v47
	v_pk_mul_f32 v[40:41], v[40:41], v[254:255] op_sel_hi:[1,0]
	v_pk_mul_f32 v[40:41], v[40:41], v[22:23]
	v_cvt_pk_bf16_f32 v47, v40, v41
	v_lshlrev_b32_e32 v6, 16, v36
	v_and_b32_e32 v7, 0xffff0000, v36
	v_pk_mul_f32 v[6:7], v[6:7], v[252:253] op_sel_hi:[1,0]
	v_pk_mul_f32 v[6:7], v[6:7], v[24:25]
	v_cvt_pk_bf16_f32 v36, v6, v7
	v_lshlrev_b32_e32 v40, 16, v48
	v_and_b32_e32 v41, 0xffff0000, v48
	v_pk_mul_f32 v[40:41], v[40:41], v[254:255] op_sel_hi:[1,0]
	v_pk_mul_f32 v[40:41], v[40:41], v[24:25]
	v_cvt_pk_bf16_f32 v48, v40, v41
	v_lshlrev_b32_e32 v6, 16, v37
	v_and_b32_e32 v7, 0xffff0000, v37
	v_pk_mul_f32 v[6:7], v[6:7], v[252:253] op_sel_hi:[1,0]
	v_pk_mul_f32 v[6:7], v[6:7], v[26:27]
	v_cvt_pk_bf16_f32 v37, v6, v7
	v_lshlrev_b32_e32 v40, 16, v49
	v_and_b32_e32 v41, 0xffff0000, v49
	v_pk_mul_f32 v[40:41], v[40:41], v[254:255] op_sel_hi:[1,0]
	v_pk_mul_f32 v[40:41], v[40:41], v[26:27]
	v_cvt_pk_bf16_f32 v49, v40, v41
	v_lshlrev_b32_e32 v6, 16, v38
	v_and_b32_e32 v7, 0xffff0000, v38
	v_pk_mul_f32 v[6:7], v[6:7], v[252:253] op_sel_hi:[1,0]
	v_pk_mul_f32 v[6:7], v[6:7], v[28:29]
	v_cvt_pk_bf16_f32 v38, v6, v7
	v_lshlrev_b32_e32 v40, 16, v50
	v_and_b32_e32 v41, 0xffff0000, v50
	v_pk_mul_f32 v[40:41], v[40:41], v[254:255] op_sel_hi:[1,0]
	v_pk_mul_f32 v[40:41], v[40:41], v[28:29]
	v_cvt_pk_bf16_f32 v50, v40, v41
	v_lshlrev_b32_e32 v6, 16, v39
	v_and_b32_e32 v7, 0xffff0000, v39
	v_pk_mul_f32 v[6:7], v[6:7], v[252:253] op_sel_hi:[1,0]
	v_pk_mul_f32 v[6:7], v[6:7], v[30:31]
	v_cvt_pk_bf16_f32 v39, v6, v7
	v_lshlrev_b32_e32 v40, 16, v51
	v_and_b32_e32 v41, 0xffff0000, v51
	v_pk_mul_f32 v[40:41], v[40:41], v[254:255] op_sel_hi:[1,0]
	v_pk_mul_f32 v[40:41], v[40:41], v[30:31]
	v_cvt_pk_bf16_f32 v51, v40, v41
	global_store_dwordx4 v[4:5], v[32:35], off
	global_store_dwordx4 v[4:5], v[36:39], off offset:16
	global_store_dwordx4 v[4:5], v[44:47], off offset:2048
	global_store_dwordx4 v[4:5], v[48:51], off offset:2064
	v_lshl_add_u64 v[4:5], v[4:5], 0, s[100:101]
	s_nop 1
	global_load_dwordx4 v[32:35], v[2:3], off
	global_load_dwordx4 v[36:39], v[2:3], off offset:16
	global_load_dwordx4 v[44:47], v[2:3], off offset:2048
	global_load_dwordx4 v[48:51], v[2:3], off offset:2064
	v_lshl_add_u64 v[2:3], v[2:3], 0, s[100:101]
	s_waitcnt vmcnt(8)
	v_lshlrev_b32_e32 v6, 16, v52
	v_and_b32_e32 v7, 0xffff0000, v52
	v_pk_mul_f32 v[8:9], v[6:7], v[6:7]
	v_lshlrev_b32_e32 v40, 16, v60
	v_and_b32_e32 v41, 0xffff0000, v60
	v_pk_mul_f32 v[250:251], v[40:41], v[40:41]
	v_lshlrev_b32_e32 v6, 16, v53
	v_and_b32_e32 v7, 0xffff0000, v53
	v_pk_fma_f32 v[8:9], v[6:7], v[6:7], v[8:9]
	v_lshlrev_b32_e32 v40, 16, v61
	v_and_b32_e32 v41, 0xffff0000, v61
	v_pk_fma_f32 v[250:251], v[40:41], v[40:41], v[250:251]
	v_lshlrev_b32_e32 v6, 16, v54
	v_and_b32_e32 v7, 0xffff0000, v54
	v_pk_fma_f32 v[8:9], v[6:7], v[6:7], v[8:9]
	v_lshlrev_b32_e32 v40, 16, v62
	v_and_b32_e32 v41, 0xffff0000, v62
	v_pk_fma_f32 v[250:251], v[40:41], v[40:41], v[250:251]
	v_lshlrev_b32_e32 v6, 16, v55
	v_and_b32_e32 v7, 0xffff0000, v55
	v_pk_fma_f32 v[8:9], v[6:7], v[6:7], v[8:9]
	v_lshlrev_b32_e32 v40, 16, v63
	v_and_b32_e32 v41, 0xffff0000, v63
	v_pk_fma_f32 v[250:251], v[40:41], v[40:41], v[250:251]
	v_lshlrev_b32_e32 v6, 16, v56
	v_and_b32_e32 v7, 0xffff0000, v56
	v_pk_fma_f32 v[8:9], v[6:7], v[6:7], v[8:9]
	v_lshlrev_b32_e32 v40, 16, v64
	v_and_b32_e32 v41, 0xffff0000, v64
	v_pk_fma_f32 v[250:251], v[40:41], v[40:41], v[250:251]
	v_lshlrev_b32_e32 v6, 16, v57
	v_and_b32_e32 v7, 0xffff0000, v57
	v_pk_fma_f32 v[8:9], v[6:7], v[6:7], v[8:9]
	v_lshlrev_b32_e32 v40, 16, v65
	v_and_b32_e32 v41, 0xffff0000, v65
	v_pk_fma_f32 v[250:251], v[40:41], v[40:41], v[250:251]
	v_lshlrev_b32_e32 v6, 16, v58
	v_and_b32_e32 v7, 0xffff0000, v58
	v_pk_fma_f32 v[8:9], v[6:7], v[6:7], v[8:9]
	v_lshlrev_b32_e32 v40, 16, v66
	v_and_b32_e32 v41, 0xffff0000, v66
	v_pk_fma_f32 v[250:251], v[40:41], v[40:41], v[250:251]
	v_lshlrev_b32_e32 v6, 16, v59
	v_and_b32_e32 v7, 0xffff0000, v59
	v_pk_fma_f32 v[8:9], v[6:7], v[6:7], v[8:9]
	v_lshlrev_b32_e32 v40, 16, v67
	v_and_b32_e32 v41, 0xffff0000, v67
	v_pk_fma_f32 v[250:251], v[40:41], v[40:41], v[250:251]
	v_add_f32_e32 v8, v8, v9
	v_add_f32_e32 v250, v250, v251
	s_nop 1
	v_add_f32_dpp v8, v8, v8 quad_perm:[1,0,3,2] row_mask:0xf bank_mask:0xf
	v_add_f32_dpp v250, v250, v250 quad_perm:[1,0,3,2] row_mask:0xf bank_mask:0xf
	s_nop 1
	v_add_f32_dpp v8, v8, v8 quad_perm:[2,3,0,1] row_mask:0xf bank_mask:0xf
	v_add_f32_dpp v250, v250, v250 quad_perm:[2,3,0,1] row_mask:0xf bank_mask:0xf
	s_nop 1
	v_add_f32_dpp v8, v8, v8 row_half_mirror row_mask:0xf bank_mask:0xf
	v_add_f32_dpp v250, v250, v250 row_half_mirror row_mask:0xf bank_mask:0xf
	s_nop 1
	v_add_f32_dpp v8, v8, v8 row_mirror row_mask:0xf bank_mask:0xf
	v_add_f32_dpp v250, v250, v250 row_mirror row_mask:0xf bank_mask:0xf
	s_nop 1
	ds_bpermute_b32 v6, v14, v8
	ds_bpermute_b32 v40, v14, v250
	s_waitcnt lgkmcnt(0)
	v_add_f32_e32 v6, v8, v6
	v_mul_f32_e32 v6, 0x3b000000, v6
	v_mul_f32_e32 v8, 0x3b800000, v8
	v_cndmask_b32_e64 v8, v8, v6, s[6:7]
	v_add_f32_e32 v8, 0x358637bd, v8
	v_rsq_f32_e32 v252, v8
	v_add_f32_e32 v40, v250, v40
	v_mul_f32_e32 v40, 0x3b000000, v40
	v_mul_f32_e32 v250, 0x3b800000, v250
	v_cndmask_b32_e64 v250, v250, v40, s[6:7]
	v_add_f32_e32 v250, 0x358637bd, v250
	v_rsq_f32_e32 v254, v250
	s_nop 1
	v_lshlrev_b32_e32 v6, 16, v52
	v_and_b32_e32 v7, 0xffff0000, v52
	v_pk_mul_f32 v[6:7], v[6:7], v[252:253] op_sel_hi:[1,0]
	v_pk_mul_f32 v[6:7], v[6:7], v[16:17]
	v_cvt_pk_bf16_f32 v52, v6, v7
	v_lshlrev_b32_e32 v40, 16, v60
	v_and_b32_e32 v41, 0xffff0000, v60
	v_pk_mul_f32 v[40:41], v[40:41], v[254:255] op_sel_hi:[1,0]
	v_pk_mul_f32 v[40:41], v[40:41], v[16:17]
	v_cvt_pk_bf16_f32 v60, v40, v41
	v_lshlrev_b32_e32 v6, 16, v53
	v_and_b32_e32 v7, 0xffff0000, v53
	v_pk_mul_f32 v[6:7], v[6:7], v[252:253] op_sel_hi:[1,0]
	v_pk_mul_f32 v[6:7], v[6:7], v[18:19]
	v_cvt_pk_bf16_f32 v53, v6, v7
	v_lshlrev_b32_e32 v40, 16, v61
	v_and_b32_e32 v41, 0xffff0000, v61
	v_pk_mul_f32 v[40:41], v[40:41], v[254:255] op_sel_hi:[1,0]
	v_pk_mul_f32 v[40:41], v[40:41], v[18:19]
	v_cvt_pk_bf16_f32 v61, v40, v41
	v_lshlrev_b32_e32 v6, 16, v54
	v_and_b32_e32 v7, 0xffff0000, v54
	v_pk_mul_f32 v[6:7], v[6:7], v[252:253] op_sel_hi:[1,0]
	v_pk_mul_f32 v[6:7], v[6:7], v[20:21]
	v_cvt_pk_bf16_f32 v54, v6, v7
	v_lshlrev_b32_e32 v40, 16, v62
	v_and_b32_e32 v41, 0xffff0000, v62
	v_pk_mul_f32 v[40:41], v[40:41], v[254:255] op_sel_hi:[1,0]
	v_pk_mul_f32 v[40:41], v[40:41], v[20:21]
	v_cvt_pk_bf16_f32 v62, v40, v41
	v_lshlrev_b32_e32 v6, 16, v55
	v_and_b32_e32 v7, 0xffff0000, v55
	v_pk_mul_f32 v[6:7], v[6:7], v[252:253] op_sel_hi:[1,0]
	v_pk_mul_f32 v[6:7], v[6:7], v[22:23]
	v_cvt_pk_bf16_f32 v55, v6, v7
	v_lshlrev_b32_e32 v40, 16, v63
	v_and_b32_e32 v41, 0xffff0000, v63
	v_pk_mul_f32 v[40:41], v[40:41], v[254:255] op_sel_hi:[1,0]
	v_pk_mul_f32 v[40:41], v[40:41], v[22:23]
	v_cvt_pk_bf16_f32 v63, v40, v41
	v_lshlrev_b32_e32 v6, 16, v56
	v_and_b32_e32 v7, 0xffff0000, v56
	v_pk_mul_f32 v[6:7], v[6:7], v[252:253] op_sel_hi:[1,0]
	v_pk_mul_f32 v[6:7], v[6:7], v[24:25]
	v_cvt_pk_bf16_f32 v56, v6, v7
	v_lshlrev_b32_e32 v40, 16, v64
	v_and_b32_e32 v41, 0xffff0000, v64
	v_pk_mul_f32 v[40:41], v[40:41], v[254:255] op_sel_hi:[1,0]
	v_pk_mul_f32 v[40:41], v[40:41], v[24:25]
	v_cvt_pk_bf16_f32 v64, v40, v41
	v_lshlrev_b32_e32 v6, 16, v57
	v_and_b32_e32 v7, 0xffff0000, v57
	v_pk_mul_f32 v[6:7], v[6:7], v[252:253] op_sel_hi:[1,0]
	v_pk_mul_f32 v[6:7], v[6:7], v[26:27]
	v_cvt_pk_bf16_f32 v57, v6, v7
	v_lshlrev_b32_e32 v40, 16, v65
	v_and_b32_e32 v41, 0xffff0000, v65
	v_pk_mul_f32 v[40:41], v[40:41], v[254:255] op_sel_hi:[1,0]
	v_pk_mul_f32 v[40:41], v[40:41], v[26:27]
	v_cvt_pk_bf16_f32 v65, v40, v41
	v_lshlrev_b32_e32 v6, 16, v58
	v_and_b32_e32 v7, 0xffff0000, v58
	v_pk_mul_f32 v[6:7], v[6:7], v[252:253] op_sel_hi:[1,0]
	v_pk_mul_f32 v[6:7], v[6:7], v[28:29]
	v_cvt_pk_bf16_f32 v58, v6, v7
	v_lshlrev_b32_e32 v40, 16, v66
	v_and_b32_e32 v41, 0xffff0000, v66
	v_pk_mul_f32 v[40:41], v[40:41], v[254:255] op_sel_hi:[1,0]
	v_pk_mul_f32 v[40:41], v[40:41], v[28:29]
	v_cvt_pk_bf16_f32 v66, v40, v41
	v_lshlrev_b32_e32 v6, 16, v59
	v_and_b32_e32 v7, 0xffff0000, v59
	v_pk_mul_f32 v[6:7], v[6:7], v[252:253] op_sel_hi:[1,0]
	v_pk_mul_f32 v[6:7], v[6:7], v[30:31]
	v_cvt_pk_bf16_f32 v59, v6, v7
	v_lshlrev_b32_e32 v40, 16, v67
	v_and_b32_e32 v41, 0xffff0000, v67
	v_pk_mul_f32 v[40:41], v[40:41], v[254:255] op_sel_hi:[1,0]
	v_pk_mul_f32 v[40:41], v[40:41], v[30:31]
	v_cvt_pk_bf16_f32 v67, v40, v41
	global_store_dwordx4 v[4:5], v[52:55], off
	global_store_dwordx4 v[4:5], v[56:59], off offset:16
	global_store_dwordx4 v[4:5], v[60:63], off offset:2048
	global_store_dwordx4 v[4:5], v[64:67], off offset:2064
	v_lshl_add_u64 v[4:5], v[4:5], 0, s[100:101]
	s_nop 1
	global_load_dwordx4 v[52:55], v[2:3], off
	global_load_dwordx4 v[56:59], v[2:3], off offset:16
	global_load_dwordx4 v[60:63], v[2:3], off offset:2048
	global_load_dwordx4 v[64:67], v[2:3], off offset:2064
	v_lshl_add_u64 v[2:3], v[2:3], 0, s[100:101]
	s_waitcnt vmcnt(8)
	v_lshlrev_b32_e32 v6, 16, v32
	v_and_b32_e32 v7, 0xffff0000, v32
	v_pk_mul_f32 v[8:9], v[6:7], v[6:7]
	v_lshlrev_b32_e32 v40, 16, v44
	v_and_b32_e32 v41, 0xffff0000, v44
	v_pk_mul_f32 v[250:251], v[40:41], v[40:41]
	v_lshlrev_b32_e32 v6, 16, v33
	v_and_b32_e32 v7, 0xffff0000, v33
	v_pk_fma_f32 v[8:9], v[6:7], v[6:7], v[8:9]
	v_lshlrev_b32_e32 v40, 16, v45
	v_and_b32_e32 v41, 0xffff0000, v45
	v_pk_fma_f32 v[250:251], v[40:41], v[40:41], v[250:251]
	v_lshlrev_b32_e32 v6, 16, v34
	v_and_b32_e32 v7, 0xffff0000, v34
	v_pk_fma_f32 v[8:9], v[6:7], v[6:7], v[8:9]
	v_lshlrev_b32_e32 v40, 16, v46
	v_and_b32_e32 v41, 0xffff0000, v46
	v_pk_fma_f32 v[250:251], v[40:41], v[40:41], v[250:251]
	v_lshlrev_b32_e32 v6, 16, v35
	v_and_b32_e32 v7, 0xffff0000, v35
	v_pk_fma_f32 v[8:9], v[6:7], v[6:7], v[8:9]
	v_lshlrev_b32_e32 v40, 16, v47
	v_and_b32_e32 v41, 0xffff0000, v47
	v_pk_fma_f32 v[250:251], v[40:41], v[40:41], v[250:251]
	v_lshlrev_b32_e32 v6, 16, v36
	v_and_b32_e32 v7, 0xffff0000, v36
	v_pk_fma_f32 v[8:9], v[6:7], v[6:7], v[8:9]
	v_lshlrev_b32_e32 v40, 16, v48
	v_and_b32_e32 v41, 0xffff0000, v48
	v_pk_fma_f32 v[250:251], v[40:41], v[40:41], v[250:251]
	v_lshlrev_b32_e32 v6, 16, v37
	v_and_b32_e32 v7, 0xffff0000, v37
	v_pk_fma_f32 v[8:9], v[6:7], v[6:7], v[8:9]
	v_lshlrev_b32_e32 v40, 16, v49
	v_and_b32_e32 v41, 0xffff0000, v49
	v_pk_fma_f32 v[250:251], v[40:41], v[40:41], v[250:251]
	v_lshlrev_b32_e32 v6, 16, v38
	v_and_b32_e32 v7, 0xffff0000, v38
	v_pk_fma_f32 v[8:9], v[6:7], v[6:7], v[8:9]
	v_lshlrev_b32_e32 v40, 16, v50
	v_and_b32_e32 v41, 0xffff0000, v50
	v_pk_fma_f32 v[250:251], v[40:41], v[40:41], v[250:251]
	v_lshlrev_b32_e32 v6, 16, v39
	v_and_b32_e32 v7, 0xffff0000, v39
	v_pk_fma_f32 v[8:9], v[6:7], v[6:7], v[8:9]
	v_lshlrev_b32_e32 v40, 16, v51
	v_and_b32_e32 v41, 0xffff0000, v51
	v_pk_fma_f32 v[250:251], v[40:41], v[40:41], v[250:251]
	v_add_f32_e32 v8, v8, v9
	v_add_f32_e32 v250, v250, v251
	s_nop 1
	v_add_f32_dpp v8, v8, v8 quad_perm:[1,0,3,2] row_mask:0xf bank_mask:0xf
	v_add_f32_dpp v250, v250, v250 quad_perm:[1,0,3,2] row_mask:0xf bank_mask:0xf
	s_nop 1
	v_add_f32_dpp v8, v8, v8 quad_perm:[2,3,0,1] row_mask:0xf bank_mask:0xf
	v_add_f32_dpp v250, v250, v250 quad_perm:[2,3,0,1] row_mask:0xf bank_mask:0xf
	s_nop 1
	v_add_f32_dpp v8, v8, v8 row_half_mirror row_mask:0xf bank_mask:0xf
	v_add_f32_dpp v250, v250, v250 row_half_mirror row_mask:0xf bank_mask:0xf
	s_nop 1
	v_add_f32_dpp v8, v8, v8 row_mirror row_mask:0xf bank_mask:0xf
	v_add_f32_dpp v250, v250, v250 row_mirror row_mask:0xf bank_mask:0xf
	s_nop 1
	ds_bpermute_b32 v6, v14, v8
	ds_bpermute_b32 v40, v14, v250
	s_waitcnt lgkmcnt(0)
	v_add_f32_e32 v6, v8, v6
	v_mul_f32_e32 v6, 0x3b000000, v6
	v_mul_f32_e32 v8, 0x3b800000, v8
	v_cndmask_b32_e64 v8, v8, v6, s[6:7]
	v_add_f32_e32 v8, 0x358637bd, v8
	v_rsq_f32_e32 v252, v8
	v_add_f32_e32 v40, v250, v40
	v_mul_f32_e32 v40, 0x3b000000, v40
	v_mul_f32_e32 v250, 0x3b800000, v250
	v_cndmask_b32_e64 v250, v250, v40, s[6:7]
	v_add_f32_e32 v250, 0x358637bd, v250
	v_rsq_f32_e32 v254, v250
	s_nop 1
	v_lshlrev_b32_e32 v6, 16, v32
	v_and_b32_e32 v7, 0xffff0000, v32
	v_pk_mul_f32 v[6:7], v[6:7], v[252:253] op_sel_hi:[1,0]
	v_pk_mul_f32 v[6:7], v[6:7], v[16:17]
	v_cvt_pk_bf16_f32 v32, v6, v7
	v_lshlrev_b32_e32 v40, 16, v44
	v_and_b32_e32 v41, 0xffff0000, v44
	v_pk_mul_f32 v[40:41], v[40:41], v[254:255] op_sel_hi:[1,0]
	v_pk_mul_f32 v[40:41], v[40:41], v[16:17]
	v_cvt_pk_bf16_f32 v44, v40, v41
	v_lshlrev_b32_e32 v6, 16, v33
	v_and_b32_e32 v7, 0xffff0000, v33
	v_pk_mul_f32 v[6:7], v[6:7], v[252:253] op_sel_hi:[1,0]
	v_pk_mul_f32 v[6:7], v[6:7], v[18:19]
	v_cvt_pk_bf16_f32 v33, v6, v7
	v_lshlrev_b32_e32 v40, 16, v45
	v_and_b32_e32 v41, 0xffff0000, v45
	v_pk_mul_f32 v[40:41], v[40:41], v[254:255] op_sel_hi:[1,0]
	v_pk_mul_f32 v[40:41], v[40:41], v[18:19]
	v_cvt_pk_bf16_f32 v45, v40, v41
	v_lshlrev_b32_e32 v6, 16, v34
	v_and_b32_e32 v7, 0xffff0000, v34
	v_pk_mul_f32 v[6:7], v[6:7], v[252:253] op_sel_hi:[1,0]
	v_pk_mul_f32 v[6:7], v[6:7], v[20:21]
	v_cvt_pk_bf16_f32 v34, v6, v7
	v_lshlrev_b32_e32 v40, 16, v46
	v_and_b32_e32 v41, 0xffff0000, v46
	v_pk_mul_f32 v[40:41], v[40:41], v[254:255] op_sel_hi:[1,0]
	v_pk_mul_f32 v[40:41], v[40:41], v[20:21]
	v_cvt_pk_bf16_f32 v46, v40, v41
	v_lshlrev_b32_e32 v6, 16, v35
	v_and_b32_e32 v7, 0xffff0000, v35
	v_pk_mul_f32 v[6:7], v[6:7], v[252:253] op_sel_hi:[1,0]
	v_pk_mul_f32 v[6:7], v[6:7], v[22:23]
	v_cvt_pk_bf16_f32 v35, v6, v7
	v_lshlrev_b32_e32 v40, 16, v47
	v_and_b32_e32 v41, 0xffff0000, v47
	v_pk_mul_f32 v[40:41], v[40:41], v[254:255] op_sel_hi:[1,0]
	v_pk_mul_f32 v[40:41], v[40:41], v[22:23]
	v_cvt_pk_bf16_f32 v47, v40, v41
	v_lshlrev_b32_e32 v6, 16, v36
	v_and_b32_e32 v7, 0xffff0000, v36
	v_pk_mul_f32 v[6:7], v[6:7], v[252:253] op_sel_hi:[1,0]
	v_pk_mul_f32 v[6:7], v[6:7], v[24:25]
	v_cvt_pk_bf16_f32 v36, v6, v7
	v_lshlrev_b32_e32 v40, 16, v48
	v_and_b32_e32 v41, 0xffff0000, v48
	v_pk_mul_f32 v[40:41], v[40:41], v[254:255] op_sel_hi:[1,0]
	v_pk_mul_f32 v[40:41], v[40:41], v[24:25]
	v_cvt_pk_bf16_f32 v48, v40, v41
	v_lshlrev_b32_e32 v6, 16, v37
	v_and_b32_e32 v7, 0xffff0000, v37
	v_pk_mul_f32 v[6:7], v[6:7], v[252:253] op_sel_hi:[1,0]
	v_pk_mul_f32 v[6:7], v[6:7], v[26:27]
	v_cvt_pk_bf16_f32 v37, v6, v7
	v_lshlrev_b32_e32 v40, 16, v49
	v_and_b32_e32 v41, 0xffff0000, v49
	v_pk_mul_f32 v[40:41], v[40:41], v[254:255] op_sel_hi:[1,0]
	v_pk_mul_f32 v[40:41], v[40:41], v[26:27]
	v_cvt_pk_bf16_f32 v49, v40, v41
	v_lshlrev_b32_e32 v6, 16, v38
	v_and_b32_e32 v7, 0xffff0000, v38
	v_pk_mul_f32 v[6:7], v[6:7], v[252:253] op_sel_hi:[1,0]
	v_pk_mul_f32 v[6:7], v[6:7], v[28:29]
	v_cvt_pk_bf16_f32 v38, v6, v7
	v_lshlrev_b32_e32 v40, 16, v50
	v_and_b32_e32 v41, 0xffff0000, v50
	v_pk_mul_f32 v[40:41], v[40:41], v[254:255] op_sel_hi:[1,0]
	v_pk_mul_f32 v[40:41], v[40:41], v[28:29]
	v_cvt_pk_bf16_f32 v50, v40, v41
	v_lshlrev_b32_e32 v6, 16, v39
	v_and_b32_e32 v7, 0xffff0000, v39
	v_pk_mul_f32 v[6:7], v[6:7], v[252:253] op_sel_hi:[1,0]
	v_pk_mul_f32 v[6:7], v[6:7], v[30:31]
	v_cvt_pk_bf16_f32 v39, v6, v7
	v_lshlrev_b32_e32 v40, 16, v51
	v_and_b32_e32 v41, 0xffff0000, v51
	v_pk_mul_f32 v[40:41], v[40:41], v[254:255] op_sel_hi:[1,0]
	v_pk_mul_f32 v[40:41], v[40:41], v[30:31]
	v_cvt_pk_bf16_f32 v51, v40, v41
	global_store_dwordx4 v[4:5], v[32:35], off
	global_store_dwordx4 v[4:5], v[36:39], off offset:16
	global_store_dwordx4 v[4:5], v[44:47], off offset:2048
	global_store_dwordx4 v[4:5], v[48:51], off offset:2064
	v_lshl_add_u64 v[4:5], v[4:5], 0, s[100:101]
	s_nop 1
	global_load_dwordx4 v[32:35], v[2:3], off
	global_load_dwordx4 v[36:39], v[2:3], off offset:16
	global_load_dwordx4 v[44:47], v[2:3], off offset:2048
	global_load_dwordx4 v[48:51], v[2:3], off offset:2064
	v_lshl_add_u64 v[2:3], v[2:3], 0, s[100:101]
	s_waitcnt vmcnt(8)
	v_lshlrev_b32_e32 v6, 16, v52
	v_and_b32_e32 v7, 0xffff0000, v52
	v_pk_mul_f32 v[8:9], v[6:7], v[6:7]
	v_lshlrev_b32_e32 v40, 16, v60
	v_and_b32_e32 v41, 0xffff0000, v60
	v_pk_mul_f32 v[250:251], v[40:41], v[40:41]
	v_lshlrev_b32_e32 v6, 16, v53
	v_and_b32_e32 v7, 0xffff0000, v53
	v_pk_fma_f32 v[8:9], v[6:7], v[6:7], v[8:9]
	v_lshlrev_b32_e32 v40, 16, v61
	v_and_b32_e32 v41, 0xffff0000, v61
	v_pk_fma_f32 v[250:251], v[40:41], v[40:41], v[250:251]
	v_lshlrev_b32_e32 v6, 16, v54
	v_and_b32_e32 v7, 0xffff0000, v54
	v_pk_fma_f32 v[8:9], v[6:7], v[6:7], v[8:9]
	v_lshlrev_b32_e32 v40, 16, v62
	v_and_b32_e32 v41, 0xffff0000, v62
	v_pk_fma_f32 v[250:251], v[40:41], v[40:41], v[250:251]
	v_lshlrev_b32_e32 v6, 16, v55
	v_and_b32_e32 v7, 0xffff0000, v55
	v_pk_fma_f32 v[8:9], v[6:7], v[6:7], v[8:9]
	v_lshlrev_b32_e32 v40, 16, v63
	v_and_b32_e32 v41, 0xffff0000, v63
	v_pk_fma_f32 v[250:251], v[40:41], v[40:41], v[250:251]
	v_lshlrev_b32_e32 v6, 16, v56
	v_and_b32_e32 v7, 0xffff0000, v56
	v_pk_fma_f32 v[8:9], v[6:7], v[6:7], v[8:9]
	v_lshlrev_b32_e32 v40, 16, v64
	v_and_b32_e32 v41, 0xffff0000, v64
	v_pk_fma_f32 v[250:251], v[40:41], v[40:41], v[250:251]
	v_lshlrev_b32_e32 v6, 16, v57
	v_and_b32_e32 v7, 0xffff0000, v57
	v_pk_fma_f32 v[8:9], v[6:7], v[6:7], v[8:9]
	v_lshlrev_b32_e32 v40, 16, v65
	v_and_b32_e32 v41, 0xffff0000, v65
	v_pk_fma_f32 v[250:251], v[40:41], v[40:41], v[250:251]
	v_lshlrev_b32_e32 v6, 16, v58
	v_and_b32_e32 v7, 0xffff0000, v58
	v_pk_fma_f32 v[8:9], v[6:7], v[6:7], v[8:9]
	v_lshlrev_b32_e32 v40, 16, v66
	v_and_b32_e32 v41, 0xffff0000, v66
	v_pk_fma_f32 v[250:251], v[40:41], v[40:41], v[250:251]
	v_lshlrev_b32_e32 v6, 16, v59
	v_and_b32_e32 v7, 0xffff0000, v59
	v_pk_fma_f32 v[8:9], v[6:7], v[6:7], v[8:9]
	v_lshlrev_b32_e32 v40, 16, v67
	v_and_b32_e32 v41, 0xffff0000, v67
	v_pk_fma_f32 v[250:251], v[40:41], v[40:41], v[250:251]
	v_add_f32_e32 v8, v8, v9
	v_add_f32_e32 v250, v250, v251
	s_nop 1
	v_add_f32_dpp v8, v8, v8 quad_perm:[1,0,3,2] row_mask:0xf bank_mask:0xf
	v_add_f32_dpp v250, v250, v250 quad_perm:[1,0,3,2] row_mask:0xf bank_mask:0xf
	s_nop 1
	v_add_f32_dpp v8, v8, v8 quad_perm:[2,3,0,1] row_mask:0xf bank_mask:0xf
	v_add_f32_dpp v250, v250, v250 quad_perm:[2,3,0,1] row_mask:0xf bank_mask:0xf
	s_nop 1
	v_add_f32_dpp v8, v8, v8 row_half_mirror row_mask:0xf bank_mask:0xf
	v_add_f32_dpp v250, v250, v250 row_half_mirror row_mask:0xf bank_mask:0xf
	s_nop 1
	v_add_f32_dpp v8, v8, v8 row_mirror row_mask:0xf bank_mask:0xf
	v_add_f32_dpp v250, v250, v250 row_mirror row_mask:0xf bank_mask:0xf
	s_nop 1
	ds_bpermute_b32 v6, v14, v8
	ds_bpermute_b32 v40, v14, v250
	s_waitcnt lgkmcnt(0)
	v_add_f32_e32 v6, v8, v6
	v_mul_f32_e32 v6, 0x3b000000, v6
	v_mul_f32_e32 v8, 0x3b800000, v8
	v_cndmask_b32_e64 v8, v8, v6, s[6:7]
	v_add_f32_e32 v8, 0x358637bd, v8
	v_rsq_f32_e32 v252, v8
	v_add_f32_e32 v40, v250, v40
	v_mul_f32_e32 v40, 0x3b000000, v40
	v_mul_f32_e32 v250, 0x3b800000, v250
	v_cndmask_b32_e64 v250, v250, v40, s[6:7]
	v_add_f32_e32 v250, 0x358637bd, v250
	v_rsq_f32_e32 v254, v250
	s_nop 1
	v_lshlrev_b32_e32 v6, 16, v52
	v_and_b32_e32 v7, 0xffff0000, v52
	v_pk_mul_f32 v[6:7], v[6:7], v[252:253] op_sel_hi:[1,0]
	v_pk_mul_f32 v[6:7], v[6:7], v[16:17]
	v_cvt_pk_bf16_f32 v52, v6, v7
	v_lshlrev_b32_e32 v40, 16, v60
	v_and_b32_e32 v41, 0xffff0000, v60
	v_pk_mul_f32 v[40:41], v[40:41], v[254:255] op_sel_hi:[1,0]
	v_pk_mul_f32 v[40:41], v[40:41], v[16:17]
	v_cvt_pk_bf16_f32 v60, v40, v41
	v_lshlrev_b32_e32 v6, 16, v53
	v_and_b32_e32 v7, 0xffff0000, v53
	v_pk_mul_f32 v[6:7], v[6:7], v[252:253] op_sel_hi:[1,0]
	v_pk_mul_f32 v[6:7], v[6:7], v[18:19]
	v_cvt_pk_bf16_f32 v53, v6, v7
	v_lshlrev_b32_e32 v40, 16, v61
	v_and_b32_e32 v41, 0xffff0000, v61
	v_pk_mul_f32 v[40:41], v[40:41], v[254:255] op_sel_hi:[1,0]
	v_pk_mul_f32 v[40:41], v[40:41], v[18:19]
	v_cvt_pk_bf16_f32 v61, v40, v41
	v_lshlrev_b32_e32 v6, 16, v54
	v_and_b32_e32 v7, 0xffff0000, v54
	v_pk_mul_f32 v[6:7], v[6:7], v[252:253] op_sel_hi:[1,0]
	v_pk_mul_f32 v[6:7], v[6:7], v[20:21]
	v_cvt_pk_bf16_f32 v54, v6, v7
	v_lshlrev_b32_e32 v40, 16, v62
	v_and_b32_e32 v41, 0xffff0000, v62
	v_pk_mul_f32 v[40:41], v[40:41], v[254:255] op_sel_hi:[1,0]
	v_pk_mul_f32 v[40:41], v[40:41], v[20:21]
	v_cvt_pk_bf16_f32 v62, v40, v41
	v_lshlrev_b32_e32 v6, 16, v55
	v_and_b32_e32 v7, 0xffff0000, v55
	v_pk_mul_f32 v[6:7], v[6:7], v[252:253] op_sel_hi:[1,0]
	v_pk_mul_f32 v[6:7], v[6:7], v[22:23]
	v_cvt_pk_bf16_f32 v55, v6, v7
	v_lshlrev_b32_e32 v40, 16, v63
	v_and_b32_e32 v41, 0xffff0000, v63
	v_pk_mul_f32 v[40:41], v[40:41], v[254:255] op_sel_hi:[1,0]
	v_pk_mul_f32 v[40:41], v[40:41], v[22:23]
	v_cvt_pk_bf16_f32 v63, v40, v41
	v_lshlrev_b32_e32 v6, 16, v56
	v_and_b32_e32 v7, 0xffff0000, v56
	v_pk_mul_f32 v[6:7], v[6:7], v[252:253] op_sel_hi:[1,0]
	v_pk_mul_f32 v[6:7], v[6:7], v[24:25]
	v_cvt_pk_bf16_f32 v56, v6, v7
	v_lshlrev_b32_e32 v40, 16, v64
	v_and_b32_e32 v41, 0xffff0000, v64
	v_pk_mul_f32 v[40:41], v[40:41], v[254:255] op_sel_hi:[1,0]
	v_pk_mul_f32 v[40:41], v[40:41], v[24:25]
	v_cvt_pk_bf16_f32 v64, v40, v41
	v_lshlrev_b32_e32 v6, 16, v57
	v_and_b32_e32 v7, 0xffff0000, v57
	v_pk_mul_f32 v[6:7], v[6:7], v[252:253] op_sel_hi:[1,0]
	v_pk_mul_f32 v[6:7], v[6:7], v[26:27]
	v_cvt_pk_bf16_f32 v57, v6, v7
	v_lshlrev_b32_e32 v40, 16, v65
	v_and_b32_e32 v41, 0xffff0000, v65
	v_pk_mul_f32 v[40:41], v[40:41], v[254:255] op_sel_hi:[1,0]
	v_pk_mul_f32 v[40:41], v[40:41], v[26:27]
	v_cvt_pk_bf16_f32 v65, v40, v41
	v_lshlrev_b32_e32 v6, 16, v58
	v_and_b32_e32 v7, 0xffff0000, v58
	v_pk_mul_f32 v[6:7], v[6:7], v[252:253] op_sel_hi:[1,0]
	v_pk_mul_f32 v[6:7], v[6:7], v[28:29]
	v_cvt_pk_bf16_f32 v58, v6, v7
	v_lshlrev_b32_e32 v40, 16, v66
	v_and_b32_e32 v41, 0xffff0000, v66
	v_pk_mul_f32 v[40:41], v[40:41], v[254:255] op_sel_hi:[1,0]
	v_pk_mul_f32 v[40:41], v[40:41], v[28:29]
	v_cvt_pk_bf16_f32 v66, v40, v41
	v_lshlrev_b32_e32 v6, 16, v59
	v_and_b32_e32 v7, 0xffff0000, v59
	v_pk_mul_f32 v[6:7], v[6:7], v[252:253] op_sel_hi:[1,0]
	v_pk_mul_f32 v[6:7], v[6:7], v[30:31]
	v_cvt_pk_bf16_f32 v59, v6, v7
	v_lshlrev_b32_e32 v40, 16, v67
	v_and_b32_e32 v41, 0xffff0000, v67
	v_pk_mul_f32 v[40:41], v[40:41], v[254:255] op_sel_hi:[1,0]
	v_pk_mul_f32 v[40:41], v[40:41], v[30:31]
	v_cvt_pk_bf16_f32 v67, v40, v41
	global_store_dwordx4 v[4:5], v[52:55], off
	global_store_dwordx4 v[4:5], v[56:59], off offset:16
	global_store_dwordx4 v[4:5], v[60:63], off offset:2048
	global_store_dwordx4 v[4:5], v[64:67], off offset:2064
	v_lshl_add_u64 v[4:5], v[4:5], 0, s[100:101]
	s_nop 1
	global_load_dwordx4 v[52:55], v[2:3], off
	global_load_dwordx4 v[56:59], v[2:3], off offset:16
	global_load_dwordx4 v[60:63], v[2:3], off offset:2048
	global_load_dwordx4 v[64:67], v[2:3], off offset:2064
	v_lshl_add_u64 v[2:3], v[2:3], 0, s[100:101]
	s_waitcnt vmcnt(8)
	v_lshlrev_b32_e32 v6, 16, v32
	v_and_b32_e32 v7, 0xffff0000, v32
	v_pk_mul_f32 v[8:9], v[6:7], v[6:7]
	v_lshlrev_b32_e32 v40, 16, v44
	v_and_b32_e32 v41, 0xffff0000, v44
	v_pk_mul_f32 v[250:251], v[40:41], v[40:41]
	v_lshlrev_b32_e32 v6, 16, v33
	v_and_b32_e32 v7, 0xffff0000, v33
	v_pk_fma_f32 v[8:9], v[6:7], v[6:7], v[8:9]
	v_lshlrev_b32_e32 v40, 16, v45
	v_and_b32_e32 v41, 0xffff0000, v45
	v_pk_fma_f32 v[250:251], v[40:41], v[40:41], v[250:251]
	v_lshlrev_b32_e32 v6, 16, v34
	v_and_b32_e32 v7, 0xffff0000, v34
	v_pk_fma_f32 v[8:9], v[6:7], v[6:7], v[8:9]
	v_lshlrev_b32_e32 v40, 16, v46
	v_and_b32_e32 v41, 0xffff0000, v46
	v_pk_fma_f32 v[250:251], v[40:41], v[40:41], v[250:251]
	v_lshlrev_b32_e32 v6, 16, v35
	v_and_b32_e32 v7, 0xffff0000, v35
	v_pk_fma_f32 v[8:9], v[6:7], v[6:7], v[8:9]
	v_lshlrev_b32_e32 v40, 16, v47
	v_and_b32_e32 v41, 0xffff0000, v47
	v_pk_fma_f32 v[250:251], v[40:41], v[40:41], v[250:251]
	v_lshlrev_b32_e32 v6, 16, v36
	v_and_b32_e32 v7, 0xffff0000, v36
	v_pk_fma_f32 v[8:9], v[6:7], v[6:7], v[8:9]
	v_lshlrev_b32_e32 v40, 16, v48
	v_and_b32_e32 v41, 0xffff0000, v48
	v_pk_fma_f32 v[250:251], v[40:41], v[40:41], v[250:251]
	v_lshlrev_b32_e32 v6, 16, v37
	v_and_b32_e32 v7, 0xffff0000, v37
	v_pk_fma_f32 v[8:9], v[6:7], v[6:7], v[8:9]
	v_lshlrev_b32_e32 v40, 16, v49
	v_and_b32_e32 v41, 0xffff0000, v49
	v_pk_fma_f32 v[250:251], v[40:41], v[40:41], v[250:251]
	v_lshlrev_b32_e32 v6, 16, v38
	v_and_b32_e32 v7, 0xffff0000, v38
	v_pk_fma_f32 v[8:9], v[6:7], v[6:7], v[8:9]
	v_lshlrev_b32_e32 v40, 16, v50
	v_and_b32_e32 v41, 0xffff0000, v50
	v_pk_fma_f32 v[250:251], v[40:41], v[40:41], v[250:251]
	v_lshlrev_b32_e32 v6, 16, v39
	v_and_b32_e32 v7, 0xffff0000, v39
	v_pk_fma_f32 v[8:9], v[6:7], v[6:7], v[8:9]
	v_lshlrev_b32_e32 v40, 16, v51
	v_and_b32_e32 v41, 0xffff0000, v51
	v_pk_fma_f32 v[250:251], v[40:41], v[40:41], v[250:251]
	v_add_f32_e32 v8, v8, v9
	v_add_f32_e32 v250, v250, v251
	s_nop 1
	v_add_f32_dpp v8, v8, v8 quad_perm:[1,0,3,2] row_mask:0xf bank_mask:0xf
	v_add_f32_dpp v250, v250, v250 quad_perm:[1,0,3,2] row_mask:0xf bank_mask:0xf
	s_nop 1
	v_add_f32_dpp v8, v8, v8 quad_perm:[2,3,0,1] row_mask:0xf bank_mask:0xf
	v_add_f32_dpp v250, v250, v250 quad_perm:[2,3,0,1] row_mask:0xf bank_mask:0xf
	s_nop 1
	v_add_f32_dpp v8, v8, v8 row_half_mirror row_mask:0xf bank_mask:0xf
	v_add_f32_dpp v250, v250, v250 row_half_mirror row_mask:0xf bank_mask:0xf
	s_nop 1
	v_add_f32_dpp v8, v8, v8 row_mirror row_mask:0xf bank_mask:0xf
	v_add_f32_dpp v250, v250, v250 row_mirror row_mask:0xf bank_mask:0xf
	s_nop 1
	ds_bpermute_b32 v6, v14, v8
	ds_bpermute_b32 v40, v14, v250
	s_waitcnt lgkmcnt(0)
	v_add_f32_e32 v6, v8, v6
	v_mul_f32_e32 v6, 0x3b000000, v6
	v_mul_f32_e32 v8, 0x3b800000, v8
	v_cndmask_b32_e64 v8, v8, v6, s[6:7]
	v_add_f32_e32 v8, 0x358637bd, v8
	v_rsq_f32_e32 v252, v8
	v_add_f32_e32 v40, v250, v40
	v_mul_f32_e32 v40, 0x3b000000, v40
	v_mul_f32_e32 v250, 0x3b800000, v250
	v_cndmask_b32_e64 v250, v250, v40, s[6:7]
	v_add_f32_e32 v250, 0x358637bd, v250
	v_rsq_f32_e32 v254, v250
	s_nop 1
	v_lshlrev_b32_e32 v6, 16, v32
	v_and_b32_e32 v7, 0xffff0000, v32
	v_pk_mul_f32 v[6:7], v[6:7], v[252:253] op_sel_hi:[1,0]
	v_pk_mul_f32 v[6:7], v[6:7], v[16:17]
	v_cvt_pk_bf16_f32 v32, v6, v7
	v_lshlrev_b32_e32 v40, 16, v44
	v_and_b32_e32 v41, 0xffff0000, v44
	v_pk_mul_f32 v[40:41], v[40:41], v[254:255] op_sel_hi:[1,0]
	v_pk_mul_f32 v[40:41], v[40:41], v[16:17]
	v_cvt_pk_bf16_f32 v44, v40, v41
	v_lshlrev_b32_e32 v6, 16, v33
	v_and_b32_e32 v7, 0xffff0000, v33
	v_pk_mul_f32 v[6:7], v[6:7], v[252:253] op_sel_hi:[1,0]
	v_pk_mul_f32 v[6:7], v[6:7], v[18:19]
	v_cvt_pk_bf16_f32 v33, v6, v7
	v_lshlrev_b32_e32 v40, 16, v45
	v_and_b32_e32 v41, 0xffff0000, v45
	v_pk_mul_f32 v[40:41], v[40:41], v[254:255] op_sel_hi:[1,0]
	v_pk_mul_f32 v[40:41], v[40:41], v[18:19]
	v_cvt_pk_bf16_f32 v45, v40, v41
	v_lshlrev_b32_e32 v6, 16, v34
	v_and_b32_e32 v7, 0xffff0000, v34
	v_pk_mul_f32 v[6:7], v[6:7], v[252:253] op_sel_hi:[1,0]
	v_pk_mul_f32 v[6:7], v[6:7], v[20:21]
	v_cvt_pk_bf16_f32 v34, v6, v7
	v_lshlrev_b32_e32 v40, 16, v46
	v_and_b32_e32 v41, 0xffff0000, v46
	v_pk_mul_f32 v[40:41], v[40:41], v[254:255] op_sel_hi:[1,0]
	v_pk_mul_f32 v[40:41], v[40:41], v[20:21]
	v_cvt_pk_bf16_f32 v46, v40, v41
	v_lshlrev_b32_e32 v6, 16, v35
	v_and_b32_e32 v7, 0xffff0000, v35
	v_pk_mul_f32 v[6:7], v[6:7], v[252:253] op_sel_hi:[1,0]
	v_pk_mul_f32 v[6:7], v[6:7], v[22:23]
	v_cvt_pk_bf16_f32 v35, v6, v7
	v_lshlrev_b32_e32 v40, 16, v47
	v_and_b32_e32 v41, 0xffff0000, v47
	v_pk_mul_f32 v[40:41], v[40:41], v[254:255] op_sel_hi:[1,0]
	v_pk_mul_f32 v[40:41], v[40:41], v[22:23]
	v_cvt_pk_bf16_f32 v47, v40, v41
	v_lshlrev_b32_e32 v6, 16, v36
	v_and_b32_e32 v7, 0xffff0000, v36
	v_pk_mul_f32 v[6:7], v[6:7], v[252:253] op_sel_hi:[1,0]
	v_pk_mul_f32 v[6:7], v[6:7], v[24:25]
	v_cvt_pk_bf16_f32 v36, v6, v7
	v_lshlrev_b32_e32 v40, 16, v48
	v_and_b32_e32 v41, 0xffff0000, v48
	v_pk_mul_f32 v[40:41], v[40:41], v[254:255] op_sel_hi:[1,0]
	v_pk_mul_f32 v[40:41], v[40:41], v[24:25]
	v_cvt_pk_bf16_f32 v48, v40, v41
	v_lshlrev_b32_e32 v6, 16, v37
	v_and_b32_e32 v7, 0xffff0000, v37
	v_pk_mul_f32 v[6:7], v[6:7], v[252:253] op_sel_hi:[1,0]
	v_pk_mul_f32 v[6:7], v[6:7], v[26:27]
	v_cvt_pk_bf16_f32 v37, v6, v7
	v_lshlrev_b32_e32 v40, 16, v49
	v_and_b32_e32 v41, 0xffff0000, v49
	v_pk_mul_f32 v[40:41], v[40:41], v[254:255] op_sel_hi:[1,0]
	v_pk_mul_f32 v[40:41], v[40:41], v[26:27]
	v_cvt_pk_bf16_f32 v49, v40, v41
	v_lshlrev_b32_e32 v6, 16, v38
	v_and_b32_e32 v7, 0xffff0000, v38
	v_pk_mul_f32 v[6:7], v[6:7], v[252:253] op_sel_hi:[1,0]
	v_pk_mul_f32 v[6:7], v[6:7], v[28:29]
	v_cvt_pk_bf16_f32 v38, v6, v7
	v_lshlrev_b32_e32 v40, 16, v50
	v_and_b32_e32 v41, 0xffff0000, v50
	v_pk_mul_f32 v[40:41], v[40:41], v[254:255] op_sel_hi:[1,0]
	v_pk_mul_f32 v[40:41], v[40:41], v[28:29]
	v_cvt_pk_bf16_f32 v50, v40, v41
	v_lshlrev_b32_e32 v6, 16, v39
	v_and_b32_e32 v7, 0xffff0000, v39
	v_pk_mul_f32 v[6:7], v[6:7], v[252:253] op_sel_hi:[1,0]
	v_pk_mul_f32 v[6:7], v[6:7], v[30:31]
	v_cvt_pk_bf16_f32 v39, v6, v7
	v_lshlrev_b32_e32 v40, 16, v51
	v_and_b32_e32 v41, 0xffff0000, v51
	v_pk_mul_f32 v[40:41], v[40:41], v[254:255] op_sel_hi:[1,0]
	v_pk_mul_f32 v[40:41], v[40:41], v[30:31]
	v_cvt_pk_bf16_f32 v51, v40, v41
	global_store_dwordx4 v[4:5], v[32:35], off
	global_store_dwordx4 v[4:5], v[36:39], off offset:16
	global_store_dwordx4 v[4:5], v[44:47], off offset:2048
	global_store_dwordx4 v[4:5], v[48:51], off offset:2064
	v_lshl_add_u64 v[4:5], v[4:5], 0, s[100:101]
	s_nop 1
	global_load_dwordx4 v[32:35], v[2:3], off
	global_load_dwordx4 v[36:39], v[2:3], off offset:16
	global_load_dwordx4 v[44:47], v[2:3], off offset:2048
	global_load_dwordx4 v[48:51], v[2:3], off offset:2064
	v_lshl_add_u64 v[2:3], v[2:3], 0, s[100:101]
	s_waitcnt vmcnt(8)
	v_lshlrev_b32_e32 v6, 16, v52
	v_and_b32_e32 v7, 0xffff0000, v52
	v_pk_mul_f32 v[8:9], v[6:7], v[6:7]
	v_lshlrev_b32_e32 v40, 16, v60
	v_and_b32_e32 v41, 0xffff0000, v60
	v_pk_mul_f32 v[250:251], v[40:41], v[40:41]
	v_lshlrev_b32_e32 v6, 16, v53
	v_and_b32_e32 v7, 0xffff0000, v53
	v_pk_fma_f32 v[8:9], v[6:7], v[6:7], v[8:9]
	v_lshlrev_b32_e32 v40, 16, v61
	v_and_b32_e32 v41, 0xffff0000, v61
	v_pk_fma_f32 v[250:251], v[40:41], v[40:41], v[250:251]
	v_lshlrev_b32_e32 v6, 16, v54
	v_and_b32_e32 v7, 0xffff0000, v54
	v_pk_fma_f32 v[8:9], v[6:7], v[6:7], v[8:9]
	v_lshlrev_b32_e32 v40, 16, v62
	v_and_b32_e32 v41, 0xffff0000, v62
	v_pk_fma_f32 v[250:251], v[40:41], v[40:41], v[250:251]
	v_lshlrev_b32_e32 v6, 16, v55
	v_and_b32_e32 v7, 0xffff0000, v55
	v_pk_fma_f32 v[8:9], v[6:7], v[6:7], v[8:9]
	v_lshlrev_b32_e32 v40, 16, v63
	v_and_b32_e32 v41, 0xffff0000, v63
	v_pk_fma_f32 v[250:251], v[40:41], v[40:41], v[250:251]
	v_lshlrev_b32_e32 v6, 16, v56
	v_and_b32_e32 v7, 0xffff0000, v56
	v_pk_fma_f32 v[8:9], v[6:7], v[6:7], v[8:9]
	v_lshlrev_b32_e32 v40, 16, v64
	v_and_b32_e32 v41, 0xffff0000, v64
	v_pk_fma_f32 v[250:251], v[40:41], v[40:41], v[250:251]
	v_lshlrev_b32_e32 v6, 16, v57
	v_and_b32_e32 v7, 0xffff0000, v57
	v_pk_fma_f32 v[8:9], v[6:7], v[6:7], v[8:9]
	v_lshlrev_b32_e32 v40, 16, v65
	v_and_b32_e32 v41, 0xffff0000, v65
	v_pk_fma_f32 v[250:251], v[40:41], v[40:41], v[250:251]
	v_lshlrev_b32_e32 v6, 16, v58
	v_and_b32_e32 v7, 0xffff0000, v58
	v_pk_fma_f32 v[8:9], v[6:7], v[6:7], v[8:9]
	v_lshlrev_b32_e32 v40, 16, v66
	v_and_b32_e32 v41, 0xffff0000, v66
	v_pk_fma_f32 v[250:251], v[40:41], v[40:41], v[250:251]
	v_lshlrev_b32_e32 v6, 16, v59
	v_and_b32_e32 v7, 0xffff0000, v59
	v_pk_fma_f32 v[8:9], v[6:7], v[6:7], v[8:9]
	v_lshlrev_b32_e32 v40, 16, v67
	v_and_b32_e32 v41, 0xffff0000, v67
	v_pk_fma_f32 v[250:251], v[40:41], v[40:41], v[250:251]
	v_add_f32_e32 v8, v8, v9
	v_add_f32_e32 v250, v250, v251
	s_nop 1
	v_add_f32_dpp v8, v8, v8 quad_perm:[1,0,3,2] row_mask:0xf bank_mask:0xf
	v_add_f32_dpp v250, v250, v250 quad_perm:[1,0,3,2] row_mask:0xf bank_mask:0xf
	s_nop 1
	v_add_f32_dpp v8, v8, v8 quad_perm:[2,3,0,1] row_mask:0xf bank_mask:0xf
	v_add_f32_dpp v250, v250, v250 quad_perm:[2,3,0,1] row_mask:0xf bank_mask:0xf
	s_nop 1
	v_add_f32_dpp v8, v8, v8 row_half_mirror row_mask:0xf bank_mask:0xf
	v_add_f32_dpp v250, v250, v250 row_half_mirror row_mask:0xf bank_mask:0xf
	s_nop 1
	v_add_f32_dpp v8, v8, v8 row_mirror row_mask:0xf bank_mask:0xf
	v_add_f32_dpp v250, v250, v250 row_mirror row_mask:0xf bank_mask:0xf
	s_nop 1
	ds_bpermute_b32 v6, v14, v8
	ds_bpermute_b32 v40, v14, v250
	s_waitcnt lgkmcnt(0)
	v_add_f32_e32 v6, v8, v6
	v_mul_f32_e32 v6, 0x3b000000, v6
	v_mul_f32_e32 v8, 0x3b800000, v8
	v_cndmask_b32_e64 v8, v8, v6, s[6:7]
	v_add_f32_e32 v8, 0x358637bd, v8
	v_rsq_f32_e32 v252, v8
	v_add_f32_e32 v40, v250, v40
	v_mul_f32_e32 v40, 0x3b000000, v40
	v_mul_f32_e32 v250, 0x3b800000, v250
	v_cndmask_b32_e64 v250, v250, v40, s[6:7]
	v_add_f32_e32 v250, 0x358637bd, v250
	v_rsq_f32_e32 v254, v250
	s_nop 1
	v_lshlrev_b32_e32 v6, 16, v52
	v_and_b32_e32 v7, 0xffff0000, v52
	v_pk_mul_f32 v[6:7], v[6:7], v[252:253] op_sel_hi:[1,0]
	v_pk_mul_f32 v[6:7], v[6:7], v[16:17]
	v_cvt_pk_bf16_f32 v52, v6, v7
	v_lshlrev_b32_e32 v40, 16, v60
	v_and_b32_e32 v41, 0xffff0000, v60
	v_pk_mul_f32 v[40:41], v[40:41], v[254:255] op_sel_hi:[1,0]
	v_pk_mul_f32 v[40:41], v[40:41], v[16:17]
	v_cvt_pk_bf16_f32 v60, v40, v41
	v_lshlrev_b32_e32 v6, 16, v53
	v_and_b32_e32 v7, 0xffff0000, v53
	v_pk_mul_f32 v[6:7], v[6:7], v[252:253] op_sel_hi:[1,0]
	v_pk_mul_f32 v[6:7], v[6:7], v[18:19]
	v_cvt_pk_bf16_f32 v53, v6, v7
	v_lshlrev_b32_e32 v40, 16, v61
	v_and_b32_e32 v41, 0xffff0000, v61
	v_pk_mul_f32 v[40:41], v[40:41], v[254:255] op_sel_hi:[1,0]
	v_pk_mul_f32 v[40:41], v[40:41], v[18:19]
	v_cvt_pk_bf16_f32 v61, v40, v41
	v_lshlrev_b32_e32 v6, 16, v54
	v_and_b32_e32 v7, 0xffff0000, v54
	v_pk_mul_f32 v[6:7], v[6:7], v[252:253] op_sel_hi:[1,0]
	v_pk_mul_f32 v[6:7], v[6:7], v[20:21]
	v_cvt_pk_bf16_f32 v54, v6, v7
	v_lshlrev_b32_e32 v40, 16, v62
	v_and_b32_e32 v41, 0xffff0000, v62
	v_pk_mul_f32 v[40:41], v[40:41], v[254:255] op_sel_hi:[1,0]
	v_pk_mul_f32 v[40:41], v[40:41], v[20:21]
	v_cvt_pk_bf16_f32 v62, v40, v41
	v_lshlrev_b32_e32 v6, 16, v55
	v_and_b32_e32 v7, 0xffff0000, v55
	v_pk_mul_f32 v[6:7], v[6:7], v[252:253] op_sel_hi:[1,0]
	v_pk_mul_f32 v[6:7], v[6:7], v[22:23]
	v_cvt_pk_bf16_f32 v55, v6, v7
	v_lshlrev_b32_e32 v40, 16, v63
	v_and_b32_e32 v41, 0xffff0000, v63
	v_pk_mul_f32 v[40:41], v[40:41], v[254:255] op_sel_hi:[1,0]
	v_pk_mul_f32 v[40:41], v[40:41], v[22:23]
	v_cvt_pk_bf16_f32 v63, v40, v41
	v_lshlrev_b32_e32 v6, 16, v56
	v_and_b32_e32 v7, 0xffff0000, v56
	v_pk_mul_f32 v[6:7], v[6:7], v[252:253] op_sel_hi:[1,0]
	v_pk_mul_f32 v[6:7], v[6:7], v[24:25]
	v_cvt_pk_bf16_f32 v56, v6, v7
	v_lshlrev_b32_e32 v40, 16, v64
	v_and_b32_e32 v41, 0xffff0000, v64
	v_pk_mul_f32 v[40:41], v[40:41], v[254:255] op_sel_hi:[1,0]
	v_pk_mul_f32 v[40:41], v[40:41], v[24:25]
	v_cvt_pk_bf16_f32 v64, v40, v41
	v_lshlrev_b32_e32 v6, 16, v57
	v_and_b32_e32 v7, 0xffff0000, v57
	v_pk_mul_f32 v[6:7], v[6:7], v[252:253] op_sel_hi:[1,0]
	v_pk_mul_f32 v[6:7], v[6:7], v[26:27]
	v_cvt_pk_bf16_f32 v57, v6, v7
	v_lshlrev_b32_e32 v40, 16, v65
	v_and_b32_e32 v41, 0xffff0000, v65
	v_pk_mul_f32 v[40:41], v[40:41], v[254:255] op_sel_hi:[1,0]
	v_pk_mul_f32 v[40:41], v[40:41], v[26:27]
	v_cvt_pk_bf16_f32 v65, v40, v41
	v_lshlrev_b32_e32 v6, 16, v58
	v_and_b32_e32 v7, 0xffff0000, v58
	v_pk_mul_f32 v[6:7], v[6:7], v[252:253] op_sel_hi:[1,0]
	v_pk_mul_f32 v[6:7], v[6:7], v[28:29]
	v_cvt_pk_bf16_f32 v58, v6, v7
	v_lshlrev_b32_e32 v40, 16, v66
	v_and_b32_e32 v41, 0xffff0000, v66
	v_pk_mul_f32 v[40:41], v[40:41], v[254:255] op_sel_hi:[1,0]
	v_pk_mul_f32 v[40:41], v[40:41], v[28:29]
	v_cvt_pk_bf16_f32 v66, v40, v41
	v_lshlrev_b32_e32 v6, 16, v59
	v_and_b32_e32 v7, 0xffff0000, v59
	v_pk_mul_f32 v[6:7], v[6:7], v[252:253] op_sel_hi:[1,0]
	v_pk_mul_f32 v[6:7], v[6:7], v[30:31]
	v_cvt_pk_bf16_f32 v59, v6, v7
	v_lshlrev_b32_e32 v40, 16, v67
	v_and_b32_e32 v41, 0xffff0000, v67
	v_pk_mul_f32 v[40:41], v[40:41], v[254:255] op_sel_hi:[1,0]
	v_pk_mul_f32 v[40:41], v[40:41], v[30:31]
	v_cvt_pk_bf16_f32 v67, v40, v41
	global_store_dwordx4 v[4:5], v[52:55], off
	global_store_dwordx4 v[4:5], v[56:59], off offset:16
	global_store_dwordx4 v[4:5], v[60:63], off offset:2048
	global_store_dwordx4 v[4:5], v[64:67], off offset:2064
	v_lshl_add_u64 v[4:5], v[4:5], 0, s[100:101]
	s_nop 1
	global_load_dwordx4 v[52:55], v[2:3], off
	global_load_dwordx4 v[56:59], v[2:3], off offset:16
	global_load_dwordx4 v[60:63], v[2:3], off offset:2048
	global_load_dwordx4 v[64:67], v[2:3], off offset:2064
	v_lshl_add_u64 v[2:3], v[2:3], 0, s[100:101]
	s_waitcnt vmcnt(8)
	v_lshlrev_b32_e32 v6, 16, v32
	v_and_b32_e32 v7, 0xffff0000, v32
	v_pk_mul_f32 v[8:9], v[6:7], v[6:7]
	v_lshlrev_b32_e32 v40, 16, v44
	v_and_b32_e32 v41, 0xffff0000, v44
	v_pk_mul_f32 v[250:251], v[40:41], v[40:41]
	v_lshlrev_b32_e32 v6, 16, v33
	v_and_b32_e32 v7, 0xffff0000, v33
	v_pk_fma_f32 v[8:9], v[6:7], v[6:7], v[8:9]
	v_lshlrev_b32_e32 v40, 16, v45
	v_and_b32_e32 v41, 0xffff0000, v45
	v_pk_fma_f32 v[250:251], v[40:41], v[40:41], v[250:251]
	v_lshlrev_b32_e32 v6, 16, v34
	v_and_b32_e32 v7, 0xffff0000, v34
	v_pk_fma_f32 v[8:9], v[6:7], v[6:7], v[8:9]
	v_lshlrev_b32_e32 v40, 16, v46
	v_and_b32_e32 v41, 0xffff0000, v46
	v_pk_fma_f32 v[250:251], v[40:41], v[40:41], v[250:251]
	v_lshlrev_b32_e32 v6, 16, v35
	v_and_b32_e32 v7, 0xffff0000, v35
	v_pk_fma_f32 v[8:9], v[6:7], v[6:7], v[8:9]
	v_lshlrev_b32_e32 v40, 16, v47
	v_and_b32_e32 v41, 0xffff0000, v47
	v_pk_fma_f32 v[250:251], v[40:41], v[40:41], v[250:251]
	v_lshlrev_b32_e32 v6, 16, v36
	v_and_b32_e32 v7, 0xffff0000, v36
	v_pk_fma_f32 v[8:9], v[6:7], v[6:7], v[8:9]
	v_lshlrev_b32_e32 v40, 16, v48
	v_and_b32_e32 v41, 0xffff0000, v48
	v_pk_fma_f32 v[250:251], v[40:41], v[40:41], v[250:251]
	v_lshlrev_b32_e32 v6, 16, v37
	v_and_b32_e32 v7, 0xffff0000, v37
	v_pk_fma_f32 v[8:9], v[6:7], v[6:7], v[8:9]
	v_lshlrev_b32_e32 v40, 16, v49
	v_and_b32_e32 v41, 0xffff0000, v49
	v_pk_fma_f32 v[250:251], v[40:41], v[40:41], v[250:251]
	v_lshlrev_b32_e32 v6, 16, v38
	v_and_b32_e32 v7, 0xffff0000, v38
	v_pk_fma_f32 v[8:9], v[6:7], v[6:7], v[8:9]
	v_lshlrev_b32_e32 v40, 16, v50
	v_and_b32_e32 v41, 0xffff0000, v50
	v_pk_fma_f32 v[250:251], v[40:41], v[40:41], v[250:251]
	v_lshlrev_b32_e32 v6, 16, v39
	v_and_b32_e32 v7, 0xffff0000, v39
	v_pk_fma_f32 v[8:9], v[6:7], v[6:7], v[8:9]
	v_lshlrev_b32_e32 v40, 16, v51
	v_and_b32_e32 v41, 0xffff0000, v51
	v_pk_fma_f32 v[250:251], v[40:41], v[40:41], v[250:251]
	v_add_f32_e32 v8, v8, v9
	v_add_f32_e32 v250, v250, v251
	s_nop 1
	v_add_f32_dpp v8, v8, v8 quad_perm:[1,0,3,2] row_mask:0xf bank_mask:0xf
	v_add_f32_dpp v250, v250, v250 quad_perm:[1,0,3,2] row_mask:0xf bank_mask:0xf
	s_nop 1
	v_add_f32_dpp v8, v8, v8 quad_perm:[2,3,0,1] row_mask:0xf bank_mask:0xf
	v_add_f32_dpp v250, v250, v250 quad_perm:[2,3,0,1] row_mask:0xf bank_mask:0xf
	s_nop 1
	v_add_f32_dpp v8, v8, v8 row_half_mirror row_mask:0xf bank_mask:0xf
	v_add_f32_dpp v250, v250, v250 row_half_mirror row_mask:0xf bank_mask:0xf
	s_nop 1
	v_add_f32_dpp v8, v8, v8 row_mirror row_mask:0xf bank_mask:0xf
	v_add_f32_dpp v250, v250, v250 row_mirror row_mask:0xf bank_mask:0xf
	s_nop 1
	ds_bpermute_b32 v6, v14, v8
	ds_bpermute_b32 v40, v14, v250
	s_waitcnt lgkmcnt(0)
	v_add_f32_e32 v6, v8, v6
	v_mul_f32_e32 v6, 0x3b000000, v6
	v_mul_f32_e32 v8, 0x3b800000, v8
	v_cndmask_b32_e64 v8, v8, v6, s[6:7]
	v_add_f32_e32 v8, 0x358637bd, v8
	v_rsq_f32_e32 v252, v8
	v_add_f32_e32 v40, v250, v40
	v_mul_f32_e32 v40, 0x3b000000, v40
	v_mul_f32_e32 v250, 0x3b800000, v250
	v_cndmask_b32_e64 v250, v250, v40, s[6:7]
	v_add_f32_e32 v250, 0x358637bd, v250
	v_rsq_f32_e32 v254, v250
	s_nop 1
	v_lshlrev_b32_e32 v6, 16, v32
	v_and_b32_e32 v7, 0xffff0000, v32
	v_pk_mul_f32 v[6:7], v[6:7], v[252:253] op_sel_hi:[1,0]
	v_pk_mul_f32 v[6:7], v[6:7], v[16:17]
	v_cvt_pk_bf16_f32 v32, v6, v7
	v_lshlrev_b32_e32 v40, 16, v44
	v_and_b32_e32 v41, 0xffff0000, v44
	v_pk_mul_f32 v[40:41], v[40:41], v[254:255] op_sel_hi:[1,0]
	v_pk_mul_f32 v[40:41], v[40:41], v[16:17]
	v_cvt_pk_bf16_f32 v44, v40, v41
	v_lshlrev_b32_e32 v6, 16, v33
	v_and_b32_e32 v7, 0xffff0000, v33
	v_pk_mul_f32 v[6:7], v[6:7], v[252:253] op_sel_hi:[1,0]
	v_pk_mul_f32 v[6:7], v[6:7], v[18:19]
	v_cvt_pk_bf16_f32 v33, v6, v7
	v_lshlrev_b32_e32 v40, 16, v45
	v_and_b32_e32 v41, 0xffff0000, v45
	v_pk_mul_f32 v[40:41], v[40:41], v[254:255] op_sel_hi:[1,0]
	v_pk_mul_f32 v[40:41], v[40:41], v[18:19]
	v_cvt_pk_bf16_f32 v45, v40, v41
	v_lshlrev_b32_e32 v6, 16, v34
	v_and_b32_e32 v7, 0xffff0000, v34
	v_pk_mul_f32 v[6:7], v[6:7], v[252:253] op_sel_hi:[1,0]
	v_pk_mul_f32 v[6:7], v[6:7], v[20:21]
	v_cvt_pk_bf16_f32 v34, v6, v7
	v_lshlrev_b32_e32 v40, 16, v46
	v_and_b32_e32 v41, 0xffff0000, v46
	v_pk_mul_f32 v[40:41], v[40:41], v[254:255] op_sel_hi:[1,0]
	v_pk_mul_f32 v[40:41], v[40:41], v[20:21]
	v_cvt_pk_bf16_f32 v46, v40, v41
	v_lshlrev_b32_e32 v6, 16, v35
	v_and_b32_e32 v7, 0xffff0000, v35
	v_pk_mul_f32 v[6:7], v[6:7], v[252:253] op_sel_hi:[1,0]
	v_pk_mul_f32 v[6:7], v[6:7], v[22:23]
	v_cvt_pk_bf16_f32 v35, v6, v7
	v_lshlrev_b32_e32 v40, 16, v47
	v_and_b32_e32 v41, 0xffff0000, v47
	v_pk_mul_f32 v[40:41], v[40:41], v[254:255] op_sel_hi:[1,0]
	v_pk_mul_f32 v[40:41], v[40:41], v[22:23]
	v_cvt_pk_bf16_f32 v47, v40, v41
	v_lshlrev_b32_e32 v6, 16, v36
	v_and_b32_e32 v7, 0xffff0000, v36
	v_pk_mul_f32 v[6:7], v[6:7], v[252:253] op_sel_hi:[1,0]
	v_pk_mul_f32 v[6:7], v[6:7], v[24:25]
	v_cvt_pk_bf16_f32 v36, v6, v7
	v_lshlrev_b32_e32 v40, 16, v48
	v_and_b32_e32 v41, 0xffff0000, v48
	v_pk_mul_f32 v[40:41], v[40:41], v[254:255] op_sel_hi:[1,0]
	v_pk_mul_f32 v[40:41], v[40:41], v[24:25]
	v_cvt_pk_bf16_f32 v48, v40, v41
	v_lshlrev_b32_e32 v6, 16, v37
	v_and_b32_e32 v7, 0xffff0000, v37
	v_pk_mul_f32 v[6:7], v[6:7], v[252:253] op_sel_hi:[1,0]
	v_pk_mul_f32 v[6:7], v[6:7], v[26:27]
	v_cvt_pk_bf16_f32 v37, v6, v7
	v_lshlrev_b32_e32 v40, 16, v49
	v_and_b32_e32 v41, 0xffff0000, v49
	v_pk_mul_f32 v[40:41], v[40:41], v[254:255] op_sel_hi:[1,0]
	v_pk_mul_f32 v[40:41], v[40:41], v[26:27]
	v_cvt_pk_bf16_f32 v49, v40, v41
	v_lshlrev_b32_e32 v6, 16, v38
	v_and_b32_e32 v7, 0xffff0000, v38
	v_pk_mul_f32 v[6:7], v[6:7], v[252:253] op_sel_hi:[1,0]
	v_pk_mul_f32 v[6:7], v[6:7], v[28:29]
	v_cvt_pk_bf16_f32 v38, v6, v7
	v_lshlrev_b32_e32 v40, 16, v50
	v_and_b32_e32 v41, 0xffff0000, v50
	v_pk_mul_f32 v[40:41], v[40:41], v[254:255] op_sel_hi:[1,0]
	v_pk_mul_f32 v[40:41], v[40:41], v[28:29]
	v_cvt_pk_bf16_f32 v50, v40, v41
	v_lshlrev_b32_e32 v6, 16, v39
	v_and_b32_e32 v7, 0xffff0000, v39
	v_pk_mul_f32 v[6:7], v[6:7], v[252:253] op_sel_hi:[1,0]
	v_pk_mul_f32 v[6:7], v[6:7], v[30:31]
	v_cvt_pk_bf16_f32 v39, v6, v7
	v_lshlrev_b32_e32 v40, 16, v51
	v_and_b32_e32 v41, 0xffff0000, v51
	v_pk_mul_f32 v[40:41], v[40:41], v[254:255] op_sel_hi:[1,0]
	v_pk_mul_f32 v[40:41], v[40:41], v[30:31]
	v_cvt_pk_bf16_f32 v51, v40, v41
	global_store_dwordx4 v[4:5], v[32:35], off
	global_store_dwordx4 v[4:5], v[36:39], off offset:16
	global_store_dwordx4 v[4:5], v[44:47], off offset:2048
	global_store_dwordx4 v[4:5], v[48:51], off offset:2064
	v_lshl_add_u64 v[4:5], v[4:5], 0, s[100:101]
	s_nop 1
	s_waitcnt vmcnt(4)
	v_lshlrev_b32_e32 v6, 16, v52
	v_and_b32_e32 v7, 0xffff0000, v52
	v_pk_mul_f32 v[8:9], v[6:7], v[6:7]
	v_lshlrev_b32_e32 v40, 16, v60
	v_and_b32_e32 v41, 0xffff0000, v60
	v_pk_mul_f32 v[250:251], v[40:41], v[40:41]
	v_lshlrev_b32_e32 v6, 16, v53
	v_and_b32_e32 v7, 0xffff0000, v53
	v_pk_fma_f32 v[8:9], v[6:7], v[6:7], v[8:9]
	v_lshlrev_b32_e32 v40, 16, v61
	v_and_b32_e32 v41, 0xffff0000, v61
	v_pk_fma_f32 v[250:251], v[40:41], v[40:41], v[250:251]
	v_lshlrev_b32_e32 v6, 16, v54
	v_and_b32_e32 v7, 0xffff0000, v54
	v_pk_fma_f32 v[8:9], v[6:7], v[6:7], v[8:9]
	v_lshlrev_b32_e32 v40, 16, v62
	v_and_b32_e32 v41, 0xffff0000, v62
	v_pk_fma_f32 v[250:251], v[40:41], v[40:41], v[250:251]
	v_lshlrev_b32_e32 v6, 16, v55
	v_and_b32_e32 v7, 0xffff0000, v55
	v_pk_fma_f32 v[8:9], v[6:7], v[6:7], v[8:9]
	v_lshlrev_b32_e32 v40, 16, v63
	v_and_b32_e32 v41, 0xffff0000, v63
	v_pk_fma_f32 v[250:251], v[40:41], v[40:41], v[250:251]
	v_lshlrev_b32_e32 v6, 16, v56
	v_and_b32_e32 v7, 0xffff0000, v56
	v_pk_fma_f32 v[8:9], v[6:7], v[6:7], v[8:9]
	v_lshlrev_b32_e32 v40, 16, v64
	v_and_b32_e32 v41, 0xffff0000, v64
	v_pk_fma_f32 v[250:251], v[40:41], v[40:41], v[250:251]
	v_lshlrev_b32_e32 v6, 16, v57
	v_and_b32_e32 v7, 0xffff0000, v57
	v_pk_fma_f32 v[8:9], v[6:7], v[6:7], v[8:9]
	v_lshlrev_b32_e32 v40, 16, v65
	v_and_b32_e32 v41, 0xffff0000, v65
	v_pk_fma_f32 v[250:251], v[40:41], v[40:41], v[250:251]
	v_lshlrev_b32_e32 v6, 16, v58
	v_and_b32_e32 v7, 0xffff0000, v58
	v_pk_fma_f32 v[8:9], v[6:7], v[6:7], v[8:9]
	v_lshlrev_b32_e32 v40, 16, v66
	v_and_b32_e32 v41, 0xffff0000, v66
	v_pk_fma_f32 v[250:251], v[40:41], v[40:41], v[250:251]
	v_lshlrev_b32_e32 v6, 16, v59
	v_and_b32_e32 v7, 0xffff0000, v59
	v_pk_fma_f32 v[8:9], v[6:7], v[6:7], v[8:9]
	v_lshlrev_b32_e32 v40, 16, v67
	v_and_b32_e32 v41, 0xffff0000, v67
	v_pk_fma_f32 v[250:251], v[40:41], v[40:41], v[250:251]
	v_add_f32_e32 v8, v8, v9
	v_add_f32_e32 v250, v250, v251
	s_nop 1
	v_add_f32_dpp v8, v8, v8 quad_perm:[1,0,3,2] row_mask:0xf bank_mask:0xf
	v_add_f32_dpp v250, v250, v250 quad_perm:[1,0,3,2] row_mask:0xf bank_mask:0xf
	s_nop 1
	v_add_f32_dpp v8, v8, v8 quad_perm:[2,3,0,1] row_mask:0xf bank_mask:0xf
	v_add_f32_dpp v250, v250, v250 quad_perm:[2,3,0,1] row_mask:0xf bank_mask:0xf
	s_nop 1
	v_add_f32_dpp v8, v8, v8 row_half_mirror row_mask:0xf bank_mask:0xf
	v_add_f32_dpp v250, v250, v250 row_half_mirror row_mask:0xf bank_mask:0xf
	s_nop 1
	v_add_f32_dpp v8, v8, v8 row_mirror row_mask:0xf bank_mask:0xf
	v_add_f32_dpp v250, v250, v250 row_mirror row_mask:0xf bank_mask:0xf
	s_nop 1
	ds_bpermute_b32 v6, v14, v8
	ds_bpermute_b32 v40, v14, v250
	s_waitcnt lgkmcnt(0)
	v_add_f32_e32 v6, v8, v6
	v_mul_f32_e32 v6, 0x3b000000, v6
	v_mul_f32_e32 v8, 0x3b800000, v8
	v_cndmask_b32_e64 v8, v8, v6, s[6:7]
	v_add_f32_e32 v8, 0x358637bd, v8
	v_rsq_f32_e32 v252, v8
	v_add_f32_e32 v40, v250, v40
	v_mul_f32_e32 v40, 0x3b000000, v40
	v_mul_f32_e32 v250, 0x3b800000, v250
	v_cndmask_b32_e64 v250, v250, v40, s[6:7]
	v_add_f32_e32 v250, 0x358637bd, v250
	v_rsq_f32_e32 v254, v250
	s_nop 1
	v_lshlrev_b32_e32 v6, 16, v52
	v_and_b32_e32 v7, 0xffff0000, v52
	v_pk_mul_f32 v[6:7], v[6:7], v[252:253] op_sel_hi:[1,0]
	v_pk_mul_f32 v[6:7], v[6:7], v[16:17]
	v_cvt_pk_bf16_f32 v52, v6, v7
	v_lshlrev_b32_e32 v40, 16, v60
	v_and_b32_e32 v41, 0xffff0000, v60
	v_pk_mul_f32 v[40:41], v[40:41], v[254:255] op_sel_hi:[1,0]
	v_pk_mul_f32 v[40:41], v[40:41], v[16:17]
	v_cvt_pk_bf16_f32 v60, v40, v41
	v_lshlrev_b32_e32 v6, 16, v53
	v_and_b32_e32 v7, 0xffff0000, v53
	v_pk_mul_f32 v[6:7], v[6:7], v[252:253] op_sel_hi:[1,0]
	v_pk_mul_f32 v[6:7], v[6:7], v[18:19]
	v_cvt_pk_bf16_f32 v53, v6, v7
	v_lshlrev_b32_e32 v40, 16, v61
	v_and_b32_e32 v41, 0xffff0000, v61
	v_pk_mul_f32 v[40:41], v[40:41], v[254:255] op_sel_hi:[1,0]
	v_pk_mul_f32 v[40:41], v[40:41], v[18:19]
	v_cvt_pk_bf16_f32 v61, v40, v41
	v_lshlrev_b32_e32 v6, 16, v54
	v_and_b32_e32 v7, 0xffff0000, v54
	v_pk_mul_f32 v[6:7], v[6:7], v[252:253] op_sel_hi:[1,0]
	v_pk_mul_f32 v[6:7], v[6:7], v[20:21]
	v_cvt_pk_bf16_f32 v54, v6, v7
	v_lshlrev_b32_e32 v40, 16, v62
	v_and_b32_e32 v41, 0xffff0000, v62
	v_pk_mul_f32 v[40:41], v[40:41], v[254:255] op_sel_hi:[1,0]
	v_pk_mul_f32 v[40:41], v[40:41], v[20:21]
	v_cvt_pk_bf16_f32 v62, v40, v41
	v_lshlrev_b32_e32 v6, 16, v55
	v_and_b32_e32 v7, 0xffff0000, v55
	v_pk_mul_f32 v[6:7], v[6:7], v[252:253] op_sel_hi:[1,0]
	v_pk_mul_f32 v[6:7], v[6:7], v[22:23]
	v_cvt_pk_bf16_f32 v55, v6, v7
	v_lshlrev_b32_e32 v40, 16, v63
	v_and_b32_e32 v41, 0xffff0000, v63
	v_pk_mul_f32 v[40:41], v[40:41], v[254:255] op_sel_hi:[1,0]
	v_pk_mul_f32 v[40:41], v[40:41], v[22:23]
	v_cvt_pk_bf16_f32 v63, v40, v41
	v_lshlrev_b32_e32 v6, 16, v56
	v_and_b32_e32 v7, 0xffff0000, v56
	v_pk_mul_f32 v[6:7], v[6:7], v[252:253] op_sel_hi:[1,0]
	v_pk_mul_f32 v[6:7], v[6:7], v[24:25]
	v_cvt_pk_bf16_f32 v56, v6, v7
	v_lshlrev_b32_e32 v40, 16, v64
	v_and_b32_e32 v41, 0xffff0000, v64
	v_pk_mul_f32 v[40:41], v[40:41], v[254:255] op_sel_hi:[1,0]
	v_pk_mul_f32 v[40:41], v[40:41], v[24:25]
	v_cvt_pk_bf16_f32 v64, v40, v41
	v_lshlrev_b32_e32 v6, 16, v57
	v_and_b32_e32 v7, 0xffff0000, v57
	v_pk_mul_f32 v[6:7], v[6:7], v[252:253] op_sel_hi:[1,0]
	v_pk_mul_f32 v[6:7], v[6:7], v[26:27]
	v_cvt_pk_bf16_f32 v57, v6, v7
	v_lshlrev_b32_e32 v40, 16, v65
	v_and_b32_e32 v41, 0xffff0000, v65
	v_pk_mul_f32 v[40:41], v[40:41], v[254:255] op_sel_hi:[1,0]
	v_pk_mul_f32 v[40:41], v[40:41], v[26:27]
	v_cvt_pk_bf16_f32 v65, v40, v41
	v_lshlrev_b32_e32 v6, 16, v58
	v_and_b32_e32 v7, 0xffff0000, v58
	v_pk_mul_f32 v[6:7], v[6:7], v[252:253] op_sel_hi:[1,0]
	v_pk_mul_f32 v[6:7], v[6:7], v[28:29]
	v_cvt_pk_bf16_f32 v58, v6, v7
	v_lshlrev_b32_e32 v40, 16, v66
	v_and_b32_e32 v41, 0xffff0000, v66
	v_pk_mul_f32 v[40:41], v[40:41], v[254:255] op_sel_hi:[1,0]
	v_pk_mul_f32 v[40:41], v[40:41], v[28:29]
	v_cvt_pk_bf16_f32 v66, v40, v41
	v_lshlrev_b32_e32 v6, 16, v59
	v_and_b32_e32 v7, 0xffff0000, v59
	v_pk_mul_f32 v[6:7], v[6:7], v[252:253] op_sel_hi:[1,0]
	v_pk_mul_f32 v[6:7], v[6:7], v[30:31]
	v_cvt_pk_bf16_f32 v59, v6, v7
	v_lshlrev_b32_e32 v40, 16, v67
	v_and_b32_e32 v41, 0xffff0000, v67
	v_pk_mul_f32 v[40:41], v[40:41], v[254:255] op_sel_hi:[1,0]
	v_pk_mul_f32 v[40:41], v[40:41], v[30:31]
	v_cvt_pk_bf16_f32 v67, v40, v41
	global_store_dwordx4 v[4:5], v[52:55], off
	global_store_dwordx4 v[4:5], v[56:59], off offset:16
	global_store_dwordx4 v[4:5], v[60:63], off offset:2048
	global_store_dwordx4 v[4:5], v[64:67], off offset:2064
	v_lshl_add_u64 v[4:5], v[4:5], 0, s[100:101]
	s_nop 1
	s_nop 1
	ds_read_b128 v[44:47], v15
	ds_read_b128 v[48:51], v15 offset:8192
	ds_read_b128 v[52:55], v15 offset:16384
	ds_read_b128 v[56:59], v15 offset:24576
	ds_read_b128 v[60:63], v15 offset:32768
	ds_read_b128 v[64:67], v15 offset:40960
	s_mov_b64 s[82:83], 0x8000
	s_mov_b32 s1, 0x800000
	s_cmpk_eq_u32 s82, 0x8000
	s_waitcnt lgkmcnt(0)
	v_readlane_b32 s1, v249, 63
	s_barrier
	s_add_i32 s0, s1, s0
	s_cmpk_gt_i32 s0, 0xff
	s_cbranch_scc0 .LBB0_1211
	v_readlane_b32 s89, v249, 63

.LBB0_1906:
	v_lshlrev_b32_e32 v15, 4, v242
	ds_write_b128 v15, v[44:47]
	ds_write_b128 v15, v[48:51] offset:8192
	ds_write_b128 v15, v[52:55] offset:16384
	ds_write_b128 v15, v[56:59] offset:24576
	ds_write_b128 v15, v[60:63] offset:32768
	ds_write_b128 v15, v[64:67] offset:40960
	s_mov_b64 s[4:5], 0x16a00000
	s_mov_b64 s[100:101], 0x1000
	v_lshl_add_u64 v[2:3], v[0:1], 0, s[4:5]
	v_lshl_add_u64 v[4:5], v[0:1], 0, s[4:5]
	global_load_dwordx4 v[16:19], v[106:107], off
	global_load_dwordx4 v[20:23], v[106:107], off offset:16
	global_load_dwordx4 v[24:27], v[106:107], off offset:32
	global_load_dwordx4 v[28:31], v[106:107], off offset:48
	s_waitcnt lgkmcnt(0)
	global_load_dwordx4 v[32:35], v[2:3], off
	global_load_dwordx4 v[36:39], v[2:3], off offset:16
	global_load_dwordx4 v[44:47], v[2:3], off offset:2048
	global_load_dwordx4 v[48:51], v[2:3], off offset:2064
	v_lshl_add_u64 v[2:3], v[2:3], 0, s[100:101]
	global_load_dwordx4 v[52:55], v[2:3], off
	global_load_dwordx4 v[56:59], v[2:3], off offset:16
	global_load_dwordx4 v[60:63], v[2:3], off offset:2048
	global_load_dwordx4 v[64:67], v[2:3], off offset:2064
	v_lshl_add_u64 v[2:3], v[2:3], 0, s[100:101]
	s_waitcnt vmcnt(4)
	v_lshlrev_b32_e32 v6, 16, v32
	v_and_b32_e32 v7, 0xffff0000, v32
	v_pk_mul_f32 v[8:9], v[6:7], v[6:7]
	v_lshlrev_b32_e32 v40, 16, v44
	v_and_b32_e32 v41, 0xffff0000, v44
	v_pk_mul_f32 v[250:251], v[40:41], v[40:41]
	v_lshlrev_b32_e32 v6, 16, v33
	v_and_b32_e32 v7, 0xffff0000, v33
	v_pk_fma_f32 v[8:9], v[6:7], v[6:7], v[8:9]
	v_lshlrev_b32_e32 v40, 16, v45
	v_and_b32_e32 v41, 0xffff0000, v45
	v_pk_fma_f32 v[250:251], v[40:41], v[40:41], v[250:251]
	v_lshlrev_b32_e32 v6, 16, v34
	v_and_b32_e32 v7, 0xffff0000, v34
	v_pk_fma_f32 v[8:9], v[6:7], v[6:7], v[8:9]
	v_lshlrev_b32_e32 v40, 16, v46
	v_and_b32_e32 v41, 0xffff0000, v46
	v_pk_fma_f32 v[250:251], v[40:41], v[40:41], v[250:251]
	v_lshlrev_b32_e32 v6, 16, v35
	v_and_b32_e32 v7, 0xffff0000, v35
	v_pk_fma_f32 v[8:9], v[6:7], v[6:7], v[8:9]
	v_lshlrev_b32_e32 v40, 16, v47
	v_and_b32_e32 v41, 0xffff0000, v47
	v_pk_fma_f32 v[250:251], v[40:41], v[40:41], v[250:251]
	v_lshlrev_b32_e32 v6, 16, v36
	v_and_b32_e32 v7, 0xffff0000, v36
	v_pk_fma_f32 v[8:9], v[6:7], v[6:7], v[8:9]
	v_lshlrev_b32_e32 v40, 16, v48
	v_and_b32_e32 v41, 0xffff0000, v48
	v_pk_fma_f32 v[250:251], v[40:41], v[40:41], v[250:251]
	v_lshlrev_b32_e32 v6, 16, v37
	v_and_b32_e32 v7, 0xffff0000, v37
	v_pk_fma_f32 v[8:9], v[6:7], v[6:7], v[8:9]
	v_lshlrev_b32_e32 v40, 16, v49
	v_and_b32_e32 v41, 0xffff0000, v49
	v_pk_fma_f32 v[250:251], v[40:41], v[40:41], v[250:251]
	v_lshlrev_b32_e32 v6, 16, v38
	v_and_b32_e32 v7, 0xffff0000, v38
	v_pk_fma_f32 v[8:9], v[6:7], v[6:7], v[8:9]
	v_lshlrev_b32_e32 v40, 16, v50
	v_and_b32_e32 v41, 0xffff0000, v50
	v_pk_fma_f32 v[250:251], v[40:41], v[40:41], v[250:251]
	v_lshlrev_b32_e32 v6, 16, v39
	v_and_b32_e32 v7, 0xffff0000, v39
	v_pk_fma_f32 v[8:9], v[6:7], v[6:7], v[8:9]
	v_lshlrev_b32_e32 v40, 16, v51
	v_and_b32_e32 v41, 0xffff0000, v51
	v_pk_fma_f32 v[250:251], v[40:41], v[40:41], v[250:251]
	v_add_f32_e32 v8, v8, v9
	v_add_f32_e32 v250, v250, v251
	s_nop 1
	v_add_f32_dpp v8, v8, v8 quad_perm:[1,0,3,2] row_mask:0xf bank_mask:0xf
	v_add_f32_dpp v250, v250, v250 quad_perm:[1,0,3,2] row_mask:0xf bank_mask:0xf
	s_nop 1
	v_add_f32_dpp v8, v8, v8 quad_perm:[2,3,0,1] row_mask:0xf bank_mask:0xf
	v_add_f32_dpp v250, v250, v250 quad_perm:[2,3,0,1] row_mask:0xf bank_mask:0xf
	s_nop 1
	v_add_f32_dpp v8, v8, v8 row_half_mirror row_mask:0xf bank_mask:0xf
	v_add_f32_dpp v250, v250, v250 row_half_mirror row_mask:0xf bank_mask:0xf
	s_nop 1
	v_add_f32_dpp v8, v8, v8 row_mirror row_mask:0xf bank_mask:0xf
	v_add_f32_dpp v250, v250, v250 row_mirror row_mask:0xf bank_mask:0xf
	s_nop 1
	ds_bpermute_b32 v6, v14, v8
	ds_bpermute_b32 v40, v14, v250
	s_waitcnt lgkmcnt(0)
	v_add_f32_e32 v6, v8, v6
	v_mul_f32_e32 v6, 0x3b000000, v6
	v_mul_f32_e32 v8, 0x3b800000, v8
	v_cndmask_b32_e64 v8, v8, v6, s[6:7]
	v_add_f32_e32 v8, 0x358637bd, v8
	v_rsq_f32_e32 v252, v8
	v_add_f32_e32 v40, v250, v40
	v_mul_f32_e32 v40, 0x3b000000, v40
	v_mul_f32_e32 v250, 0x3b800000, v250
	v_cndmask_b32_e64 v250, v250, v40, s[6:7]
	v_add_f32_e32 v250, 0x358637bd, v250
	v_rsq_f32_e32 v254, v250
	s_nop 1
	v_lshlrev_b32_e32 v6, 16, v32
	v_and_b32_e32 v7, 0xffff0000, v32
	v_pk_mul_f32 v[6:7], v[6:7], v[252:253] op_sel_hi:[1,0]
	v_pk_mul_f32 v[6:7], v[6:7], v[16:17]
	v_cvt_pk_bf16_f32 v32, v6, v7
	v_lshlrev_b32_e32 v40, 16, v44
	v_and_b32_e32 v41, 0xffff0000, v44
	v_pk_mul_f32 v[40:41], v[40:41], v[254:255] op_sel_hi:[1,0]
	v_pk_mul_f32 v[40:41], v[40:41], v[16:17]
	v_cvt_pk_bf16_f32 v44, v40, v41
	v_lshlrev_b32_e32 v6, 16, v33
	v_and_b32_e32 v7, 0xffff0000, v33
	v_pk_mul_f32 v[6:7], v[6:7], v[252:253] op_sel_hi:[1,0]
	v_pk_mul_f32 v[6:7], v[6:7], v[18:19]
	v_cvt_pk_bf16_f32 v33, v6, v7
	v_lshlrev_b32_e32 v40, 16, v45
	v_and_b32_e32 v41, 0xffff0000, v45
	v_pk_mul_f32 v[40:41], v[40:41], v[254:255] op_sel_hi:[1,0]
	v_pk_mul_f32 v[40:41], v[40:41], v[18:19]
	v_cvt_pk_bf16_f32 v45, v40, v41
	v_lshlrev_b32_e32 v6, 16, v34
	v_and_b32_e32 v7, 0xffff0000, v34
	v_pk_mul_f32 v[6:7], v[6:7], v[252:253] op_sel_hi:[1,0]
	v_pk_mul_f32 v[6:7], v[6:7], v[20:21]
	v_cvt_pk_bf16_f32 v34, v6, v7
	v_lshlrev_b32_e32 v40, 16, v46
	v_and_b32_e32 v41, 0xffff0000, v46
	v_pk_mul_f32 v[40:41], v[40:41], v[254:255] op_sel_hi:[1,0]
	v_pk_mul_f32 v[40:41], v[40:41], v[20:21]
	v_cvt_pk_bf16_f32 v46, v40, v41
	v_lshlrev_b32_e32 v6, 16, v35
	v_and_b32_e32 v7, 0xffff0000, v35
	v_pk_mul_f32 v[6:7], v[6:7], v[252:253] op_sel_hi:[1,0]
	v_pk_mul_f32 v[6:7], v[6:7], v[22:23]
	v_cvt_pk_bf16_f32 v35, v6, v7
	v_lshlrev_b32_e32 v40, 16, v47
; DEVI unsigned pk2(float lo, float hi) { unsigned r; asm("v_cvt_pk_bf16_f32 %0, %1, %2" : "=v"(r) : "v"(lo), "v"(hi)); return r; }
; DEVI float bflo(unsigned w) { return __uint_as_float(w << 16); }
; DEVI float bfhi(unsigned w) { return __uint_as_float(w & 0xffff0000u); }
; DEVI void phase_m3(const Params& p, int l, unsigned char* smem) {
;     ...
;             for (int tt = 0; tt < 16; ++tt) {
;                 const int t = wave * 16 + tt;
;                 bf16_t* rowp = mix + (size_t)(row0 + t) * DM + lane * 16;
;                 const u32x4 a = *(const u32x4*)rowp, b = *(const u32x4*)(rowp + 8);
;                 float v[16] = {bflo(a.x), bfhi(a.x), bflo(a.y), bfhi(a.y), bflo(a.z), bfhi(a.z), bflo(a.w), bfhi(a.w), bflo(b.x), bfhi(b.x), bflo(b.y), bfhi(b.y), bflo(b.z), bfhi(b.z), bflo(b.w), bfhi(b.w)};
;                 float ss = 0.f;
; #pragma unroll
;                 for (int e = 0; e < 16; ++e) ss += v[e] * v[e];
;                 ss += __shfl_xor(ss, 1); ss += __shfl_xor(ss, 2); ss += __shfl_xor(ss, 4); ss += __shfl_xor(ss, 8);
;                 const float s16 = __shfl_xor(ss, 16);
;                 float rn;
;                 if (lane < 32) rn = rsqrtf((ss + s16) * (1.0f / 512.0f) + RMS_EPS); else rn = rsqrtf(ss * (1.0f / 256.0f) + RMS_EPS);
;                 const f32x4 g0 = *(const f32x4*)(gain + lane * 16), g1 = *(const f32x4*)(gain + lane * 16 + 4), g2 = *(const f32x4*)(gain + lane * 16 + 8), g3 = *(const f32x4*)(gain + lane * 16 + 12);
;                 u32x4 o1, o2;
;                 o1.x = pk2(v[0] * rn * g0[0], v[1] * rn * g0[1]); o1.y = pk2(v[2] * rn * g0[2], v[3] * rn * g0[3]); o1.z = pk2(v[4] * rn * g1[0], v[5] * rn * g1[1]); o1.w = pk2(v[6] * rn * g1[2], v[7] * rn * g1[3]);
;                 o2.x = pk2(v[8] * rn * g2[0], v[9] * rn * g2[1]); o2.y = pk2(v[10] * rn * g2[2], v[11] * rn * g2[3]); o2.z = pk2(v[12] * rn * g3[0], v[13] * rn * g3[1]); o2.w = pk2(v[14] * rn * g3[2], v[15] * rn * g3[3]);
;                 *(u32x4*)rowp = o1; *(u32x4*)(rowp + 8) = o2;
;             }
	v_and_b32_e32 v41, 0xffff0000, v47
	v_pk_mul_f32 v[40:41], v[40:41], v[254:255] op_sel_hi:[1,0]
	v_pk_mul_f32 v[40:41], v[40:41], v[22:23]
	v_cvt_pk_bf16_f32 v47, v40, v41
	v_lshlrev_b32_e32 v6, 16, v36
	v_and_b32_e32 v7, 0xffff0000, v36
	v_pk_mul_f32 v[6:7], v[6:7], v[252:253] op_sel_hi:[1,0]
	v_pk_mul_f32 v[6:7], v[6:7], v[24:25]
	v_cvt_pk_bf16_f32 v36, v6, v7
	v_lshlrev_b32_e32 v40, 16, v48
	v_and_b32_e32 v41, 0xffff0000, v48
	v_pk_mul_f32 v[40:41], v[40:41], v[254:255] op_sel_hi:[1,0]
	v_pk_mul_f32 v[40:41], v[40:41], v[24:25]
	v_cvt_pk_bf16_f32 v48, v40, v41
	v_lshlrev_b32_e32 v6, 16, v37
	v_and_b32_e32 v7, 0xffff0000, v37
	v_pk_mul_f32 v[6:7], v[6:7], v[252:253] op_sel_hi:[1,0]
	v_pk_mul_f32 v[6:7], v[6:7], v[26:27]
	v_cvt_pk_bf16_f32 v37, v6, v7
	v_lshlrev_b32_e32 v40, 16, v49
	v_and_b32_e32 v41, 0xffff0000, v49
	v_pk_mul_f32 v[40:41], v[40:41], v[254:255] op_sel_hi:[1,0]
	v_pk_mul_f32 v[40:41], v[40:41], v[26:27]
	v_cvt_pk_bf16_f32 v49, v40, v41
	v_lshlrev_b32_e32 v6, 16, v38
	v_and_b32_e32 v7, 0xffff0000, v38
	v_pk_mul_f32 v[6:7], v[6:7], v[252:253] op_sel_hi:[1,0]
	v_pk_mul_f32 v[6:7], v[6:7], v[28:29]
	v_cvt_pk_bf16_f32 v38, v6, v7
	v_lshlrev_b32_e32 v40, 16, v50
	v_and_b32_e32 v41, 0xffff0000, v50
	v_pk_mul_f32 v[40:41], v[40:41], v[254:255] op_sel_hi:[1,0]
	v_pk_mul_f32 v[40:41], v[40:41], v[28:29]
	v_cvt_pk_bf16_f32 v50, v40, v41
	v_lshlrev_b32_e32 v6, 16, v39
	v_and_b32_e32 v7, 0xffff0000, v39
	v_pk_mul_f32 v[6:7], v[6:7], v[252:253] op_sel_hi:[1,0]
	v_pk_mul_f32 v[6:7], v[6:7], v[30:31]
	v_cvt_pk_bf16_f32 v39, v6, v7
	v_lshlrev_b32_e32 v40, 16, v51
	v_and_b32_e32 v41, 0xffff0000, v51
	v_pk_mul_f32 v[40:41], v[40:41], v[254:255] op_sel_hi:[1,0]
	v_pk_mul_f32 v[40:41], v[40:41], v[30:31]
	v_cvt_pk_bf16_f32 v51, v40, v41
	global_store_dwordx4 v[4:5], v[32:35], off
	global_store_dwordx4 v[4:5], v[36:39], off offset:16
	global_store_dwordx4 v[4:5], v[44:47], off offset:2048
	global_store_dwordx4 v[4:5], v[48:51], off offset:2064
	v_lshl_add_u64 v[4:5], v[4:5], 0, s[100:101]
	s_nop 1
	global_load_dwordx4 v[32:35], v[2:3], off
	global_load_dwordx4 v[36:39], v[2:3], off offset:16
	global_load_dwordx4 v[44:47], v[2:3], off offset:2048
	global_load_dwordx4 v[48:51], v[2:3], off offset:2064
	v_lshl_add_u64 v[2:3], v[2:3], 0, s[100:101]
	s_waitcnt vmcnt(8)
	v_lshlrev_b32_e32 v6, 16, v52
	v_and_b32_e32 v7, 0xffff0000, v52
	v_pk_mul_f32 v[8:9], v[6:7], v[6:7]
	v_lshlrev_b32_e32 v40, 16, v60
	v_and_b32_e32 v41, 0xffff0000, v60
	v_pk_mul_f32 v[250:251], v[40:41], v[40:41]
	v_lshlrev_b32_e32 v6, 16, v53
	v_and_b32_e32 v7, 0xffff0000, v53
	v_pk_fma_f32 v[8:9], v[6:7], v[6:7], v[8:9]
	v_lshlrev_b32_e32 v40, 16, v61
	v_and_b32_e32 v41, 0xffff0000, v61
	v_pk_fma_f32 v[250:251], v[40:41], v[40:41], v[250:251]
	v_lshlrev_b32_e32 v6, 16, v54
	v_and_b32_e32 v7, 0xffff0000, v54
	v_pk_fma_f32 v[8:9], v[6:7], v[6:7], v[8:9]
	v_lshlrev_b32_e32 v40, 16, v62
	v_and_b32_e32 v41, 0xffff0000, v62
	v_pk_fma_f32 v[250:251], v[40:41], v[40:41], v[250:251]
	v_lshlrev_b32_e32 v6, 16, v55
	v_and_b32_e32 v7, 0xffff0000, v55
	v_pk_fma_f32 v[8:9], v[6:7], v[6:7], v[8:9]
	v_lshlrev_b32_e32 v40, 16, v63
	v_and_b32_e32 v41, 0xffff0000, v63
	v_pk_fma_f32 v[250:251], v[40:41], v[40:41], v[250:251]
	v_lshlrev_b32_e32 v6, 16, v56
	v_and_b32_e32 v7, 0xffff0000, v56
	v_pk_fma_f32 v[8:9], v[6:7], v[6:7], v[8:9]
	v_lshlrev_b32_e32 v40, 16, v64
	v_and_b32_e32 v41, 0xffff0000, v64
	v_pk_fma_f32 v[250:251], v[40:41], v[40:41], v[250:251]
	v_lshlrev_b32_e32 v6, 16, v57
	v_and_b32_e32 v7, 0xffff0000, v57
	v_pk_fma_f32 v[8:9], v[6:7], v[6:7], v[8:9]
	v_lshlrev_b32_e32 v40, 16, v65
	v_and_b32_e32 v41, 0xffff0000, v65
	v_pk_fma_f32 v[250:251], v[40:41], v[40:41], v[250:251]
	v_lshlrev_b32_e32 v6, 16, v58
	v_and_b32_e32 v7, 0xffff0000, v58
	v_pk_fma_f32 v[8:9], v[6:7], v[6:7], v[8:9]
	v_lshlrev_b32_e32 v40, 16, v66
	v_and_b32_e32 v41, 0xffff0000, v66
	v_pk_fma_f32 v[250:251], v[40:41], v[40:41], v[250:251]
	v_lshlrev_b32_e32 v6, 16, v59
	v_and_b32_e32 v7, 0xffff0000, v59
	v_pk_fma_f32 v[8:9], v[6:7], v[6:7], v[8:9]
	v_lshlrev_b32_e32 v40, 16, v67
	v_and_b32_e32 v41, 0xffff0000, v67
	v_pk_fma_f32 v[250:251], v[40:41], v[40:41], v[250:251]
	v_add_f32_e32 v8, v8, v9
	v_add_f32_e32 v250, v250, v251
	s_nop 1
	v_add_f32_dpp v8, v8, v8 quad_perm:[1,0,3,2] row_mask:0xf bank_mask:0xf
	v_add_f32_dpp v250, v250, v250 quad_perm:[1,0,3,2] row_mask:0xf bank_mask:0xf
	s_nop 1
	v_add_f32_dpp v8, v8, v8 quad_perm:[2,3,0,1] row_mask:0xf bank_mask:0xf
	v_add_f32_dpp v250, v250, v250 quad_perm:[2,3,0,1] row_mask:0xf bank_mask:0xf
	s_nop 1
	v_add_f32_dpp v8, v8, v8 row_half_mirror row_mask:0xf bank_mask:0xf
	v_add_f32_dpp v250, v250, v250 row_half_mirror row_mask:0xf bank_mask:0xf
	s_nop 1
	v_add_f32_dpp v8, v8, v8 row_mirror row_mask:0xf bank_mask:0xf
	v_add_f32_dpp v250, v250, v250 row_mirror row_mask:0xf bank_mask:0xf
	s_nop 1
	ds_bpermute_b32 v6, v14, v8
	ds_bpermute_b32 v40, v14, v250
	s_waitcnt lgkmcnt(0)
; DEVI unsigned pk2(float lo, float hi) { unsigned r; asm("v_cvt_pk_bf16_f32 %0, %1, %2" : "=v"(r) : "v"(lo), "v"(hi)); return r; }
; DEVI float bflo(unsigned w) { return __uint_as_float(w << 16); }
; DEVI float bfhi(unsigned w) { return __uint_as_float(w & 0xffff0000u); }
; DEVI void phase_m3(const Params& p, int l, unsigned char* smem) {
;     ...
;             for (int tt = 0; tt < 16; ++tt) {
;                 const int t = wave * 16 + tt;
;                 bf16_t* rowp = mix + (size_t)(row0 + t) * DM + lane * 16;
;                 const u32x4 a = *(const u32x4*)rowp, b = *(const u32x4*)(rowp + 8);
;                 float v[16] = {bflo(a.x), bfhi(a.x), bflo(a.y), bfhi(a.y), bflo(a.z), bfhi(a.z), bflo(a.w), bfhi(a.w), bflo(b.x), bfhi(b.x), bflo(b.y), bfhi(b.y), bflo(b.z), bfhi(b.z), bflo(b.w), bfhi(b.w)};
;                 float ss = 0.f;
; #pragma unroll
;                 for (int e = 0; e < 16; ++e) ss += v[e] * v[e];
;                 ss += __shfl_xor(ss, 1); ss += __shfl_xor(ss, 2); ss += __shfl_xor(ss, 4); ss += __shfl_xor(ss, 8);
;                 const float s16 = __shfl_xor(ss, 16);
;                 float rn;
;                 if (lane < 32) rn = rsqrtf((ss + s16) * (1.0f / 512.0f) + RMS_EPS); else rn = rsqrtf(ss * (1.0f / 256.0f) + RMS_EPS);
;                 const f32x4 g0 = *(const f32x4*)(gain + lane * 16), g1 = *(const f32x4*)(gain + lane * 16 + 4), g2 = *(const f32x4*)(gain + lane * 16 + 8), g3 = *(const f32x4*)(gain + lane * 16 + 12);
;                 u32x4 o1, o2;
;                 o1.x = pk2(v[0] * rn * g0[0], v[1] * rn * g0[1]); o1.y = pk2(v[2] * rn * g0[2], v[3] * rn * g0[3]); o1.z = pk2(v[4] * rn * g1[0], v[5] * rn * g1[1]); o1.w = pk2(v[6] * rn * g1[2], v[7] * rn * g1[3]);
;                 o2.x = pk2(v[8] * rn * g2[0], v[9] * rn * g2[1]); o2.y = pk2(v[10] * rn * g2[2], v[11] * rn * g2[3]); o2.z = pk2(v[12] * rn * g3[0], v[13] * rn * g3[1]); o2.w = pk2(v[14] * rn * g3[2], v[15] * rn * g3[3]);
;                 *(u32x4*)rowp = o1; *(u32x4*)(rowp + 8) = o2;
;             }
	v_add_f32_e32 v6, v8, v6
	v_mul_f32_e32 v6, 0x3b000000, v6
	v_mul_f32_e32 v8, 0x3b800000, v8
	v_cndmask_b32_e64 v8, v8, v6, s[6:7]
	v_add_f32_e32 v8, 0x358637bd, v8
	v_rsq_f32_e32 v252, v8
	v_add_f32_e32 v40, v250, v40
	v_mul_f32_e32 v40, 0x3b000000, v40
	v_mul_f32_e32 v250, 0x3b800000, v250
	v_cndmask_b32_e64 v250, v250, v40, s[6:7]
	v_add_f32_e32 v250, 0x358637bd, v250
	v_rsq_f32_e32 v254, v250
	s_nop 1
	v_lshlrev_b32_e32 v6, 16, v52
	v_and_b32_e32 v7, 0xffff0000, v52
	v_pk_mul_f32 v[6:7], v[6:7], v[252:253] op_sel_hi:[1,0]
	v_pk_mul_f32 v[6:7], v[6:7], v[16:17]
	v_cvt_pk_bf16_f32 v52, v6, v7
	v_lshlrev_b32_e32 v40, 16, v60
	v_and_b32_e32 v41, 0xffff0000, v60
	v_pk_mul_f32 v[40:41], v[40:41], v[254:255] op_sel_hi:[1,0]
	v_pk_mul_f32 v[40:41], v[40:41], v[16:17]
	v_cvt_pk_bf16_f32 v60, v40, v41
	v_lshlrev_b32_e32 v6, 16, v53
	v_and_b32_e32 v7, 0xffff0000, v53
	v_pk_mul_f32 v[6:7], v[6:7], v[252:253] op_sel_hi:[1,0]
	v_pk_mul_f32 v[6:7], v[6:7], v[18:19]
	v_cvt_pk_bf16_f32 v53, v6, v7
	v_lshlrev_b32_e32 v40, 16, v61
	v_and_b32_e32 v41, 0xffff0000, v61
	v_pk_mul_f32 v[40:41], v[40:41], v[254:255] op_sel_hi:[1,0]
	v_pk_mul_f32 v[40:41], v[40:41], v[18:19]
	v_cvt_pk_bf16_f32 v61, v40, v41
	v_lshlrev_b32_e32 v6, 16, v54
	v_and_b32_e32 v7, 0xffff0000, v54
	v_pk_mul_f32 v[6:7], v[6:7], v[252:253] op_sel_hi:[1,0]
	v_pk_mul_f32 v[6:7], v[6:7], v[20:21]
	v_cvt_pk_bf16_f32 v54, v6, v7
	v_lshlrev_b32_e32 v40, 16, v62
	v_and_b32_e32 v41, 0xffff0000, v62
	v_pk_mul_f32 v[40:41], v[40:41], v[254:255] op_sel_hi:[1,0]
	v_pk_mul_f32 v[40:41], v[40:41], v[20:21]
	v_cvt_pk_bf16_f32 v62, v40, v41
	v_lshlrev_b32_e32 v6, 16, v55
	v_and_b32_e32 v7, 0xffff0000, v55
	v_pk_mul_f32 v[6:7], v[6:7], v[252:253] op_sel_hi:[1,0]
	v_pk_mul_f32 v[6:7], v[6:7], v[22:23]
	v_cvt_pk_bf16_f32 v55, v6, v7
	v_lshlrev_b32_e32 v40, 16, v63
	v_and_b32_e32 v41, 0xffff0000, v63
	v_pk_mul_f32 v[40:41], v[40:41], v[254:255] op_sel_hi:[1,0]
	v_pk_mul_f32 v[40:41], v[40:41], v[22:23]
	v_cvt_pk_bf16_f32 v63, v40, v41
	v_lshlrev_b32_e32 v6, 16, v56
	v_and_b32_e32 v7, 0xffff0000, v56
	v_pk_mul_f32 v[6:7], v[6:7], v[252:253] op_sel_hi:[1,0]
	v_pk_mul_f32 v[6:7], v[6:7], v[24:25]
	v_cvt_pk_bf16_f32 v56, v6, v7
	v_lshlrev_b32_e32 v40, 16, v64
	v_and_b32_e32 v41, 0xffff0000, v64
	v_pk_mul_f32 v[40:41], v[40:41], v[254:255] op_sel_hi:[1,0]
	v_pk_mul_f32 v[40:41], v[40:41], v[24:25]
	v_cvt_pk_bf16_f32 v64, v40, v41
	v_lshlrev_b32_e32 v6, 16, v57
	v_and_b32_e32 v7, 0xffff0000, v57
	v_pk_mul_f32 v[6:7], v[6:7], v[252:253] op_sel_hi:[1,0]
	v_pk_mul_f32 v[6:7], v[6:7], v[26:27]
	v_cvt_pk_bf16_f32 v57, v6, v7
	v_lshlrev_b32_e32 v40, 16, v65
	v_and_b32_e32 v41, 0xffff0000, v65
	v_pk_mul_f32 v[40:41], v[40:41], v[254:255] op_sel_hi:[1,0]
	v_pk_mul_f32 v[40:41], v[40:41], v[26:27]
	v_cvt_pk_bf16_f32 v65, v40, v41
	v_lshlrev_b32_e32 v6, 16, v58
	v_and_b32_e32 v7, 0xffff0000, v58
	v_pk_mul_f32 v[6:7], v[6:7], v[252:253] op_sel_hi:[1,0]
	v_pk_mul_f32 v[6:7], v[6:7], v[28:29]
	v_cvt_pk_bf16_f32 v58, v6, v7
	v_lshlrev_b32_e32 v40, 16, v66
	v_and_b32_e32 v41, 0xffff0000, v66
	v_pk_mul_f32 v[40:41], v[40:41], v[254:255] op_sel_hi:[1,0]
	v_pk_mul_f32 v[40:41], v[40:41], v[28:29]
	v_cvt_pk_bf16_f32 v66, v40, v41
	v_lshlrev_b32_e32 v6, 16, v59
	v_and_b32_e32 v7, 0xffff0000, v59
	v_pk_mul_f32 v[6:7], v[6:7], v[252:253] op_sel_hi:[1,0]
	v_pk_mul_f32 v[6:7], v[6:7], v[30:31]
	v_cvt_pk_bf16_f32 v59, v6, v7
	v_lshlrev_b32_e32 v40, 16, v67
	v_and_b32_e32 v41, 0xffff0000, v67
	v_pk_mul_f32 v[40:41], v[40:41], v[254:255] op_sel_hi:[1,0]
	v_pk_mul_f32 v[40:41], v[40:41], v[30:31]
	v_cvt_pk_bf16_f32 v67, v40, v41
	global_store_dwordx4 v[4:5], v[52:55], off
	global_store_dwordx4 v[4:5], v[56:59], off offset:16
	global_store_dwordx4 v[4:5], v[60:63], off offset:2048
	global_store_dwordx4 v[4:5], v[64:67], off offset:2064
	v_lshl_add_u64 v[4:5], v[4:5], 0, s[100:101]
	s_nop 1
	global_load_dwordx4 v[52:55], v[2:3], off
	global_load_dwordx4 v[56:59], v[2:3], off offset:16
	global_load_dwordx4 v[60:63], v[2:3], off offset:2048
	global_load_dwordx4 v[64:67], v[2:3], off offset:2064
	v_lshl_add_u64 v[2:3], v[2:3], 0, s[100:101]
	s_waitcnt vmcnt(8)
	v_lshlrev_b32_e32 v6, 16, v32
	v_and_b32_e32 v7, 0xffff0000, v32
	v_pk_mul_f32 v[8:9], v[6:7], v[6:7]
	v_lshlrev_b32_e32 v40, 16, v44
	v_and_b32_e32 v41, 0xffff0000, v44
	v_pk_mul_f32 v[250:251], v[40:41], v[40:41]
	v_lshlrev_b32_e32 v6, 16, v33
	v_and_b32_e32 v7, 0xffff0000, v33
	v_pk_fma_f32 v[8:9], v[6:7], v[6:7], v[8:9]
	v_lshlrev_b32_e32 v40, 16, v45
	v_and_b32_e32 v41, 0xffff0000, v45
	v_pk_fma_f32 v[250:251], v[40:41], v[40:41], v[250:251]
	v_lshlrev_b32_e32 v6, 16, v34
	v_and_b32_e32 v7, 0xffff0000, v34
	v_pk_fma_f32 v[8:9], v[6:7], v[6:7], v[8:9]
	v_lshlrev_b32_e32 v40, 16, v46
	v_and_b32_e32 v41, 0xffff0000, v46
	v_pk_fma_f32 v[250:251], v[40:41], v[40:41], v[250:251]
	v_lshlrev_b32_e32 v6, 16, v35
	v_and_b32_e32 v7, 0xffff0000, v35
	v_pk_fma_f32 v[8:9], v[6:7], v[6:7], v[8:9]
	v_lshlrev_b32_e32 v40, 16, v47
	v_and_b32_e32 v41, 0xffff0000, v47
	v_pk_fma_f32 v[250:251], v[40:41], v[40:41], v[250:251]
	v_lshlrev_b32_e32 v6, 16, v36
	v_and_b32_e32 v7, 0xffff0000, v36
	v_pk_fma_f32 v[8:9], v[6:7], v[6:7], v[8:9]
	v_lshlrev_b32_e32 v40, 16, v48
	v_and_b32_e32 v41, 0xffff0000, v48
	v_pk_fma_f32 v[250:251], v[40:41], v[40:41], v[250:251]
	v_lshlrev_b32_e32 v6, 16, v37
	v_and_b32_e32 v7, 0xffff0000, v37
	v_pk_fma_f32 v[8:9], v[6:7], v[6:7], v[8:9]
	v_lshlrev_b32_e32 v40, 16, v49
	v_and_b32_e32 v41, 0xffff0000, v49
	v_pk_fma_f32 v[250:251], v[40:41], v[40:41], v[250:251]
	v_lshlrev_b32_e32 v6, 16, v38
	v_and_b32_e32 v7, 0xffff0000, v38
	v_pk_fma_f32 v[8:9], v[6:7], v[6:7], v[8:9]
	v_lshlrev_b32_e32 v40, 16, v50
	v_and_b32_e32 v41, 0xffff0000, v50
	v_pk_fma_f32 v[250:251], v[40:41], v[40:41], v[250:251]
	v_lshlrev_b32_e32 v6, 16, v39
	v_and_b32_e32 v7, 0xffff0000, v39
	v_pk_fma_f32 v[8:9], v[6:7], v[6:7], v[8:9]
	v_lshlrev_b32_e32 v40, 16, v51
	v_and_b32_e32 v41, 0xffff0000, v51
	v_pk_fma_f32 v[250:251], v[40:41], v[40:41], v[250:251]
	v_add_f32_e32 v8, v8, v9
	v_add_f32_e32 v250, v250, v251
	s_nop 1
	v_add_f32_dpp v8, v8, v8 quad_perm:[1,0,3,2] row_mask:0xf bank_mask:0xf
	v_add_f32_dpp v250, v250, v250 quad_perm:[1,0,3,2] row_mask:0xf bank_mask:0xf
	s_nop 1
	v_add_f32_dpp v8, v8, v8 quad_perm:[2,3,0,1] row_mask:0xf bank_mask:0xf
	v_add_f32_dpp v250, v250, v250 quad_perm:[2,3,0,1] row_mask:0xf bank_mask:0xf
	s_nop 1
	v_add_f32_dpp v8, v8, v8 row_half_mirror row_mask:0xf bank_mask:0xf
	v_add_f32_dpp v250, v250, v250 row_half_mirror row_mask:0xf bank_mask:0xf
	s_nop 1
	v_add_f32_dpp v8, v8, v8 row_mirror row_mask:0xf bank_mask:0xf
	v_add_f32_dpp v250, v250, v250 row_mirror row_mask:0xf bank_mask:0xf
	s_nop 1
	ds_bpermute_b32 v6, v14, v8
	ds_bpermute_b32 v40, v14, v250
	s_waitcnt lgkmcnt(0)
; DEVI unsigned pk2(float lo, float hi) { unsigned r; asm("v_cvt_pk_bf16_f32 %0, %1, %2" : "=v"(r) : "v"(lo), "v"(hi)); return r; }
; DEVI float bflo(unsigned w) { return __uint_as_float(w << 16); }
; DEVI float bfhi(unsigned w) { return __uint_as_float(w & 0xffff0000u); }
; DEVI void phase_m3(const Params& p, int l, unsigned char* smem) {
;     ...
;             for (int tt = 0; tt < 16; ++tt) {
;                 const int t = wave * 16 + tt;
;                 bf16_t* rowp = mix + (size_t)(row0 + t) * DM + lane * 16;
;                 const u32x4 a = *(const u32x4*)rowp, b = *(const u32x4*)(rowp + 8);
;                 float v[16] = {bflo(a.x), bfhi(a.x), bflo(a.y), bfhi(a.y), bflo(a.z), bfhi(a.z), bflo(a.w), bfhi(a.w), bflo(b.x), bfhi(b.x), bflo(b.y), bfhi(b.y), bflo(b.z), bfhi(b.z), bflo(b.w), bfhi(b.w)};
;                 float ss = 0.f;
; #pragma unroll
;                 for (int e = 0; e < 16; ++e) ss += v[e] * v[e];
;                 ss += __shfl_xor(ss, 1); ss += __shfl_xor(ss, 2); ss += __shfl_xor(ss, 4); ss += __shfl_xor(ss, 8);
;                 const float s16 = __shfl_xor(ss, 16);
;                 float rn;
;                 if (lane < 32) rn = rsqrtf((ss + s16) * (1.0f / 512.0f) + RMS_EPS); else rn = rsqrtf(ss * (1.0f / 256.0f) + RMS_EPS);
;                 const f32x4 g0 = *(const f32x4*)(gain + lane * 16), g1 = *(const f32x4*)(gain + lane * 16 + 4), g2 = *(const f32x4*)(gain + lane * 16 + 8), g3 = *(const f32x4*)(gain + lane * 16 + 12);
;                 u32x4 o1, o2;
;                 o1.x = pk2(v[0] * rn * g0[0], v[1] * rn * g0[1]); o1.y = pk2(v[2] * rn * g0[2], v[3] * rn * g0[3]); o1.z = pk2(v[4] * rn * g1[0], v[5] * rn * g1[1]); o1.w = pk2(v[6] * rn * g1[2], v[7] * rn * g1[3]);
;                 o2.x = pk2(v[8] * rn * g2[0], v[9] * rn * g2[1]); o2.y = pk2(v[10] * rn * g2[2], v[11] * rn * g2[3]); o2.z = pk2(v[12] * rn * g3[0], v[13] * rn * g3[1]); o2.w = pk2(v[14] * rn * g3[2], v[15] * rn * g3[3]);
;                 *(u32x4*)rowp = o1; *(u32x4*)(rowp + 8) = o2;
;             }
	v_add_f32_e32 v6, v8, v6
	v_mul_f32_e32 v6, 0x3b000000, v6
	v_mul_f32_e32 v8, 0x3b800000, v8
	v_cndmask_b32_e64 v8, v8, v6, s[6:7]
	v_add_f32_e32 v8, 0x358637bd, v8
	v_rsq_f32_e32 v252, v8
	v_add_f32_e32 v40, v250, v40
	v_mul_f32_e32 v40, 0x3b000000, v40
	v_mul_f32_e32 v250, 0x3b800000, v250
	v_cndmask_b32_e64 v250, v250, v40, s[6:7]
	v_add_f32_e32 v250, 0x358637bd, v250
	v_rsq_f32_e32 v254, v250
	s_nop 1
	v_lshlrev_b32_e32 v6, 16, v32
	v_and_b32_e32 v7, 0xffff0000, v32
	v_pk_mul_f32 v[6:7], v[6:7], v[252:253] op_sel_hi:[1,0]
	v_pk_mul_f32 v[6:7], v[6:7], v[16:17]
	v_cvt_pk_bf16_f32 v32, v6, v7
	v_lshlrev_b32_e32 v40, 16, v44
	v_and_b32_e32 v41, 0xffff0000, v44
	v_pk_mul_f32 v[40:41], v[40:41], v[254:255] op_sel_hi:[1,0]
	v_pk_mul_f32 v[40:41], v[40:41], v[16:17]
	v_cvt_pk_bf16_f32 v44, v40, v41
	v_lshlrev_b32_e32 v6, 16, v33
	v_and_b32_e32 v7, 0xffff0000, v33
	v_pk_mul_f32 v[6:7], v[6:7], v[252:253] op_sel_hi:[1,0]
	v_pk_mul_f32 v[6:7], v[6:7], v[18:19]
	v_cvt_pk_bf16_f32 v33, v6, v7
	v_lshlrev_b32_e32 v40, 16, v45
	v_and_b32_e32 v41, 0xffff0000, v45
	v_pk_mul_f32 v[40:41], v[40:41], v[254:255] op_sel_hi:[1,0]
	v_pk_mul_f32 v[40:41], v[40:41], v[18:19]
	v_cvt_pk_bf16_f32 v45, v40, v41
	v_lshlrev_b32_e32 v6, 16, v34
	v_and_b32_e32 v7, 0xffff0000, v34
	v_pk_mul_f32 v[6:7], v[6:7], v[252:253] op_sel_hi:[1,0]
	v_pk_mul_f32 v[6:7], v[6:7], v[20:21]
	v_cvt_pk_bf16_f32 v34, v6, v7
	v_lshlrev_b32_e32 v40, 16, v46
	v_and_b32_e32 v41, 0xffff0000, v46
	v_pk_mul_f32 v[40:41], v[40:41], v[254:255] op_sel_hi:[1,0]
	v_pk_mul_f32 v[40:41], v[40:41], v[20:21]
	v_cvt_pk_bf16_f32 v46, v40, v41
	v_lshlrev_b32_e32 v6, 16, v35
	v_and_b32_e32 v7, 0xffff0000, v35
	v_pk_mul_f32 v[6:7], v[6:7], v[252:253] op_sel_hi:[1,0]
	v_pk_mul_f32 v[6:7], v[6:7], v[22:23]
	v_cvt_pk_bf16_f32 v35, v6, v7
	v_lshlrev_b32_e32 v40, 16, v47
	v_and_b32_e32 v41, 0xffff0000, v47
	v_pk_mul_f32 v[40:41], v[40:41], v[254:255] op_sel_hi:[1,0]
	v_pk_mul_f32 v[40:41], v[40:41], v[22:23]
	v_cvt_pk_bf16_f32 v47, v40, v41
	v_lshlrev_b32_e32 v6, 16, v36
	v_and_b32_e32 v7, 0xffff0000, v36
	v_pk_mul_f32 v[6:7], v[6:7], v[252:253] op_sel_hi:[1,0]
	v_pk_mul_f32 v[6:7], v[6:7], v[24:25]
	v_cvt_pk_bf16_f32 v36, v6, v7
	v_lshlrev_b32_e32 v40, 16, v48
	v_and_b32_e32 v41, 0xffff0000, v48
	v_pk_mul_f32 v[40:41], v[40:41], v[254:255] op_sel_hi:[1,0]
	v_pk_mul_f32 v[40:41], v[40:41], v[24:25]
	v_cvt_pk_bf16_f32 v48, v40, v41
	v_lshlrev_b32_e32 v6, 16, v37
	v_and_b32_e32 v7, 0xffff0000, v37
	v_pk_mul_f32 v[6:7], v[6:7], v[252:253] op_sel_hi:[1,0]
	v_pk_mul_f32 v[6:7], v[6:7], v[26:27]
	v_cvt_pk_bf16_f32 v37, v6, v7
	v_lshlrev_b32_e32 v40, 16, v49
	v_and_b32_e32 v41, 0xffff0000, v49
	v_pk_mul_f32 v[40:41], v[40:41], v[254:255] op_sel_hi:[1,0]
	v_pk_mul_f32 v[40:41], v[40:41], v[26:27]
	v_cvt_pk_bf16_f32 v49, v40, v41
	v_lshlrev_b32_e32 v6, 16, v38
	v_and_b32_e32 v7, 0xffff0000, v38
	v_pk_mul_f32 v[6:7], v[6:7], v[252:253] op_sel_hi:[1,0]
	v_pk_mul_f32 v[6:7], v[6:7], v[28:29]
	v_cvt_pk_bf16_f32 v38, v6, v7
	v_lshlrev_b32_e32 v40, 16, v50
	v_and_b32_e32 v41, 0xffff0000, v50
	v_pk_mul_f32 v[40:41], v[40:41], v[254:255] op_sel_hi:[1,0]
	v_pk_mul_f32 v[40:41], v[40:41], v[28:29]
	v_cvt_pk_bf16_f32 v50, v40, v41
	v_lshlrev_b32_e32 v6, 16, v39
	v_and_b32_e32 v7, 0xffff0000, v39
	v_pk_mul_f32 v[6:7], v[6:7], v[252:253] op_sel_hi:[1,0]
	v_pk_mul_f32 v[6:7], v[6:7], v[30:31]
	v_cvt_pk_bf16_f32 v39, v6, v7
	v_lshlrev_b32_e32 v40, 16, v51
	v_and_b32_e32 v41, 0xffff0000, v51
	v_pk_mul_f32 v[40:41], v[40:41], v[254:255] op_sel_hi:[1,0]
	v_pk_mul_f32 v[40:41], v[40:41], v[30:31]
	v_cvt_pk_bf16_f32 v51, v40, v41
	global_store_dwordx4 v[4:5], v[32:35], off
	global_store_dwordx4 v[4:5], v[36:39], off offset:16
	global_store_dwordx4 v[4:5], v[44:47], off offset:2048
	global_store_dwordx4 v[4:5], v[48:51], off offset:2064
	v_lshl_add_u64 v[4:5], v[4:5], 0, s[100:101]
	s_nop 1
	global_load_dwordx4 v[32:35], v[2:3], off
	global_load_dwordx4 v[36:39], v[2:3], off offset:16
	global_load_dwordx4 v[44:47], v[2:3], off offset:2048
	global_load_dwordx4 v[48:51], v[2:3], off offset:2064
	v_lshl_add_u64 v[2:3], v[2:3], 0, s[100:101]
	s_waitcnt vmcnt(8)
	v_lshlrev_b32_e32 v6, 16, v52
	v_and_b32_e32 v7, 0xffff0000, v52
	v_pk_mul_f32 v[8:9], v[6:7], v[6:7]
	v_lshlrev_b32_e32 v40, 16, v60
	v_and_b32_e32 v41, 0xffff0000, v60
	v_pk_mul_f32 v[250:251], v[40:41], v[40:41]
	v_lshlrev_b32_e32 v6, 16, v53
	v_and_b32_e32 v7, 0xffff0000, v53
	v_pk_fma_f32 v[8:9], v[6:7], v[6:7], v[8:9]
	v_lshlrev_b32_e32 v40, 16, v61
	v_and_b32_e32 v41, 0xffff0000, v61
	v_pk_fma_f32 v[250:251], v[40:41], v[40:41], v[250:251]
	v_lshlrev_b32_e32 v6, 16, v54
	v_and_b32_e32 v7, 0xffff0000, v54
	v_pk_fma_f32 v[8:9], v[6:7], v[6:7], v[8:9]
	v_lshlrev_b32_e32 v40, 16, v62
	v_and_b32_e32 v41, 0xffff0000, v62
	v_pk_fma_f32 v[250:251], v[40:41], v[40:41], v[250:251]
	v_lshlrev_b32_e32 v6, 16, v55
	v_and_b32_e32 v7, 0xffff0000, v55
	v_pk_fma_f32 v[8:9], v[6:7], v[6:7], v[8:9]
	v_lshlrev_b32_e32 v40, 16, v63
	v_and_b32_e32 v41, 0xffff0000, v63
	v_pk_fma_f32 v[250:251], v[40:41], v[40:41], v[250:251]
	v_lshlrev_b32_e32 v6, 16, v56
	v_and_b32_e32 v7, 0xffff0000, v56
	v_pk_fma_f32 v[8:9], v[6:7], v[6:7], v[8:9]
	v_lshlrev_b32_e32 v40, 16, v64
	v_and_b32_e32 v41, 0xffff0000, v64
	v_pk_fma_f32 v[250:251], v[40:41], v[40:41], v[250:251]
	v_lshlrev_b32_e32 v6, 16, v57
	v_and_b32_e32 v7, 0xffff0000, v57
	v_pk_fma_f32 v[8:9], v[6:7], v[6:7], v[8:9]
	v_lshlrev_b32_e32 v40, 16, v65
	v_and_b32_e32 v41, 0xffff0000, v65
	v_pk_fma_f32 v[250:251], v[40:41], v[40:41], v[250:251]
	v_lshlrev_b32_e32 v6, 16, v58
	v_and_b32_e32 v7, 0xffff0000, v58
	v_pk_fma_f32 v[8:9], v[6:7], v[6:7], v[8:9]
	v_lshlrev_b32_e32 v40, 16, v66
	v_and_b32_e32 v41, 0xffff0000, v66
	v_pk_fma_f32 v[250:251], v[40:41], v[40:41], v[250:251]
	v_lshlrev_b32_e32 v6, 16, v59
	v_and_b32_e32 v7, 0xffff0000, v59
	v_pk_fma_f32 v[8:9], v[6:7], v[6:7], v[8:9]
	v_lshlrev_b32_e32 v40, 16, v67
	v_and_b32_e32 v41, 0xffff0000, v67
	v_pk_fma_f32 v[250:251], v[40:41], v[40:41], v[250:251]
	v_add_f32_e32 v8, v8, v9
	v_add_f32_e32 v250, v250, v251
	s_nop 1
	v_add_f32_dpp v8, v8, v8 quad_perm:[1,0,3,2] row_mask:0xf bank_mask:0xf
	v_add_f32_dpp v250, v250, v250 quad_perm:[1,0,3,2] row_mask:0xf bank_mask:0xf
	s_nop 1
	v_add_f32_dpp v8, v8, v8 quad_perm:[2,3,0,1] row_mask:0xf bank_mask:0xf
	v_add_f32_dpp v250, v250, v250 quad_perm:[2,3,0,1] row_mask:0xf bank_mask:0xf
	s_nop 1
	v_add_f32_dpp v8, v8, v8 row_half_mirror row_mask:0xf bank_mask:0xf
	v_add_f32_dpp v250, v250, v250 row_half_mirror row_mask:0xf bank_mask:0xf
	s_nop 1
	v_add_f32_dpp v8, v8, v8 row_mirror row_mask:0xf bank_mask:0xf
	v_add_f32_dpp v250, v250, v250 row_mirror row_mask:0xf bank_mask:0xf
	s_nop 1
	ds_bpermute_b32 v6, v14, v8
	ds_bpermute_b32 v40, v14, v250
	s_waitcnt lgkmcnt(0)
; DEVI unsigned pk2(float lo, float hi) { unsigned r; asm("v_cvt_pk_bf16_f32 %0, %1, %2" : "=v"(r) : "v"(lo), "v"(hi)); return r; }
; DEVI float bflo(unsigned w) { return __uint_as_float(w << 16); }
; DEVI float bfhi(unsigned w) { return __uint_as_float(w & 0xffff0000u); }
; DEVI void phase_m3(const Params& p, int l, unsigned char* smem) {
;     ...
;             for (int tt = 0; tt < 16; ++tt) {
;                 const int t = wave * 16 + tt;
;                 bf16_t* rowp = mix + (size_t)(row0 + t) * DM + lane * 16;
;                 const u32x4 a = *(const u32x4*)rowp, b = *(const u32x4*)(rowp + 8);
;                 float v[16] = {bflo(a.x), bfhi(a.x), bflo(a.y), bfhi(a.y), bflo(a.z), bfhi(a.z), bflo(a.w), bfhi(a.w), bflo(b.x), bfhi(b.x), bflo(b.y), bfhi(b.y), bflo(b.z), bfhi(b.z), bflo(b.w), bfhi(b.w)};
;                 float ss = 0.f;
; #pragma unroll
;                 for (int e = 0; e < 16; ++e) ss += v[e] * v[e];
;                 ss += __shfl_xor(ss, 1); ss += __shfl_xor(ss, 2); ss += __shfl_xor(ss, 4); ss += __shfl_xor(ss, 8);
;                 const float s16 = __shfl_xor(ss, 16);
;                 float rn;
;                 if (lane < 32) rn = rsqrtf((ss + s16) * (1.0f / 512.0f) + RMS_EPS); else rn = rsqrtf(ss * (1.0f / 256.0f) + RMS_EPS);
;                 const f32x4 g0 = *(const f32x4*)(gain + lane * 16), g1 = *(const f32x4*)(gain + lane * 16 + 4), g2 = *(const f32x4*)(gain + lane * 16 + 8), g3 = *(const f32x4*)(gain + lane * 16 + 12);
;                 u32x4 o1, o2;
;                 o1.x = pk2(v[0] * rn * g0[0], v[1] * rn * g0[1]); o1.y = pk2(v[2] * rn * g0[2], v[3] * rn * g0[3]); o1.z = pk2(v[4] * rn * g1[0], v[5] * rn * g1[1]); o1.w = pk2(v[6] * rn * g1[2], v[7] * rn * g1[3]);
;                 o2.x = pk2(v[8] * rn * g2[0], v[9] * rn * g2[1]); o2.y = pk2(v[10] * rn * g2[2], v[11] * rn * g2[3]); o2.z = pk2(v[12] * rn * g3[0], v[13] * rn * g3[1]); o2.w = pk2(v[14] * rn * g3[2], v[15] * rn * g3[3]);
;                 *(u32x4*)rowp = o1; *(u32x4*)(rowp + 8) = o2;
;             }
	v_add_f32_e32 v6, v8, v6
	v_mul_f32_e32 v6, 0x3b000000, v6
	v_mul_f32_e32 v8, 0x3b800000, v8
	v_cndmask_b32_e64 v8, v8, v6, s[6:7]
	v_add_f32_e32 v8, 0x358637bd, v8
	v_rsq_f32_e32 v252, v8
	v_add_f32_e32 v40, v250, v40
	v_mul_f32_e32 v40, 0x3b000000, v40
	v_mul_f32_e32 v250, 0x3b800000, v250
	v_cndmask_b32_e64 v250, v250, v40, s[6:7]
	v_add_f32_e32 v250, 0x358637bd, v250
	v_rsq_f32_e32 v254, v250
	s_nop 1
	v_lshlrev_b32_e32 v6, 16, v52
	v_and_b32_e32 v7, 0xffff0000, v52
	v_pk_mul_f32 v[6:7], v[6:7], v[252:253] op_sel_hi:[1,0]
	v_pk_mul_f32 v[6:7], v[6:7], v[16:17]
	v_cvt_pk_bf16_f32 v52, v6, v7
	v_lshlrev_b32_e32 v40, 16, v60
	v_and_b32_e32 v41, 0xffff0000, v60
	v_pk_mul_f32 v[40:41], v[40:41], v[254:255] op_sel_hi:[1,0]
	v_pk_mul_f32 v[40:41], v[40:41], v[16:17]
	v_cvt_pk_bf16_f32 v60, v40, v41
	v_lshlrev_b32_e32 v6, 16, v53
	v_and_b32_e32 v7, 0xffff0000, v53
	v_pk_mul_f32 v[6:7], v[6:7], v[252:253] op_sel_hi:[1,0]
	v_pk_mul_f32 v[6:7], v[6:7], v[18:19]
	v_cvt_pk_bf16_f32 v53, v6, v7
	v_lshlrev_b32_e32 v40, 16, v61
	v_and_b32_e32 v41, 0xffff0000, v61
	v_pk_mul_f32 v[40:41], v[40:41], v[254:255] op_sel_hi:[1,0]
	v_pk_mul_f32 v[40:41], v[40:41], v[18:19]
	v_cvt_pk_bf16_f32 v61, v40, v41
	v_lshlrev_b32_e32 v6, 16, v54
	v_and_b32_e32 v7, 0xffff0000, v54
	v_pk_mul_f32 v[6:7], v[6:7], v[252:253] op_sel_hi:[1,0]
	v_pk_mul_f32 v[6:7], v[6:7], v[20:21]
	v_cvt_pk_bf16_f32 v54, v6, v7
	v_lshlrev_b32_e32 v40, 16, v62
	v_and_b32_e32 v41, 0xffff0000, v62
	v_pk_mul_f32 v[40:41], v[40:41], v[254:255] op_sel_hi:[1,0]
	v_pk_mul_f32 v[40:41], v[40:41], v[20:21]
	v_cvt_pk_bf16_f32 v62, v40, v41
	v_lshlrev_b32_e32 v6, 16, v55
	v_and_b32_e32 v7, 0xffff0000, v55
	v_pk_mul_f32 v[6:7], v[6:7], v[252:253] op_sel_hi:[1,0]
	v_pk_mul_f32 v[6:7], v[6:7], v[22:23]
	v_cvt_pk_bf16_f32 v55, v6, v7
	v_lshlrev_b32_e32 v40, 16, v63
	v_and_b32_e32 v41, 0xffff0000, v63
	v_pk_mul_f32 v[40:41], v[40:41], v[254:255] op_sel_hi:[1,0]
	v_pk_mul_f32 v[40:41], v[40:41], v[22:23]
	v_cvt_pk_bf16_f32 v63, v40, v41
	v_lshlrev_b32_e32 v6, 16, v56
	v_and_b32_e32 v7, 0xffff0000, v56
	v_pk_mul_f32 v[6:7], v[6:7], v[252:253] op_sel_hi:[1,0]
	v_pk_mul_f32 v[6:7], v[6:7], v[24:25]
	v_cvt_pk_bf16_f32 v56, v6, v7
	v_lshlrev_b32_e32 v40, 16, v64
	v_and_b32_e32 v41, 0xffff0000, v64
	v_pk_mul_f32 v[40:41], v[40:41], v[254:255] op_sel_hi:[1,0]
	v_pk_mul_f32 v[40:41], v[40:41], v[24:25]
	v_cvt_pk_bf16_f32 v64, v40, v41
	v_lshlrev_b32_e32 v6, 16, v57
	v_and_b32_e32 v7, 0xffff0000, v57
	v_pk_mul_f32 v[6:7], v[6:7], v[252:253] op_sel_hi:[1,0]
	v_pk_mul_f32 v[6:7], v[6:7], v[26:27]
	v_cvt_pk_bf16_f32 v57, v6, v7
	v_lshlrev_b32_e32 v40, 16, v65
	v_and_b32_e32 v41, 0xffff0000, v65
	v_pk_mul_f32 v[40:41], v[40:41], v[254:255] op_sel_hi:[1,0]
	v_pk_mul_f32 v[40:41], v[40:41], v[26:27]
	v_cvt_pk_bf16_f32 v65, v40, v41
	v_lshlrev_b32_e32 v6, 16, v58
	v_and_b32_e32 v7, 0xffff0000, v58
	v_pk_mul_f32 v[6:7], v[6:7], v[252:253] op_sel_hi:[1,0]
	v_pk_mul_f32 v[6:7], v[6:7], v[28:29]
	v_cvt_pk_bf16_f32 v58, v6, v7
	v_lshlrev_b32_e32 v40, 16, v66
	v_and_b32_e32 v41, 0xffff0000, v66
	v_pk_mul_f32 v[40:41], v[40:41], v[254:255] op_sel_hi:[1,0]
	v_pk_mul_f32 v[40:41], v[40:41], v[28:29]
	v_cvt_pk_bf16_f32 v66, v40, v41
	v_lshlrev_b32_e32 v6, 16, v59
	v_and_b32_e32 v7, 0xffff0000, v59
	v_pk_mul_f32 v[6:7], v[6:7], v[252:253] op_sel_hi:[1,0]
	v_pk_mul_f32 v[6:7], v[6:7], v[30:31]
	v_cvt_pk_bf16_f32 v59, v6, v7
	v_lshlrev_b32_e32 v40, 16, v67
	v_and_b32_e32 v41, 0xffff0000, v67
	v_pk_mul_f32 v[40:41], v[40:41], v[254:255] op_sel_hi:[1,0]
	v_pk_mul_f32 v[40:41], v[40:41], v[30:31]
	v_cvt_pk_bf16_f32 v67, v40, v41
	global_store_dwordx4 v[4:5], v[52:55], off
	global_store_dwordx4 v[4:5], v[56:59], off offset:16
	global_store_dwordx4 v[4:5], v[60:63], off offset:2048
	global_store_dwordx4 v[4:5], v[64:67], off offset:2064
	v_lshl_add_u64 v[4:5], v[4:5], 0, s[100:101]
	s_nop 1
	global_load_dwordx4 v[52:55], v[2:3], off
	global_load_dwordx4 v[56:59], v[2:3], off offset:16
	global_load_dwordx4 v[60:63], v[2:3], off offset:2048
	global_load_dwordx4 v[64:67], v[2:3], off offset:2064
	v_lshl_add_u64 v[2:3], v[2:3], 0, s[100:101]
	s_waitcnt vmcnt(8)
	v_lshlrev_b32_e32 v6, 16, v32
	v_and_b32_e32 v7, 0xffff0000, v32
	v_pk_mul_f32 v[8:9], v[6:7], v[6:7]
	v_lshlrev_b32_e32 v40, 16, v44
	v_and_b32_e32 v41, 0xffff0000, v44
	v_pk_mul_f32 v[250:251], v[40:41], v[40:41]
	v_lshlrev_b32_e32 v6, 16, v33
	v_and_b32_e32 v7, 0xffff0000, v33
	v_pk_fma_f32 v[8:9], v[6:7], v[6:7], v[8:9]
	v_lshlrev_b32_e32 v40, 16, v45
	v_and_b32_e32 v41, 0xffff0000, v45
	v_pk_fma_f32 v[250:251], v[40:41], v[40:41], v[250:251]
	v_lshlrev_b32_e32 v6, 16, v34
	v_and_b32_e32 v7, 0xffff0000, v34
	v_pk_fma_f32 v[8:9], v[6:7], v[6:7], v[8:9]
	v_lshlrev_b32_e32 v40, 16, v46
	v_and_b32_e32 v41, 0xffff0000, v46
	v_pk_fma_f32 v[250:251], v[40:41], v[40:41], v[250:251]
	v_lshlrev_b32_e32 v6, 16, v35
	v_and_b32_e32 v7, 0xffff0000, v35
	v_pk_fma_f32 v[8:9], v[6:7], v[6:7], v[8:9]
	v_lshlrev_b32_e32 v40, 16, v47
	v_and_b32_e32 v41, 0xffff0000, v47
	v_pk_fma_f32 v[250:251], v[40:41], v[40:41], v[250:251]
	v_lshlrev_b32_e32 v6, 16, v36
	v_and_b32_e32 v7, 0xffff0000, v36
	v_pk_fma_f32 v[8:9], v[6:7], v[6:7], v[8:9]
	v_lshlrev_b32_e32 v40, 16, v48
	v_and_b32_e32 v41, 0xffff0000, v48
	v_pk_fma_f32 v[250:251], v[40:41], v[40:41], v[250:251]
	v_lshlrev_b32_e32 v6, 16, v37
	v_and_b32_e32 v7, 0xffff0000, v37
	v_pk_fma_f32 v[8:9], v[6:7], v[6:7], v[8:9]
	v_lshlrev_b32_e32 v40, 16, v49
	v_and_b32_e32 v41, 0xffff0000, v49
	v_pk_fma_f32 v[250:251], v[40:41], v[40:41], v[250:251]
	v_lshlrev_b32_e32 v6, 16, v38
	v_and_b32_e32 v7, 0xffff0000, v38
	v_pk_fma_f32 v[8:9], v[6:7], v[6:7], v[8:9]
	v_lshlrev_b32_e32 v40, 16, v50
	v_and_b32_e32 v41, 0xffff0000, v50
	v_pk_fma_f32 v[250:251], v[40:41], v[40:41], v[250:251]
	v_lshlrev_b32_e32 v6, 16, v39
	v_and_b32_e32 v7, 0xffff0000, v39
	v_pk_fma_f32 v[8:9], v[6:7], v[6:7], v[8:9]
	v_lshlrev_b32_e32 v40, 16, v51
	v_and_b32_e32 v41, 0xffff0000, v51
	v_pk_fma_f32 v[250:251], v[40:41], v[40:41], v[250:251]
	v_add_f32_e32 v8, v8, v9
	v_add_f32_e32 v250, v250, v251
	s_nop 1
	v_add_f32_dpp v8, v8, v8 quad_perm:[1,0,3,2] row_mask:0xf bank_mask:0xf
	v_add_f32_dpp v250, v250, v250 quad_perm:[1,0,3,2] row_mask:0xf bank_mask:0xf
	s_nop 1
	v_add_f32_dpp v8, v8, v8 quad_perm:[2,3,0,1] row_mask:0xf bank_mask:0xf
	v_add_f32_dpp v250, v250, v250 quad_perm:[2,3,0,1] row_mask:0xf bank_mask:0xf
	s_nop 1
	v_add_f32_dpp v8, v8, v8 row_half_mirror row_mask:0xf bank_mask:0xf
	v_add_f32_dpp v250, v250, v250 row_half_mirror row_mask:0xf bank_mask:0xf
	s_nop 1
	v_add_f32_dpp v8, v8, v8 row_mirror row_mask:0xf bank_mask:0xf
	v_add_f32_dpp v250, v250, v250 row_mirror row_mask:0xf bank_mask:0xf
	s_nop 1
	ds_bpermute_b32 v6, v14, v8
	ds_bpermute_b32 v40, v14, v250
	s_waitcnt lgkmcnt(0)
; DEVI unsigned pk2(float lo, float hi) { unsigned r; asm("v_cvt_pk_bf16_f32 %0, %1, %2" : "=v"(r) : "v"(lo), "v"(hi)); return r; }
; DEVI float bflo(unsigned w) { return __uint_as_float(w << 16); }
; DEVI float bfhi(unsigned w) { return __uint_as_float(w & 0xffff0000u); }
; DEVI void phase_m3(const Params& p, int l, unsigned char* smem) {
;     ...
;             for (int tt = 0; tt < 16; ++tt) {
;                 const int t = wave * 16 + tt;
;                 bf16_t* rowp = mix + (size_t)(row0 + t) * DM + lane * 16;
;                 const u32x4 a = *(const u32x4*)rowp, b = *(const u32x4*)(rowp + 8);
;                 float v[16] = {bflo(a.x), bfhi(a.x), bflo(a.y), bfhi(a.y), bflo(a.z), bfhi(a.z), bflo(a.w), bfhi(a.w), bflo(b.x), bfhi(b.x), bflo(b.y), bfhi(b.y), bflo(b.z), bfhi(b.z), bflo(b.w), bfhi(b.w)};
;                 float ss = 0.f;
; #pragma unroll
;                 for (int e = 0; e < 16; ++e) ss += v[e] * v[e];
;                 ss += __shfl_xor(ss, 1); ss += __shfl_xor(ss, 2); ss += __shfl_xor(ss, 4); ss += __shfl_xor(ss, 8);
;                 const float s16 = __shfl_xor(ss, 16);
;                 float rn;
;                 if (lane < 32) rn = rsqrtf((ss + s16) * (1.0f / 512.0f) + RMS_EPS); else rn = rsqrtf(ss * (1.0f / 256.0f) + RMS_EPS);
;                 const f32x4 g0 = *(const f32x4*)(gain + lane * 16), g1 = *(const f32x4*)(gain + lane * 16 + 4), g2 = *(const f32x4*)(gain + lane * 16 + 8), g3 = *(const f32x4*)(gain + lane * 16 + 12);
;                 u32x4 o1, o2;
;                 o1.x = pk2(v[0] * rn * g0[0], v[1] * rn * g0[1]); o1.y = pk2(v[2] * rn * g0[2], v[3] * rn * g0[3]); o1.z = pk2(v[4] * rn * g1[0], v[5] * rn * g1[1]); o1.w = pk2(v[6] * rn * g1[2], v[7] * rn * g1[3]);
;                 o2.x = pk2(v[8] * rn * g2[0], v[9] * rn * g2[1]); o2.y = pk2(v[10] * rn * g2[2], v[11] * rn * g2[3]); o2.z = pk2(v[12] * rn * g3[0], v[13] * rn * g3[1]); o2.w = pk2(v[14] * rn * g3[2], v[15] * rn * g3[3]);
;                 *(u32x4*)rowp = o1; *(u32x4*)(rowp + 8) = o2;
;             }
	v_add_f32_e32 v6, v8, v6
	v_mul_f32_e32 v6, 0x3b000000, v6
	v_mul_f32_e32 v8, 0x3b800000, v8
	v_cndmask_b32_e64 v8, v8, v6, s[6:7]
	v_add_f32_e32 v8, 0x358637bd, v8
	v_rsq_f32_e32 v252, v8
	v_add_f32_e32 v40, v250, v40
	v_mul_f32_e32 v40, 0x3b000000, v40
	v_mul_f32_e32 v250, 0x3b800000, v250
	v_cndmask_b32_e64 v250, v250, v40, s[6:7]
	v_add_f32_e32 v250, 0x358637bd, v250
	v_rsq_f32_e32 v254, v250
	s_nop 1
	v_lshlrev_b32_e32 v6, 16, v32
	v_and_b32_e32 v7, 0xffff0000, v32
	v_pk_mul_f32 v[6:7], v[6:7], v[252:253] op_sel_hi:[1,0]
	v_pk_mul_f32 v[6:7], v[6:7], v[16:17]
	v_cvt_pk_bf16_f32 v32, v6, v7
	v_lshlrev_b32_e32 v40, 16, v44
	v_and_b32_e32 v41, 0xffff0000, v44
	v_pk_mul_f32 v[40:41], v[40:41], v[254:255] op_sel_hi:[1,0]
	v_pk_mul_f32 v[40:41], v[40:41], v[16:17]
	v_cvt_pk_bf16_f32 v44, v40, v41
	v_lshlrev_b32_e32 v6, 16, v33
	v_and_b32_e32 v7, 0xffff0000, v33
	v_pk_mul_f32 v[6:7], v[6:7], v[252:253] op_sel_hi:[1,0]
	v_pk_mul_f32 v[6:7], v[6:7], v[18:19]
	v_cvt_pk_bf16_f32 v33, v6, v7
	v_lshlrev_b32_e32 v40, 16, v45
	v_and_b32_e32 v41, 0xffff0000, v45
	v_pk_mul_f32 v[40:41], v[40:41], v[254:255] op_sel_hi:[1,0]
	v_pk_mul_f32 v[40:41], v[40:41], v[18:19]
	v_cvt_pk_bf16_f32 v45, v40, v41
	v_lshlrev_b32_e32 v6, 16, v34
	v_and_b32_e32 v7, 0xffff0000, v34
	v_pk_mul_f32 v[6:7], v[6:7], v[252:253] op_sel_hi:[1,0]
	v_pk_mul_f32 v[6:7], v[6:7], v[20:21]
	v_cvt_pk_bf16_f32 v34, v6, v7
	v_lshlrev_b32_e32 v40, 16, v46
	v_and_b32_e32 v41, 0xffff0000, v46
	v_pk_mul_f32 v[40:41], v[40:41], v[254:255] op_sel_hi:[1,0]
	v_pk_mul_f32 v[40:41], v[40:41], v[20:21]
	v_cvt_pk_bf16_f32 v46, v40, v41
	v_lshlrev_b32_e32 v6, 16, v35
	v_and_b32_e32 v7, 0xffff0000, v35
	v_pk_mul_f32 v[6:7], v[6:7], v[252:253] op_sel_hi:[1,0]
	v_pk_mul_f32 v[6:7], v[6:7], v[22:23]
	v_cvt_pk_bf16_f32 v35, v6, v7
	v_lshlrev_b32_e32 v40, 16, v47
	v_and_b32_e32 v41, 0xffff0000, v47
	v_pk_mul_f32 v[40:41], v[40:41], v[254:255] op_sel_hi:[1,0]
	v_pk_mul_f32 v[40:41], v[40:41], v[22:23]
	v_cvt_pk_bf16_f32 v47, v40, v41
	v_lshlrev_b32_e32 v6, 16, v36
	v_and_b32_e32 v7, 0xffff0000, v36
	v_pk_mul_f32 v[6:7], v[6:7], v[252:253] op_sel_hi:[1,0]
	v_pk_mul_f32 v[6:7], v[6:7], v[24:25]
	v_cvt_pk_bf16_f32 v36, v6, v7
	v_lshlrev_b32_e32 v40, 16, v48
	v_and_b32_e32 v41, 0xffff0000, v48
	v_pk_mul_f32 v[40:41], v[40:41], v[254:255] op_sel_hi:[1,0]
	v_pk_mul_f32 v[40:41], v[40:41], v[24:25]
	v_cvt_pk_bf16_f32 v48, v40, v41
	v_lshlrev_b32_e32 v6, 16, v37
	v_and_b32_e32 v7, 0xffff0000, v37
	v_pk_mul_f32 v[6:7], v[6:7], v[252:253] op_sel_hi:[1,0]
	v_pk_mul_f32 v[6:7], v[6:7], v[26:27]
	v_cvt_pk_bf16_f32 v37, v6, v7
	v_lshlrev_b32_e32 v40, 16, v49
	v_and_b32_e32 v41, 0xffff0000, v49
	v_pk_mul_f32 v[40:41], v[40:41], v[254:255] op_sel_hi:[1,0]
	v_pk_mul_f32 v[40:41], v[40:41], v[26:27]
	v_cvt_pk_bf16_f32 v49, v40, v41
	v_lshlrev_b32_e32 v6, 16, v38
	v_and_b32_e32 v7, 0xffff0000, v38
	v_pk_mul_f32 v[6:7], v[6:7], v[252:253] op_sel_hi:[1,0]
	v_pk_mul_f32 v[6:7], v[6:7], v[28:29]
	v_cvt_pk_bf16_f32 v38, v6, v7
	v_lshlrev_b32_e32 v40, 16, v50
	v_and_b32_e32 v41, 0xffff0000, v50
	v_pk_mul_f32 v[40:41], v[40:41], v[254:255] op_sel_hi:[1,0]
	v_pk_mul_f32 v[40:41], v[40:41], v[28:29]
	v_cvt_pk_bf16_f32 v50, v40, v41
	v_lshlrev_b32_e32 v6, 16, v39
	v_and_b32_e32 v7, 0xffff0000, v39
	v_pk_mul_f32 v[6:7], v[6:7], v[252:253] op_sel_hi:[1,0]
	v_pk_mul_f32 v[6:7], v[6:7], v[30:31]
	v_cvt_pk_bf16_f32 v39, v6, v7
	v_lshlrev_b32_e32 v40, 16, v51
	v_and_b32_e32 v41, 0xffff0000, v51
	v_pk_mul_f32 v[40:41], v[40:41], v[254:255] op_sel_hi:[1,0]
	v_pk_mul_f32 v[40:41], v[40:41], v[30:31]
	v_cvt_pk_bf16_f32 v51, v40, v41
	global_store_dwordx4 v[4:5], v[32:35], off
	global_store_dwordx4 v[4:5], v[36:39], off offset:16
	global_store_dwordx4 v[4:5], v[44:47], off offset:2048
	global_store_dwordx4 v[4:5], v[48:51], off offset:2064
	v_lshl_add_u64 v[4:5], v[4:5], 0, s[100:101]
	s_nop 1
	global_load_dwordx4 v[32:35], v[2:3], off
	global_load_dwordx4 v[36:39], v[2:3], off offset:16
	global_load_dwordx4 v[44:47], v[2:3], off offset:2048
	global_load_dwordx4 v[48:51], v[2:3], off offset:2064
	v_lshl_add_u64 v[2:3], v[2:3], 0, s[100:101]
	s_waitcnt vmcnt(8)
	v_lshlrev_b32_e32 v6, 16, v52
	v_and_b32_e32 v7, 0xffff0000, v52
	v_pk_mul_f32 v[8:9], v[6:7], v[6:7]
	v_lshlrev_b32_e32 v40, 16, v60
	v_and_b32_e32 v41, 0xffff0000, v60
	v_pk_mul_f32 v[250:251], v[40:41], v[40:41]
	v_lshlrev_b32_e32 v6, 16, v53
	v_and_b32_e32 v7, 0xffff0000, v53
	v_pk_fma_f32 v[8:9], v[6:7], v[6:7], v[8:9]
	v_lshlrev_b32_e32 v40, 16, v61
	v_and_b32_e32 v41, 0xffff0000, v61
	v_pk_fma_f32 v[250:251], v[40:41], v[40:41], v[250:251]
	v_lshlrev_b32_e32 v6, 16, v54
	v_and_b32_e32 v7, 0xffff0000, v54
	v_pk_fma_f32 v[8:9], v[6:7], v[6:7], v[8:9]
	v_lshlrev_b32_e32 v40, 16, v62
	v_and_b32_e32 v41, 0xffff0000, v62
	v_pk_fma_f32 v[250:251], v[40:41], v[40:41], v[250:251]
	v_lshlrev_b32_e32 v6, 16, v55
	v_and_b32_e32 v7, 0xffff0000, v55
	v_pk_fma_f32 v[8:9], v[6:7], v[6:7], v[8:9]
	v_lshlrev_b32_e32 v40, 16, v63
	v_and_b32_e32 v41, 0xffff0000, v63
	v_pk_fma_f32 v[250:251], v[40:41], v[40:41], v[250:251]
	v_lshlrev_b32_e32 v6, 16, v56
	v_and_b32_e32 v7, 0xffff0000, v56
	v_pk_fma_f32 v[8:9], v[6:7], v[6:7], v[8:9]
	v_lshlrev_b32_e32 v40, 16, v64
	v_and_b32_e32 v41, 0xffff0000, v64
	v_pk_fma_f32 v[250:251], v[40:41], v[40:41], v[250:251]
	v_lshlrev_b32_e32 v6, 16, v57
	v_and_b32_e32 v7, 0xffff0000, v57
	v_pk_fma_f32 v[8:9], v[6:7], v[6:7], v[8:9]
	v_lshlrev_b32_e32 v40, 16, v65
	v_and_b32_e32 v41, 0xffff0000, v65
	v_pk_fma_f32 v[250:251], v[40:41], v[40:41], v[250:251]
	v_lshlrev_b32_e32 v6, 16, v58
	v_and_b32_e32 v7, 0xffff0000, v58
	v_pk_fma_f32 v[8:9], v[6:7], v[6:7], v[8:9]
	v_lshlrev_b32_e32 v40, 16, v66
	v_and_b32_e32 v41, 0xffff0000, v66
	v_pk_fma_f32 v[250:251], v[40:41], v[40:41], v[250:251]
	v_lshlrev_b32_e32 v6, 16, v59
	v_and_b32_e32 v7, 0xffff0000, v59
	v_pk_fma_f32 v[8:9], v[6:7], v[6:7], v[8:9]
	v_lshlrev_b32_e32 v40, 16, v67
	v_and_b32_e32 v41, 0xffff0000, v67
	v_pk_fma_f32 v[250:251], v[40:41], v[40:41], v[250:251]
	v_add_f32_e32 v8, v8, v9
	v_add_f32_e32 v250, v250, v251
	s_nop 1
	v_add_f32_dpp v8, v8, v8 quad_perm:[1,0,3,2] row_mask:0xf bank_mask:0xf
	v_add_f32_dpp v250, v250, v250 quad_perm:[1,0,3,2] row_mask:0xf bank_mask:0xf
	s_nop 1
	v_add_f32_dpp v8, v8, v8 quad_perm:[2,3,0,1] row_mask:0xf bank_mask:0xf
	v_add_f32_dpp v250, v250, v250 quad_perm:[2,3,0,1] row_mask:0xf bank_mask:0xf
	s_nop 1
	v_add_f32_dpp v8, v8, v8 row_half_mirror row_mask:0xf bank_mask:0xf
	v_add_f32_dpp v250, v250, v250 row_half_mirror row_mask:0xf bank_mask:0xf
	s_nop 1
	v_add_f32_dpp v8, v8, v8 row_mirror row_mask:0xf bank_mask:0xf
	v_add_f32_dpp v250, v250, v250 row_mirror row_mask:0xf bank_mask:0xf
	s_nop 1
	ds_bpermute_b32 v6, v14, v8
	ds_bpermute_b32 v40, v14, v250
	s_waitcnt lgkmcnt(0)
; DEVI unsigned pk2(float lo, float hi) { unsigned r; asm("v_cvt_pk_bf16_f32 %0, %1, %2" : "=v"(r) : "v"(lo), "v"(hi)); return r; }
; DEVI float bflo(unsigned w) { return __uint_as_float(w << 16); }
; DEVI float bfhi(unsigned w) { return __uint_as_float(w & 0xffff0000u); }
; DEVI void phase_m3(const Params& p, int l, unsigned char* smem) {
;     ...
;             for (int tt = 0; tt < 16; ++tt) {
;                 const int t = wave * 16 + tt;
;                 bf16_t* rowp = mix + (size_t)(row0 + t) * DM + lane * 16;
;                 const u32x4 a = *(const u32x4*)rowp, b = *(const u32x4*)(rowp + 8);
;                 float v[16] = {bflo(a.x), bfhi(a.x), bflo(a.y), bfhi(a.y), bflo(a.z), bfhi(a.z), bflo(a.w), bfhi(a.w), bflo(b.x), bfhi(b.x), bflo(b.y), bfhi(b.y), bflo(b.z), bfhi(b.z), bflo(b.w), bfhi(b.w)};
;                 float ss = 0.f;
; #pragma unroll
;                 for (int e = 0; e < 16; ++e) ss += v[e] * v[e];
;                 ss += __shfl_xor(ss, 1); ss += __shfl_xor(ss, 2); ss += __shfl_xor(ss, 4); ss += __shfl_xor(ss, 8);
;                 const float s16 = __shfl_xor(ss, 16);
;                 float rn;
;                 if (lane < 32) rn = rsqrtf((ss + s16) * (1.0f / 512.0f) + RMS_EPS); else rn = rsqrtf(ss * (1.0f / 256.0f) + RMS_EPS);
;                 const f32x4 g0 = *(const f32x4*)(gain + lane * 16), g1 = *(const f32x4*)(gain + lane * 16 + 4), g2 = *(const f32x4*)(gain + lane * 16 + 8), g3 = *(const f32x4*)(gain + lane * 16 + 12);
;                 u32x4 o1, o2;
;                 o1.x = pk2(v[0] * rn * g0[0], v[1] * rn * g0[1]); o1.y = pk2(v[2] * rn * g0[2], v[3] * rn * g0[3]); o1.z = pk2(v[4] * rn * g1[0], v[5] * rn * g1[1]); o1.w = pk2(v[6] * rn * g1[2], v[7] * rn * g1[3]);
;                 o2.x = pk2(v[8] * rn * g2[0], v[9] * rn * g2[1]); o2.y = pk2(v[10] * rn * g2[2], v[11] * rn * g2[3]); o2.z = pk2(v[12] * rn * g3[0], v[13] * rn * g3[1]); o2.w = pk2(v[14] * rn * g3[2], v[15] * rn * g3[3]);
;                 *(u32x4*)rowp = o1; *(u32x4*)(rowp + 8) = o2;
;             }
	v_add_f32_e32 v6, v8, v6
	v_mul_f32_e32 v6, 0x3b000000, v6
	v_mul_f32_e32 v8, 0x3b800000, v8
	v_cndmask_b32_e64 v8, v8, v6, s[6:7]
	v_add_f32_e32 v8, 0x358637bd, v8
	v_rsq_f32_e32 v252, v8
	v_add_f32_e32 v40, v250, v40
	v_mul_f32_e32 v40, 0x3b000000, v40
	v_mul_f32_e32 v250, 0x3b800000, v250
	v_cndmask_b32_e64 v250, v250, v40, s[6:7]
	v_add_f32_e32 v250, 0x358637bd, v250
	v_rsq_f32_e32 v254, v250
	s_nop 1
	v_lshlrev_b32_e32 v6, 16, v52
	v_and_b32_e32 v7, 0xffff0000, v52
	v_pk_mul_f32 v[6:7], v[6:7], v[252:253] op_sel_hi:[1,0]
	v_pk_mul_f32 v[6:7], v[6:7], v[16:17]
	v_cvt_pk_bf16_f32 v52, v6, v7
	v_lshlrev_b32_e32 v40, 16, v60
	v_and_b32_e32 v41, 0xffff0000, v60
	v_pk_mul_f32 v[40:41], v[40:41], v[254:255] op_sel_hi:[1,0]
	v_pk_mul_f32 v[40:41], v[40:41], v[16:17]
	v_cvt_pk_bf16_f32 v60, v40, v41
	v_lshlrev_b32_e32 v6, 16, v53
	v_and_b32_e32 v7, 0xffff0000, v53
	v_pk_mul_f32 v[6:7], v[6:7], v[252:253] op_sel_hi:[1,0]
	v_pk_mul_f32 v[6:7], v[6:7], v[18:19]
	v_cvt_pk_bf16_f32 v53, v6, v7
	v_lshlrev_b32_e32 v40, 16, v61
	v_and_b32_e32 v41, 0xffff0000, v61
	v_pk_mul_f32 v[40:41], v[40:41], v[254:255] op_sel_hi:[1,0]
	v_pk_mul_f32 v[40:41], v[40:41], v[18:19]
	v_cvt_pk_bf16_f32 v61, v40, v41
	v_lshlrev_b32_e32 v6, 16, v54
	v_and_b32_e32 v7, 0xffff0000, v54
	v_pk_mul_f32 v[6:7], v[6:7], v[252:253] op_sel_hi:[1,0]
	v_pk_mul_f32 v[6:7], v[6:7], v[20:21]
	v_cvt_pk_bf16_f32 v54, v6, v7
	v_lshlrev_b32_e32 v40, 16, v62
	v_and_b32_e32 v41, 0xffff0000, v62
	v_pk_mul_f32 v[40:41], v[40:41], v[254:255] op_sel_hi:[1,0]
	v_pk_mul_f32 v[40:41], v[40:41], v[20:21]
	v_cvt_pk_bf16_f32 v62, v40, v41
	v_lshlrev_b32_e32 v6, 16, v55
	v_and_b32_e32 v7, 0xffff0000, v55
	v_pk_mul_f32 v[6:7], v[6:7], v[252:253] op_sel_hi:[1,0]
	v_pk_mul_f32 v[6:7], v[6:7], v[22:23]
	v_cvt_pk_bf16_f32 v55, v6, v7
	v_lshlrev_b32_e32 v40, 16, v63
	v_and_b32_e32 v41, 0xffff0000, v63
	v_pk_mul_f32 v[40:41], v[40:41], v[254:255] op_sel_hi:[1,0]
	v_pk_mul_f32 v[40:41], v[40:41], v[22:23]
	v_cvt_pk_bf16_f32 v63, v40, v41
	v_lshlrev_b32_e32 v6, 16, v56
	v_and_b32_e32 v7, 0xffff0000, v56
	v_pk_mul_f32 v[6:7], v[6:7], v[252:253] op_sel_hi:[1,0]
	v_pk_mul_f32 v[6:7], v[6:7], v[24:25]
	v_cvt_pk_bf16_f32 v56, v6, v7
	v_lshlrev_b32_e32 v40, 16, v64
	v_and_b32_e32 v41, 0xffff0000, v64
	v_pk_mul_f32 v[40:41], v[40:41], v[254:255] op_sel_hi:[1,0]
	v_pk_mul_f32 v[40:41], v[40:41], v[24:25]
	v_cvt_pk_bf16_f32 v64, v40, v41
	v_lshlrev_b32_e32 v6, 16, v57
	v_and_b32_e32 v7, 0xffff0000, v57
	v_pk_mul_f32 v[6:7], v[6:7], v[252:253] op_sel_hi:[1,0]
	v_pk_mul_f32 v[6:7], v[6:7], v[26:27]
	v_cvt_pk_bf16_f32 v57, v6, v7
	v_lshlrev_b32_e32 v40, 16, v65
	v_and_b32_e32 v41, 0xffff0000, v65
	v_pk_mul_f32 v[40:41], v[40:41], v[254:255] op_sel_hi:[1,0]
	v_pk_mul_f32 v[40:41], v[40:41], v[26:27]
	v_cvt_pk_bf16_f32 v65, v40, v41
	v_lshlrev_b32_e32 v6, 16, v58
	v_and_b32_e32 v7, 0xffff0000, v58
	v_pk_mul_f32 v[6:7], v[6:7], v[252:253] op_sel_hi:[1,0]
	v_pk_mul_f32 v[6:7], v[6:7], v[28:29]
	v_cvt_pk_bf16_f32 v58, v6, v7
	v_lshlrev_b32_e32 v40, 16, v66
	v_and_b32_e32 v41, 0xffff0000, v66
	v_pk_mul_f32 v[40:41], v[40:41], v[254:255] op_sel_hi:[1,0]
	v_pk_mul_f32 v[40:41], v[40:41], v[28:29]
	v_cvt_pk_bf16_f32 v66, v40, v41
	v_lshlrev_b32_e32 v6, 16, v59
	v_and_b32_e32 v7, 0xffff0000, v59
	v_pk_mul_f32 v[6:7], v[6:7], v[252:253] op_sel_hi:[1,0]
	v_pk_mul_f32 v[6:7], v[6:7], v[30:31]
	v_cvt_pk_bf16_f32 v59, v6, v7
	v_lshlrev_b32_e32 v40, 16, v67
	v_and_b32_e32 v41, 0xffff0000, v67
	v_pk_mul_f32 v[40:41], v[40:41], v[254:255] op_sel_hi:[1,0]
	v_pk_mul_f32 v[40:41], v[40:41], v[30:31]
	v_cvt_pk_bf16_f32 v67, v40, v41
	global_store_dwordx4 v[4:5], v[52:55], off
	global_store_dwordx4 v[4:5], v[56:59], off offset:16
	global_store_dwordx4 v[4:5], v[60:63], off offset:2048
	global_store_dwordx4 v[4:5], v[64:67], off offset:2064
	v_lshl_add_u64 v[4:5], v[4:5], 0, s[100:101]
	s_nop 1
	global_load_dwordx4 v[52:55], v[2:3], off
	global_load_dwordx4 v[56:59], v[2:3], off offset:16
	global_load_dwordx4 v[60:63], v[2:3], off offset:2048
	global_load_dwordx4 v[64:67], v[2:3], off offset:2064
	v_lshl_add_u64 v[2:3], v[2:3], 0, s[100:101]
	s_waitcnt vmcnt(8)
	v_lshlrev_b32_e32 v6, 16, v32
	v_and_b32_e32 v7, 0xffff0000, v32
	v_pk_mul_f32 v[8:9], v[6:7], v[6:7]
	v_lshlrev_b32_e32 v40, 16, v44
	v_and_b32_e32 v41, 0xffff0000, v44
	v_pk_mul_f32 v[250:251], v[40:41], v[40:41]
	v_lshlrev_b32_e32 v6, 16, v33
	v_and_b32_e32 v7, 0xffff0000, v33
	v_pk_fma_f32 v[8:9], v[6:7], v[6:7], v[8:9]
	v_lshlrev_b32_e32 v40, 16, v45
	v_and_b32_e32 v41, 0xffff0000, v45
	v_pk_fma_f32 v[250:251], v[40:41], v[40:41], v[250:251]
	v_lshlrev_b32_e32 v6, 16, v34
	v_and_b32_e32 v7, 0xffff0000, v34
	v_pk_fma_f32 v[8:9], v[6:7], v[6:7], v[8:9]
	v_lshlrev_b32_e32 v40, 16, v46
	v_and_b32_e32 v41, 0xffff0000, v46
	v_pk_fma_f32 v[250:251], v[40:41], v[40:41], v[250:251]
	v_lshlrev_b32_e32 v6, 16, v35
	v_and_b32_e32 v7, 0xffff0000, v35
	v_pk_fma_f32 v[8:9], v[6:7], v[6:7], v[8:9]
	v_lshlrev_b32_e32 v40, 16, v47
	v_and_b32_e32 v41, 0xffff0000, v47
	v_pk_fma_f32 v[250:251], v[40:41], v[40:41], v[250:251]
	v_lshlrev_b32_e32 v6, 16, v36
	v_and_b32_e32 v7, 0xffff0000, v36
	v_pk_fma_f32 v[8:9], v[6:7], v[6:7], v[8:9]
	v_lshlrev_b32_e32 v40, 16, v48
	v_and_b32_e32 v41, 0xffff0000, v48
	v_pk_fma_f32 v[250:251], v[40:41], v[40:41], v[250:251]
	v_lshlrev_b32_e32 v6, 16, v37
	v_and_b32_e32 v7, 0xffff0000, v37
	v_pk_fma_f32 v[8:9], v[6:7], v[6:7], v[8:9]
	v_lshlrev_b32_e32 v40, 16, v49
	v_and_b32_e32 v41, 0xffff0000, v49
	v_pk_fma_f32 v[250:251], v[40:41], v[40:41], v[250:251]
	v_lshlrev_b32_e32 v6, 16, v38
	v_and_b32_e32 v7, 0xffff0000, v38
	v_pk_fma_f32 v[8:9], v[6:7], v[6:7], v[8:9]
	v_lshlrev_b32_e32 v40, 16, v50
	v_and_b32_e32 v41, 0xffff0000, v50
	v_pk_fma_f32 v[250:251], v[40:41], v[40:41], v[250:251]
	v_lshlrev_b32_e32 v6, 16, v39
	v_and_b32_e32 v7, 0xffff0000, v39
	v_pk_fma_f32 v[8:9], v[6:7], v[6:7], v[8:9]
	v_lshlrev_b32_e32 v40, 16, v51
	v_and_b32_e32 v41, 0xffff0000, v51
	v_pk_fma_f32 v[250:251], v[40:41], v[40:41], v[250:251]
	v_add_f32_e32 v8, v8, v9
	v_add_f32_e32 v250, v250, v251
	s_nop 1
	v_add_f32_dpp v8, v8, v8 quad_perm:[1,0,3,2] row_mask:0xf bank_mask:0xf
	v_add_f32_dpp v250, v250, v250 quad_perm:[1,0,3,2] row_mask:0xf bank_mask:0xf
	s_nop 1
	v_add_f32_dpp v8, v8, v8 quad_perm:[2,3,0,1] row_mask:0xf bank_mask:0xf
	v_add_f32_dpp v250, v250, v250 quad_perm:[2,3,0,1] row_mask:0xf bank_mask:0xf
	s_nop 1
	v_add_f32_dpp v8, v8, v8 row_half_mirror row_mask:0xf bank_mask:0xf
	v_add_f32_dpp v250, v250, v250 row_half_mirror row_mask:0xf bank_mask:0xf
	s_nop 1
	v_add_f32_dpp v8, v8, v8 row_mirror row_mask:0xf bank_mask:0xf
	v_add_f32_dpp v250, v250, v250 row_mirror row_mask:0xf bank_mask:0xf
	s_nop 1
	ds_bpermute_b32 v6, v14, v8
	ds_bpermute_b32 v40, v14, v250
	s_waitcnt lgkmcnt(0)
; DEVI unsigned pk2(float lo, float hi) { unsigned r; asm("v_cvt_pk_bf16_f32 %0, %1, %2" : "=v"(r) : "v"(lo), "v"(hi)); return r; }
; DEVI float bflo(unsigned w) { return __uint_as_float(w << 16); }
; DEVI float bfhi(unsigned w) { return __uint_as_float(w & 0xffff0000u); }
; DEVI void phase_m3(const Params& p, int l, unsigned char* smem) {
;     ...
;             for (int tt = 0; tt < 16; ++tt) {
;                 const int t = wave * 16 + tt;
;                 bf16_t* rowp = mix + (size_t)(row0 + t) * DM + lane * 16;
;                 const u32x4 a = *(const u32x4*)rowp, b = *(const u32x4*)(rowp + 8);
;                 float v[16] = {bflo(a.x), bfhi(a.x), bflo(a.y), bfhi(a.y), bflo(a.z), bfhi(a.z), bflo(a.w), bfhi(a.w), bflo(b.x), bfhi(b.x), bflo(b.y), bfhi(b.y), bflo(b.z), bfhi(b.z), bflo(b.w), bfhi(b.w)};
;                 float ss = 0.f;
; #pragma unroll
;                 for (int e = 0; e < 16; ++e) ss += v[e] * v[e];
;                 ss += __shfl_xor(ss, 1); ss += __shfl_xor(ss, 2); ss += __shfl_xor(ss, 4); ss += __shfl_xor(ss, 8);
;                 const float s16 = __shfl_xor(ss, 16);
;                 float rn;
;                 if (lane < 32) rn = rsqrtf((ss + s16) * (1.0f / 512.0f) + RMS_EPS); else rn = rsqrtf(ss * (1.0f / 256.0f) + RMS_EPS);
;                 const f32x4 g0 = *(const f32x4*)(gain + lane * 16), g1 = *(const f32x4*)(gain + lane * 16 + 4), g2 = *(const f32x4*)(gain + lane * 16 + 8), g3 = *(const f32x4*)(gain + lane * 16 + 12);
;                 u32x4 o1, o2;
;                 o1.x = pk2(v[0] * rn * g0[0], v[1] * rn * g0[1]); o1.y = pk2(v[2] * rn * g0[2], v[3] * rn * g0[3]); o1.z = pk2(v[4] * rn * g1[0], v[5] * rn * g1[1]); o1.w = pk2(v[6] * rn * g1[2], v[7] * rn * g1[3]);
;                 o2.x = pk2(v[8] * rn * g2[0], v[9] * rn * g2[1]); o2.y = pk2(v[10] * rn * g2[2], v[11] * rn * g2[3]); o2.z = pk2(v[12] * rn * g3[0], v[13] * rn * g3[1]); o2.w = pk2(v[14] * rn * g3[2], v[15] * rn * g3[3]);
;                 *(u32x4*)rowp = o1; *(u32x4*)(rowp + 8) = o2;
;             }
	v_add_f32_e32 v6, v8, v6
	v_mul_f32_e32 v6, 0x3b000000, v6
	v_mul_f32_e32 v8, 0x3b800000, v8
	v_cndmask_b32_e64 v8, v8, v6, s[6:7]
	v_add_f32_e32 v8, 0x358637bd, v8
	v_rsq_f32_e32 v252, v8
	v_add_f32_e32 v40, v250, v40
	v_mul_f32_e32 v40, 0x3b000000, v40
	v_mul_f32_e32 v250, 0x3b800000, v250
	v_cndmask_b32_e64 v250, v250, v40, s[6:7]
	v_add_f32_e32 v250, 0x358637bd, v250
	v_rsq_f32_e32 v254, v250
	s_nop 1
	v_lshlrev_b32_e32 v6, 16, v32
	v_and_b32_e32 v7, 0xffff0000, v32
	v_pk_mul_f32 v[6:7], v[6:7], v[252:253] op_sel_hi:[1,0]
	v_pk_mul_f32 v[6:7], v[6:7], v[16:17]
	v_cvt_pk_bf16_f32 v32, v6, v7
	v_lshlrev_b32_e32 v40, 16, v44
	v_and_b32_e32 v41, 0xffff0000, v44
	v_pk_mul_f32 v[40:41], v[40:41], v[254:255] op_sel_hi:[1,0]
	v_pk_mul_f32 v[40:41], v[40:41], v[16:17]
	v_cvt_pk_bf16_f32 v44, v40, v41
	v_lshlrev_b32_e32 v6, 16, v33
	v_and_b32_e32 v7, 0xffff0000, v33
	v_pk_mul_f32 v[6:7], v[6:7], v[252:253] op_sel_hi:[1,0]
	v_pk_mul_f32 v[6:7], v[6:7], v[18:19]
	v_cvt_pk_bf16_f32 v33, v6, v7
	v_lshlrev_b32_e32 v40, 16, v45
	v_and_b32_e32 v41, 0xffff0000, v45
	v_pk_mul_f32 v[40:41], v[40:41], v[254:255] op_sel_hi:[1,0]
	v_pk_mul_f32 v[40:41], v[40:41], v[18:19]
	v_cvt_pk_bf16_f32 v45, v40, v41
	v_lshlrev_b32_e32 v6, 16, v34
	v_and_b32_e32 v7, 0xffff0000, v34
	v_pk_mul_f32 v[6:7], v[6:7], v[252:253] op_sel_hi:[1,0]
	v_pk_mul_f32 v[6:7], v[6:7], v[20:21]
	v_cvt_pk_bf16_f32 v34, v6, v7
	v_lshlrev_b32_e32 v40, 16, v46
	v_and_b32_e32 v41, 0xffff0000, v46
	v_pk_mul_f32 v[40:41], v[40:41], v[254:255] op_sel_hi:[1,0]
	v_pk_mul_f32 v[40:41], v[40:41], v[20:21]
	v_cvt_pk_bf16_f32 v46, v40, v41
	v_lshlrev_b32_e32 v6, 16, v35
	v_and_b32_e32 v7, 0xffff0000, v35
	v_pk_mul_f32 v[6:7], v[6:7], v[252:253] op_sel_hi:[1,0]
	v_pk_mul_f32 v[6:7], v[6:7], v[22:23]
	v_cvt_pk_bf16_f32 v35, v6, v7
	v_lshlrev_b32_e32 v40, 16, v47
	v_and_b32_e32 v41, 0xffff0000, v47
	v_pk_mul_f32 v[40:41], v[40:41], v[254:255] op_sel_hi:[1,0]
	v_pk_mul_f32 v[40:41], v[40:41], v[22:23]
	v_cvt_pk_bf16_f32 v47, v40, v41
	v_lshlrev_b32_e32 v6, 16, v36
	v_and_b32_e32 v7, 0xffff0000, v36
	v_pk_mul_f32 v[6:7], v[6:7], v[252:253] op_sel_hi:[1,0]
	v_pk_mul_f32 v[6:7], v[6:7], v[24:25]
	v_cvt_pk_bf16_f32 v36, v6, v7
	v_lshlrev_b32_e32 v40, 16, v48
	v_and_b32_e32 v41, 0xffff0000, v48
	v_pk_mul_f32 v[40:41], v[40:41], v[254:255] op_sel_hi:[1,0]
	v_pk_mul_f32 v[40:41], v[40:41], v[24:25]
	v_cvt_pk_bf16_f32 v48, v40, v41
	v_lshlrev_b32_e32 v6, 16, v37
	v_and_b32_e32 v7, 0xffff0000, v37
	v_pk_mul_f32 v[6:7], v[6:7], v[252:253] op_sel_hi:[1,0]
	v_pk_mul_f32 v[6:7], v[6:7], v[26:27]
	v_cvt_pk_bf16_f32 v37, v6, v7
	v_lshlrev_b32_e32 v40, 16, v49
	v_and_b32_e32 v41, 0xffff0000, v49
	v_pk_mul_f32 v[40:41], v[40:41], v[254:255] op_sel_hi:[1,0]
	v_pk_mul_f32 v[40:41], v[40:41], v[26:27]
	v_cvt_pk_bf16_f32 v49, v40, v41
	v_lshlrev_b32_e32 v6, 16, v38
	v_and_b32_e32 v7, 0xffff0000, v38
	v_pk_mul_f32 v[6:7], v[6:7], v[252:253] op_sel_hi:[1,0]
	v_pk_mul_f32 v[6:7], v[6:7], v[28:29]
	v_cvt_pk_bf16_f32 v38, v6, v7
	v_lshlrev_b32_e32 v40, 16, v50
	v_and_b32_e32 v41, 0xffff0000, v50
	v_pk_mul_f32 v[40:41], v[40:41], v[254:255] op_sel_hi:[1,0]
	v_pk_mul_f32 v[40:41], v[40:41], v[28:29]
	v_cvt_pk_bf16_f32 v50, v40, v41
	v_lshlrev_b32_e32 v6, 16, v39
	v_and_b32_e32 v7, 0xffff0000, v39
	v_pk_mul_f32 v[6:7], v[6:7], v[252:253] op_sel_hi:[1,0]
	v_pk_mul_f32 v[6:7], v[6:7], v[30:31]
	v_cvt_pk_bf16_f32 v39, v6, v7
	v_lshlrev_b32_e32 v40, 16, v51
	v_and_b32_e32 v41, 0xffff0000, v51
	v_pk_mul_f32 v[40:41], v[40:41], v[254:255] op_sel_hi:[1,0]
	v_pk_mul_f32 v[40:41], v[40:41], v[30:31]
	v_cvt_pk_bf16_f32 v51, v40, v41
	global_store_dwordx4 v[4:5], v[32:35], off
	global_store_dwordx4 v[4:5], v[36:39], off offset:16
	global_store_dwordx4 v[4:5], v[44:47], off offset:2048
	global_store_dwordx4 v[4:5], v[48:51], off offset:2064
	v_lshl_add_u64 v[4:5], v[4:5], 0, s[100:101]
	s_nop 1
	s_waitcnt vmcnt(4)
	v_lshlrev_b32_e32 v6, 16, v52
	v_and_b32_e32 v7, 0xffff0000, v52
	v_pk_mul_f32 v[8:9], v[6:7], v[6:7]
	v_lshlrev_b32_e32 v40, 16, v60
	v_and_b32_e32 v41, 0xffff0000, v60
	v_pk_mul_f32 v[250:251], v[40:41], v[40:41]
	v_lshlrev_b32_e32 v6, 16, v53
	v_and_b32_e32 v7, 0xffff0000, v53
	v_pk_fma_f32 v[8:9], v[6:7], v[6:7], v[8:9]
	v_lshlrev_b32_e32 v40, 16, v61
	v_and_b32_e32 v41, 0xffff0000, v61
	v_pk_fma_f32 v[250:251], v[40:41], v[40:41], v[250:251]
	v_lshlrev_b32_e32 v6, 16, v54
	v_and_b32_e32 v7, 0xffff0000, v54
	v_pk_fma_f32 v[8:9], v[6:7], v[6:7], v[8:9]
	v_lshlrev_b32_e32 v40, 16, v62
	v_and_b32_e32 v41, 0xffff0000, v62
	v_pk_fma_f32 v[250:251], v[40:41], v[40:41], v[250:251]
	v_lshlrev_b32_e32 v6, 16, v55
	v_and_b32_e32 v7, 0xffff0000, v55
	v_pk_fma_f32 v[8:9], v[6:7], v[6:7], v[8:9]
	v_lshlrev_b32_e32 v40, 16, v63
	v_and_b32_e32 v41, 0xffff0000, v63
	v_pk_fma_f32 v[250:251], v[40:41], v[40:41], v[250:251]
	v_lshlrev_b32_e32 v6, 16, v56
	v_and_b32_e32 v7, 0xffff0000, v56
	v_pk_fma_f32 v[8:9], v[6:7], v[6:7], v[8:9]
	v_lshlrev_b32_e32 v40, 16, v64
	v_and_b32_e32 v41, 0xffff0000, v64
	v_pk_fma_f32 v[250:251], v[40:41], v[40:41], v[250:251]
	v_lshlrev_b32_e32 v6, 16, v57
	v_and_b32_e32 v7, 0xffff0000, v57
	v_pk_fma_f32 v[8:9], v[6:7], v[6:7], v[8:9]
	v_lshlrev_b32_e32 v40, 16, v65
	v_and_b32_e32 v41, 0xffff0000, v65
	v_pk_fma_f32 v[250:251], v[40:41], v[40:41], v[250:251]
	v_lshlrev_b32_e32 v6, 16, v58
	v_and_b32_e32 v7, 0xffff0000, v58
	v_pk_fma_f32 v[8:9], v[6:7], v[6:7], v[8:9]
	v_lshlrev_b32_e32 v40, 16, v66
	v_and_b32_e32 v41, 0xffff0000, v66
	v_pk_fma_f32 v[250:251], v[40:41], v[40:41], v[250:251]
	v_lshlrev_b32_e32 v6, 16, v59
	v_and_b32_e32 v7, 0xffff0000, v59
	v_pk_fma_f32 v[8:9], v[6:7], v[6:7], v[8:9]
	v_lshlrev_b32_e32 v40, 16, v67
	v_and_b32_e32 v41, 0xffff0000, v67
	v_pk_fma_f32 v[250:251], v[40:41], v[40:41], v[250:251]
	v_add_f32_e32 v8, v8, v9
	v_add_f32_e32 v250, v250, v251
	s_nop 1
	v_add_f32_dpp v8, v8, v8 quad_perm:[1,0,3,2] row_mask:0xf bank_mask:0xf
	v_add_f32_dpp v250, v250, v250 quad_perm:[1,0,3,2] row_mask:0xf bank_mask:0xf
	s_nop 1
	v_add_f32_dpp v8, v8, v8 quad_perm:[2,3,0,1] row_mask:0xf bank_mask:0xf
	v_add_f32_dpp v250, v250, v250 quad_perm:[2,3,0,1] row_mask:0xf bank_mask:0xf
	s_nop 1
	v_add_f32_dpp v8, v8, v8 row_half_mirror row_mask:0xf bank_mask:0xf
	v_add_f32_dpp v250, v250, v250 row_half_mirror row_mask:0xf bank_mask:0xf
	s_nop 1
	v_add_f32_dpp v8, v8, v8 row_mirror row_mask:0xf bank_mask:0xf
	v_add_f32_dpp v250, v250, v250 row_mirror row_mask:0xf bank_mask:0xf
	s_nop 1
	ds_bpermute_b32 v6, v14, v8
	ds_bpermute_b32 v40, v14, v250
	s_waitcnt lgkmcnt(0)
; DEVI int bid_() { int t = blockIdx.x; asm volatile("" : "+s"(t)); return t; }
; DEVI int gdim_() { int t = gridDim.x; asm volatile("" : "+s"(t)); return t; }
; DEVI unsigned pk2(float lo, float hi) { unsigned r; asm("v_cvt_pk_bf16_f32 %0, %1, %2" : "=v"(r) : "v"(lo), "v"(hi)); return r; }
; DEVI float bflo(unsigned w) { return __uint_as_float(w << 16); }
; DEVI float bfhi(unsigned w) { return __uint_as_float(w & 0xffff0000u); }
; DEVI void phase_m3(const Params& p, int l, unsigned char* smem) {
;     ...
;     for (int tile = bid_(); tile < NTILE; tile += gdim_()) {
;     ...
;             for (int tt = 0; tt < 16; ++tt) {
;                 const int t = wave * 16 + tt;
;                 bf16_t* rowp = mix + (size_t)(row0 + t) * DM + lane * 16;
;                 const u32x4 a = *(const u32x4*)rowp, b = *(const u32x4*)(rowp + 8);
;                 float v[16] = {bflo(a.x), bfhi(a.x), bflo(a.y), bfhi(a.y), bflo(a.z), bfhi(a.z), bflo(a.w), bfhi(a.w), bflo(b.x), bfhi(b.x), bflo(b.y), bfhi(b.y), bflo(b.z), bfhi(b.z), bflo(b.w), bfhi(b.w)};
;                 float ss = 0.f;
; #pragma unroll
;                 for (int e = 0; e < 16; ++e) ss += v[e] * v[e];
;                 ss += __shfl_xor(ss, 1); ss += __shfl_xor(ss, 2); ss += __shfl_xor(ss, 4); ss += __shfl_xor(ss, 8);
;                 const float s16 = __shfl_xor(ss, 16);
;                 float rn;
;                 if (lane < 32) rn = rsqrtf((ss + s16) * (1.0f / 512.0f) + RMS_EPS); else rn = rsqrtf(ss * (1.0f / 256.0f) + RMS_EPS);
;                 const f32x4 g0 = *(const f32x4*)(gain + lane * 16), g1 = *(const f32x4*)(gain + lane * 16 + 4), g2 = *(const f32x4*)(gain + lane * 16 + 8), g3 = *(const f32x4*)(gain + lane * 16 + 12);
;                 u32x4 o1, o2;
;                 o1.x = pk2(v[0] * rn * g0[0], v[1] * rn * g0[1]); o1.y = pk2(v[2] * rn * g0[2], v[3] * rn * g0[3]); o1.z = pk2(v[4] * rn * g1[0], v[5] * rn * g1[1]); o1.w = pk2(v[6] * rn * g1[2], v[7] * rn * g1[3]);
;                 o2.x = pk2(v[8] * rn * g2[0], v[9] * rn * g2[1]); o2.y = pk2(v[10] * rn * g2[2], v[11] * rn * g2[3]); o2.z = pk2(v[12] * rn * g3[0], v[13] * rn * g3[1]); o2.w = pk2(v[14] * rn * g3[2], v[15] * rn * g3[3]);
;                 *(u32x4*)rowp = o1; *(u32x4*)(rowp + 8) = o2;
;             }
	v_add_f32_e32 v6, v8, v6
	v_mul_f32_e32 v6, 0x3b000000, v6
	v_mul_f32_e32 v8, 0x3b800000, v8
	v_cndmask_b32_e64 v8, v8, v6, s[6:7]
	v_add_f32_e32 v8, 0x358637bd, v8
	v_rsq_f32_e32 v252, v8
	v_add_f32_e32 v40, v250, v40
	v_mul_f32_e32 v40, 0x3b000000, v40
	v_mul_f32_e32 v250, 0x3b800000, v250
	v_cndmask_b32_e64 v250, v250, v40, s[6:7]
	v_add_f32_e32 v250, 0x358637bd, v250
	v_rsq_f32_e32 v254, v250
	s_nop 1
	v_lshlrev_b32_e32 v6, 16, v52
	v_and_b32_e32 v7, 0xffff0000, v52
	v_pk_mul_f32 v[6:7], v[6:7], v[252:253] op_sel_hi:[1,0]
	v_pk_mul_f32 v[6:7], v[6:7], v[16:17]
	v_cvt_pk_bf16_f32 v52, v6, v7
	v_lshlrev_b32_e32 v40, 16, v60
	v_and_b32_e32 v41, 0xffff0000, v60
	v_pk_mul_f32 v[40:41], v[40:41], v[254:255] op_sel_hi:[1,0]
	v_pk_mul_f32 v[40:41], v[40:41], v[16:17]
	v_cvt_pk_bf16_f32 v60, v40, v41
	v_lshlrev_b32_e32 v6, 16, v53
	v_and_b32_e32 v7, 0xffff0000, v53
	v_pk_mul_f32 v[6:7], v[6:7], v[252:253] op_sel_hi:[1,0]
	v_pk_mul_f32 v[6:7], v[6:7], v[18:19]
	v_cvt_pk_bf16_f32 v53, v6, v7
	v_lshlrev_b32_e32 v40, 16, v61
	v_and_b32_e32 v41, 0xffff0000, v61
	v_pk_mul_f32 v[40:41], v[40:41], v[254:255] op_sel_hi:[1,0]
	v_pk_mul_f32 v[40:41], v[40:41], v[18:19]
	v_cvt_pk_bf16_f32 v61, v40, v41
	v_lshlrev_b32_e32 v6, 16, v54
	v_and_b32_e32 v7, 0xffff0000, v54
	v_pk_mul_f32 v[6:7], v[6:7], v[252:253] op_sel_hi:[1,0]
	v_pk_mul_f32 v[6:7], v[6:7], v[20:21]
	v_cvt_pk_bf16_f32 v54, v6, v7
	v_lshlrev_b32_e32 v40, 16, v62
	v_and_b32_e32 v41, 0xffff0000, v62
	v_pk_mul_f32 v[40:41], v[40:41], v[254:255] op_sel_hi:[1,0]
	v_pk_mul_f32 v[40:41], v[40:41], v[20:21]
	v_cvt_pk_bf16_f32 v62, v40, v41
	v_lshlrev_b32_e32 v6, 16, v55
	v_and_b32_e32 v7, 0xffff0000, v55
	v_pk_mul_f32 v[6:7], v[6:7], v[252:253] op_sel_hi:[1,0]
	v_pk_mul_f32 v[6:7], v[6:7], v[22:23]
	v_cvt_pk_bf16_f32 v55, v6, v7
	v_lshlrev_b32_e32 v40, 16, v63
	v_and_b32_e32 v41, 0xffff0000, v63
	v_pk_mul_f32 v[40:41], v[40:41], v[254:255] op_sel_hi:[1,0]
	v_pk_mul_f32 v[40:41], v[40:41], v[22:23]
	v_cvt_pk_bf16_f32 v63, v40, v41
	v_lshlrev_b32_e32 v6, 16, v56
	v_and_b32_e32 v7, 0xffff0000, v56
	v_pk_mul_f32 v[6:7], v[6:7], v[252:253] op_sel_hi:[1,0]
	v_pk_mul_f32 v[6:7], v[6:7], v[24:25]
	v_cvt_pk_bf16_f32 v56, v6, v7
	v_lshlrev_b32_e32 v40, 16, v64
	v_and_b32_e32 v41, 0xffff0000, v64
	v_pk_mul_f32 v[40:41], v[40:41], v[254:255] op_sel_hi:[1,0]
	v_pk_mul_f32 v[40:41], v[40:41], v[24:25]
	v_cvt_pk_bf16_f32 v64, v40, v41
	v_lshlrev_b32_e32 v6, 16, v57
	v_and_b32_e32 v7, 0xffff0000, v57
	v_pk_mul_f32 v[6:7], v[6:7], v[252:253] op_sel_hi:[1,0]
	v_pk_mul_f32 v[6:7], v[6:7], v[26:27]
	v_cvt_pk_bf16_f32 v57, v6, v7
	v_lshlrev_b32_e32 v40, 16, v65
	v_and_b32_e32 v41, 0xffff0000, v65
	v_pk_mul_f32 v[40:41], v[40:41], v[254:255] op_sel_hi:[1,0]
	v_pk_mul_f32 v[40:41], v[40:41], v[26:27]
	v_cvt_pk_bf16_f32 v65, v40, v41
	v_lshlrev_b32_e32 v6, 16, v58
	v_and_b32_e32 v7, 0xffff0000, v58
	v_pk_mul_f32 v[6:7], v[6:7], v[252:253] op_sel_hi:[1,0]
	v_pk_mul_f32 v[6:7], v[6:7], v[28:29]
	v_cvt_pk_bf16_f32 v58, v6, v7
	v_lshlrev_b32_e32 v40, 16, v66
	v_and_b32_e32 v41, 0xffff0000, v66
	v_pk_mul_f32 v[40:41], v[40:41], v[254:255] op_sel_hi:[1,0]
	v_pk_mul_f32 v[40:41], v[40:41], v[28:29]
	v_cvt_pk_bf16_f32 v66, v40, v41
	v_lshlrev_b32_e32 v6, 16, v59
	v_and_b32_e32 v7, 0xffff0000, v59
	v_pk_mul_f32 v[6:7], v[6:7], v[252:253] op_sel_hi:[1,0]
	v_pk_mul_f32 v[6:7], v[6:7], v[30:31]
	v_cvt_pk_bf16_f32 v59, v6, v7
	v_lshlrev_b32_e32 v40, 16, v67
	v_and_b32_e32 v41, 0xffff0000, v67
	v_pk_mul_f32 v[40:41], v[40:41], v[254:255] op_sel_hi:[1,0]
	v_pk_mul_f32 v[40:41], v[40:41], v[30:31]
	v_cvt_pk_bf16_f32 v67, v40, v41
	global_store_dwordx4 v[4:5], v[52:55], off
	global_store_dwordx4 v[4:5], v[56:59], off offset:16
	global_store_dwordx4 v[4:5], v[60:63], off offset:2048
	global_store_dwordx4 v[4:5], v[64:67], off offset:2064
	v_lshl_add_u64 v[4:5], v[4:5], 0, s[100:101]
	s_nop 1
	s_nop 1
	ds_read_b128 v[44:47], v15
	ds_read_b128 v[48:51], v15 offset:8192
	ds_read_b128 v[52:55], v15 offset:16384
	ds_read_b128 v[56:59], v15 offset:24576
	ds_read_b128 v[60:63], v15 offset:32768
	ds_read_b128 v[64:67], v15 offset:40960
	s_mov_b64 s[80:81], 0x8000
	s_mov_b32 s1, 0x800000
	s_cmpk_eq_u32 s80, 0x8000
	s_waitcnt lgkmcnt(0)
	v_readlane_b32 s1, v249, 63
	s_barrier
	s_add_i32 s0, s1, s0
	s_cmpk_gt_i32 s0, 0xff
	s_cbranch_scc0 .LBB0_1865
	v_readlane_b32 s44, v249, 59
	v_readlane_b32 s89, v249, 63
	v_readlane_b32 s45, v249, 60
	v_readlane_b32 s46, v249, 61
	v_readlane_b32 s47, v249, 62

; DEVI unsigned pk2(float lo, float hi) { unsigned r; asm("v_cvt_pk_bf16_f32 %0, %1, %2" : "=v"(r) : "v"(lo), "v"(hi)); return r; }
; DEVI float bflo(unsigned w) { return __uint_as_float(w << 16); }
; DEVI float bfhi(unsigned w) { return __uint_as_float(w & 0xffff0000u); }
; DEVI void phase_m3(const Params& p, int l, unsigned char* smem) {
;     ...
;             const float* gain = p.in[21] + (size_t)l * DM;
;             for (int tt = 0; tt < 16; ++tt) {
;                 const int t = wave * 16 + tt;
;                 bf16_t* rowp = mix + (size_t)(row0 + t) * DM + lane * 16;
;                 const u32x4 a = *(const u32x4*)rowp, b = *(const u32x4*)(rowp + 8);
;                 float v[16] = {bflo(a.x), bfhi(a.x), bflo(a.y), bfhi(a.y), bflo(a.z), bfhi(a.z), bflo(a.w), bfhi(a.w), bflo(b.x), bfhi(b.x), bflo(b.y), bfhi(b.y), bflo(b.z), bfhi(b.z), bflo(b.w), bfhi(b.w)};
;                 float ss = 0.f;
; #pragma unroll
;                 for (int e = 0; e < 16; ++e) ss += v[e] * v[e];
;                 ss += __shfl_xor(ss, 1); ss += __shfl_xor(ss, 2); ss += __shfl_xor(ss, 4); ss += __shfl_xor(ss, 8);
;                 const float s16 = __shfl_xor(ss, 16);
;                 float rn;
;                 if (lane < 32) rn = rsqrtf((ss + s16) * (1.0f / 512.0f) + RMS_EPS); else rn = rsqrtf(ss * (1.0f / 256.0f) + RMS_EPS);
;                 const f32x4 g0 = *(const f32x4*)(gain + lane * 16), g1 = *(const f32x4*)(gain + lane * 16 + 4), g2 = *(const f32x4*)(gain + lane * 16 + 8), g3 = *(const f32x4*)(gain + lane * 16 + 12);
;                 u32x4 o1, o2;
;                 o1.x = pk2(v[0] * rn * g0[0], v[1] * rn * g0[1]); o1.y = pk2(v[2] * rn * g0[2], v[3] * rn * g0[3]); o1.z = pk2(v[4] * rn * g1[0], v[5] * rn * g1[1]); o1.w = pk2(v[6] * rn * g1[2], v[7] * rn * g1[3]);
;                 o2.x = pk2(v[8] * rn * g2[0], v[9] * rn * g2[1]); o2.y = pk2(v[10] * rn * g2[2], v[11] * rn * g2[3]); o2.z = pk2(v[12] * rn * g3[0], v[13] * rn * g3[1]); o2.w = pk2(v[14] * rn * g3[2], v[15] * rn * g3[3]);
;                 *(u32x4*)rowp = o1; *(u32x4*)(rowp + 8) = o2;
;             }
.LBB0_2560:
	v_lshlrev_b32_e32 v15, 4, v242
	ds_write_b128 v15, v[44:47]
	ds_write_b128 v15, v[48:51] offset:8192
	ds_write_b128 v15, v[52:55] offset:16384
	ds_write_b128 v15, v[56:59] offset:24576
	ds_write_b128 v15, v[60:63] offset:32768
	ds_write_b128 v15, v[64:67] offset:40960
	s_mov_b64 s[48:49], 0x16a00000
	s_mov_b64 s[100:101], 0x1000
	v_lshl_add_u64 v[2:3], v[0:1], 0, s[48:49]
	v_lshl_add_u64 v[4:5], v[0:1], 0, s[48:49]
	global_load_dwordx4 v[16:19], v[106:107], off
	global_load_dwordx4 v[20:23], v[106:107], off offset:16
	global_load_dwordx4 v[24:27], v[106:107], off offset:32
	global_load_dwordx4 v[28:31], v[106:107], off offset:48
	s_waitcnt lgkmcnt(0)
	global_load_dwordx4 v[32:35], v[2:3], off
	global_load_dwordx4 v[36:39], v[2:3], off offset:16
	global_load_dwordx4 v[44:47], v[2:3], off offset:2048
	global_load_dwordx4 v[48:51], v[2:3], off offset:2064
	v_lshl_add_u64 v[2:3], v[2:3], 0, s[100:101]
	global_load_dwordx4 v[52:55], v[2:3], off
	global_load_dwordx4 v[56:59], v[2:3], off offset:16
	global_load_dwordx4 v[60:63], v[2:3], off offset:2048
	global_load_dwordx4 v[64:67], v[2:3], off offset:2064
	v_lshl_add_u64 v[2:3], v[2:3], 0, s[100:101]
	s_waitcnt vmcnt(4)
	v_lshlrev_b32_e32 v6, 16, v32
	v_and_b32_e32 v7, 0xffff0000, v32
	v_pk_mul_f32 v[8:9], v[6:7], v[6:7]
	v_lshlrev_b32_e32 v40, 16, v44
	v_and_b32_e32 v41, 0xffff0000, v44
	v_pk_mul_f32 v[250:251], v[40:41], v[40:41]
	v_lshlrev_b32_e32 v6, 16, v33
	v_and_b32_e32 v7, 0xffff0000, v33
	v_pk_fma_f32 v[8:9], v[6:7], v[6:7], v[8:9]
	v_lshlrev_b32_e32 v40, 16, v45
	v_and_b32_e32 v41, 0xffff0000, v45
	v_pk_fma_f32 v[250:251], v[40:41], v[40:41], v[250:251]
	v_lshlrev_b32_e32 v6, 16, v34
	v_and_b32_e32 v7, 0xffff0000, v34
	v_pk_fma_f32 v[8:9], v[6:7], v[6:7], v[8:9]
	v_lshlrev_b32_e32 v40, 16, v46
	v_and_b32_e32 v41, 0xffff0000, v46
	v_pk_fma_f32 v[250:251], v[40:41], v[40:41], v[250:251]
	v_lshlrev_b32_e32 v6, 16, v35
	v_and_b32_e32 v7, 0xffff0000, v35
	v_pk_fma_f32 v[8:9], v[6:7], v[6:7], v[8:9]
	v_lshlrev_b32_e32 v40, 16, v47
	v_and_b32_e32 v41, 0xffff0000, v47
	v_pk_fma_f32 v[250:251], v[40:41], v[40:41], v[250:251]
	v_lshlrev_b32_e32 v6, 16, v36
	v_and_b32_e32 v7, 0xffff0000, v36
	v_pk_fma_f32 v[8:9], v[6:7], v[6:7], v[8:9]
	v_lshlrev_b32_e32 v40, 16, v48
	v_and_b32_e32 v41, 0xffff0000, v48
	v_pk_fma_f32 v[250:251], v[40:41], v[40:41], v[250:251]
	v_lshlrev_b32_e32 v6, 16, v37
	v_and_b32_e32 v7, 0xffff0000, v37
	v_pk_fma_f32 v[8:9], v[6:7], v[6:7], v[8:9]
	v_lshlrev_b32_e32 v40, 16, v49
	v_and_b32_e32 v41, 0xffff0000, v49
	v_pk_fma_f32 v[250:251], v[40:41], v[40:41], v[250:251]
	v_lshlrev_b32_e32 v6, 16, v38
	v_and_b32_e32 v7, 0xffff0000, v38
	v_pk_fma_f32 v[8:9], v[6:7], v[6:7], v[8:9]
	v_lshlrev_b32_e32 v40, 16, v50
	v_and_b32_e32 v41, 0xffff0000, v50
	v_pk_fma_f32 v[250:251], v[40:41], v[40:41], v[250:251]
	v_lshlrev_b32_e32 v6, 16, v39
	v_and_b32_e32 v7, 0xffff0000, v39
	v_pk_fma_f32 v[8:9], v[6:7], v[6:7], v[8:9]
	v_lshlrev_b32_e32 v40, 16, v51
	v_and_b32_e32 v41, 0xffff0000, v51
	v_pk_fma_f32 v[250:251], v[40:41], v[40:41], v[250:251]
	v_add_f32_e32 v8, v8, v9
	v_add_f32_e32 v250, v250, v251
	s_nop 1
	v_add_f32_dpp v8, v8, v8 quad_perm:[1,0,3,2] row_mask:0xf bank_mask:0xf
	v_add_f32_dpp v250, v250, v250 quad_perm:[1,0,3,2] row_mask:0xf bank_mask:0xf
	s_nop 1
	v_add_f32_dpp v8, v8, v8 quad_perm:[2,3,0,1] row_mask:0xf bank_mask:0xf
	v_add_f32_dpp v250, v250, v250 quad_perm:[2,3,0,1] row_mask:0xf bank_mask:0xf
	s_nop 1
	v_add_f32_dpp v8, v8, v8 row_half_mirror row_mask:0xf bank_mask:0xf
	v_add_f32_dpp v250, v250, v250 row_half_mirror row_mask:0xf bank_mask:0xf
	s_nop 1
	v_add_f32_dpp v8, v8, v8 row_mirror row_mask:0xf bank_mask:0xf
	v_add_f32_dpp v250, v250, v250 row_mirror row_mask:0xf bank_mask:0xf
	s_nop 1
	ds_bpermute_b32 v6, v14, v8
	ds_bpermute_b32 v40, v14, v250
	s_waitcnt lgkmcnt(0)
	v_add_f32_e32 v6, v8, v6
	v_mul_f32_e32 v6, 0x3b000000, v6
	v_mul_f32_e32 v8, 0x3b800000, v8
	v_cndmask_b32_e64 v8, v8, v6, s[6:7]
	v_add_f32_e32 v8, 0x358637bd, v8
	v_rsq_f32_e32 v252, v8
	v_add_f32_e32 v40, v250, v40
	v_mul_f32_e32 v40, 0x3b000000, v40
	v_mul_f32_e32 v250, 0x3b800000, v250
	v_cndmask_b32_e64 v250, v250, v40, s[6:7]
	v_add_f32_e32 v250, 0x358637bd, v250
	v_rsq_f32_e32 v254, v250
	s_nop 1
	v_lshlrev_b32_e32 v6, 16, v32
	v_and_b32_e32 v7, 0xffff0000, v32
	v_pk_mul_f32 v[6:7], v[6:7], v[252:253] op_sel_hi:[1,0]
	v_pk_mul_f32 v[6:7], v[6:7], v[16:17]
	v_cvt_pk_bf16_f32 v32, v6, v7
	v_lshlrev_b32_e32 v40, 16, v44
	v_and_b32_e32 v41, 0xffff0000, v44
	v_pk_mul_f32 v[40:41], v[40:41], v[254:255] op_sel_hi:[1,0]
	v_pk_mul_f32 v[40:41], v[40:41], v[16:17]
	v_cvt_pk_bf16_f32 v44, v40, v41
	v_lshlrev_b32_e32 v6, 16, v33
	v_and_b32_e32 v7, 0xffff0000, v33
	v_pk_mul_f32 v[6:7], v[6:7], v[252:253] op_sel_hi:[1,0]
	v_pk_mul_f32 v[6:7], v[6:7], v[18:19]
	v_cvt_pk_bf16_f32 v33, v6, v7
	v_lshlrev_b32_e32 v40, 16, v45
	v_and_b32_e32 v41, 0xffff0000, v45
	v_pk_mul_f32 v[40:41], v[40:41], v[254:255] op_sel_hi:[1,0]
	v_pk_mul_f32 v[40:41], v[40:41], v[18:19]
	v_cvt_pk_bf16_f32 v45, v40, v41
	v_lshlrev_b32_e32 v6, 16, v34
	v_and_b32_e32 v7, 0xffff0000, v34
	v_pk_mul_f32 v[6:7], v[6:7], v[252:253] op_sel_hi:[1,0]
	v_pk_mul_f32 v[6:7], v[6:7], v[20:21]
	v_cvt_pk_bf16_f32 v34, v6, v7
	v_lshlrev_b32_e32 v40, 16, v46
	v_and_b32_e32 v41, 0xffff0000, v46
	v_pk_mul_f32 v[40:41], v[40:41], v[254:255] op_sel_hi:[1,0]
	v_pk_mul_f32 v[40:41], v[40:41], v[20:21]
	v_cvt_pk_bf16_f32 v46, v40, v41
	v_lshlrev_b32_e32 v6, 16, v35
	v_and_b32_e32 v7, 0xffff0000, v35
	v_pk_mul_f32 v[6:7], v[6:7], v[252:253] op_sel_hi:[1,0]
	v_pk_mul_f32 v[6:7], v[6:7], v[22:23]
	v_cvt_pk_bf16_f32 v35, v6, v7
; DEVI unsigned pk2(float lo, float hi) { unsigned r; asm("v_cvt_pk_bf16_f32 %0, %1, %2" : "=v"(r) : "v"(lo), "v"(hi)); return r; }
; DEVI float bflo(unsigned w) { return __uint_as_float(w << 16); }
; DEVI float bfhi(unsigned w) { return __uint_as_float(w & 0xffff0000u); }
; DEVI void phase_m3(const Params& p, int l, unsigned char* smem) {
;     ...
;             for (int tt = 0; tt < 16; ++tt) {
;                 const int t = wave * 16 + tt;
;                 bf16_t* rowp = mix + (size_t)(row0 + t) * DM + lane * 16;
;                 const u32x4 a = *(const u32x4*)rowp, b = *(const u32x4*)(rowp + 8);
;                 float v[16] = {bflo(a.x), bfhi(a.x), bflo(a.y), bfhi(a.y), bflo(a.z), bfhi(a.z), bflo(a.w), bfhi(a.w), bflo(b.x), bfhi(b.x), bflo(b.y), bfhi(b.y), bflo(b.z), bfhi(b.z), bflo(b.w), bfhi(b.w)};
;                 float ss = 0.f;
; #pragma unroll
;                 for (int e = 0; e < 16; ++e) ss += v[e] * v[e];
;                 ss += __shfl_xor(ss, 1); ss += __shfl_xor(ss, 2); ss += __shfl_xor(ss, 4); ss += __shfl_xor(ss, 8);
;                 const float s16 = __shfl_xor(ss, 16);
;                 float rn;
;                 if (lane < 32) rn = rsqrtf((ss + s16) * (1.0f / 512.0f) + RMS_EPS); else rn = rsqrtf(ss * (1.0f / 256.0f) + RMS_EPS);
;                 const f32x4 g0 = *(const f32x4*)(gain + lane * 16), g1 = *(const f32x4*)(gain + lane * 16 + 4), g2 = *(const f32x4*)(gain + lane * 16 + 8), g3 = *(const f32x4*)(gain + lane * 16 + 12);
;                 u32x4 o1, o2;
;                 o1.x = pk2(v[0] * rn * g0[0], v[1] * rn * g0[1]); o1.y = pk2(v[2] * rn * g0[2], v[3] * rn * g0[3]); o1.z = pk2(v[4] * rn * g1[0], v[5] * rn * g1[1]); o1.w = pk2(v[6] * rn * g1[2], v[7] * rn * g1[3]);
;                 o2.x = pk2(v[8] * rn * g2[0], v[9] * rn * g2[1]); o2.y = pk2(v[10] * rn * g2[2], v[11] * rn * g2[3]); o2.z = pk2(v[12] * rn * g3[0], v[13] * rn * g3[1]); o2.w = pk2(v[14] * rn * g3[2], v[15] * rn * g3[3]);
;                 *(u32x4*)rowp = o1; *(u32x4*)(rowp + 8) = o2;
;             }
	v_lshlrev_b32_e32 v40, 16, v47
	v_and_b32_e32 v41, 0xffff0000, v47
	v_pk_mul_f32 v[40:41], v[40:41], v[254:255] op_sel_hi:[1,0]
	v_pk_mul_f32 v[40:41], v[40:41], v[22:23]
	v_cvt_pk_bf16_f32 v47, v40, v41
	v_lshlrev_b32_e32 v6, 16, v36
	v_and_b32_e32 v7, 0xffff0000, v36
	v_pk_mul_f32 v[6:7], v[6:7], v[252:253] op_sel_hi:[1,0]
	v_pk_mul_f32 v[6:7], v[6:7], v[24:25]
	v_cvt_pk_bf16_f32 v36, v6, v7
	v_lshlrev_b32_e32 v40, 16, v48
	v_and_b32_e32 v41, 0xffff0000, v48
	v_pk_mul_f32 v[40:41], v[40:41], v[254:255] op_sel_hi:[1,0]
	v_pk_mul_f32 v[40:41], v[40:41], v[24:25]
	v_cvt_pk_bf16_f32 v48, v40, v41
	v_lshlrev_b32_e32 v6, 16, v37
	v_and_b32_e32 v7, 0xffff0000, v37
	v_pk_mul_f32 v[6:7], v[6:7], v[252:253] op_sel_hi:[1,0]
	v_pk_mul_f32 v[6:7], v[6:7], v[26:27]
	v_cvt_pk_bf16_f32 v37, v6, v7
	v_lshlrev_b32_e32 v40, 16, v49
	v_and_b32_e32 v41, 0xffff0000, v49
	v_pk_mul_f32 v[40:41], v[40:41], v[254:255] op_sel_hi:[1,0]
	v_pk_mul_f32 v[40:41], v[40:41], v[26:27]
	v_cvt_pk_bf16_f32 v49, v40, v41
	v_lshlrev_b32_e32 v6, 16, v38
	v_and_b32_e32 v7, 0xffff0000, v38
	v_pk_mul_f32 v[6:7], v[6:7], v[252:253] op_sel_hi:[1,0]
	v_pk_mul_f32 v[6:7], v[6:7], v[28:29]
	v_cvt_pk_bf16_f32 v38, v6, v7
	v_lshlrev_b32_e32 v40, 16, v50
	v_and_b32_e32 v41, 0xffff0000, v50
	v_pk_mul_f32 v[40:41], v[40:41], v[254:255] op_sel_hi:[1,0]
	v_pk_mul_f32 v[40:41], v[40:41], v[28:29]
	v_cvt_pk_bf16_f32 v50, v40, v41
	v_lshlrev_b32_e32 v6, 16, v39
	v_and_b32_e32 v7, 0xffff0000, v39
	v_pk_mul_f32 v[6:7], v[6:7], v[252:253] op_sel_hi:[1,0]
	v_pk_mul_f32 v[6:7], v[6:7], v[30:31]
	v_cvt_pk_bf16_f32 v39, v6, v7
	v_lshlrev_b32_e32 v40, 16, v51
	v_and_b32_e32 v41, 0xffff0000, v51
	v_pk_mul_f32 v[40:41], v[40:41], v[254:255] op_sel_hi:[1,0]
	v_pk_mul_f32 v[40:41], v[40:41], v[30:31]
	v_cvt_pk_bf16_f32 v51, v40, v41
	global_store_dwordx4 v[4:5], v[32:35], off
	global_store_dwordx4 v[4:5], v[36:39], off offset:16
	global_store_dwordx4 v[4:5], v[44:47], off offset:2048
	global_store_dwordx4 v[4:5], v[48:51], off offset:2064
	v_lshl_add_u64 v[4:5], v[4:5], 0, s[100:101]
	s_nop 1
	global_load_dwordx4 v[32:35], v[2:3], off
	global_load_dwordx4 v[36:39], v[2:3], off offset:16
	global_load_dwordx4 v[44:47], v[2:3], off offset:2048
	global_load_dwordx4 v[48:51], v[2:3], off offset:2064
	v_lshl_add_u64 v[2:3], v[2:3], 0, s[100:101]
	s_waitcnt vmcnt(8)
	v_lshlrev_b32_e32 v6, 16, v52
	v_and_b32_e32 v7, 0xffff0000, v52
	v_pk_mul_f32 v[8:9], v[6:7], v[6:7]
	v_lshlrev_b32_e32 v40, 16, v60
	v_and_b32_e32 v41, 0xffff0000, v60
	v_pk_mul_f32 v[250:251], v[40:41], v[40:41]
	v_lshlrev_b32_e32 v6, 16, v53
	v_and_b32_e32 v7, 0xffff0000, v53
	v_pk_fma_f32 v[8:9], v[6:7], v[6:7], v[8:9]
	v_lshlrev_b32_e32 v40, 16, v61
	v_and_b32_e32 v41, 0xffff0000, v61
	v_pk_fma_f32 v[250:251], v[40:41], v[40:41], v[250:251]
	v_lshlrev_b32_e32 v6, 16, v54
	v_and_b32_e32 v7, 0xffff0000, v54
	v_pk_fma_f32 v[8:9], v[6:7], v[6:7], v[8:9]
	v_lshlrev_b32_e32 v40, 16, v62
	v_and_b32_e32 v41, 0xffff0000, v62
	v_pk_fma_f32 v[250:251], v[40:41], v[40:41], v[250:251]
	v_lshlrev_b32_e32 v6, 16, v55
	v_and_b32_e32 v7, 0xffff0000, v55
	v_pk_fma_f32 v[8:9], v[6:7], v[6:7], v[8:9]
	v_lshlrev_b32_e32 v40, 16, v63
	v_and_b32_e32 v41, 0xffff0000, v63
	v_pk_fma_f32 v[250:251], v[40:41], v[40:41], v[250:251]
	v_lshlrev_b32_e32 v6, 16, v56
	v_and_b32_e32 v7, 0xffff0000, v56
	v_pk_fma_f32 v[8:9], v[6:7], v[6:7], v[8:9]
	v_lshlrev_b32_e32 v40, 16, v64
	v_and_b32_e32 v41, 0xffff0000, v64
	v_pk_fma_f32 v[250:251], v[40:41], v[40:41], v[250:251]
	v_lshlrev_b32_e32 v6, 16, v57
	v_and_b32_e32 v7, 0xffff0000, v57
	v_pk_fma_f32 v[8:9], v[6:7], v[6:7], v[8:9]
	v_lshlrev_b32_e32 v40, 16, v65
	v_and_b32_e32 v41, 0xffff0000, v65
	v_pk_fma_f32 v[250:251], v[40:41], v[40:41], v[250:251]
	v_lshlrev_b32_e32 v6, 16, v58
	v_and_b32_e32 v7, 0xffff0000, v58
	v_pk_fma_f32 v[8:9], v[6:7], v[6:7], v[8:9]
	v_lshlrev_b32_e32 v40, 16, v66
	v_and_b32_e32 v41, 0xffff0000, v66
	v_pk_fma_f32 v[250:251], v[40:41], v[40:41], v[250:251]
	v_lshlrev_b32_e32 v6, 16, v59
	v_and_b32_e32 v7, 0xffff0000, v59
	v_pk_fma_f32 v[8:9], v[6:7], v[6:7], v[8:9]
	v_lshlrev_b32_e32 v40, 16, v67
	v_and_b32_e32 v41, 0xffff0000, v67
	v_pk_fma_f32 v[250:251], v[40:41], v[40:41], v[250:251]
	v_add_f32_e32 v8, v8, v9
	v_add_f32_e32 v250, v250, v251
	s_nop 1
	v_add_f32_dpp v8, v8, v8 quad_perm:[1,0,3,2] row_mask:0xf bank_mask:0xf
	v_add_f32_dpp v250, v250, v250 quad_perm:[1,0,3,2] row_mask:0xf bank_mask:0xf
	s_nop 1
	v_add_f32_dpp v8, v8, v8 quad_perm:[2,3,0,1] row_mask:0xf bank_mask:0xf
	v_add_f32_dpp v250, v250, v250 quad_perm:[2,3,0,1] row_mask:0xf bank_mask:0xf
	s_nop 1
	v_add_f32_dpp v8, v8, v8 row_half_mirror row_mask:0xf bank_mask:0xf
	v_add_f32_dpp v250, v250, v250 row_half_mirror row_mask:0xf bank_mask:0xf
	s_nop 1
	v_add_f32_dpp v8, v8, v8 row_mirror row_mask:0xf bank_mask:0xf
	v_add_f32_dpp v250, v250, v250 row_mirror row_mask:0xf bank_mask:0xf
	s_nop 1
	ds_bpermute_b32 v6, v14, v8
	ds_bpermute_b32 v40, v14, v250
	s_waitcnt lgkmcnt(0)
; DEVI unsigned pk2(float lo, float hi) { unsigned r; asm("v_cvt_pk_bf16_f32 %0, %1, %2" : "=v"(r) : "v"(lo), "v"(hi)); return r; }
; DEVI float bflo(unsigned w) { return __uint_as_float(w << 16); }
; DEVI float bfhi(unsigned w) { return __uint_as_float(w & 0xffff0000u); }
; DEVI void phase_m3(const Params& p, int l, unsigned char* smem) {
;     ...
;             for (int tt = 0; tt < 16; ++tt) {
;                 const int t = wave * 16 + tt;
;                 bf16_t* rowp = mix + (size_t)(row0 + t) * DM + lane * 16;
;                 const u32x4 a = *(const u32x4*)rowp, b = *(const u32x4*)(rowp + 8);
;                 float v[16] = {bflo(a.x), bfhi(a.x), bflo(a.y), bfhi(a.y), bflo(a.z), bfhi(a.z), bflo(a.w), bfhi(a.w), bflo(b.x), bfhi(b.x), bflo(b.y), bfhi(b.y), bflo(b.z), bfhi(b.z), bflo(b.w), bfhi(b.w)};
;                 float ss = 0.f;
; #pragma unroll
;                 for (int e = 0; e < 16; ++e) ss += v[e] * v[e];
;                 ss += __shfl_xor(ss, 1); ss += __shfl_xor(ss, 2); ss += __shfl_xor(ss, 4); ss += __shfl_xor(ss, 8);
;                 const float s16 = __shfl_xor(ss, 16);
;                 float rn;
;                 if (lane < 32) rn = rsqrtf((ss + s16) * (1.0f / 512.0f) + RMS_EPS); else rn = rsqrtf(ss * (1.0f / 256.0f) + RMS_EPS);
;                 const f32x4 g0 = *(const f32x4*)(gain + lane * 16), g1 = *(const f32x4*)(gain + lane * 16 + 4), g2 = *(const f32x4*)(gain + lane * 16 + 8), g3 = *(const f32x4*)(gain + lane * 16 + 12);
;                 u32x4 o1, o2;
;                 o1.x = pk2(v[0] * rn * g0[0], v[1] * rn * g0[1]); o1.y = pk2(v[2] * rn * g0[2], v[3] * rn * g0[3]); o1.z = pk2(v[4] * rn * g1[0], v[5] * rn * g1[1]); o1.w = pk2(v[6] * rn * g1[2], v[7] * rn * g1[3]);
;                 o2.x = pk2(v[8] * rn * g2[0], v[9] * rn * g2[1]); o2.y = pk2(v[10] * rn * g2[2], v[11] * rn * g2[3]); o2.z = pk2(v[12] * rn * g3[0], v[13] * rn * g3[1]); o2.w = pk2(v[14] * rn * g3[2], v[15] * rn * g3[3]);
;                 *(u32x4*)rowp = o1; *(u32x4*)(rowp + 8) = o2;
;             }
	v_add_f32_e32 v6, v8, v6
	v_mul_f32_e32 v6, 0x3b000000, v6
	v_mul_f32_e32 v8, 0x3b800000, v8
	v_cndmask_b32_e64 v8, v8, v6, s[6:7]
	v_add_f32_e32 v8, 0x358637bd, v8
	v_rsq_f32_e32 v252, v8
	v_add_f32_e32 v40, v250, v40
	v_mul_f32_e32 v40, 0x3b000000, v40
	v_mul_f32_e32 v250, 0x3b800000, v250
	v_cndmask_b32_e64 v250, v250, v40, s[6:7]
	v_add_f32_e32 v250, 0x358637bd, v250
	v_rsq_f32_e32 v254, v250
	s_nop 1
	v_lshlrev_b32_e32 v6, 16, v52
	v_and_b32_e32 v7, 0xffff0000, v52
	v_pk_mul_f32 v[6:7], v[6:7], v[252:253] op_sel_hi:[1,0]
	v_pk_mul_f32 v[6:7], v[6:7], v[16:17]
	v_cvt_pk_bf16_f32 v52, v6, v7
	v_lshlrev_b32_e32 v40, 16, v60
	v_and_b32_e32 v41, 0xffff0000, v60
	v_pk_mul_f32 v[40:41], v[40:41], v[254:255] op_sel_hi:[1,0]
	v_pk_mul_f32 v[40:41], v[40:41], v[16:17]
	v_cvt_pk_bf16_f32 v60, v40, v41
	v_lshlrev_b32_e32 v6, 16, v53
	v_and_b32_e32 v7, 0xffff0000, v53
	v_pk_mul_f32 v[6:7], v[6:7], v[252:253] op_sel_hi:[1,0]
	v_pk_mul_f32 v[6:7], v[6:7], v[18:19]
	v_cvt_pk_bf16_f32 v53, v6, v7
	v_lshlrev_b32_e32 v40, 16, v61
	v_and_b32_e32 v41, 0xffff0000, v61
	v_pk_mul_f32 v[40:41], v[40:41], v[254:255] op_sel_hi:[1,0]
	v_pk_mul_f32 v[40:41], v[40:41], v[18:19]
	v_cvt_pk_bf16_f32 v61, v40, v41
	v_lshlrev_b32_e32 v6, 16, v54
	v_and_b32_e32 v7, 0xffff0000, v54
	v_pk_mul_f32 v[6:7], v[6:7], v[252:253] op_sel_hi:[1,0]
	v_pk_mul_f32 v[6:7], v[6:7], v[20:21]
	v_cvt_pk_bf16_f32 v54, v6, v7
	v_lshlrev_b32_e32 v40, 16, v62
	v_and_b32_e32 v41, 0xffff0000, v62
	v_pk_mul_f32 v[40:41], v[40:41], v[254:255] op_sel_hi:[1,0]
	v_pk_mul_f32 v[40:41], v[40:41], v[20:21]
	v_cvt_pk_bf16_f32 v62, v40, v41
	v_lshlrev_b32_e32 v6, 16, v55
	v_and_b32_e32 v7, 0xffff0000, v55
	v_pk_mul_f32 v[6:7], v[6:7], v[252:253] op_sel_hi:[1,0]
	v_pk_mul_f32 v[6:7], v[6:7], v[22:23]
	v_cvt_pk_bf16_f32 v55, v6, v7
	v_lshlrev_b32_e32 v40, 16, v63
	v_and_b32_e32 v41, 0xffff0000, v63
	v_pk_mul_f32 v[40:41], v[40:41], v[254:255] op_sel_hi:[1,0]
	v_pk_mul_f32 v[40:41], v[40:41], v[22:23]
	v_cvt_pk_bf16_f32 v63, v40, v41
	v_lshlrev_b32_e32 v6, 16, v56
	v_and_b32_e32 v7, 0xffff0000, v56
	v_pk_mul_f32 v[6:7], v[6:7], v[252:253] op_sel_hi:[1,0]
	v_pk_mul_f32 v[6:7], v[6:7], v[24:25]
	v_cvt_pk_bf16_f32 v56, v6, v7
	v_lshlrev_b32_e32 v40, 16, v64
	v_and_b32_e32 v41, 0xffff0000, v64
	v_pk_mul_f32 v[40:41], v[40:41], v[254:255] op_sel_hi:[1,0]
	v_pk_mul_f32 v[40:41], v[40:41], v[24:25]
	v_cvt_pk_bf16_f32 v64, v40, v41
	v_lshlrev_b32_e32 v6, 16, v57
	v_and_b32_e32 v7, 0xffff0000, v57
	v_pk_mul_f32 v[6:7], v[6:7], v[252:253] op_sel_hi:[1,0]
	v_pk_mul_f32 v[6:7], v[6:7], v[26:27]
	v_cvt_pk_bf16_f32 v57, v6, v7
	v_lshlrev_b32_e32 v40, 16, v65
	v_and_b32_e32 v41, 0xffff0000, v65
	v_pk_mul_f32 v[40:41], v[40:41], v[254:255] op_sel_hi:[1,0]
	v_pk_mul_f32 v[40:41], v[40:41], v[26:27]
	v_cvt_pk_bf16_f32 v65, v40, v41
	v_lshlrev_b32_e32 v6, 16, v58
	v_and_b32_e32 v7, 0xffff0000, v58
	v_pk_mul_f32 v[6:7], v[6:7], v[252:253] op_sel_hi:[1,0]
	v_pk_mul_f32 v[6:7], v[6:7], v[28:29]
	v_cvt_pk_bf16_f32 v58, v6, v7
	v_lshlrev_b32_e32 v40, 16, v66
	v_and_b32_e32 v41, 0xffff0000, v66
	v_pk_mul_f32 v[40:41], v[40:41], v[254:255] op_sel_hi:[1,0]
	v_pk_mul_f32 v[40:41], v[40:41], v[28:29]
	v_cvt_pk_bf16_f32 v66, v40, v41
	v_lshlrev_b32_e32 v6, 16, v59
	v_and_b32_e32 v7, 0xffff0000, v59
	v_pk_mul_f32 v[6:7], v[6:7], v[252:253] op_sel_hi:[1,0]
	v_pk_mul_f32 v[6:7], v[6:7], v[30:31]
	v_cvt_pk_bf16_f32 v59, v6, v7
	v_lshlrev_b32_e32 v40, 16, v67
	v_and_b32_e32 v41, 0xffff0000, v67
	v_pk_mul_f32 v[40:41], v[40:41], v[254:255] op_sel_hi:[1,0]
	v_pk_mul_f32 v[40:41], v[40:41], v[30:31]
	v_cvt_pk_bf16_f32 v67, v40, v41
	global_store_dwordx4 v[4:5], v[52:55], off
	global_store_dwordx4 v[4:5], v[56:59], off offset:16
	global_store_dwordx4 v[4:5], v[60:63], off offset:2048
	global_store_dwordx4 v[4:5], v[64:67], off offset:2064
	v_lshl_add_u64 v[4:5], v[4:5], 0, s[100:101]
	s_nop 1
	global_load_dwordx4 v[52:55], v[2:3], off
	global_load_dwordx4 v[56:59], v[2:3], off offset:16
	global_load_dwordx4 v[60:63], v[2:3], off offset:2048
	global_load_dwordx4 v[64:67], v[2:3], off offset:2064
	v_lshl_add_u64 v[2:3], v[2:3], 0, s[100:101]
	s_waitcnt vmcnt(8)
	v_lshlrev_b32_e32 v6, 16, v32
	v_and_b32_e32 v7, 0xffff0000, v32
	v_pk_mul_f32 v[8:9], v[6:7], v[6:7]
	v_lshlrev_b32_e32 v40, 16, v44
	v_and_b32_e32 v41, 0xffff0000, v44
	v_pk_mul_f32 v[250:251], v[40:41], v[40:41]
	v_lshlrev_b32_e32 v6, 16, v33
	v_and_b32_e32 v7, 0xffff0000, v33
	v_pk_fma_f32 v[8:9], v[6:7], v[6:7], v[8:9]
	v_lshlrev_b32_e32 v40, 16, v45
	v_and_b32_e32 v41, 0xffff0000, v45
	v_pk_fma_f32 v[250:251], v[40:41], v[40:41], v[250:251]
	v_lshlrev_b32_e32 v6, 16, v34
	v_and_b32_e32 v7, 0xffff0000, v34
	v_pk_fma_f32 v[8:9], v[6:7], v[6:7], v[8:9]
	v_lshlrev_b32_e32 v40, 16, v46
	v_and_b32_e32 v41, 0xffff0000, v46
	v_pk_fma_f32 v[250:251], v[40:41], v[40:41], v[250:251]
	v_lshlrev_b32_e32 v6, 16, v35
	v_and_b32_e32 v7, 0xffff0000, v35
	v_pk_fma_f32 v[8:9], v[6:7], v[6:7], v[8:9]
	v_lshlrev_b32_e32 v40, 16, v47
	v_and_b32_e32 v41, 0xffff0000, v47
	v_pk_fma_f32 v[250:251], v[40:41], v[40:41], v[250:251]
	v_lshlrev_b32_e32 v6, 16, v36
	v_and_b32_e32 v7, 0xffff0000, v36
	v_pk_fma_f32 v[8:9], v[6:7], v[6:7], v[8:9]
	v_lshlrev_b32_e32 v40, 16, v48
	v_and_b32_e32 v41, 0xffff0000, v48
	v_pk_fma_f32 v[250:251], v[40:41], v[40:41], v[250:251]
	v_lshlrev_b32_e32 v6, 16, v37
	v_and_b32_e32 v7, 0xffff0000, v37
	v_pk_fma_f32 v[8:9], v[6:7], v[6:7], v[8:9]
	v_lshlrev_b32_e32 v40, 16, v49
	v_and_b32_e32 v41, 0xffff0000, v49
	v_pk_fma_f32 v[250:251], v[40:41], v[40:41], v[250:251]
	v_lshlrev_b32_e32 v6, 16, v38
	v_and_b32_e32 v7, 0xffff0000, v38
	v_pk_fma_f32 v[8:9], v[6:7], v[6:7], v[8:9]
	v_lshlrev_b32_e32 v40, 16, v50
	v_and_b32_e32 v41, 0xffff0000, v50
	v_pk_fma_f32 v[250:251], v[40:41], v[40:41], v[250:251]
	v_lshlrev_b32_e32 v6, 16, v39
	v_and_b32_e32 v7, 0xffff0000, v39
	v_pk_fma_f32 v[8:9], v[6:7], v[6:7], v[8:9]
	v_lshlrev_b32_e32 v40, 16, v51
	v_and_b32_e32 v41, 0xffff0000, v51
	v_pk_fma_f32 v[250:251], v[40:41], v[40:41], v[250:251]
	v_add_f32_e32 v8, v8, v9
	v_add_f32_e32 v250, v250, v251
	s_nop 1
	v_add_f32_dpp v8, v8, v8 quad_perm:[1,0,3,2] row_mask:0xf bank_mask:0xf
	v_add_f32_dpp v250, v250, v250 quad_perm:[1,0,3,2] row_mask:0xf bank_mask:0xf
	s_nop 1
	v_add_f32_dpp v8, v8, v8 quad_perm:[2,3,0,1] row_mask:0xf bank_mask:0xf
	v_add_f32_dpp v250, v250, v250 quad_perm:[2,3,0,1] row_mask:0xf bank_mask:0xf
	s_nop 1
	v_add_f32_dpp v8, v8, v8 row_half_mirror row_mask:0xf bank_mask:0xf
	v_add_f32_dpp v250, v250, v250 row_half_mirror row_mask:0xf bank_mask:0xf
	s_nop 1
	v_add_f32_dpp v8, v8, v8 row_mirror row_mask:0xf bank_mask:0xf
	v_add_f32_dpp v250, v250, v250 row_mirror row_mask:0xf bank_mask:0xf
	s_nop 1
	ds_bpermute_b32 v6, v14, v8
	ds_bpermute_b32 v40, v14, v250
	s_waitcnt lgkmcnt(0)
; DEVI unsigned pk2(float lo, float hi) { unsigned r; asm("v_cvt_pk_bf16_f32 %0, %1, %2" : "=v"(r) : "v"(lo), "v"(hi)); return r; }
; DEVI float bflo(unsigned w) { return __uint_as_float(w << 16); }
; DEVI float bfhi(unsigned w) { return __uint_as_float(w & 0xffff0000u); }
; DEVI void phase_m3(const Params& p, int l, unsigned char* smem) {
;     ...
;             for (int tt = 0; tt < 16; ++tt) {
;                 const int t = wave * 16 + tt;
;                 bf16_t* rowp = mix + (size_t)(row0 + t) * DM + lane * 16;
;                 const u32x4 a = *(const u32x4*)rowp, b = *(const u32x4*)(rowp + 8);
;                 float v[16] = {bflo(a.x), bfhi(a.x), bflo(a.y), bfhi(a.y), bflo(a.z), bfhi(a.z), bflo(a.w), bfhi(a.w), bflo(b.x), bfhi(b.x), bflo(b.y), bfhi(b.y), bflo(b.z), bfhi(b.z), bflo(b.w), bfhi(b.w)};
;                 float ss = 0.f;
; #pragma unroll
;                 for (int e = 0; e < 16; ++e) ss += v[e] * v[e];
;                 ss += __shfl_xor(ss, 1); ss += __shfl_xor(ss, 2); ss += __shfl_xor(ss, 4); ss += __shfl_xor(ss, 8);
;                 const float s16 = __shfl_xor(ss, 16);
;                 float rn;
;                 if (lane < 32) rn = rsqrtf((ss + s16) * (1.0f / 512.0f) + RMS_EPS); else rn = rsqrtf(ss * (1.0f / 256.0f) + RMS_EPS);
;                 const f32x4 g0 = *(const f32x4*)(gain + lane * 16), g1 = *(const f32x4*)(gain + lane * 16 + 4), g2 = *(const f32x4*)(gain + lane * 16 + 8), g3 = *(const f32x4*)(gain + lane * 16 + 12);
;                 u32x4 o1, o2;
;                 o1.x = pk2(v[0] * rn * g0[0], v[1] * rn * g0[1]); o1.y = pk2(v[2] * rn * g0[2], v[3] * rn * g0[3]); o1.z = pk2(v[4] * rn * g1[0], v[5] * rn * g1[1]); o1.w = pk2(v[6] * rn * g1[2], v[7] * rn * g1[3]);
;                 o2.x = pk2(v[8] * rn * g2[0], v[9] * rn * g2[1]); o2.y = pk2(v[10] * rn * g2[2], v[11] * rn * g2[3]); o2.z = pk2(v[12] * rn * g3[0], v[13] * rn * g3[1]); o2.w = pk2(v[14] * rn * g3[2], v[15] * rn * g3[3]);
;                 *(u32x4*)rowp = o1; *(u32x4*)(rowp + 8) = o2;
;             }
	v_add_f32_e32 v6, v8, v6
	v_mul_f32_e32 v6, 0x3b000000, v6
	v_mul_f32_e32 v8, 0x3b800000, v8
	v_cndmask_b32_e64 v8, v8, v6, s[6:7]
	v_add_f32_e32 v8, 0x358637bd, v8
	v_rsq_f32_e32 v252, v8
	v_add_f32_e32 v40, v250, v40
	v_mul_f32_e32 v40, 0x3b000000, v40
	v_mul_f32_e32 v250, 0x3b800000, v250
	v_cndmask_b32_e64 v250, v250, v40, s[6:7]
	v_add_f32_e32 v250, 0x358637bd, v250
	v_rsq_f32_e32 v254, v250
	s_nop 1
	v_lshlrev_b32_e32 v6, 16, v32
	v_and_b32_e32 v7, 0xffff0000, v32
	v_pk_mul_f32 v[6:7], v[6:7], v[252:253] op_sel_hi:[1,0]
	v_pk_mul_f32 v[6:7], v[6:7], v[16:17]
	v_cvt_pk_bf16_f32 v32, v6, v7
	v_lshlrev_b32_e32 v40, 16, v44
	v_and_b32_e32 v41, 0xffff0000, v44
	v_pk_mul_f32 v[40:41], v[40:41], v[254:255] op_sel_hi:[1,0]
	v_pk_mul_f32 v[40:41], v[40:41], v[16:17]
	v_cvt_pk_bf16_f32 v44, v40, v41
	v_lshlrev_b32_e32 v6, 16, v33
	v_and_b32_e32 v7, 0xffff0000, v33
	v_pk_mul_f32 v[6:7], v[6:7], v[252:253] op_sel_hi:[1,0]
	v_pk_mul_f32 v[6:7], v[6:7], v[18:19]
	v_cvt_pk_bf16_f32 v33, v6, v7
	v_lshlrev_b32_e32 v40, 16, v45
	v_and_b32_e32 v41, 0xffff0000, v45
	v_pk_mul_f32 v[40:41], v[40:41], v[254:255] op_sel_hi:[1,0]
	v_pk_mul_f32 v[40:41], v[40:41], v[18:19]
	v_cvt_pk_bf16_f32 v45, v40, v41
	v_lshlrev_b32_e32 v6, 16, v34
	v_and_b32_e32 v7, 0xffff0000, v34
	v_pk_mul_f32 v[6:7], v[6:7], v[252:253] op_sel_hi:[1,0]
	v_pk_mul_f32 v[6:7], v[6:7], v[20:21]
	v_cvt_pk_bf16_f32 v34, v6, v7
	v_lshlrev_b32_e32 v40, 16, v46
	v_and_b32_e32 v41, 0xffff0000, v46
	v_pk_mul_f32 v[40:41], v[40:41], v[254:255] op_sel_hi:[1,0]
	v_pk_mul_f32 v[40:41], v[40:41], v[20:21]
	v_cvt_pk_bf16_f32 v46, v40, v41
	v_lshlrev_b32_e32 v6, 16, v35
	v_and_b32_e32 v7, 0xffff0000, v35
	v_pk_mul_f32 v[6:7], v[6:7], v[252:253] op_sel_hi:[1,0]
	v_pk_mul_f32 v[6:7], v[6:7], v[22:23]
	v_cvt_pk_bf16_f32 v35, v6, v7
	v_lshlrev_b32_e32 v40, 16, v47
	v_and_b32_e32 v41, 0xffff0000, v47
	v_pk_mul_f32 v[40:41], v[40:41], v[254:255] op_sel_hi:[1,0]
	v_pk_mul_f32 v[40:41], v[40:41], v[22:23]
	v_cvt_pk_bf16_f32 v47, v40, v41
	v_lshlrev_b32_e32 v6, 16, v36
	v_and_b32_e32 v7, 0xffff0000, v36
	v_pk_mul_f32 v[6:7], v[6:7], v[252:253] op_sel_hi:[1,0]
	v_pk_mul_f32 v[6:7], v[6:7], v[24:25]
	v_cvt_pk_bf16_f32 v36, v6, v7
	v_lshlrev_b32_e32 v40, 16, v48
	v_and_b32_e32 v41, 0xffff0000, v48
	v_pk_mul_f32 v[40:41], v[40:41], v[254:255] op_sel_hi:[1,0]
	v_pk_mul_f32 v[40:41], v[40:41], v[24:25]
	v_cvt_pk_bf16_f32 v48, v40, v41
	v_lshlrev_b32_e32 v6, 16, v37
	v_and_b32_e32 v7, 0xffff0000, v37
	v_pk_mul_f32 v[6:7], v[6:7], v[252:253] op_sel_hi:[1,0]
	v_pk_mul_f32 v[6:7], v[6:7], v[26:27]
	v_cvt_pk_bf16_f32 v37, v6, v7
	v_lshlrev_b32_e32 v40, 16, v49
	v_and_b32_e32 v41, 0xffff0000, v49
	v_pk_mul_f32 v[40:41], v[40:41], v[254:255] op_sel_hi:[1,0]
	v_pk_mul_f32 v[40:41], v[40:41], v[26:27]
	v_cvt_pk_bf16_f32 v49, v40, v41
	v_lshlrev_b32_e32 v6, 16, v38
	v_and_b32_e32 v7, 0xffff0000, v38
	v_pk_mul_f32 v[6:7], v[6:7], v[252:253] op_sel_hi:[1,0]
	v_pk_mul_f32 v[6:7], v[6:7], v[28:29]
	v_cvt_pk_bf16_f32 v38, v6, v7
	v_lshlrev_b32_e32 v40, 16, v50
	v_and_b32_e32 v41, 0xffff0000, v50
	v_pk_mul_f32 v[40:41], v[40:41], v[254:255] op_sel_hi:[1,0]
	v_pk_mul_f32 v[40:41], v[40:41], v[28:29]
	v_cvt_pk_bf16_f32 v50, v40, v41
	v_lshlrev_b32_e32 v6, 16, v39
	v_and_b32_e32 v7, 0xffff0000, v39
	v_pk_mul_f32 v[6:7], v[6:7], v[252:253] op_sel_hi:[1,0]
	v_pk_mul_f32 v[6:7], v[6:7], v[30:31]
	v_cvt_pk_bf16_f32 v39, v6, v7
	v_lshlrev_b32_e32 v40, 16, v51
	v_and_b32_e32 v41, 0xffff0000, v51
	v_pk_mul_f32 v[40:41], v[40:41], v[254:255] op_sel_hi:[1,0]
	v_pk_mul_f32 v[40:41], v[40:41], v[30:31]
	v_cvt_pk_bf16_f32 v51, v40, v41
	global_store_dwordx4 v[4:5], v[32:35], off
	global_store_dwordx4 v[4:5], v[36:39], off offset:16
	global_store_dwordx4 v[4:5], v[44:47], off offset:2048
	global_store_dwordx4 v[4:5], v[48:51], off offset:2064
	v_lshl_add_u64 v[4:5], v[4:5], 0, s[100:101]
	s_nop 1
	global_load_dwordx4 v[32:35], v[2:3], off
	global_load_dwordx4 v[36:39], v[2:3], off offset:16
	global_load_dwordx4 v[44:47], v[2:3], off offset:2048
	global_load_dwordx4 v[48:51], v[2:3], off offset:2064
	v_lshl_add_u64 v[2:3], v[2:3], 0, s[100:101]
	s_waitcnt vmcnt(8)
	v_lshlrev_b32_e32 v6, 16, v52
	v_and_b32_e32 v7, 0xffff0000, v52
	v_pk_mul_f32 v[8:9], v[6:7], v[6:7]
	v_lshlrev_b32_e32 v40, 16, v60
	v_and_b32_e32 v41, 0xffff0000, v60
	v_pk_mul_f32 v[250:251], v[40:41], v[40:41]
	v_lshlrev_b32_e32 v6, 16, v53
	v_and_b32_e32 v7, 0xffff0000, v53
	v_pk_fma_f32 v[8:9], v[6:7], v[6:7], v[8:9]
	v_lshlrev_b32_e32 v40, 16, v61
	v_and_b32_e32 v41, 0xffff0000, v61
	v_pk_fma_f32 v[250:251], v[40:41], v[40:41], v[250:251]
	v_lshlrev_b32_e32 v6, 16, v54
	v_and_b32_e32 v7, 0xffff0000, v54
	v_pk_fma_f32 v[8:9], v[6:7], v[6:7], v[8:9]
	v_lshlrev_b32_e32 v40, 16, v62
	v_and_b32_e32 v41, 0xffff0000, v62
	v_pk_fma_f32 v[250:251], v[40:41], v[40:41], v[250:251]
	v_lshlrev_b32_e32 v6, 16, v55
	v_and_b32_e32 v7, 0xffff0000, v55
	v_pk_fma_f32 v[8:9], v[6:7], v[6:7], v[8:9]
	v_lshlrev_b32_e32 v40, 16, v63
	v_and_b32_e32 v41, 0xffff0000, v63
	v_pk_fma_f32 v[250:251], v[40:41], v[40:41], v[250:251]
	v_lshlrev_b32_e32 v6, 16, v56
	v_and_b32_e32 v7, 0xffff0000, v56
	v_pk_fma_f32 v[8:9], v[6:7], v[6:7], v[8:9]
	v_lshlrev_b32_e32 v40, 16, v64
	v_and_b32_e32 v41, 0xffff0000, v64
	v_pk_fma_f32 v[250:251], v[40:41], v[40:41], v[250:251]
	v_lshlrev_b32_e32 v6, 16, v57
	v_and_b32_e32 v7, 0xffff0000, v57
	v_pk_fma_f32 v[8:9], v[6:7], v[6:7], v[8:9]
	v_lshlrev_b32_e32 v40, 16, v65
	v_and_b32_e32 v41, 0xffff0000, v65
	v_pk_fma_f32 v[250:251], v[40:41], v[40:41], v[250:251]
	v_lshlrev_b32_e32 v6, 16, v58
	v_and_b32_e32 v7, 0xffff0000, v58
	v_pk_fma_f32 v[8:9], v[6:7], v[6:7], v[8:9]
	v_lshlrev_b32_e32 v40, 16, v66
	v_and_b32_e32 v41, 0xffff0000, v66
	v_pk_fma_f32 v[250:251], v[40:41], v[40:41], v[250:251]
	v_lshlrev_b32_e32 v6, 16, v59
	v_and_b32_e32 v7, 0xffff0000, v59
	v_pk_fma_f32 v[8:9], v[6:7], v[6:7], v[8:9]
	v_lshlrev_b32_e32 v40, 16, v67
	v_and_b32_e32 v41, 0xffff0000, v67
	v_pk_fma_f32 v[250:251], v[40:41], v[40:41], v[250:251]
	v_add_f32_e32 v8, v8, v9
	v_add_f32_e32 v250, v250, v251
	s_nop 1
	v_add_f32_dpp v8, v8, v8 quad_perm:[1,0,3,2] row_mask:0xf bank_mask:0xf
	v_add_f32_dpp v250, v250, v250 quad_perm:[1,0,3,2] row_mask:0xf bank_mask:0xf
	s_nop 1
	v_add_f32_dpp v8, v8, v8 quad_perm:[2,3,0,1] row_mask:0xf bank_mask:0xf
	v_add_f32_dpp v250, v250, v250 quad_perm:[2,3,0,1] row_mask:0xf bank_mask:0xf
	s_nop 1
	v_add_f32_dpp v8, v8, v8 row_half_mirror row_mask:0xf bank_mask:0xf
	v_add_f32_dpp v250, v250, v250 row_half_mirror row_mask:0xf bank_mask:0xf
	s_nop 1
	v_add_f32_dpp v8, v8, v8 row_mirror row_mask:0xf bank_mask:0xf
	v_add_f32_dpp v250, v250, v250 row_mirror row_mask:0xf bank_mask:0xf
	s_nop 1
	ds_bpermute_b32 v6, v14, v8
	ds_bpermute_b32 v40, v14, v250
	s_waitcnt lgkmcnt(0)
; DEVI unsigned pk2(float lo, float hi) { unsigned r; asm("v_cvt_pk_bf16_f32 %0, %1, %2" : "=v"(r) : "v"(lo), "v"(hi)); return r; }
; DEVI float bflo(unsigned w) { return __uint_as_float(w << 16); }
; DEVI float bfhi(unsigned w) { return __uint_as_float(w & 0xffff0000u); }
; DEVI void phase_m3(const Params& p, int l, unsigned char* smem) {
;     ...
;             for (int tt = 0; tt < 16; ++tt) {
;                 const int t = wave * 16 + tt;
;                 bf16_t* rowp = mix + (size_t)(row0 + t) * DM + lane * 16;
;                 const u32x4 a = *(const u32x4*)rowp, b = *(const u32x4*)(rowp + 8);
;                 float v[16] = {bflo(a.x), bfhi(a.x), bflo(a.y), bfhi(a.y), bflo(a.z), bfhi(a.z), bflo(a.w), bfhi(a.w), bflo(b.x), bfhi(b.x), bflo(b.y), bfhi(b.y), bflo(b.z), bfhi(b.z), bflo(b.w), bfhi(b.w)};
;                 float ss = 0.f;
; #pragma unroll
;                 for (int e = 0; e < 16; ++e) ss += v[e] * v[e];
;                 ss += __shfl_xor(ss, 1); ss += __shfl_xor(ss, 2); ss += __shfl_xor(ss, 4); ss += __shfl_xor(ss, 8);
;                 const float s16 = __shfl_xor(ss, 16);
;                 float rn;
;                 if (lane < 32) rn = rsqrtf((ss + s16) * (1.0f / 512.0f) + RMS_EPS); else rn = rsqrtf(ss * (1.0f / 256.0f) + RMS_EPS);
;                 const f32x4 g0 = *(const f32x4*)(gain + lane * 16), g1 = *(const f32x4*)(gain + lane * 16 + 4), g2 = *(const f32x4*)(gain + lane * 16 + 8), g3 = *(const f32x4*)(gain + lane * 16 + 12);
;                 u32x4 o1, o2;
;                 o1.x = pk2(v[0] * rn * g0[0], v[1] * rn * g0[1]); o1.y = pk2(v[2] * rn * g0[2], v[3] * rn * g0[3]); o1.z = pk2(v[4] * rn * g1[0], v[5] * rn * g1[1]); o1.w = pk2(v[6] * rn * g1[2], v[7] * rn * g1[3]);
;                 o2.x = pk2(v[8] * rn * g2[0], v[9] * rn * g2[1]); o2.y = pk2(v[10] * rn * g2[2], v[11] * rn * g2[3]); o2.z = pk2(v[12] * rn * g3[0], v[13] * rn * g3[1]); o2.w = pk2(v[14] * rn * g3[2], v[15] * rn * g3[3]);
;                 *(u32x4*)rowp = o1; *(u32x4*)(rowp + 8) = o2;
;             }
	v_add_f32_e32 v6, v8, v6
	v_mul_f32_e32 v6, 0x3b000000, v6
	v_mul_f32_e32 v8, 0x3b800000, v8
	v_cndmask_b32_e64 v8, v8, v6, s[6:7]
	v_add_f32_e32 v8, 0x358637bd, v8
	v_rsq_f32_e32 v252, v8
	v_add_f32_e32 v40, v250, v40
	v_mul_f32_e32 v40, 0x3b000000, v40
	v_mul_f32_e32 v250, 0x3b800000, v250
	v_cndmask_b32_e64 v250, v250, v40, s[6:7]
	v_add_f32_e32 v250, 0x358637bd, v250
	v_rsq_f32_e32 v254, v250
	s_nop 1
	v_lshlrev_b32_e32 v6, 16, v52
	v_and_b32_e32 v7, 0xffff0000, v52
	v_pk_mul_f32 v[6:7], v[6:7], v[252:253] op_sel_hi:[1,0]
	v_pk_mul_f32 v[6:7], v[6:7], v[16:17]
	v_cvt_pk_bf16_f32 v52, v6, v7
	v_lshlrev_b32_e32 v40, 16, v60
	v_and_b32_e32 v41, 0xffff0000, v60
	v_pk_mul_f32 v[40:41], v[40:41], v[254:255] op_sel_hi:[1,0]
	v_pk_mul_f32 v[40:41], v[40:41], v[16:17]
	v_cvt_pk_bf16_f32 v60, v40, v41
	v_lshlrev_b32_e32 v6, 16, v53
	v_and_b32_e32 v7, 0xffff0000, v53
	v_pk_mul_f32 v[6:7], v[6:7], v[252:253] op_sel_hi:[1,0]
	v_pk_mul_f32 v[6:7], v[6:7], v[18:19]
	v_cvt_pk_bf16_f32 v53, v6, v7
	v_lshlrev_b32_e32 v40, 16, v61
	v_and_b32_e32 v41, 0xffff0000, v61
	v_pk_mul_f32 v[40:41], v[40:41], v[254:255] op_sel_hi:[1,0]
	v_pk_mul_f32 v[40:41], v[40:41], v[18:19]
	v_cvt_pk_bf16_f32 v61, v40, v41
	v_lshlrev_b32_e32 v6, 16, v54
	v_and_b32_e32 v7, 0xffff0000, v54
	v_pk_mul_f32 v[6:7], v[6:7], v[252:253] op_sel_hi:[1,0]
	v_pk_mul_f32 v[6:7], v[6:7], v[20:21]
	v_cvt_pk_bf16_f32 v54, v6, v7
	v_lshlrev_b32_e32 v40, 16, v62
	v_and_b32_e32 v41, 0xffff0000, v62
	v_pk_mul_f32 v[40:41], v[40:41], v[254:255] op_sel_hi:[1,0]
	v_pk_mul_f32 v[40:41], v[40:41], v[20:21]
	v_cvt_pk_bf16_f32 v62, v40, v41
	v_lshlrev_b32_e32 v6, 16, v55
	v_and_b32_e32 v7, 0xffff0000, v55
	v_pk_mul_f32 v[6:7], v[6:7], v[252:253] op_sel_hi:[1,0]
	v_pk_mul_f32 v[6:7], v[6:7], v[22:23]
	v_cvt_pk_bf16_f32 v55, v6, v7
	v_lshlrev_b32_e32 v40, 16, v63
	v_and_b32_e32 v41, 0xffff0000, v63
	v_pk_mul_f32 v[40:41], v[40:41], v[254:255] op_sel_hi:[1,0]
	v_pk_mul_f32 v[40:41], v[40:41], v[22:23]
	v_cvt_pk_bf16_f32 v63, v40, v41
	v_lshlrev_b32_e32 v6, 16, v56
	v_and_b32_e32 v7, 0xffff0000, v56
	v_pk_mul_f32 v[6:7], v[6:7], v[252:253] op_sel_hi:[1,0]
	v_pk_mul_f32 v[6:7], v[6:7], v[24:25]
	v_cvt_pk_bf16_f32 v56, v6, v7
	v_lshlrev_b32_e32 v40, 16, v64
	v_and_b32_e32 v41, 0xffff0000, v64
	v_pk_mul_f32 v[40:41], v[40:41], v[254:255] op_sel_hi:[1,0]
	v_pk_mul_f32 v[40:41], v[40:41], v[24:25]
	v_cvt_pk_bf16_f32 v64, v40, v41
	v_lshlrev_b32_e32 v6, 16, v57
	v_and_b32_e32 v7, 0xffff0000, v57
	v_pk_mul_f32 v[6:7], v[6:7], v[252:253] op_sel_hi:[1,0]
	v_pk_mul_f32 v[6:7], v[6:7], v[26:27]
	v_cvt_pk_bf16_f32 v57, v6, v7
	v_lshlrev_b32_e32 v40, 16, v65
	v_and_b32_e32 v41, 0xffff0000, v65
	v_pk_mul_f32 v[40:41], v[40:41], v[254:255] op_sel_hi:[1,0]
	v_pk_mul_f32 v[40:41], v[40:41], v[26:27]
	v_cvt_pk_bf16_f32 v65, v40, v41
	v_lshlrev_b32_e32 v6, 16, v58
	v_and_b32_e32 v7, 0xffff0000, v58
	v_pk_mul_f32 v[6:7], v[6:7], v[252:253] op_sel_hi:[1,0]
	v_pk_mul_f32 v[6:7], v[6:7], v[28:29]
	v_cvt_pk_bf16_f32 v58, v6, v7
	v_lshlrev_b32_e32 v40, 16, v66
	v_and_b32_e32 v41, 0xffff0000, v66
	v_pk_mul_f32 v[40:41], v[40:41], v[254:255] op_sel_hi:[1,0]
	v_pk_mul_f32 v[40:41], v[40:41], v[28:29]
	v_cvt_pk_bf16_f32 v66, v40, v41
	v_lshlrev_b32_e32 v6, 16, v59
	v_and_b32_e32 v7, 0xffff0000, v59
	v_pk_mul_f32 v[6:7], v[6:7], v[252:253] op_sel_hi:[1,0]
	v_pk_mul_f32 v[6:7], v[6:7], v[30:31]
	v_cvt_pk_bf16_f32 v59, v6, v7
	v_lshlrev_b32_e32 v40, 16, v67
	v_and_b32_e32 v41, 0xffff0000, v67
	v_pk_mul_f32 v[40:41], v[40:41], v[254:255] op_sel_hi:[1,0]
	v_pk_mul_f32 v[40:41], v[40:41], v[30:31]
	v_cvt_pk_bf16_f32 v67, v40, v41
	global_store_dwordx4 v[4:5], v[52:55], off
	global_store_dwordx4 v[4:5], v[56:59], off offset:16
	global_store_dwordx4 v[4:5], v[60:63], off offset:2048
	global_store_dwordx4 v[4:5], v[64:67], off offset:2064
	v_lshl_add_u64 v[4:5], v[4:5], 0, s[100:101]
	s_nop 1
	global_load_dwordx4 v[52:55], v[2:3], off
	global_load_dwordx4 v[56:59], v[2:3], off offset:16
	global_load_dwordx4 v[60:63], v[2:3], off offset:2048
	global_load_dwordx4 v[64:67], v[2:3], off offset:2064
	v_lshl_add_u64 v[2:3], v[2:3], 0, s[100:101]
	s_waitcnt vmcnt(8)
	v_lshlrev_b32_e32 v6, 16, v32
	v_and_b32_e32 v7, 0xffff0000, v32
	v_pk_mul_f32 v[8:9], v[6:7], v[6:7]
	v_lshlrev_b32_e32 v40, 16, v44
	v_and_b32_e32 v41, 0xffff0000, v44
	v_pk_mul_f32 v[250:251], v[40:41], v[40:41]
	v_lshlrev_b32_e32 v6, 16, v33
	v_and_b32_e32 v7, 0xffff0000, v33
	v_pk_fma_f32 v[8:9], v[6:7], v[6:7], v[8:9]
	v_lshlrev_b32_e32 v40, 16, v45
	v_and_b32_e32 v41, 0xffff0000, v45
	v_pk_fma_f32 v[250:251], v[40:41], v[40:41], v[250:251]
	v_lshlrev_b32_e32 v6, 16, v34
	v_and_b32_e32 v7, 0xffff0000, v34
	v_pk_fma_f32 v[8:9], v[6:7], v[6:7], v[8:9]
	v_lshlrev_b32_e32 v40, 16, v46
	v_and_b32_e32 v41, 0xffff0000, v46
	v_pk_fma_f32 v[250:251], v[40:41], v[40:41], v[250:251]
	v_lshlrev_b32_e32 v6, 16, v35
	v_and_b32_e32 v7, 0xffff0000, v35
	v_pk_fma_f32 v[8:9], v[6:7], v[6:7], v[8:9]
	v_lshlrev_b32_e32 v40, 16, v47
	v_and_b32_e32 v41, 0xffff0000, v47
	v_pk_fma_f32 v[250:251], v[40:41], v[40:41], v[250:251]
	v_lshlrev_b32_e32 v6, 16, v36
	v_and_b32_e32 v7, 0xffff0000, v36
	v_pk_fma_f32 v[8:9], v[6:7], v[6:7], v[8:9]
	v_lshlrev_b32_e32 v40, 16, v48
	v_and_b32_e32 v41, 0xffff0000, v48
	v_pk_fma_f32 v[250:251], v[40:41], v[40:41], v[250:251]
	v_lshlrev_b32_e32 v6, 16, v37
	v_and_b32_e32 v7, 0xffff0000, v37
	v_pk_fma_f32 v[8:9], v[6:7], v[6:7], v[8:9]
	v_lshlrev_b32_e32 v40, 16, v49
	v_and_b32_e32 v41, 0xffff0000, v49
	v_pk_fma_f32 v[250:251], v[40:41], v[40:41], v[250:251]
	v_lshlrev_b32_e32 v6, 16, v38
	v_and_b32_e32 v7, 0xffff0000, v38
	v_pk_fma_f32 v[8:9], v[6:7], v[6:7], v[8:9]
	v_lshlrev_b32_e32 v40, 16, v50
	v_and_b32_e32 v41, 0xffff0000, v50
	v_pk_fma_f32 v[250:251], v[40:41], v[40:41], v[250:251]
	v_lshlrev_b32_e32 v6, 16, v39
	v_and_b32_e32 v7, 0xffff0000, v39
	v_pk_fma_f32 v[8:9], v[6:7], v[6:7], v[8:9]
	v_lshlrev_b32_e32 v40, 16, v51
	v_and_b32_e32 v41, 0xffff0000, v51
	v_pk_fma_f32 v[250:251], v[40:41], v[40:41], v[250:251]
	v_add_f32_e32 v8, v8, v9
	v_add_f32_e32 v250, v250, v251
	s_nop 1
	v_add_f32_dpp v8, v8, v8 quad_perm:[1,0,3,2] row_mask:0xf bank_mask:0xf
	v_add_f32_dpp v250, v250, v250 quad_perm:[1,0,3,2] row_mask:0xf bank_mask:0xf
	s_nop 1
	v_add_f32_dpp v8, v8, v8 quad_perm:[2,3,0,1] row_mask:0xf bank_mask:0xf
	v_add_f32_dpp v250, v250, v250 quad_perm:[2,3,0,1] row_mask:0xf bank_mask:0xf
	s_nop 1
	v_add_f32_dpp v8, v8, v8 row_half_mirror row_mask:0xf bank_mask:0xf
	v_add_f32_dpp v250, v250, v250 row_half_mirror row_mask:0xf bank_mask:0xf
	s_nop 1
	v_add_f32_dpp v8, v8, v8 row_mirror row_mask:0xf bank_mask:0xf
	v_add_f32_dpp v250, v250, v250 row_mirror row_mask:0xf bank_mask:0xf
	s_nop 1
	ds_bpermute_b32 v6, v14, v8
	ds_bpermute_b32 v40, v14, v250
	s_waitcnt lgkmcnt(0)
; DEVI unsigned pk2(float lo, float hi) { unsigned r; asm("v_cvt_pk_bf16_f32 %0, %1, %2" : "=v"(r) : "v"(lo), "v"(hi)); return r; }
; DEVI float bflo(unsigned w) { return __uint_as_float(w << 16); }
; DEVI float bfhi(unsigned w) { return __uint_as_float(w & 0xffff0000u); }
; DEVI void phase_m3(const Params& p, int l, unsigned char* smem) {
;     ...
;             for (int tt = 0; tt < 16; ++tt) {
;                 const int t = wave * 16 + tt;
;                 bf16_t* rowp = mix + (size_t)(row0 + t) * DM + lane * 16;
;                 const u32x4 a = *(const u32x4*)rowp, b = *(const u32x4*)(rowp + 8);
;                 float v[16] = {bflo(a.x), bfhi(a.x), bflo(a.y), bfhi(a.y), bflo(a.z), bfhi(a.z), bflo(a.w), bfhi(a.w), bflo(b.x), bfhi(b.x), bflo(b.y), bfhi(b.y), bflo(b.z), bfhi(b.z), bflo(b.w), bfhi(b.w)};
;                 float ss = 0.f;
; #pragma unroll
;                 for (int e = 0; e < 16; ++e) ss += v[e] * v[e];
;                 ss += __shfl_xor(ss, 1); ss += __shfl_xor(ss, 2); ss += __shfl_xor(ss, 4); ss += __shfl_xor(ss, 8);
;                 const float s16 = __shfl_xor(ss, 16);
;                 float rn;
;                 if (lane < 32) rn = rsqrtf((ss + s16) * (1.0f / 512.0f) + RMS_EPS); else rn = rsqrtf(ss * (1.0f / 256.0f) + RMS_EPS);
;                 const f32x4 g0 = *(const f32x4*)(gain + lane * 16), g1 = *(const f32x4*)(gain + lane * 16 + 4), g2 = *(const f32x4*)(gain + lane * 16 + 8), g3 = *(const f32x4*)(gain + lane * 16 + 12);
;                 u32x4 o1, o2;
;                 o1.x = pk2(v[0] * rn * g0[0], v[1] * rn * g0[1]); o1.y = pk2(v[2] * rn * g0[2], v[3] * rn * g0[3]); o1.z = pk2(v[4] * rn * g1[0], v[5] * rn * g1[1]); o1.w = pk2(v[6] * rn * g1[2], v[7] * rn * g1[3]);
;                 o2.x = pk2(v[8] * rn * g2[0], v[9] * rn * g2[1]); o2.y = pk2(v[10] * rn * g2[2], v[11] * rn * g2[3]); o2.z = pk2(v[12] * rn * g3[0], v[13] * rn * g3[1]); o2.w = pk2(v[14] * rn * g3[2], v[15] * rn * g3[3]);
;                 *(u32x4*)rowp = o1; *(u32x4*)(rowp + 8) = o2;
;             }
	v_add_f32_e32 v6, v8, v6
	v_mul_f32_e32 v6, 0x3b000000, v6
	v_mul_f32_e32 v8, 0x3b800000, v8
	v_cndmask_b32_e64 v8, v8, v6, s[6:7]
	v_add_f32_e32 v8, 0x358637bd, v8
	v_rsq_f32_e32 v252, v8
	v_add_f32_e32 v40, v250, v40
	v_mul_f32_e32 v40, 0x3b000000, v40
	v_mul_f32_e32 v250, 0x3b800000, v250
	v_cndmask_b32_e64 v250, v250, v40, s[6:7]
	v_add_f32_e32 v250, 0x358637bd, v250
	v_rsq_f32_e32 v254, v250
	s_nop 1
	v_lshlrev_b32_e32 v6, 16, v32
	v_and_b32_e32 v7, 0xffff0000, v32
	v_pk_mul_f32 v[6:7], v[6:7], v[252:253] op_sel_hi:[1,0]
	v_pk_mul_f32 v[6:7], v[6:7], v[16:17]
	v_cvt_pk_bf16_f32 v32, v6, v7
	v_lshlrev_b32_e32 v40, 16, v44
	v_and_b32_e32 v41, 0xffff0000, v44
	v_pk_mul_f32 v[40:41], v[40:41], v[254:255] op_sel_hi:[1,0]
	v_pk_mul_f32 v[40:41], v[40:41], v[16:17]
	v_cvt_pk_bf16_f32 v44, v40, v41
	v_lshlrev_b32_e32 v6, 16, v33
	v_and_b32_e32 v7, 0xffff0000, v33
	v_pk_mul_f32 v[6:7], v[6:7], v[252:253] op_sel_hi:[1,0]
	v_pk_mul_f32 v[6:7], v[6:7], v[18:19]
	v_cvt_pk_bf16_f32 v33, v6, v7
	v_lshlrev_b32_e32 v40, 16, v45
	v_and_b32_e32 v41, 0xffff0000, v45
	v_pk_mul_f32 v[40:41], v[40:41], v[254:255] op_sel_hi:[1,0]
	v_pk_mul_f32 v[40:41], v[40:41], v[18:19]
	v_cvt_pk_bf16_f32 v45, v40, v41
	v_lshlrev_b32_e32 v6, 16, v34
	v_and_b32_e32 v7, 0xffff0000, v34
	v_pk_mul_f32 v[6:7], v[6:7], v[252:253] op_sel_hi:[1,0]
	v_pk_mul_f32 v[6:7], v[6:7], v[20:21]
	v_cvt_pk_bf16_f32 v34, v6, v7
	v_lshlrev_b32_e32 v40, 16, v46
	v_and_b32_e32 v41, 0xffff0000, v46
	v_pk_mul_f32 v[40:41], v[40:41], v[254:255] op_sel_hi:[1,0]
	v_pk_mul_f32 v[40:41], v[40:41], v[20:21]
	v_cvt_pk_bf16_f32 v46, v40, v41
	v_lshlrev_b32_e32 v6, 16, v35
	v_and_b32_e32 v7, 0xffff0000, v35
	v_pk_mul_f32 v[6:7], v[6:7], v[252:253] op_sel_hi:[1,0]
	v_pk_mul_f32 v[6:7], v[6:7], v[22:23]
	v_cvt_pk_bf16_f32 v35, v6, v7
	v_lshlrev_b32_e32 v40, 16, v47
	v_and_b32_e32 v41, 0xffff0000, v47
	v_pk_mul_f32 v[40:41], v[40:41], v[254:255] op_sel_hi:[1,0]
	v_pk_mul_f32 v[40:41], v[40:41], v[22:23]
	v_cvt_pk_bf16_f32 v47, v40, v41
	v_lshlrev_b32_e32 v6, 16, v36
	v_and_b32_e32 v7, 0xffff0000, v36
	v_pk_mul_f32 v[6:7], v[6:7], v[252:253] op_sel_hi:[1,0]
	v_pk_mul_f32 v[6:7], v[6:7], v[24:25]
	v_cvt_pk_bf16_f32 v36, v6, v7
	v_lshlrev_b32_e32 v40, 16, v48
	v_and_b32_e32 v41, 0xffff0000, v48
	v_pk_mul_f32 v[40:41], v[40:41], v[254:255] op_sel_hi:[1,0]
	v_pk_mul_f32 v[40:41], v[40:41], v[24:25]
	v_cvt_pk_bf16_f32 v48, v40, v41
	v_lshlrev_b32_e32 v6, 16, v37
	v_and_b32_e32 v7, 0xffff0000, v37
	v_pk_mul_f32 v[6:7], v[6:7], v[252:253] op_sel_hi:[1,0]
	v_pk_mul_f32 v[6:7], v[6:7], v[26:27]
	v_cvt_pk_bf16_f32 v37, v6, v7
	v_lshlrev_b32_e32 v40, 16, v49
	v_and_b32_e32 v41, 0xffff0000, v49
	v_pk_mul_f32 v[40:41], v[40:41], v[254:255] op_sel_hi:[1,0]
	v_pk_mul_f32 v[40:41], v[40:41], v[26:27]
	v_cvt_pk_bf16_f32 v49, v40, v41
	v_lshlrev_b32_e32 v6, 16, v38
	v_and_b32_e32 v7, 0xffff0000, v38
	v_pk_mul_f32 v[6:7], v[6:7], v[252:253] op_sel_hi:[1,0]
	v_pk_mul_f32 v[6:7], v[6:7], v[28:29]
	v_cvt_pk_bf16_f32 v38, v6, v7
	v_lshlrev_b32_e32 v40, 16, v50
	v_and_b32_e32 v41, 0xffff0000, v50
	v_pk_mul_f32 v[40:41], v[40:41], v[254:255] op_sel_hi:[1,0]
	v_pk_mul_f32 v[40:41], v[40:41], v[28:29]
	v_cvt_pk_bf16_f32 v50, v40, v41
	v_lshlrev_b32_e32 v6, 16, v39
	v_and_b32_e32 v7, 0xffff0000, v39
	v_pk_mul_f32 v[6:7], v[6:7], v[252:253] op_sel_hi:[1,0]
	v_pk_mul_f32 v[6:7], v[6:7], v[30:31]
	v_cvt_pk_bf16_f32 v39, v6, v7
	v_lshlrev_b32_e32 v40, 16, v51
	v_and_b32_e32 v41, 0xffff0000, v51
	v_pk_mul_f32 v[40:41], v[40:41], v[254:255] op_sel_hi:[1,0]
	v_pk_mul_f32 v[40:41], v[40:41], v[30:31]
	v_cvt_pk_bf16_f32 v51, v40, v41
	global_store_dwordx4 v[4:5], v[32:35], off
	global_store_dwordx4 v[4:5], v[36:39], off offset:16
	global_store_dwordx4 v[4:5], v[44:47], off offset:2048
	global_store_dwordx4 v[4:5], v[48:51], off offset:2064
	v_lshl_add_u64 v[4:5], v[4:5], 0, s[100:101]
	s_nop 1
	global_load_dwordx4 v[32:35], v[2:3], off
	global_load_dwordx4 v[36:39], v[2:3], off offset:16
	global_load_dwordx4 v[44:47], v[2:3], off offset:2048
	global_load_dwordx4 v[48:51], v[2:3], off offset:2064
	v_lshl_add_u64 v[2:3], v[2:3], 0, s[100:101]
	s_waitcnt vmcnt(8)
	v_lshlrev_b32_e32 v6, 16, v52
	v_and_b32_e32 v7, 0xffff0000, v52
	v_pk_mul_f32 v[8:9], v[6:7], v[6:7]
	v_lshlrev_b32_e32 v40, 16, v60
	v_and_b32_e32 v41, 0xffff0000, v60
	v_pk_mul_f32 v[250:251], v[40:41], v[40:41]
	v_lshlrev_b32_e32 v6, 16, v53
	v_and_b32_e32 v7, 0xffff0000, v53
	v_pk_fma_f32 v[8:9], v[6:7], v[6:7], v[8:9]
	v_lshlrev_b32_e32 v40, 16, v61
	v_and_b32_e32 v41, 0xffff0000, v61
	v_pk_fma_f32 v[250:251], v[40:41], v[40:41], v[250:251]
	v_lshlrev_b32_e32 v6, 16, v54
	v_and_b32_e32 v7, 0xffff0000, v54
	v_pk_fma_f32 v[8:9], v[6:7], v[6:7], v[8:9]
	v_lshlrev_b32_e32 v40, 16, v62
	v_and_b32_e32 v41, 0xffff0000, v62
	v_pk_fma_f32 v[250:251], v[40:41], v[40:41], v[250:251]
	v_lshlrev_b32_e32 v6, 16, v55
	v_and_b32_e32 v7, 0xffff0000, v55
	v_pk_fma_f32 v[8:9], v[6:7], v[6:7], v[8:9]
	v_lshlrev_b32_e32 v40, 16, v63
	v_and_b32_e32 v41, 0xffff0000, v63
	v_pk_fma_f32 v[250:251], v[40:41], v[40:41], v[250:251]
	v_lshlrev_b32_e32 v6, 16, v56
	v_and_b32_e32 v7, 0xffff0000, v56
	v_pk_fma_f32 v[8:9], v[6:7], v[6:7], v[8:9]
	v_lshlrev_b32_e32 v40, 16, v64
	v_and_b32_e32 v41, 0xffff0000, v64
	v_pk_fma_f32 v[250:251], v[40:41], v[40:41], v[250:251]
	v_lshlrev_b32_e32 v6, 16, v57
	v_and_b32_e32 v7, 0xffff0000, v57
	v_pk_fma_f32 v[8:9], v[6:7], v[6:7], v[8:9]
	v_lshlrev_b32_e32 v40, 16, v65
	v_and_b32_e32 v41, 0xffff0000, v65
	v_pk_fma_f32 v[250:251], v[40:41], v[40:41], v[250:251]
	v_lshlrev_b32_e32 v6, 16, v58
	v_and_b32_e32 v7, 0xffff0000, v58
	v_pk_fma_f32 v[8:9], v[6:7], v[6:7], v[8:9]
	v_lshlrev_b32_e32 v40, 16, v66
	v_and_b32_e32 v41, 0xffff0000, v66
	v_pk_fma_f32 v[250:251], v[40:41], v[40:41], v[250:251]
	v_lshlrev_b32_e32 v6, 16, v59
	v_and_b32_e32 v7, 0xffff0000, v59
	v_pk_fma_f32 v[8:9], v[6:7], v[6:7], v[8:9]
	v_lshlrev_b32_e32 v40, 16, v67
	v_and_b32_e32 v41, 0xffff0000, v67
	v_pk_fma_f32 v[250:251], v[40:41], v[40:41], v[250:251]
	v_add_f32_e32 v8, v8, v9
	v_add_f32_e32 v250, v250, v251
	s_nop 1
	v_add_f32_dpp v8, v8, v8 quad_perm:[1,0,3,2] row_mask:0xf bank_mask:0xf
	v_add_f32_dpp v250, v250, v250 quad_perm:[1,0,3,2] row_mask:0xf bank_mask:0xf
	s_nop 1
	v_add_f32_dpp v8, v8, v8 quad_perm:[2,3,0,1] row_mask:0xf bank_mask:0xf
	v_add_f32_dpp v250, v250, v250 quad_perm:[2,3,0,1] row_mask:0xf bank_mask:0xf
	s_nop 1
	v_add_f32_dpp v8, v8, v8 row_half_mirror row_mask:0xf bank_mask:0xf
	v_add_f32_dpp v250, v250, v250 row_half_mirror row_mask:0xf bank_mask:0xf
	s_nop 1
	v_add_f32_dpp v8, v8, v8 row_mirror row_mask:0xf bank_mask:0xf
	v_add_f32_dpp v250, v250, v250 row_mirror row_mask:0xf bank_mask:0xf
	s_nop 1
	ds_bpermute_b32 v6, v14, v8
	ds_bpermute_b32 v40, v14, v250
	s_waitcnt lgkmcnt(0)
; DEVI unsigned pk2(float lo, float hi) { unsigned r; asm("v_cvt_pk_bf16_f32 %0, %1, %2" : "=v"(r) : "v"(lo), "v"(hi)); return r; }
; DEVI float bflo(unsigned w) { return __uint_as_float(w << 16); }
; DEVI float bfhi(unsigned w) { return __uint_as_float(w & 0xffff0000u); }
; DEVI void phase_m3(const Params& p, int l, unsigned char* smem) {
;     ...
;             for (int tt = 0; tt < 16; ++tt) {
;                 const int t = wave * 16 + tt;
;                 bf16_t* rowp = mix + (size_t)(row0 + t) * DM + lane * 16;
;                 const u32x4 a = *(const u32x4*)rowp, b = *(const u32x4*)(rowp + 8);
;                 float v[16] = {bflo(a.x), bfhi(a.x), bflo(a.y), bfhi(a.y), bflo(a.z), bfhi(a.z), bflo(a.w), bfhi(a.w), bflo(b.x), bfhi(b.x), bflo(b.y), bfhi(b.y), bflo(b.z), bfhi(b.z), bflo(b.w), bfhi(b.w)};
;                 float ss = 0.f;
; #pragma unroll
;                 for (int e = 0; e < 16; ++e) ss += v[e] * v[e];
;                 ss += __shfl_xor(ss, 1); ss += __shfl_xor(ss, 2); ss += __shfl_xor(ss, 4); ss += __shfl_xor(ss, 8);
;                 const float s16 = __shfl_xor(ss, 16);
;                 float rn;
;                 if (lane < 32) rn = rsqrtf((ss + s16) * (1.0f / 512.0f) + RMS_EPS); else rn = rsqrtf(ss * (1.0f / 256.0f) + RMS_EPS);
;                 const f32x4 g0 = *(const f32x4*)(gain + lane * 16), g1 = *(const f32x4*)(gain + lane * 16 + 4), g2 = *(const f32x4*)(gain + lane * 16 + 8), g3 = *(const f32x4*)(gain + lane * 16 + 12);
;                 u32x4 o1, o2;
;                 o1.x = pk2(v[0] * rn * g0[0], v[1] * rn * g0[1]); o1.y = pk2(v[2] * rn * g0[2], v[3] * rn * g0[3]); o1.z = pk2(v[4] * rn * g1[0], v[5] * rn * g1[1]); o1.w = pk2(v[6] * rn * g1[2], v[7] * rn * g1[3]);
;                 o2.x = pk2(v[8] * rn * g2[0], v[9] * rn * g2[1]); o2.y = pk2(v[10] * rn * g2[2], v[11] * rn * g2[3]); o2.z = pk2(v[12] * rn * g3[0], v[13] * rn * g3[1]); o2.w = pk2(v[14] * rn * g3[2], v[15] * rn * g3[3]);
;                 *(u32x4*)rowp = o1; *(u32x4*)(rowp + 8) = o2;
;             }
	v_add_f32_e32 v6, v8, v6
	v_mul_f32_e32 v6, 0x3b000000, v6
	v_mul_f32_e32 v8, 0x3b800000, v8
	v_cndmask_b32_e64 v8, v8, v6, s[6:7]
	v_add_f32_e32 v8, 0x358637bd, v8
	v_rsq_f32_e32 v252, v8
	v_add_f32_e32 v40, v250, v40
	v_mul_f32_e32 v40, 0x3b000000, v40
	v_mul_f32_e32 v250, 0x3b800000, v250
	v_cndmask_b32_e64 v250, v250, v40, s[6:7]
	v_add_f32_e32 v250, 0x358637bd, v250
	v_rsq_f32_e32 v254, v250
	s_nop 1
	v_lshlrev_b32_e32 v6, 16, v52
	v_and_b32_e32 v7, 0xffff0000, v52
	v_pk_mul_f32 v[6:7], v[6:7], v[252:253] op_sel_hi:[1,0]
	v_pk_mul_f32 v[6:7], v[6:7], v[16:17]
	v_cvt_pk_bf16_f32 v52, v6, v7
	v_lshlrev_b32_e32 v40, 16, v60
	v_and_b32_e32 v41, 0xffff0000, v60
	v_pk_mul_f32 v[40:41], v[40:41], v[254:255] op_sel_hi:[1,0]
	v_pk_mul_f32 v[40:41], v[40:41], v[16:17]
	v_cvt_pk_bf16_f32 v60, v40, v41
	v_lshlrev_b32_e32 v6, 16, v53
	v_and_b32_e32 v7, 0xffff0000, v53
	v_pk_mul_f32 v[6:7], v[6:7], v[252:253] op_sel_hi:[1,0]
	v_pk_mul_f32 v[6:7], v[6:7], v[18:19]
	v_cvt_pk_bf16_f32 v53, v6, v7
	v_lshlrev_b32_e32 v40, 16, v61
	v_and_b32_e32 v41, 0xffff0000, v61
	v_pk_mul_f32 v[40:41], v[40:41], v[254:255] op_sel_hi:[1,0]
	v_pk_mul_f32 v[40:41], v[40:41], v[18:19]
	v_cvt_pk_bf16_f32 v61, v40, v41
	v_lshlrev_b32_e32 v6, 16, v54
	v_and_b32_e32 v7, 0xffff0000, v54
	v_pk_mul_f32 v[6:7], v[6:7], v[252:253] op_sel_hi:[1,0]
	v_pk_mul_f32 v[6:7], v[6:7], v[20:21]
	v_cvt_pk_bf16_f32 v54, v6, v7
	v_lshlrev_b32_e32 v40, 16, v62
	v_and_b32_e32 v41, 0xffff0000, v62
	v_pk_mul_f32 v[40:41], v[40:41], v[254:255] op_sel_hi:[1,0]
	v_pk_mul_f32 v[40:41], v[40:41], v[20:21]
	v_cvt_pk_bf16_f32 v62, v40, v41
	v_lshlrev_b32_e32 v6, 16, v55
	v_and_b32_e32 v7, 0xffff0000, v55
	v_pk_mul_f32 v[6:7], v[6:7], v[252:253] op_sel_hi:[1,0]
	v_pk_mul_f32 v[6:7], v[6:7], v[22:23]
	v_cvt_pk_bf16_f32 v55, v6, v7
	v_lshlrev_b32_e32 v40, 16, v63
	v_and_b32_e32 v41, 0xffff0000, v63
	v_pk_mul_f32 v[40:41], v[40:41], v[254:255] op_sel_hi:[1,0]
	v_pk_mul_f32 v[40:41], v[40:41], v[22:23]
	v_cvt_pk_bf16_f32 v63, v40, v41
	v_lshlrev_b32_e32 v6, 16, v56
	v_and_b32_e32 v7, 0xffff0000, v56
	v_pk_mul_f32 v[6:7], v[6:7], v[252:253] op_sel_hi:[1,0]
	v_pk_mul_f32 v[6:7], v[6:7], v[24:25]
	v_cvt_pk_bf16_f32 v56, v6, v7
	v_lshlrev_b32_e32 v40, 16, v64
	v_and_b32_e32 v41, 0xffff0000, v64
	v_pk_mul_f32 v[40:41], v[40:41], v[254:255] op_sel_hi:[1,0]
	v_pk_mul_f32 v[40:41], v[40:41], v[24:25]
	v_cvt_pk_bf16_f32 v64, v40, v41
	v_lshlrev_b32_e32 v6, 16, v57
	v_and_b32_e32 v7, 0xffff0000, v57
	v_pk_mul_f32 v[6:7], v[6:7], v[252:253] op_sel_hi:[1,0]
	v_pk_mul_f32 v[6:7], v[6:7], v[26:27]
	v_cvt_pk_bf16_f32 v57, v6, v7
	v_lshlrev_b32_e32 v40, 16, v65
	v_and_b32_e32 v41, 0xffff0000, v65
	v_pk_mul_f32 v[40:41], v[40:41], v[254:255] op_sel_hi:[1,0]
	v_pk_mul_f32 v[40:41], v[40:41], v[26:27]
	v_cvt_pk_bf16_f32 v65, v40, v41
	v_lshlrev_b32_e32 v6, 16, v58
	v_and_b32_e32 v7, 0xffff0000, v58
	v_pk_mul_f32 v[6:7], v[6:7], v[252:253] op_sel_hi:[1,0]
	v_pk_mul_f32 v[6:7], v[6:7], v[28:29]
	v_cvt_pk_bf16_f32 v58, v6, v7
	v_lshlrev_b32_e32 v40, 16, v66
	v_and_b32_e32 v41, 0xffff0000, v66
	v_pk_mul_f32 v[40:41], v[40:41], v[254:255] op_sel_hi:[1,0]
	v_pk_mul_f32 v[40:41], v[40:41], v[28:29]
	v_cvt_pk_bf16_f32 v66, v40, v41
	v_lshlrev_b32_e32 v6, 16, v59
	v_and_b32_e32 v7, 0xffff0000, v59
	v_pk_mul_f32 v[6:7], v[6:7], v[252:253] op_sel_hi:[1,0]
	v_pk_mul_f32 v[6:7], v[6:7], v[30:31]
	v_cvt_pk_bf16_f32 v59, v6, v7
	v_lshlrev_b32_e32 v40, 16, v67
	v_and_b32_e32 v41, 0xffff0000, v67
	v_pk_mul_f32 v[40:41], v[40:41], v[254:255] op_sel_hi:[1,0]
	v_pk_mul_f32 v[40:41], v[40:41], v[30:31]
	v_cvt_pk_bf16_f32 v67, v40, v41
	global_store_dwordx4 v[4:5], v[52:55], off
	global_store_dwordx4 v[4:5], v[56:59], off offset:16
	global_store_dwordx4 v[4:5], v[60:63], off offset:2048
	global_store_dwordx4 v[4:5], v[64:67], off offset:2064
	v_lshl_add_u64 v[4:5], v[4:5], 0, s[100:101]
	s_nop 1
	global_load_dwordx4 v[52:55], v[2:3], off
	global_load_dwordx4 v[56:59], v[2:3], off offset:16
	global_load_dwordx4 v[60:63], v[2:3], off offset:2048
	global_load_dwordx4 v[64:67], v[2:3], off offset:2064
	v_lshl_add_u64 v[2:3], v[2:3], 0, s[100:101]
	s_waitcnt vmcnt(8)
	v_lshlrev_b32_e32 v6, 16, v32
	v_and_b32_e32 v7, 0xffff0000, v32
	v_pk_mul_f32 v[8:9], v[6:7], v[6:7]
	v_lshlrev_b32_e32 v40, 16, v44
	v_and_b32_e32 v41, 0xffff0000, v44
	v_pk_mul_f32 v[250:251], v[40:41], v[40:41]
	v_lshlrev_b32_e32 v6, 16, v33
	v_and_b32_e32 v7, 0xffff0000, v33
	v_pk_fma_f32 v[8:9], v[6:7], v[6:7], v[8:9]
	v_lshlrev_b32_e32 v40, 16, v45
	v_and_b32_e32 v41, 0xffff0000, v45
	v_pk_fma_f32 v[250:251], v[40:41], v[40:41], v[250:251]
	v_lshlrev_b32_e32 v6, 16, v34
	v_and_b32_e32 v7, 0xffff0000, v34
	v_pk_fma_f32 v[8:9], v[6:7], v[6:7], v[8:9]
	v_lshlrev_b32_e32 v40, 16, v46
	v_and_b32_e32 v41, 0xffff0000, v46
	v_pk_fma_f32 v[250:251], v[40:41], v[40:41], v[250:251]
	v_lshlrev_b32_e32 v6, 16, v35
	v_and_b32_e32 v7, 0xffff0000, v35
	v_pk_fma_f32 v[8:9], v[6:7], v[6:7], v[8:9]
	v_lshlrev_b32_e32 v40, 16, v47
	v_and_b32_e32 v41, 0xffff0000, v47
	v_pk_fma_f32 v[250:251], v[40:41], v[40:41], v[250:251]
	v_lshlrev_b32_e32 v6, 16, v36
	v_and_b32_e32 v7, 0xffff0000, v36
	v_pk_fma_f32 v[8:9], v[6:7], v[6:7], v[8:9]
	v_lshlrev_b32_e32 v40, 16, v48
	v_and_b32_e32 v41, 0xffff0000, v48
	v_pk_fma_f32 v[250:251], v[40:41], v[40:41], v[250:251]
	v_lshlrev_b32_e32 v6, 16, v37
	v_and_b32_e32 v7, 0xffff0000, v37
	v_pk_fma_f32 v[8:9], v[6:7], v[6:7], v[8:9]
	v_lshlrev_b32_e32 v40, 16, v49
	v_and_b32_e32 v41, 0xffff0000, v49
	v_pk_fma_f32 v[250:251], v[40:41], v[40:41], v[250:251]
	v_lshlrev_b32_e32 v6, 16, v38
	v_and_b32_e32 v7, 0xffff0000, v38
	v_pk_fma_f32 v[8:9], v[6:7], v[6:7], v[8:9]
	v_lshlrev_b32_e32 v40, 16, v50
	v_and_b32_e32 v41, 0xffff0000, v50
	v_pk_fma_f32 v[250:251], v[40:41], v[40:41], v[250:251]
	v_lshlrev_b32_e32 v6, 16, v39
	v_and_b32_e32 v7, 0xffff0000, v39
	v_pk_fma_f32 v[8:9], v[6:7], v[6:7], v[8:9]
	v_lshlrev_b32_e32 v40, 16, v51
	v_and_b32_e32 v41, 0xffff0000, v51
	v_pk_fma_f32 v[250:251], v[40:41], v[40:41], v[250:251]
	v_add_f32_e32 v8, v8, v9
	v_add_f32_e32 v250, v250, v251
	s_nop 1
	v_add_f32_dpp v8, v8, v8 quad_perm:[1,0,3,2] row_mask:0xf bank_mask:0xf
	v_add_f32_dpp v250, v250, v250 quad_perm:[1,0,3,2] row_mask:0xf bank_mask:0xf
	s_nop 1
	v_add_f32_dpp v8, v8, v8 quad_perm:[2,3,0,1] row_mask:0xf bank_mask:0xf
	v_add_f32_dpp v250, v250, v250 quad_perm:[2,3,0,1] row_mask:0xf bank_mask:0xf
	s_nop 1
	v_add_f32_dpp v8, v8, v8 row_half_mirror row_mask:0xf bank_mask:0xf
	v_add_f32_dpp v250, v250, v250 row_half_mirror row_mask:0xf bank_mask:0xf
	s_nop 1
	v_add_f32_dpp v8, v8, v8 row_mirror row_mask:0xf bank_mask:0xf
	v_add_f32_dpp v250, v250, v250 row_mirror row_mask:0xf bank_mask:0xf
	s_nop 1
	ds_bpermute_b32 v6, v14, v8
	ds_bpermute_b32 v40, v14, v250
	s_waitcnt lgkmcnt(0)
; DEVI unsigned pk2(float lo, float hi) { unsigned r; asm("v_cvt_pk_bf16_f32 %0, %1, %2" : "=v"(r) : "v"(lo), "v"(hi)); return r; }
; DEVI float bflo(unsigned w) { return __uint_as_float(w << 16); }
; DEVI float bfhi(unsigned w) { return __uint_as_float(w & 0xffff0000u); }
; DEVI void phase_m3(const Params& p, int l, unsigned char* smem) {
;     ...
;             for (int tt = 0; tt < 16; ++tt) {
;                 const int t = wave * 16 + tt;
;                 bf16_t* rowp = mix + (size_t)(row0 + t) * DM + lane * 16;
;                 const u32x4 a = *(const u32x4*)rowp, b = *(const u32x4*)(rowp + 8);
;                 float v[16] = {bflo(a.x), bfhi(a.x), bflo(a.y), bfhi(a.y), bflo(a.z), bfhi(a.z), bflo(a.w), bfhi(a.w), bflo(b.x), bfhi(b.x), bflo(b.y), bfhi(b.y), bflo(b.z), bfhi(b.z), bflo(b.w), bfhi(b.w)};
;                 float ss = 0.f;
; #pragma unroll
;                 for (int e = 0; e < 16; ++e) ss += v[e] * v[e];
;                 ss += __shfl_xor(ss, 1); ss += __shfl_xor(ss, 2); ss += __shfl_xor(ss, 4); ss += __shfl_xor(ss, 8);
;                 const float s16 = __shfl_xor(ss, 16);
;                 float rn;
;                 if (lane < 32) rn = rsqrtf((ss + s16) * (1.0f / 512.0f) + RMS_EPS); else rn = rsqrtf(ss * (1.0f / 256.0f) + RMS_EPS);
;                 const f32x4 g0 = *(const f32x4*)(gain + lane * 16), g1 = *(const f32x4*)(gain + lane * 16 + 4), g2 = *(const f32x4*)(gain + lane * 16 + 8), g3 = *(const f32x4*)(gain + lane * 16 + 12);
;                 u32x4 o1, o2;
;                 o1.x = pk2(v[0] * rn * g0[0], v[1] * rn * g0[1]); o1.y = pk2(v[2] * rn * g0[2], v[3] * rn * g0[3]); o1.z = pk2(v[4] * rn * g1[0], v[5] * rn * g1[1]); o1.w = pk2(v[6] * rn * g1[2], v[7] * rn * g1[3]);
;                 o2.x = pk2(v[8] * rn * g2[0], v[9] * rn * g2[1]); o2.y = pk2(v[10] * rn * g2[2], v[11] * rn * g2[3]); o2.z = pk2(v[12] * rn * g3[0], v[13] * rn * g3[1]); o2.w = pk2(v[14] * rn * g3[2], v[15] * rn * g3[3]);
;                 *(u32x4*)rowp = o1; *(u32x4*)(rowp + 8) = o2;
;             }
	v_add_f32_e32 v6, v8, v6
	v_mul_f32_e32 v6, 0x3b000000, v6
	v_mul_f32_e32 v8, 0x3b800000, v8
	v_cndmask_b32_e64 v8, v8, v6, s[6:7]
	v_add_f32_e32 v8, 0x358637bd, v8
	v_rsq_f32_e32 v252, v8
	v_add_f32_e32 v40, v250, v40
	v_mul_f32_e32 v40, 0x3b000000, v40
	v_mul_f32_e32 v250, 0x3b800000, v250
	v_cndmask_b32_e64 v250, v250, v40, s[6:7]
	v_add_f32_e32 v250, 0x358637bd, v250
	v_rsq_f32_e32 v254, v250
	s_nop 1
	v_lshlrev_b32_e32 v6, 16, v32
	v_and_b32_e32 v7, 0xffff0000, v32
	v_pk_mul_f32 v[6:7], v[6:7], v[252:253] op_sel_hi:[1,0]
	v_pk_mul_f32 v[6:7], v[6:7], v[16:17]
	v_cvt_pk_bf16_f32 v32, v6, v7
	v_lshlrev_b32_e32 v40, 16, v44
	v_and_b32_e32 v41, 0xffff0000, v44
	v_pk_mul_f32 v[40:41], v[40:41], v[254:255] op_sel_hi:[1,0]
	v_pk_mul_f32 v[40:41], v[40:41], v[16:17]
	v_cvt_pk_bf16_f32 v44, v40, v41
	v_lshlrev_b32_e32 v6, 16, v33
	v_and_b32_e32 v7, 0xffff0000, v33
	v_pk_mul_f32 v[6:7], v[6:7], v[252:253] op_sel_hi:[1,0]
	v_pk_mul_f32 v[6:7], v[6:7], v[18:19]
	v_cvt_pk_bf16_f32 v33, v6, v7
	v_lshlrev_b32_e32 v40, 16, v45
	v_and_b32_e32 v41, 0xffff0000, v45
	v_pk_mul_f32 v[40:41], v[40:41], v[254:255] op_sel_hi:[1,0]
	v_pk_mul_f32 v[40:41], v[40:41], v[18:19]
	v_cvt_pk_bf16_f32 v45, v40, v41
	v_lshlrev_b32_e32 v6, 16, v34
	v_and_b32_e32 v7, 0xffff0000, v34
	v_pk_mul_f32 v[6:7], v[6:7], v[252:253] op_sel_hi:[1,0]
	v_pk_mul_f32 v[6:7], v[6:7], v[20:21]
	v_cvt_pk_bf16_f32 v34, v6, v7
	v_lshlrev_b32_e32 v40, 16, v46
	v_and_b32_e32 v41, 0xffff0000, v46
	v_pk_mul_f32 v[40:41], v[40:41], v[254:255] op_sel_hi:[1,0]
	v_pk_mul_f32 v[40:41], v[40:41], v[20:21]
	v_cvt_pk_bf16_f32 v46, v40, v41
	v_lshlrev_b32_e32 v6, 16, v35
	v_and_b32_e32 v7, 0xffff0000, v35
	v_pk_mul_f32 v[6:7], v[6:7], v[252:253] op_sel_hi:[1,0]
	v_pk_mul_f32 v[6:7], v[6:7], v[22:23]
	v_cvt_pk_bf16_f32 v35, v6, v7
	v_lshlrev_b32_e32 v40, 16, v47
	v_and_b32_e32 v41, 0xffff0000, v47
	v_pk_mul_f32 v[40:41], v[40:41], v[254:255] op_sel_hi:[1,0]
	v_pk_mul_f32 v[40:41], v[40:41], v[22:23]
	v_cvt_pk_bf16_f32 v47, v40, v41
	v_lshlrev_b32_e32 v6, 16, v36
	v_and_b32_e32 v7, 0xffff0000, v36
	v_pk_mul_f32 v[6:7], v[6:7], v[252:253] op_sel_hi:[1,0]
	v_pk_mul_f32 v[6:7], v[6:7], v[24:25]
	v_cvt_pk_bf16_f32 v36, v6, v7
	v_lshlrev_b32_e32 v40, 16, v48
	v_and_b32_e32 v41, 0xffff0000, v48
	v_pk_mul_f32 v[40:41], v[40:41], v[254:255] op_sel_hi:[1,0]
	v_pk_mul_f32 v[40:41], v[40:41], v[24:25]
	v_cvt_pk_bf16_f32 v48, v40, v41
	v_lshlrev_b32_e32 v6, 16, v37
	v_and_b32_e32 v7, 0xffff0000, v37
	v_pk_mul_f32 v[6:7], v[6:7], v[252:253] op_sel_hi:[1,0]
	v_pk_mul_f32 v[6:7], v[6:7], v[26:27]
	v_cvt_pk_bf16_f32 v37, v6, v7
	v_lshlrev_b32_e32 v40, 16, v49
	v_and_b32_e32 v41, 0xffff0000, v49
	v_pk_mul_f32 v[40:41], v[40:41], v[254:255] op_sel_hi:[1,0]
	v_pk_mul_f32 v[40:41], v[40:41], v[26:27]
	v_cvt_pk_bf16_f32 v49, v40, v41
	v_lshlrev_b32_e32 v6, 16, v38
	v_and_b32_e32 v7, 0xffff0000, v38
	v_pk_mul_f32 v[6:7], v[6:7], v[252:253] op_sel_hi:[1,0]
	v_pk_mul_f32 v[6:7], v[6:7], v[28:29]
	v_cvt_pk_bf16_f32 v38, v6, v7
	v_lshlrev_b32_e32 v40, 16, v50
	v_and_b32_e32 v41, 0xffff0000, v50
	v_pk_mul_f32 v[40:41], v[40:41], v[254:255] op_sel_hi:[1,0]
	v_pk_mul_f32 v[40:41], v[40:41], v[28:29]
	v_cvt_pk_bf16_f32 v50, v40, v41
	v_lshlrev_b32_e32 v6, 16, v39
	v_and_b32_e32 v7, 0xffff0000, v39
	v_pk_mul_f32 v[6:7], v[6:7], v[252:253] op_sel_hi:[1,0]
	v_pk_mul_f32 v[6:7], v[6:7], v[30:31]
	v_cvt_pk_bf16_f32 v39, v6, v7
	v_lshlrev_b32_e32 v40, 16, v51
	v_and_b32_e32 v41, 0xffff0000, v51
	v_pk_mul_f32 v[40:41], v[40:41], v[254:255] op_sel_hi:[1,0]
	v_pk_mul_f32 v[40:41], v[40:41], v[30:31]
	v_cvt_pk_bf16_f32 v51, v40, v41
	global_store_dwordx4 v[4:5], v[32:35], off
	global_store_dwordx4 v[4:5], v[36:39], off offset:16
	global_store_dwordx4 v[4:5], v[44:47], off offset:2048
	global_store_dwordx4 v[4:5], v[48:51], off offset:2064
	v_lshl_add_u64 v[4:5], v[4:5], 0, s[100:101]
	s_nop 1
	s_waitcnt vmcnt(4)
	v_lshlrev_b32_e32 v6, 16, v52
	v_and_b32_e32 v7, 0xffff0000, v52
	v_pk_mul_f32 v[8:9], v[6:7], v[6:7]
	v_lshlrev_b32_e32 v40, 16, v60
	v_and_b32_e32 v41, 0xffff0000, v60
	v_pk_mul_f32 v[250:251], v[40:41], v[40:41]
	v_lshlrev_b32_e32 v6, 16, v53
	v_and_b32_e32 v7, 0xffff0000, v53
	v_pk_fma_f32 v[8:9], v[6:7], v[6:7], v[8:9]
	v_lshlrev_b32_e32 v40, 16, v61
	v_and_b32_e32 v41, 0xffff0000, v61
	v_pk_fma_f32 v[250:251], v[40:41], v[40:41], v[250:251]
	v_lshlrev_b32_e32 v6, 16, v54
	v_and_b32_e32 v7, 0xffff0000, v54
	v_pk_fma_f32 v[8:9], v[6:7], v[6:7], v[8:9]
	v_lshlrev_b32_e32 v40, 16, v62
	v_and_b32_e32 v41, 0xffff0000, v62
	v_pk_fma_f32 v[250:251], v[40:41], v[40:41], v[250:251]
	v_lshlrev_b32_e32 v6, 16, v55
	v_and_b32_e32 v7, 0xffff0000, v55
	v_pk_fma_f32 v[8:9], v[6:7], v[6:7], v[8:9]
	v_lshlrev_b32_e32 v40, 16, v63
	v_and_b32_e32 v41, 0xffff0000, v63
	v_pk_fma_f32 v[250:251], v[40:41], v[40:41], v[250:251]
	v_lshlrev_b32_e32 v6, 16, v56
	v_and_b32_e32 v7, 0xffff0000, v56
	v_pk_fma_f32 v[8:9], v[6:7], v[6:7], v[8:9]
	v_lshlrev_b32_e32 v40, 16, v64
	v_and_b32_e32 v41, 0xffff0000, v64
	v_pk_fma_f32 v[250:251], v[40:41], v[40:41], v[250:251]
	v_lshlrev_b32_e32 v6, 16, v57
	v_and_b32_e32 v7, 0xffff0000, v57
	v_pk_fma_f32 v[8:9], v[6:7], v[6:7], v[8:9]
	v_lshlrev_b32_e32 v40, 16, v65
	v_and_b32_e32 v41, 0xffff0000, v65
	v_pk_fma_f32 v[250:251], v[40:41], v[40:41], v[250:251]
	v_lshlrev_b32_e32 v6, 16, v58
	v_and_b32_e32 v7, 0xffff0000, v58
	v_pk_fma_f32 v[8:9], v[6:7], v[6:7], v[8:9]
	v_lshlrev_b32_e32 v40, 16, v66
	v_and_b32_e32 v41, 0xffff0000, v66
	v_pk_fma_f32 v[250:251], v[40:41], v[40:41], v[250:251]
	v_lshlrev_b32_e32 v6, 16, v59
	v_and_b32_e32 v7, 0xffff0000, v59
	v_pk_fma_f32 v[8:9], v[6:7], v[6:7], v[8:9]
	v_lshlrev_b32_e32 v40, 16, v67
	v_and_b32_e32 v41, 0xffff0000, v67
	v_pk_fma_f32 v[250:251], v[40:41], v[40:41], v[250:251]
	v_add_f32_e32 v8, v8, v9
	v_add_f32_e32 v250, v250, v251
	s_nop 1
	v_add_f32_dpp v8, v8, v8 quad_perm:[1,0,3,2] row_mask:0xf bank_mask:0xf
	v_add_f32_dpp v250, v250, v250 quad_perm:[1,0,3,2] row_mask:0xf bank_mask:0xf
	s_nop 1
	v_add_f32_dpp v8, v8, v8 quad_perm:[2,3,0,1] row_mask:0xf bank_mask:0xf
	v_add_f32_dpp v250, v250, v250 quad_perm:[2,3,0,1] row_mask:0xf bank_mask:0xf
	s_nop 1
	v_add_f32_dpp v8, v8, v8 row_half_mirror row_mask:0xf bank_mask:0xf
	v_add_f32_dpp v250, v250, v250 row_half_mirror row_mask:0xf bank_mask:0xf
	s_nop 1
	v_add_f32_dpp v8, v8, v8 row_mirror row_mask:0xf bank_mask:0xf
	v_add_f32_dpp v250, v250, v250 row_mirror row_mask:0xf bank_mask:0xf
	s_nop 1
	ds_bpermute_b32 v6, v14, v8
	ds_bpermute_b32 v40, v14, v250
	s_waitcnt lgkmcnt(0)
; DEVI int bid_() { int t = blockIdx.x; asm volatile("" : "+s"(t)); return t; }
; DEVI int gdim_() { int t = gridDim.x; asm volatile("" : "+s"(t)); return t; }
; DEVI unsigned pk2(float lo, float hi) { unsigned r; asm("v_cvt_pk_bf16_f32 %0, %1, %2" : "=v"(r) : "v"(lo), "v"(hi)); return r; }
; DEVI float bflo(unsigned w) { return __uint_as_float(w << 16); }
; DEVI float bfhi(unsigned w) { return __uint_as_float(w & 0xffff0000u); }
; DEVI void phase_m3(const Params& p, int l, unsigned char* smem) {
;     ...
;     for (int tile = bid_(); tile < NTILE; tile += gdim_()) {
;     ...
;             for (int tt = 0; tt < 16; ++tt) {
;                 const int t = wave * 16 + tt;
;                 bf16_t* rowp = mix + (size_t)(row0 + t) * DM + lane * 16;
;                 const u32x4 a = *(const u32x4*)rowp, b = *(const u32x4*)(rowp + 8);
;                 float v[16] = {bflo(a.x), bfhi(a.x), bflo(a.y), bfhi(a.y), bflo(a.z), bfhi(a.z), bflo(a.w), bfhi(a.w), bflo(b.x), bfhi(b.x), bflo(b.y), bfhi(b.y), bflo(b.z), bfhi(b.z), bflo(b.w), bfhi(b.w)};
;                 float ss = 0.f;
; #pragma unroll
;                 for (int e = 0; e < 16; ++e) ss += v[e] * v[e];
;                 ss += __shfl_xor(ss, 1); ss += __shfl_xor(ss, 2); ss += __shfl_xor(ss, 4); ss += __shfl_xor(ss, 8);
;                 const float s16 = __shfl_xor(ss, 16);
;                 float rn;
;                 if (lane < 32) rn = rsqrtf((ss + s16) * (1.0f / 512.0f) + RMS_EPS); else rn = rsqrtf(ss * (1.0f / 256.0f) + RMS_EPS);
;                 const f32x4 g0 = *(const f32x4*)(gain + lane * 16), g1 = *(const f32x4*)(gain + lane * 16 + 4), g2 = *(const f32x4*)(gain + lane * 16 + 8), g3 = *(const f32x4*)(gain + lane * 16 + 12);
;                 u32x4 o1, o2;
;                 o1.x = pk2(v[0] * rn * g0[0], v[1] * rn * g0[1]); o1.y = pk2(v[2] * rn * g0[2], v[3] * rn * g0[3]); o1.z = pk2(v[4] * rn * g1[0], v[5] * rn * g1[1]); o1.w = pk2(v[6] * rn * g1[2], v[7] * rn * g1[3]);
;                 o2.x = pk2(v[8] * rn * g2[0], v[9] * rn * g2[1]); o2.y = pk2(v[10] * rn * g2[2], v[11] * rn * g2[3]); o2.z = pk2(v[12] * rn * g3[0], v[13] * rn * g3[1]); o2.w = pk2(v[14] * rn * g3[2], v[15] * rn * g3[3]);
;                 *(u32x4*)rowp = o1; *(u32x4*)(rowp + 8) = o2;
;             }
	v_add_f32_e32 v6, v8, v6
	v_mul_f32_e32 v6, 0x3b000000, v6
	v_mul_f32_e32 v8, 0x3b800000, v8
	v_cndmask_b32_e64 v8, v8, v6, s[6:7]
	v_add_f32_e32 v8, 0x358637bd, v8
	v_rsq_f32_e32 v252, v8
	v_add_f32_e32 v40, v250, v40
	v_mul_f32_e32 v40, 0x3b000000, v40
	v_mul_f32_e32 v250, 0x3b800000, v250
	v_cndmask_b32_e64 v250, v250, v40, s[6:7]
	v_add_f32_e32 v250, 0x358637bd, v250
	v_rsq_f32_e32 v254, v250
	s_nop 1
	v_lshlrev_b32_e32 v6, 16, v52
	v_and_b32_e32 v7, 0xffff0000, v52
	v_pk_mul_f32 v[6:7], v[6:7], v[252:253] op_sel_hi:[1,0]
	v_pk_mul_f32 v[6:7], v[6:7], v[16:17]
	v_cvt_pk_bf16_f32 v52, v6, v7
	v_lshlrev_b32_e32 v40, 16, v60
	v_and_b32_e32 v41, 0xffff0000, v60
	v_pk_mul_f32 v[40:41], v[40:41], v[254:255] op_sel_hi:[1,0]
	v_pk_mul_f32 v[40:41], v[40:41], v[16:17]
	v_cvt_pk_bf16_f32 v60, v40, v41
	v_lshlrev_b32_e32 v6, 16, v53
	v_and_b32_e32 v7, 0xffff0000, v53
	v_pk_mul_f32 v[6:7], v[6:7], v[252:253] op_sel_hi:[1,0]
	v_pk_mul_f32 v[6:7], v[6:7], v[18:19]
	v_cvt_pk_bf16_f32 v53, v6, v7
	v_lshlrev_b32_e32 v40, 16, v61
	v_and_b32_e32 v41, 0xffff0000, v61
	v_pk_mul_f32 v[40:41], v[40:41], v[254:255] op_sel_hi:[1,0]
	v_pk_mul_f32 v[40:41], v[40:41], v[18:19]
	v_cvt_pk_bf16_f32 v61, v40, v41
	v_lshlrev_b32_e32 v6, 16, v54
	v_and_b32_e32 v7, 0xffff0000, v54
	v_pk_mul_f32 v[6:7], v[6:7], v[252:253] op_sel_hi:[1,0]
	v_pk_mul_f32 v[6:7], v[6:7], v[20:21]
	v_cvt_pk_bf16_f32 v54, v6, v7
	v_lshlrev_b32_e32 v40, 16, v62
	v_and_b32_e32 v41, 0xffff0000, v62
	v_pk_mul_f32 v[40:41], v[40:41], v[254:255] op_sel_hi:[1,0]
	v_pk_mul_f32 v[40:41], v[40:41], v[20:21]
	v_cvt_pk_bf16_f32 v62, v40, v41
	v_lshlrev_b32_e32 v6, 16, v55
	v_and_b32_e32 v7, 0xffff0000, v55
	v_pk_mul_f32 v[6:7], v[6:7], v[252:253] op_sel_hi:[1,0]
	v_pk_mul_f32 v[6:7], v[6:7], v[22:23]
	v_cvt_pk_bf16_f32 v55, v6, v7
	v_lshlrev_b32_e32 v40, 16, v63
	v_and_b32_e32 v41, 0xffff0000, v63
	v_pk_mul_f32 v[40:41], v[40:41], v[254:255] op_sel_hi:[1,0]
	v_pk_mul_f32 v[40:41], v[40:41], v[22:23]
	v_cvt_pk_bf16_f32 v63, v40, v41
	v_lshlrev_b32_e32 v6, 16, v56
	v_and_b32_e32 v7, 0xffff0000, v56
	v_pk_mul_f32 v[6:7], v[6:7], v[252:253] op_sel_hi:[1,0]
	v_pk_mul_f32 v[6:7], v[6:7], v[24:25]
	v_cvt_pk_bf16_f32 v56, v6, v7
	v_lshlrev_b32_e32 v40, 16, v64
	v_and_b32_e32 v41, 0xffff0000, v64
	v_pk_mul_f32 v[40:41], v[40:41], v[254:255] op_sel_hi:[1,0]
	v_pk_mul_f32 v[40:41], v[40:41], v[24:25]
	v_cvt_pk_bf16_f32 v64, v40, v41
	v_lshlrev_b32_e32 v6, 16, v57
	v_and_b32_e32 v7, 0xffff0000, v57
	v_pk_mul_f32 v[6:7], v[6:7], v[252:253] op_sel_hi:[1,0]
	v_pk_mul_f32 v[6:7], v[6:7], v[26:27]
	v_cvt_pk_bf16_f32 v57, v6, v7
	v_lshlrev_b32_e32 v40, 16, v65
	v_and_b32_e32 v41, 0xffff0000, v65
	v_pk_mul_f32 v[40:41], v[40:41], v[254:255] op_sel_hi:[1,0]
	v_pk_mul_f32 v[40:41], v[40:41], v[26:27]
	v_cvt_pk_bf16_f32 v65, v40, v41
	v_lshlrev_b32_e32 v6, 16, v58
	v_and_b32_e32 v7, 0xffff0000, v58
	v_pk_mul_f32 v[6:7], v[6:7], v[252:253] op_sel_hi:[1,0]
	v_pk_mul_f32 v[6:7], v[6:7], v[28:29]
	v_cvt_pk_bf16_f32 v58, v6, v7
	v_lshlrev_b32_e32 v40, 16, v66
	v_and_b32_e32 v41, 0xffff0000, v66
	v_pk_mul_f32 v[40:41], v[40:41], v[254:255] op_sel_hi:[1,0]
	v_pk_mul_f32 v[40:41], v[40:41], v[28:29]
	v_cvt_pk_bf16_f32 v66, v40, v41
	v_lshlrev_b32_e32 v6, 16, v59
	v_and_b32_e32 v7, 0xffff0000, v59
	v_pk_mul_f32 v[6:7], v[6:7], v[252:253] op_sel_hi:[1,0]
	v_pk_mul_f32 v[6:7], v[6:7], v[30:31]
	v_cvt_pk_bf16_f32 v59, v6, v7
	v_lshlrev_b32_e32 v40, 16, v67
	v_and_b32_e32 v41, 0xffff0000, v67
	v_pk_mul_f32 v[40:41], v[40:41], v[254:255] op_sel_hi:[1,0]
	v_pk_mul_f32 v[40:41], v[40:41], v[30:31]
	v_cvt_pk_bf16_f32 v67, v40, v41
	global_store_dwordx4 v[4:5], v[52:55], off
	global_store_dwordx4 v[4:5], v[56:59], off offset:16
	global_store_dwordx4 v[4:5], v[60:63], off offset:2048
	global_store_dwordx4 v[4:5], v[64:67], off offset:2064
	v_lshl_add_u64 v[4:5], v[4:5], 0, s[100:101]
	s_nop 1
	s_nop 1
	ds_read_b128 v[44:47], v15
	ds_read_b128 v[48:51], v15 offset:8192
	ds_read_b128 v[52:55], v15 offset:16384
	ds_read_b128 v[56:59], v15 offset:24576
	ds_read_b128 v[60:63], v15 offset:32768
	ds_read_b128 v[64:67], v15 offset:40960
	s_mov_b64 s[72:73], 0x8000
	s_mov_b32 s1, 0x800000
	s_cmpk_eq_u32 s72, 0x8000
	s_waitcnt lgkmcnt(0)
	s_mov_b32 s1, s89
	s_barrier
	s_add_i32 s0, s1, s0
	s_cmpk_gt_i32 s0, 0xff
	s_cbranch_scc0 .LBB0_2519

; __global__ void __launch_bounds__(512, 2) mega_all(Params p) {
	.amdhsa_kernel _Z8mega_all6Params
		.amdhsa_group_segment_fixed_size 0
		.amdhsa_private_segment_fixed_size 0
		.amdhsa_kernarg_size 536
		.amdhsa_user_sgpr_count 2
		.amdhsa_user_sgpr_dispatch_ptr 0
		.amdhsa_user_sgpr_queue_ptr 0
		.amdhsa_user_sgpr_kernarg_segment_ptr 1
		.amdhsa_user_sgpr_dispatch_id 0
		.amdhsa_user_sgpr_kernarg_preload_length 0
		.amdhsa_user_sgpr_kernarg_preload_offset 0
		.amdhsa_user_sgpr_private_segment_size 0
		.amdhsa_uses_dynamic_stack 0
		.amdhsa_enable_private_segment 0
		.amdhsa_system_sgpr_workgroup_id_x 1
		.amdhsa_system_sgpr_workgroup_id_y 0
		.amdhsa_system_sgpr_workgroup_id_z 0
		.amdhsa_system_sgpr_workgroup_info 0
		.amdhsa_system_vgpr_workitem_id 2
		.amdhsa_next_free_vgpr 256
		.amdhsa_next_free_sgpr 102
		.amdhsa_accum_offset 256
		.amdhsa_reserve_vcc 1
		.amdhsa_float_round_mode_32 0
		.amdhsa_float_round_mode_16_64 0
		.amdhsa_float_denorm_mode_32 3
		.amdhsa_float_denorm_mode_16_64 3
		.amdhsa_dx10_clamp 1
		.amdhsa_ieee_mode 1
		.amdhsa_fp16_overflow 0
		.amdhsa_tg_split 0
		.amdhsa_exception_fp_ieee_invalid_op 0
		.amdhsa_exception_fp_denorm_src 0
		.amdhsa_exception_fp_ieee_div_zero 0
		.amdhsa_exception_fp_ieee_overflow 0
		.amdhsa_exception_fp_ieee_underflow 0
		.amdhsa_exception_fp_ieee_inexact 0
		.amdhsa_exception_int_div_zero 0
	.end_amdhsa_kernel

; __global__ void __launch_bounds__(512, 2) mega_all(Params p) {
amdhsa.kernels:
  - .agpr_count:     0
    .args:
      - .offset:         0
        .size:           280
        .value_kind:     by_value
      - .offset:         280
        .size:           4
        .value_kind:     hidden_block_count_x
      - .offset:         284
        .size:           4
        .value_kind:     hidden_block_count_y
      - .offset:         288
        .size:           4
        .value_kind:     hidden_block_count_z
      - .offset:         292
        .size:           2
        .value_kind:     hidden_group_size_x
      - .offset:         294
        .size:           2
        .value_kind:     hidden_group_size_y
      - .offset:         296
        .size:           2
        .value_kind:     hidden_group_size_z
      - .offset:         298
        .size:           2
        .value_kind:     hidden_remainder_x
      - .offset:         300
        .size:           2
        .value_kind:     hidden_remainder_y
      - .offset:         302
        .size:           2
        .value_kind:     hidden_remainder_z
      - .offset:         320
        .size:           8
        .value_kind:     hidden_global_offset_x
      - .offset:         328
        .size:           8
        .value_kind:     hidden_global_offset_y
      - .offset:         336
        .size:           8
        .value_kind:     hidden_global_offset_z
      - .offset:         344
        .size:           2
        .value_kind:     hidden_grid_dims
      - .offset:         368
        .size:           8
        .value_kind:     hidden_multigrid_sync_arg
      - .offset:         400
        .size:           4
        .value_kind:     hidden_dynamic_lds_size
    .group_segment_fixed_size: 0
    .kernarg_segment_align: 8
    .kernarg_segment_size: 536
    .language:       OpenCL C
    .language_version:
      - 2
      - 0
    .max_flat_workgroup_size: 512
    .name:           _Z8mega_all6Params
    .private_segment_fixed_size: 0
    .sgpr_count:     108
    .sgpr_spill_count: 79
    .symbol:         _Z8mega_all6Params.kd
    .uniform_work_group_size: 1
    .uses_dynamic_stack: false
    .vgpr_count:     256
    .vgpr_spill_count: 0
    .wavefront_size: 64
